# P3 sample state stream regenerated with a 20-quad load ring (both copies) + P4 pipelined, aligned
# baseline (speedup 1.0000x reference)
; #define LAS __attribute__((address_space(3)))
; #define RS_LOAD(dst, it0) do { _Pragma("unroll") for (int u = 0; u < 8; ++u) dst[u] = __builtin_nontemporal_load((const f32x4*)(S0 + (size_t)(4 * ((it0) + u)) * DV)); } while (0)
; __device__ __forceinline__ void ret_sample_item(Frame& F, int item) {
;     ...
;     const float gam = 1.0f - exp2f(-5.0f - (float)h);
;     const float g7 = exp2f(7.0f * log2f(gam)), g8 = g7 * gam;
;     const int r0 = MP + 8 * b;
;     LAS float* qs = (LAS float*)(F.lds + SQ_OFF); LAS float* kt = (LAS float*)(F.lds + SK_OFF); LAS float* vs = (LAS float*)(F.lds + SV_OFF);
;     ...
;     f32x4 v4[8];
; #pragma unroll
;     for (int m = 0; m < 8; ++m) v4[m] = *(const LAS f32x4*)(vs + m * 512 + e4);
;     f32x4 oacc[4];
; #pragma unroll
;     for (int i = 0; i < 4; ++i) oacc[i] = (f32x4){0.f, 0.f, 0.f, 0.f};
;     ...
;     for (int it0 = 0; it0 < 64; it0 += 16) {
;         RS_LOAD(sb, it0 + 8);
;         RS_PROC(sa, it0);
;         { const int itn = it0 + 16 < 64 ? it0 + 16 : it0; RS_LOAD(sa, itn); }
.LBB0_584:
	s_or_b64 exec, exec, s[78:79]
	v_cvt_f32_ubyte0_e32 v2, s10
	v_sub_f32_e32 v2, 0xc0a00000, v2
	v_cmp_gt_f32_e32 vcc, s82, v2
	s_and_b64 s[68:69], vcc, exec
	s_cselect_b32 s10, 0xffffffc0, 0
	v_cndmask_b32_e32 v3, 0, v169, vcc
	v_add_f32_e32 v2, v2, v3
	v_exp_f32_e32 v2, v2
	s_waitcnt lgkmcnt(0)
	s_barrier
	v_ldexp_f32 v2, v2, s10
	v_sub_f32_e32 v138, 1.0, v2
	v_cmp_gt_f32_e32 vcc, s83, v138
	s_and_b64 s[68:69], vcc, exec
	s_cselect_b32 s10, 32, 0
	v_ldexp_f32 v3, v138, s10
	v_log_f32_e32 v3, v3
	v_cndmask_b32_e32 v2, 0, v170, vcc
	v_mov_b32_e32 v98, 0
	s_mov_b32 s10, 0
	v_sub_f32_e32 v2, v3, v2
	v_mul_f32_e32 v3, 0x40e00000, v2
	v_cmp_gt_f32_e32 vcc, s82, v3
	s_and_b64 s[68:69], vcc, exec
	s_cselect_b32 s22, 0xffffffc0, 0
	v_cndmask_b32_e32 v3, 0, v169, vcc
	v_fmac_f32_e32 v3, 0x40e00000, v2
	v_exp_f32_e32 v2, v3
	v_mov_b64_e32 v[148:149], v[130:131]
	v_mov_b64_e32 v[150:151], v[128:129]
	v_mov_b32_e32 v171, v161
	v_ldexp_f32 v140, v2, s22
	ds_read_b128 v[30:33], v139 offset:16512
	ds_read_b128 v[26:29], v139 offset:18560
	ds_read_b128 v[22:25], v139 offset:20608
	ds_read_b128 v[18:21], v139 offset:22656
	ds_read_b128 v[14:17], v139 offset:24704
	ds_read_b128 v[10:13], v139 offset:26752
	ds_read_b128 v[6:9], v139 offset:28800
	ds_read_b128 v[2:5], v139 offset:30848
	v_mul_f32_e32 v142, v138, v140
	v_mov_b32_e32 v144, v142
	v_mov_b32_e32 v145, v142
	v_mov_b32_e32 v146, v140
	v_mov_b32_e32 v147, v140
	v_mov_b32_e32 v172, v160
	v_mov_b32_e32 v99, v98
	v_mov_b32_e32 v100, v98
	v_mov_b32_e32 v101, v98
	v_mov_b32_e32 v102, v98
	v_mov_b32_e32 v103, v98
	v_mov_b32_e32 v104, v98
	v_mov_b32_e32 v105, v98
	v_mov_b32_e32 v106, v98
	v_mov_b32_e32 v107, v98
	v_mov_b32_e32 v108, v98
	v_mov_b32_e32 v109, v98
	v_mov_b32_e32 v110, v98
	v_mov_b32_e32 v111, v98
	v_mov_b32_e32 v112, v98
	v_mov_b32_e32 v113, v98
	v_lshl_add_u64 v[148:149], v[130:131], 0, v[122:123]
	v_lshl_add_u64 v[150:151], v[128:129], 0, v[122:123]
	s_mov_b32 s74, 0x10000
	s_mov_b32 s75, 0
	v_add_co_u32_e32 v150, vcc, 0x5878000, v150
	v_lshl_add_u64 v[148:149], v[148:149], 0, s[74:75]
	s_mov_b32 s74, 0x2000
	v_addc_co_u32_e32 v151, vcc, 0, v151, vcc
	ds_read_b32 v141, v160
	ds_read_b128 v[114:117], v161
	ds_read_b128 v[176:179], v161 offset:16
	global_load_dwordx4 v[58:61], v[148:149], off nt
	v_lshl_add_u64 v[148:149], v[148:149], 0, s[74:75]
	global_load_dwordx4 v[66:69], v[148:149], off nt
	v_lshl_add_u64 v[148:149], v[148:149], 0, s[74:75]
	global_load_dwordx4 v[74:77], v[148:149], off nt
	v_lshl_add_u64 v[148:149], v[148:149], 0, s[74:75]
	global_load_dwordx4 v[78:81], v[148:149], off nt
	v_lshl_add_u64 v[148:149], v[148:149], 0, s[74:75]
	global_load_dwordx4 v[82:85], v[148:149], off nt
	v_lshl_add_u64 v[148:149], v[148:149], 0, s[74:75]
	global_load_dwordx4 v[86:89], v[148:149], off nt
	v_lshl_add_u64 v[148:149], v[148:149], 0, s[74:75]
	global_load_dwordx4 v[90:93], v[148:149], off nt
	v_lshl_add_u64 v[148:149], v[148:149], 0, s[74:75]
	global_load_dwordx4 v[94:97], v[148:149], off nt
	v_lshl_add_u64 v[148:149], v[148:149], 0, s[74:75]
	global_load_dwordx4 v[212:215], v[148:149], off nt
	v_lshl_add_u64 v[148:149], v[148:149], 0, s[74:75]
	global_load_dwordx4 v[216:219], v[148:149], off nt
	v_lshl_add_u64 v[148:149], v[148:149], 0, s[74:75]
	global_load_dwordx4 v[224:227], v[148:149], off nt
	v_lshl_add_u64 v[148:149], v[148:149], 0, s[74:75]
	global_load_dwordx4 v[228:231], v[148:149], off nt
	v_lshl_add_u64 v[148:149], v[148:149], 0, s[74:75]
	ds_read_b32 v143, v160 offset:16
	ds_read_b128 v[172:175], v161 offset:128
	ds_read_b128 v[232:235], v161 offset:144
	s_waitcnt lgkmcnt(3)
	v_cndmask_b32_e64 v141, 0, v141, s[8:9]
	v_pk_mul_f32 v[180:181], v[26:27], v[114:115] op_sel:[0,1]
	v_pk_mul_f32 v[192:193], v[28:29], v[114:115] op_sel:[0,1]
	v_mfma_f32_16x16x4_f32 v[110:113], v141, v70, v[110:113]
	v_pk_fma_f32 v[180:181], v[30:31], v[114:115], v[180:181] op_sel_hi:[1,0,1]
	v_pk_fma_f32 v[192:193], v[32:33], v[114:115], v[192:193] op_sel_hi:[1,0,1]
	v_pk_fma_f32 v[180:181], v[22:23], v[116:117], v[180:181] op_sel_hi:[1,0,1]
	v_pk_fma_f32 v[192:193], v[24:25], v[116:117], v[192:193] op_sel_hi:[1,0,1]
	v_mfma_f32_16x16x4_f32 v[106:109], v141, v71, v[106:109]
	v_pk_fma_f32 v[180:181], v[18:19], v[116:117], v[180:181] op_sel:[0,1,0]
	v_pk_fma_f32 v[192:193], v[20:21], v[116:117], v[192:193] op_sel:[0,1,0]
	v_pk_fma_f32 v[180:181], v[14:15], v[176:177], v[180:181] op_sel_hi:[1,0,1]
	v_pk_fma_f32 v[192:193], v[16:17], v[176:177], v[192:193] op_sel_hi:[1,0,1]
	v_mfma_f32_16x16x4_f32 v[102:105], v141, v72, v[102:105]
	v_pk_fma_f32 v[180:181], v[10:11], v[176:177], v[180:181] op_sel:[0,1,0]
	v_pk_fma_f32 v[192:193], v[12:13], v[176:177], v[192:193] op_sel:[0,1,0]
	v_pk_fma_f32 v[180:181], v[6:7], v[178:179], v[180:181] op_sel_hi:[1,0,1]
	v_pk_fma_f32 v[192:193], v[8:9], v[178:179], v[192:193] op_sel_hi:[1,0,1]
	v_mfma_f32_16x16x4_f32 v[98:101], v141, v73, v[98:101]
	v_pk_fma_f32 v[180:181], v[2:3], v[178:179], v[180:181] op_sel:[0,1,0]
	v_pk_fma_f32 v[192:193], v[4:5], v[178:179], v[192:193] op_sel:[0,1,0]
	v_pk_mul_f32 v[180:181], v[146:147], v[180:181]
	v_pk_mul_f32 v[192:193], v[146:147], v[192:193]
	v_pk_fma_f32 v[236:237], v[144:145], v[70:71], v[180:181]
	v_pk_fma_f32 v[238:239], v[144:145], v[72:73], v[192:193]
	global_store_dwordx4 v[150:151], v[236:239], off nt
	v_lshl_add_u64 v[150:151], v[150:151], 0, s[74:75]
	global_load_dwordx4 v[70:73], v[148:149], off nt
	v_lshl_add_u64 v[148:149], v[148:149], 0, s[74:75]
	ds_read_b32 v141, v160 offset:32
	ds_read_b128 v[114:117], v161 offset:256
	ds_read_b128 v[176:179], v161 offset:272
	s_waitcnt lgkmcnt(3)
; #define RS_LOAD(dst, it0) do { _Pragma("unroll") for (int u = 0; u < 8; ++u) dst[u] = __builtin_nontemporal_load((const f32x4*)(S0 + (size_t)(4 * ((it0) + u)) * DV)); } while (0)
; __device__ __forceinline__ void ret_sample_item(Frame& F, int item) {
;     ...
;     for (int it0 = 0; it0 < 64; it0 += 16) {
;         RS_LOAD(sb, it0 + 8);
;         RS_PROC(sa, it0);
;         { const int itn = it0 + 16 < 64 ? it0 + 16 : it0; RS_LOAD(sa, itn); }
	v_cndmask_b32_e64 v143, 0, v143, s[8:9]
	v_pk_mul_f32 v[180:181], v[26:27], v[172:173] op_sel:[0,1]
	v_pk_mul_f32 v[192:193], v[28:29], v[172:173] op_sel:[0,1]
	v_mfma_f32_16x16x4_f32 v[110:113], v143, v62, v[110:113]
	v_pk_fma_f32 v[180:181], v[30:31], v[172:173], v[180:181] op_sel_hi:[1,0,1]
	v_pk_fma_f32 v[192:193], v[32:33], v[172:173], v[192:193] op_sel_hi:[1,0,1]
	v_pk_fma_f32 v[180:181], v[22:23], v[174:175], v[180:181] op_sel_hi:[1,0,1]
	v_pk_fma_f32 v[192:193], v[24:25], v[174:175], v[192:193] op_sel_hi:[1,0,1]
	v_mfma_f32_16x16x4_f32 v[106:109], v143, v63, v[106:109]
	v_pk_fma_f32 v[180:181], v[18:19], v[174:175], v[180:181] op_sel:[0,1,0]
	v_pk_fma_f32 v[192:193], v[20:21], v[174:175], v[192:193] op_sel:[0,1,0]
	v_pk_fma_f32 v[180:181], v[14:15], v[232:233], v[180:181] op_sel_hi:[1,0,1]
	v_pk_fma_f32 v[192:193], v[16:17], v[232:233], v[192:193] op_sel_hi:[1,0,1]
	v_mfma_f32_16x16x4_f32 v[102:105], v143, v64, v[102:105]
	v_pk_fma_f32 v[180:181], v[10:11], v[232:233], v[180:181] op_sel:[0,1,0]
	v_pk_fma_f32 v[192:193], v[12:13], v[232:233], v[192:193] op_sel:[0,1,0]
	v_pk_fma_f32 v[180:181], v[6:7], v[234:235], v[180:181] op_sel_hi:[1,0,1]
	v_pk_fma_f32 v[192:193], v[8:9], v[234:235], v[192:193] op_sel_hi:[1,0,1]
	v_mfma_f32_16x16x4_f32 v[98:101], v143, v65, v[98:101]
	v_pk_fma_f32 v[180:181], v[2:3], v[234:235], v[180:181] op_sel:[0,1,0]
	v_pk_fma_f32 v[192:193], v[4:5], v[234:235], v[192:193] op_sel:[0,1,0]
	v_pk_mul_f32 v[180:181], v[146:147], v[180:181]
	v_pk_mul_f32 v[192:193], v[146:147], v[192:193]
	v_pk_fma_f32 v[236:237], v[144:145], v[62:63], v[180:181]
	v_pk_fma_f32 v[238:239], v[144:145], v[64:65], v[192:193]
	global_store_dwordx4 v[150:151], v[236:239], off nt
	v_lshl_add_u64 v[150:151], v[150:151], 0, s[74:75]
	global_load_dwordx4 v[62:65], v[148:149], off nt
	v_lshl_add_u64 v[148:149], v[148:149], 0, s[74:75]
	ds_read_b32 v143, v160 offset:48
	ds_read_b128 v[172:175], v161 offset:384
	ds_read_b128 v[232:235], v161 offset:400
	s_waitcnt lgkmcnt(3)
	v_cndmask_b32_e64 v141, 0, v141, s[8:9]
	v_pk_mul_f32 v[180:181], v[26:27], v[114:115] op_sel:[0,1]
	v_pk_mul_f32 v[192:193], v[28:29], v[114:115] op_sel:[0,1]
	v_mfma_f32_16x16x4_f32 v[110:113], v141, v54, v[110:113]
	v_pk_fma_f32 v[180:181], v[30:31], v[114:115], v[180:181] op_sel_hi:[1,0,1]
	v_pk_fma_f32 v[192:193], v[32:33], v[114:115], v[192:193] op_sel_hi:[1,0,1]
	v_pk_fma_f32 v[180:181], v[22:23], v[116:117], v[180:181] op_sel_hi:[1,0,1]
	v_pk_fma_f32 v[192:193], v[24:25], v[116:117], v[192:193] op_sel_hi:[1,0,1]
	v_mfma_f32_16x16x4_f32 v[106:109], v141, v55, v[106:109]
	v_pk_fma_f32 v[180:181], v[18:19], v[116:117], v[180:181] op_sel:[0,1,0]
	v_pk_fma_f32 v[192:193], v[20:21], v[116:117], v[192:193] op_sel:[0,1,0]
	v_pk_fma_f32 v[180:181], v[14:15], v[176:177], v[180:181] op_sel_hi:[1,0,1]
	v_pk_fma_f32 v[192:193], v[16:17], v[176:177], v[192:193] op_sel_hi:[1,0,1]
	v_mfma_f32_16x16x4_f32 v[102:105], v141, v56, v[102:105]
	v_pk_fma_f32 v[180:181], v[10:11], v[176:177], v[180:181] op_sel:[0,1,0]
	v_pk_fma_f32 v[192:193], v[12:13], v[176:177], v[192:193] op_sel:[0,1,0]
	v_pk_fma_f32 v[180:181], v[6:7], v[178:179], v[180:181] op_sel_hi:[1,0,1]
	v_pk_fma_f32 v[192:193], v[8:9], v[178:179], v[192:193] op_sel_hi:[1,0,1]
	v_mfma_f32_16x16x4_f32 v[98:101], v141, v57, v[98:101]
	v_pk_fma_f32 v[180:181], v[2:3], v[178:179], v[180:181] op_sel:[0,1,0]
	v_pk_fma_f32 v[192:193], v[4:5], v[178:179], v[192:193] op_sel:[0,1,0]
	v_pk_mul_f32 v[180:181], v[146:147], v[180:181]
	v_pk_mul_f32 v[192:193], v[146:147], v[192:193]
	v_pk_fma_f32 v[236:237], v[144:145], v[54:55], v[180:181]
	v_pk_fma_f32 v[238:239], v[144:145], v[56:57], v[192:193]
	global_store_dwordx4 v[150:151], v[236:239], off nt
	v_lshl_add_u64 v[150:151], v[150:151], 0, s[74:75]
	global_load_dwordx4 v[54:57], v[148:149], off nt
	v_lshl_add_u64 v[148:149], v[148:149], 0, s[74:75]
	ds_read_b32 v141, v160 offset:64
	ds_read_b128 v[114:117], v161 offset:512
	ds_read_b128 v[176:179], v161 offset:528
	s_waitcnt lgkmcnt(3)
	v_cndmask_b32_e64 v143, 0, v143, s[8:9]
	v_pk_mul_f32 v[180:181], v[26:27], v[172:173] op_sel:[0,1]
	v_pk_mul_f32 v[192:193], v[28:29], v[172:173] op_sel:[0,1]
	v_mfma_f32_16x16x4_f32 v[110:113], v143, v50, v[110:113]
	v_pk_fma_f32 v[180:181], v[30:31], v[172:173], v[180:181] op_sel_hi:[1,0,1]
	v_pk_fma_f32 v[192:193], v[32:33], v[172:173], v[192:193] op_sel_hi:[1,0,1]
	v_pk_fma_f32 v[180:181], v[22:23], v[174:175], v[180:181] op_sel_hi:[1,0,1]
	v_pk_fma_f32 v[192:193], v[24:25], v[174:175], v[192:193] op_sel_hi:[1,0,1]
	v_mfma_f32_16x16x4_f32 v[106:109], v143, v51, v[106:109]
	v_pk_fma_f32 v[180:181], v[18:19], v[174:175], v[180:181] op_sel:[0,1,0]
	v_pk_fma_f32 v[192:193], v[20:21], v[174:175], v[192:193] op_sel:[0,1,0]
	v_pk_fma_f32 v[180:181], v[14:15], v[232:233], v[180:181] op_sel_hi:[1,0,1]
	v_pk_fma_f32 v[192:193], v[16:17], v[232:233], v[192:193] op_sel_hi:[1,0,1]
	v_mfma_f32_16x16x4_f32 v[102:105], v143, v52, v[102:105]
	v_pk_fma_f32 v[180:181], v[10:11], v[232:233], v[180:181] op_sel:[0,1,0]
	v_pk_fma_f32 v[192:193], v[12:13], v[232:233], v[192:193] op_sel:[0,1,0]
	v_pk_fma_f32 v[180:181], v[6:7], v[234:235], v[180:181] op_sel_hi:[1,0,1]
	v_pk_fma_f32 v[192:193], v[8:9], v[234:235], v[192:193] op_sel_hi:[1,0,1]
	v_mfma_f32_16x16x4_f32 v[98:101], v143, v53, v[98:101]
	v_pk_fma_f32 v[180:181], v[2:3], v[234:235], v[180:181] op_sel:[0,1,0]
	v_pk_fma_f32 v[192:193], v[4:5], v[234:235], v[192:193] op_sel:[0,1,0]
	v_pk_mul_f32 v[180:181], v[146:147], v[180:181]
	v_pk_mul_f32 v[192:193], v[146:147], v[192:193]
	v_pk_fma_f32 v[236:237], v[144:145], v[50:51], v[180:181]
	v_pk_fma_f32 v[238:239], v[144:145], v[52:53], v[192:193]
	global_store_dwordx4 v[150:151], v[236:239], off nt
	v_lshl_add_u64 v[150:151], v[150:151], 0, s[74:75]
	global_load_dwordx4 v[50:53], v[148:149], off nt
	v_lshl_add_u64 v[148:149], v[148:149], 0, s[74:75]
	ds_read_b32 v143, v160 offset:80
	ds_read_b128 v[172:175], v161 offset:640
	ds_read_b128 v[232:235], v161 offset:656
	s_waitcnt lgkmcnt(3)
; #define RS_LOAD(dst, it0) do { _Pragma("unroll") for (int u = 0; u < 8; ++u) dst[u] = __builtin_nontemporal_load((const f32x4*)(S0 + (size_t)(4 * ((it0) + u)) * DV)); } while (0)
; __device__ __forceinline__ void ret_sample_item(Frame& F, int item) {
;     ...
;     for (int it0 = 0; it0 < 64; it0 += 16) {
;         RS_LOAD(sb, it0 + 8);
;         RS_PROC(sa, it0);
;         { const int itn = it0 + 16 < 64 ? it0 + 16 : it0; RS_LOAD(sa, itn); }
	v_cndmask_b32_e64 v141, 0, v141, s[8:9]
	v_pk_mul_f32 v[180:181], v[26:27], v[114:115] op_sel:[0,1]
	v_pk_mul_f32 v[192:193], v[28:29], v[114:115] op_sel:[0,1]
	v_mfma_f32_16x16x4_f32 v[110:113], v141, v46, v[110:113]
	v_pk_fma_f32 v[180:181], v[30:31], v[114:115], v[180:181] op_sel_hi:[1,0,1]
	v_pk_fma_f32 v[192:193], v[32:33], v[114:115], v[192:193] op_sel_hi:[1,0,1]
	v_pk_fma_f32 v[180:181], v[22:23], v[116:117], v[180:181] op_sel_hi:[1,0,1]
	v_pk_fma_f32 v[192:193], v[24:25], v[116:117], v[192:193] op_sel_hi:[1,0,1]
	v_mfma_f32_16x16x4_f32 v[106:109], v141, v47, v[106:109]
	v_pk_fma_f32 v[180:181], v[18:19], v[116:117], v[180:181] op_sel:[0,1,0]
	v_pk_fma_f32 v[192:193], v[20:21], v[116:117], v[192:193] op_sel:[0,1,0]
	v_pk_fma_f32 v[180:181], v[14:15], v[176:177], v[180:181] op_sel_hi:[1,0,1]
	v_pk_fma_f32 v[192:193], v[16:17], v[176:177], v[192:193] op_sel_hi:[1,0,1]
	v_mfma_f32_16x16x4_f32 v[102:105], v141, v48, v[102:105]
	v_pk_fma_f32 v[180:181], v[10:11], v[176:177], v[180:181] op_sel:[0,1,0]
	v_pk_fma_f32 v[192:193], v[12:13], v[176:177], v[192:193] op_sel:[0,1,0]
	v_pk_fma_f32 v[180:181], v[6:7], v[178:179], v[180:181] op_sel_hi:[1,0,1]
	v_pk_fma_f32 v[192:193], v[8:9], v[178:179], v[192:193] op_sel_hi:[1,0,1]
	v_mfma_f32_16x16x4_f32 v[98:101], v141, v49, v[98:101]
	v_pk_fma_f32 v[180:181], v[2:3], v[178:179], v[180:181] op_sel:[0,1,0]
	v_pk_fma_f32 v[192:193], v[4:5], v[178:179], v[192:193] op_sel:[0,1,0]
	v_pk_mul_f32 v[180:181], v[146:147], v[180:181]
	v_pk_mul_f32 v[192:193], v[146:147], v[192:193]
	v_pk_fma_f32 v[236:237], v[144:145], v[46:47], v[180:181]
	v_pk_fma_f32 v[238:239], v[144:145], v[48:49], v[192:193]
	global_store_dwordx4 v[150:151], v[236:239], off nt
	v_lshl_add_u64 v[150:151], v[150:151], 0, s[74:75]
	global_load_dwordx4 v[46:49], v[148:149], off nt
	v_lshl_add_u64 v[148:149], v[148:149], 0, s[74:75]
	ds_read_b32 v141, v160 offset:96
	ds_read_b128 v[114:117], v161 offset:768
	ds_read_b128 v[176:179], v161 offset:784
	s_waitcnt lgkmcnt(3)
	v_cndmask_b32_e64 v143, 0, v143, s[8:9]
	v_pk_mul_f32 v[180:181], v[26:27], v[172:173] op_sel:[0,1]
	v_pk_mul_f32 v[192:193], v[28:29], v[172:173] op_sel:[0,1]
	v_mfma_f32_16x16x4_f32 v[110:113], v143, v42, v[110:113]
	v_pk_fma_f32 v[180:181], v[30:31], v[172:173], v[180:181] op_sel_hi:[1,0,1]
	v_pk_fma_f32 v[192:193], v[32:33], v[172:173], v[192:193] op_sel_hi:[1,0,1]
	v_pk_fma_f32 v[180:181], v[22:23], v[174:175], v[180:181] op_sel_hi:[1,0,1]
	v_pk_fma_f32 v[192:193], v[24:25], v[174:175], v[192:193] op_sel_hi:[1,0,1]
	v_mfma_f32_16x16x4_f32 v[106:109], v143, v43, v[106:109]
	v_pk_fma_f32 v[180:181], v[18:19], v[174:175], v[180:181] op_sel:[0,1,0]
	v_pk_fma_f32 v[192:193], v[20:21], v[174:175], v[192:193] op_sel:[0,1,0]
	v_pk_fma_f32 v[180:181], v[14:15], v[232:233], v[180:181] op_sel_hi:[1,0,1]
	v_pk_fma_f32 v[192:193], v[16:17], v[232:233], v[192:193] op_sel_hi:[1,0,1]
	v_mfma_f32_16x16x4_f32 v[102:105], v143, v44, v[102:105]
	v_pk_fma_f32 v[180:181], v[10:11], v[232:233], v[180:181] op_sel:[0,1,0]
	v_pk_fma_f32 v[192:193], v[12:13], v[232:233], v[192:193] op_sel:[0,1,0]
	v_pk_fma_f32 v[180:181], v[6:7], v[234:235], v[180:181] op_sel_hi:[1,0,1]
	v_pk_fma_f32 v[192:193], v[8:9], v[234:235], v[192:193] op_sel_hi:[1,0,1]
	v_mfma_f32_16x16x4_f32 v[98:101], v143, v45, v[98:101]
	v_pk_fma_f32 v[180:181], v[2:3], v[234:235], v[180:181] op_sel:[0,1,0]
	v_pk_fma_f32 v[192:193], v[4:5], v[234:235], v[192:193] op_sel:[0,1,0]
	v_pk_mul_f32 v[180:181], v[146:147], v[180:181]
	v_pk_mul_f32 v[192:193], v[146:147], v[192:193]
	v_pk_fma_f32 v[236:237], v[144:145], v[42:43], v[180:181]
	v_pk_fma_f32 v[238:239], v[144:145], v[44:45], v[192:193]
	global_store_dwordx4 v[150:151], v[236:239], off nt
	v_lshl_add_u64 v[150:151], v[150:151], 0, s[74:75]
	global_load_dwordx4 v[42:45], v[148:149], off nt
	v_lshl_add_u64 v[148:149], v[148:149], 0, s[74:75]
	ds_read_b32 v143, v160 offset:112
	ds_read_b128 v[172:175], v161 offset:896
	ds_read_b128 v[232:235], v161 offset:912
	s_waitcnt lgkmcnt(3)
	v_cndmask_b32_e64 v141, 0, v141, s[8:9]
	v_pk_mul_f32 v[180:181], v[26:27], v[114:115] op_sel:[0,1]
	v_pk_mul_f32 v[192:193], v[28:29], v[114:115] op_sel:[0,1]
	v_mfma_f32_16x16x4_f32 v[110:113], v141, v38, v[110:113]
	v_pk_fma_f32 v[180:181], v[30:31], v[114:115], v[180:181] op_sel_hi:[1,0,1]
	v_pk_fma_f32 v[192:193], v[32:33], v[114:115], v[192:193] op_sel_hi:[1,0,1]
	v_pk_fma_f32 v[180:181], v[22:23], v[116:117], v[180:181] op_sel_hi:[1,0,1]
	v_pk_fma_f32 v[192:193], v[24:25], v[116:117], v[192:193] op_sel_hi:[1,0,1]
	v_mfma_f32_16x16x4_f32 v[106:109], v141, v39, v[106:109]
	v_pk_fma_f32 v[180:181], v[18:19], v[116:117], v[180:181] op_sel:[0,1,0]
	v_pk_fma_f32 v[192:193], v[20:21], v[116:117], v[192:193] op_sel:[0,1,0]
	v_pk_fma_f32 v[180:181], v[14:15], v[176:177], v[180:181] op_sel_hi:[1,0,1]
	v_pk_fma_f32 v[192:193], v[16:17], v[176:177], v[192:193] op_sel_hi:[1,0,1]
	v_mfma_f32_16x16x4_f32 v[102:105], v141, v40, v[102:105]
	v_pk_fma_f32 v[180:181], v[10:11], v[176:177], v[180:181] op_sel:[0,1,0]
	v_pk_fma_f32 v[192:193], v[12:13], v[176:177], v[192:193] op_sel:[0,1,0]
	v_pk_fma_f32 v[180:181], v[6:7], v[178:179], v[180:181] op_sel_hi:[1,0,1]
	v_pk_fma_f32 v[192:193], v[8:9], v[178:179], v[192:193] op_sel_hi:[1,0,1]
	v_mfma_f32_16x16x4_f32 v[98:101], v141, v41, v[98:101]
	v_pk_fma_f32 v[180:181], v[2:3], v[178:179], v[180:181] op_sel:[0,1,0]
	v_pk_fma_f32 v[192:193], v[4:5], v[178:179], v[192:193] op_sel:[0,1,0]
	v_pk_mul_f32 v[180:181], v[146:147], v[180:181]
	v_pk_mul_f32 v[192:193], v[146:147], v[192:193]
	v_pk_fma_f32 v[236:237], v[144:145], v[38:39], v[180:181]
	v_pk_fma_f32 v[238:239], v[144:145], v[40:41], v[192:193]
	global_store_dwordx4 v[150:151], v[236:239], off nt
	v_lshl_add_u64 v[150:151], v[150:151], 0, s[74:75]
	global_load_dwordx4 v[38:41], v[148:149], off nt
	v_lshl_add_u64 v[148:149], v[148:149], 0, s[74:75]
	ds_read_b32 v141, v160 offset:128
	ds_read_b128 v[114:117], v161 offset:1024
	ds_read_b128 v[176:179], v161 offset:1040
	s_waitcnt lgkmcnt(3)
; #define RS_LOAD(dst, it0) do { _Pragma("unroll") for (int u = 0; u < 8; ++u) dst[u] = __builtin_nontemporal_load((const f32x4*)(S0 + (size_t)(4 * ((it0) + u)) * DV)); } while (0)
; __device__ __forceinline__ void ret_sample_item(Frame& F, int item) {
;     ...
;     for (int it0 = 0; it0 < 64; it0 += 16) {
;         RS_LOAD(sb, it0 + 8);
;         RS_PROC(sa, it0);
;         { const int itn = it0 + 16 < 64 ? it0 + 16 : it0; RS_LOAD(sa, itn); }
	v_cndmask_b32_e64 v143, 0, v143, s[8:9]
	v_pk_mul_f32 v[180:181], v[26:27], v[172:173] op_sel:[0,1]
	v_pk_mul_f32 v[192:193], v[28:29], v[172:173] op_sel:[0,1]
	v_mfma_f32_16x16x4_f32 v[110:113], v143, v34, v[110:113]
	v_pk_fma_f32 v[180:181], v[30:31], v[172:173], v[180:181] op_sel_hi:[1,0,1]
	v_pk_fma_f32 v[192:193], v[32:33], v[172:173], v[192:193] op_sel_hi:[1,0,1]
	v_pk_fma_f32 v[180:181], v[22:23], v[174:175], v[180:181] op_sel_hi:[1,0,1]
	v_pk_fma_f32 v[192:193], v[24:25], v[174:175], v[192:193] op_sel_hi:[1,0,1]
	v_mfma_f32_16x16x4_f32 v[106:109], v143, v35, v[106:109]
	v_pk_fma_f32 v[180:181], v[18:19], v[174:175], v[180:181] op_sel:[0,1,0]
	v_pk_fma_f32 v[192:193], v[20:21], v[174:175], v[192:193] op_sel:[0,1,0]
	v_pk_fma_f32 v[180:181], v[14:15], v[232:233], v[180:181] op_sel_hi:[1,0,1]
	v_pk_fma_f32 v[192:193], v[16:17], v[232:233], v[192:193] op_sel_hi:[1,0,1]
	v_mfma_f32_16x16x4_f32 v[102:105], v143, v36, v[102:105]
	v_pk_fma_f32 v[180:181], v[10:11], v[232:233], v[180:181] op_sel:[0,1,0]
	v_pk_fma_f32 v[192:193], v[12:13], v[232:233], v[192:193] op_sel:[0,1,0]
	v_pk_fma_f32 v[180:181], v[6:7], v[234:235], v[180:181] op_sel_hi:[1,0,1]
	v_pk_fma_f32 v[192:193], v[8:9], v[234:235], v[192:193] op_sel_hi:[1,0,1]
	v_mfma_f32_16x16x4_f32 v[98:101], v143, v37, v[98:101]
	v_pk_fma_f32 v[180:181], v[2:3], v[234:235], v[180:181] op_sel:[0,1,0]
	v_pk_fma_f32 v[192:193], v[4:5], v[234:235], v[192:193] op_sel:[0,1,0]
	v_pk_mul_f32 v[180:181], v[146:147], v[180:181]
	v_pk_mul_f32 v[192:193], v[146:147], v[192:193]
	v_pk_fma_f32 v[236:237], v[144:145], v[34:35], v[180:181]
	v_pk_fma_f32 v[238:239], v[144:145], v[36:37], v[192:193]
	global_store_dwordx4 v[150:151], v[236:239], off nt
	v_lshl_add_u64 v[150:151], v[150:151], 0, s[74:75]
	global_load_dwordx4 v[34:37], v[148:149], off nt
	v_lshl_add_u64 v[148:149], v[148:149], 0, s[74:75]
	ds_read_b32 v143, v160 offset:144
	ds_read_b128 v[172:175], v161 offset:1152
	ds_read_b128 v[232:235], v161 offset:1168
	s_waitcnt vmcnt(27)
	s_waitcnt lgkmcnt(3)
	v_cndmask_b32_e64 v141, 0, v141, s[8:9]
	v_pk_mul_f32 v[180:181], v[26:27], v[114:115] op_sel:[0,1]
	v_pk_mul_f32 v[192:193], v[28:29], v[114:115] op_sel:[0,1]
	v_mfma_f32_16x16x4_f32 v[110:113], v141, v58, v[110:113]
	v_pk_fma_f32 v[180:181], v[30:31], v[114:115], v[180:181] op_sel_hi:[1,0,1]
	v_pk_fma_f32 v[192:193], v[32:33], v[114:115], v[192:193] op_sel_hi:[1,0,1]
	v_pk_fma_f32 v[180:181], v[22:23], v[116:117], v[180:181] op_sel_hi:[1,0,1]
	v_pk_fma_f32 v[192:193], v[24:25], v[116:117], v[192:193] op_sel_hi:[1,0,1]
	v_mfma_f32_16x16x4_f32 v[106:109], v141, v59, v[106:109]
	v_pk_fma_f32 v[180:181], v[18:19], v[116:117], v[180:181] op_sel:[0,1,0]
	v_pk_fma_f32 v[192:193], v[20:21], v[116:117], v[192:193] op_sel:[0,1,0]
	v_pk_fma_f32 v[180:181], v[14:15], v[176:177], v[180:181] op_sel_hi:[1,0,1]
	v_pk_fma_f32 v[192:193], v[16:17], v[176:177], v[192:193] op_sel_hi:[1,0,1]
	v_mfma_f32_16x16x4_f32 v[102:105], v141, v60, v[102:105]
	v_pk_fma_f32 v[180:181], v[10:11], v[176:177], v[180:181] op_sel:[0,1,0]
	v_pk_fma_f32 v[192:193], v[12:13], v[176:177], v[192:193] op_sel:[0,1,0]
	v_pk_fma_f32 v[180:181], v[6:7], v[178:179], v[180:181] op_sel_hi:[1,0,1]
	v_pk_fma_f32 v[192:193], v[8:9], v[178:179], v[192:193] op_sel_hi:[1,0,1]
	v_mfma_f32_16x16x4_f32 v[98:101], v141, v61, v[98:101]
	v_pk_fma_f32 v[180:181], v[2:3], v[178:179], v[180:181] op_sel:[0,1,0]
	v_pk_fma_f32 v[192:193], v[4:5], v[178:179], v[192:193] op_sel:[0,1,0]
	v_pk_mul_f32 v[180:181], v[146:147], v[180:181]
	v_pk_mul_f32 v[192:193], v[146:147], v[192:193]
	v_pk_fma_f32 v[236:237], v[144:145], v[58:59], v[180:181]
	v_pk_fma_f32 v[238:239], v[144:145], v[60:61], v[192:193]
	global_store_dwordx4 v[150:151], v[236:239], off nt
	v_lshl_add_u64 v[150:151], v[150:151], 0, s[74:75]
	global_load_dwordx4 v[58:61], v[148:149], off nt
	v_lshl_add_u64 v[148:149], v[148:149], 0, s[74:75]
	ds_read_b32 v141, v160 offset:160
	ds_read_b128 v[114:117], v161 offset:1280
	ds_read_b128 v[176:179], v161 offset:1296
	s_waitcnt vmcnt(28)
	s_waitcnt lgkmcnt(3)
	v_cndmask_b32_e64 v143, 0, v143, s[8:9]
	v_pk_mul_f32 v[180:181], v[26:27], v[172:173] op_sel:[0,1]
	v_pk_mul_f32 v[192:193], v[28:29], v[172:173] op_sel:[0,1]
	v_mfma_f32_16x16x4_f32 v[110:113], v143, v66, v[110:113]
	v_pk_fma_f32 v[180:181], v[30:31], v[172:173], v[180:181] op_sel_hi:[1,0,1]
	v_pk_fma_f32 v[192:193], v[32:33], v[172:173], v[192:193] op_sel_hi:[1,0,1]
	v_pk_fma_f32 v[180:181], v[22:23], v[174:175], v[180:181] op_sel_hi:[1,0,1]
	v_pk_fma_f32 v[192:193], v[24:25], v[174:175], v[192:193] op_sel_hi:[1,0,1]
	v_mfma_f32_16x16x4_f32 v[106:109], v143, v67, v[106:109]
	v_pk_fma_f32 v[180:181], v[18:19], v[174:175], v[180:181] op_sel:[0,1,0]
	v_pk_fma_f32 v[192:193], v[20:21], v[174:175], v[192:193] op_sel:[0,1,0]
	v_pk_fma_f32 v[180:181], v[14:15], v[232:233], v[180:181] op_sel_hi:[1,0,1]
	v_pk_fma_f32 v[192:193], v[16:17], v[232:233], v[192:193] op_sel_hi:[1,0,1]
	v_mfma_f32_16x16x4_f32 v[102:105], v143, v68, v[102:105]
	v_pk_fma_f32 v[180:181], v[10:11], v[232:233], v[180:181] op_sel:[0,1,0]
	v_pk_fma_f32 v[192:193], v[12:13], v[232:233], v[192:193] op_sel:[0,1,0]
	v_pk_fma_f32 v[180:181], v[6:7], v[234:235], v[180:181] op_sel_hi:[1,0,1]
	v_pk_fma_f32 v[192:193], v[8:9], v[234:235], v[192:193] op_sel_hi:[1,0,1]
	v_mfma_f32_16x16x4_f32 v[98:101], v143, v69, v[98:101]
	v_pk_fma_f32 v[180:181], v[2:3], v[234:235], v[180:181] op_sel:[0,1,0]
	v_pk_fma_f32 v[192:193], v[4:5], v[234:235], v[192:193] op_sel:[0,1,0]
	v_pk_mul_f32 v[180:181], v[146:147], v[180:181]
	v_pk_mul_f32 v[192:193], v[146:147], v[192:193]
	v_pk_fma_f32 v[236:237], v[144:145], v[66:67], v[180:181]
	v_pk_fma_f32 v[238:239], v[144:145], v[68:69], v[192:193]
	global_store_dwordx4 v[150:151], v[236:239], off nt
	v_lshl_add_u64 v[150:151], v[150:151], 0, s[74:75]
	global_load_dwordx4 v[66:69], v[148:149], off nt
	v_lshl_add_u64 v[148:149], v[148:149], 0, s[74:75]
	ds_read_b32 v143, v160 offset:176
	ds_read_b128 v[172:175], v161 offset:1408
	ds_read_b128 v[232:235], v161 offset:1424
	s_waitcnt vmcnt(29)
; #define RS_LOAD(dst, it0) do { _Pragma("unroll") for (int u = 0; u < 8; ++u) dst[u] = __builtin_nontemporal_load((const f32x4*)(S0 + (size_t)(4 * ((it0) + u)) * DV)); } while (0)
; __device__ __forceinline__ void ret_sample_item(Frame& F, int item) {
;     ...
;     for (int it0 = 0; it0 < 64; it0 += 16) {
;         RS_LOAD(sb, it0 + 8);
;         RS_PROC(sa, it0);
;         { const int itn = it0 + 16 < 64 ? it0 + 16 : it0; RS_LOAD(sa, itn); }
	s_waitcnt lgkmcnt(3)
	v_cndmask_b32_e64 v141, 0, v141, s[8:9]
	v_pk_mul_f32 v[180:181], v[26:27], v[114:115] op_sel:[0,1]
	v_pk_mul_f32 v[192:193], v[28:29], v[114:115] op_sel:[0,1]
	v_mfma_f32_16x16x4_f32 v[110:113], v141, v74, v[110:113]
	v_pk_fma_f32 v[180:181], v[30:31], v[114:115], v[180:181] op_sel_hi:[1,0,1]
	v_pk_fma_f32 v[192:193], v[32:33], v[114:115], v[192:193] op_sel_hi:[1,0,1]
	v_pk_fma_f32 v[180:181], v[22:23], v[116:117], v[180:181] op_sel_hi:[1,0,1]
	v_pk_fma_f32 v[192:193], v[24:25], v[116:117], v[192:193] op_sel_hi:[1,0,1]
	v_mfma_f32_16x16x4_f32 v[106:109], v141, v75, v[106:109]
	v_pk_fma_f32 v[180:181], v[18:19], v[116:117], v[180:181] op_sel:[0,1,0]
	v_pk_fma_f32 v[192:193], v[20:21], v[116:117], v[192:193] op_sel:[0,1,0]
	v_pk_fma_f32 v[180:181], v[14:15], v[176:177], v[180:181] op_sel_hi:[1,0,1]
	v_pk_fma_f32 v[192:193], v[16:17], v[176:177], v[192:193] op_sel_hi:[1,0,1]
	v_mfma_f32_16x16x4_f32 v[102:105], v141, v76, v[102:105]
	v_pk_fma_f32 v[180:181], v[10:11], v[176:177], v[180:181] op_sel:[0,1,0]
	v_pk_fma_f32 v[192:193], v[12:13], v[176:177], v[192:193] op_sel:[0,1,0]
	v_pk_fma_f32 v[180:181], v[6:7], v[178:179], v[180:181] op_sel_hi:[1,0,1]
	v_pk_fma_f32 v[192:193], v[8:9], v[178:179], v[192:193] op_sel_hi:[1,0,1]
	v_mfma_f32_16x16x4_f32 v[98:101], v141, v77, v[98:101]
	v_pk_fma_f32 v[180:181], v[2:3], v[178:179], v[180:181] op_sel:[0,1,0]
	v_pk_fma_f32 v[192:193], v[4:5], v[178:179], v[192:193] op_sel:[0,1,0]
	v_pk_mul_f32 v[180:181], v[146:147], v[180:181]
	v_pk_mul_f32 v[192:193], v[146:147], v[192:193]
	v_pk_fma_f32 v[236:237], v[144:145], v[74:75], v[180:181]
	v_pk_fma_f32 v[238:239], v[144:145], v[76:77], v[192:193]
	global_store_dwordx4 v[150:151], v[236:239], off nt
	v_lshl_add_u64 v[150:151], v[150:151], 0, s[74:75]
	global_load_dwordx4 v[74:77], v[148:149], off nt
	v_lshl_add_u64 v[148:149], v[148:149], 0, s[74:75]
	ds_read_b32 v141, v160 offset:192
	ds_read_b128 v[114:117], v161 offset:1536
	ds_read_b128 v[176:179], v161 offset:1552
	s_waitcnt vmcnt(30)
	s_waitcnt lgkmcnt(3)
	v_cndmask_b32_e64 v143, 0, v143, s[8:9]
	v_pk_mul_f32 v[180:181], v[26:27], v[172:173] op_sel:[0,1]
	v_pk_mul_f32 v[192:193], v[28:29], v[172:173] op_sel:[0,1]
	v_mfma_f32_16x16x4_f32 v[110:113], v143, v78, v[110:113]
	v_pk_fma_f32 v[180:181], v[30:31], v[172:173], v[180:181] op_sel_hi:[1,0,1]
	v_pk_fma_f32 v[192:193], v[32:33], v[172:173], v[192:193] op_sel_hi:[1,0,1]
	v_pk_fma_f32 v[180:181], v[22:23], v[174:175], v[180:181] op_sel_hi:[1,0,1]
	v_pk_fma_f32 v[192:193], v[24:25], v[174:175], v[192:193] op_sel_hi:[1,0,1]
	v_mfma_f32_16x16x4_f32 v[106:109], v143, v79, v[106:109]
	v_pk_fma_f32 v[180:181], v[18:19], v[174:175], v[180:181] op_sel:[0,1,0]
	v_pk_fma_f32 v[192:193], v[20:21], v[174:175], v[192:193] op_sel:[0,1,0]
	v_pk_fma_f32 v[180:181], v[14:15], v[232:233], v[180:181] op_sel_hi:[1,0,1]
	v_pk_fma_f32 v[192:193], v[16:17], v[232:233], v[192:193] op_sel_hi:[1,0,1]
	v_mfma_f32_16x16x4_f32 v[102:105], v143, v80, v[102:105]
	v_pk_fma_f32 v[180:181], v[10:11], v[232:233], v[180:181] op_sel:[0,1,0]
	v_pk_fma_f32 v[192:193], v[12:13], v[232:233], v[192:193] op_sel:[0,1,0]
	v_pk_fma_f32 v[180:181], v[6:7], v[234:235], v[180:181] op_sel_hi:[1,0,1]
	v_pk_fma_f32 v[192:193], v[8:9], v[234:235], v[192:193] op_sel_hi:[1,0,1]
	v_mfma_f32_16x16x4_f32 v[98:101], v143, v81, v[98:101]
	v_pk_fma_f32 v[180:181], v[2:3], v[234:235], v[180:181] op_sel:[0,1,0]
	v_pk_fma_f32 v[192:193], v[4:5], v[234:235], v[192:193] op_sel:[0,1,0]
	v_pk_mul_f32 v[180:181], v[146:147], v[180:181]
	v_pk_mul_f32 v[192:193], v[146:147], v[192:193]
	v_pk_fma_f32 v[236:237], v[144:145], v[78:79], v[180:181]
	v_pk_fma_f32 v[238:239], v[144:145], v[80:81], v[192:193]
	global_store_dwordx4 v[150:151], v[236:239], off nt
	v_lshl_add_u64 v[150:151], v[150:151], 0, s[74:75]
	global_load_dwordx4 v[78:81], v[148:149], off nt
	v_lshl_add_u64 v[148:149], v[148:149], 0, s[74:75]
	ds_read_b32 v143, v160 offset:208
	ds_read_b128 v[172:175], v161 offset:1664
	ds_read_b128 v[232:235], v161 offset:1680
	s_waitcnt vmcnt(31)
	s_waitcnt lgkmcnt(3)
	v_cndmask_b32_e64 v141, 0, v141, s[8:9]
	v_pk_mul_f32 v[180:181], v[26:27], v[114:115] op_sel:[0,1]
	v_pk_mul_f32 v[192:193], v[28:29], v[114:115] op_sel:[0,1]
	v_mfma_f32_16x16x4_f32 v[110:113], v141, v82, v[110:113]
	v_pk_fma_f32 v[180:181], v[30:31], v[114:115], v[180:181] op_sel_hi:[1,0,1]
	v_pk_fma_f32 v[192:193], v[32:33], v[114:115], v[192:193] op_sel_hi:[1,0,1]
	v_pk_fma_f32 v[180:181], v[22:23], v[116:117], v[180:181] op_sel_hi:[1,0,1]
	v_pk_fma_f32 v[192:193], v[24:25], v[116:117], v[192:193] op_sel_hi:[1,0,1]
	v_mfma_f32_16x16x4_f32 v[106:109], v141, v83, v[106:109]
	v_pk_fma_f32 v[180:181], v[18:19], v[116:117], v[180:181] op_sel:[0,1,0]
	v_pk_fma_f32 v[192:193], v[20:21], v[116:117], v[192:193] op_sel:[0,1,0]
	v_pk_fma_f32 v[180:181], v[14:15], v[176:177], v[180:181] op_sel_hi:[1,0,1]
	v_pk_fma_f32 v[192:193], v[16:17], v[176:177], v[192:193] op_sel_hi:[1,0,1]
	v_mfma_f32_16x16x4_f32 v[102:105], v141, v84, v[102:105]
	v_pk_fma_f32 v[180:181], v[10:11], v[176:177], v[180:181] op_sel:[0,1,0]
	v_pk_fma_f32 v[192:193], v[12:13], v[176:177], v[192:193] op_sel:[0,1,0]
	v_pk_fma_f32 v[180:181], v[6:7], v[178:179], v[180:181] op_sel_hi:[1,0,1]
	v_pk_fma_f32 v[192:193], v[8:9], v[178:179], v[192:193] op_sel_hi:[1,0,1]
	v_mfma_f32_16x16x4_f32 v[98:101], v141, v85, v[98:101]
	v_pk_fma_f32 v[180:181], v[2:3], v[178:179], v[180:181] op_sel:[0,1,0]
	v_pk_fma_f32 v[192:193], v[4:5], v[178:179], v[192:193] op_sel:[0,1,0]
	v_pk_mul_f32 v[180:181], v[146:147], v[180:181]
	v_pk_mul_f32 v[192:193], v[146:147], v[192:193]
	v_pk_fma_f32 v[236:237], v[144:145], v[82:83], v[180:181]
	v_pk_fma_f32 v[238:239], v[144:145], v[84:85], v[192:193]
	global_store_dwordx4 v[150:151], v[236:239], off nt
	v_lshl_add_u64 v[150:151], v[150:151], 0, s[74:75]
	global_load_dwordx4 v[82:85], v[148:149], off nt
	v_lshl_add_u64 v[148:149], v[148:149], 0, s[74:75]
	ds_read_b32 v141, v160 offset:224
	ds_read_b128 v[114:117], v161 offset:1792
	ds_read_b128 v[176:179], v161 offset:1808
	s_waitcnt vmcnt(32)
; #define RS_LOAD(dst, it0) do { _Pragma("unroll") for (int u = 0; u < 8; ++u) dst[u] = __builtin_nontemporal_load((const f32x4*)(S0 + (size_t)(4 * ((it0) + u)) * DV)); } while (0)
; __device__ __forceinline__ void ret_sample_item(Frame& F, int item) {
;     ...
;     for (int it0 = 0; it0 < 64; it0 += 16) {
;         RS_LOAD(sb, it0 + 8);
;         RS_PROC(sa, it0);
;         { const int itn = it0 + 16 < 64 ? it0 + 16 : it0; RS_LOAD(sa, itn); }
	s_waitcnt lgkmcnt(3)
	v_cndmask_b32_e64 v143, 0, v143, s[8:9]
	v_pk_mul_f32 v[180:181], v[26:27], v[172:173] op_sel:[0,1]
	v_pk_mul_f32 v[192:193], v[28:29], v[172:173] op_sel:[0,1]
	v_mfma_f32_16x16x4_f32 v[110:113], v143, v86, v[110:113]
	v_pk_fma_f32 v[180:181], v[30:31], v[172:173], v[180:181] op_sel_hi:[1,0,1]
	v_pk_fma_f32 v[192:193], v[32:33], v[172:173], v[192:193] op_sel_hi:[1,0,1]
	v_pk_fma_f32 v[180:181], v[22:23], v[174:175], v[180:181] op_sel_hi:[1,0,1]
	v_pk_fma_f32 v[192:193], v[24:25], v[174:175], v[192:193] op_sel_hi:[1,0,1]
	v_mfma_f32_16x16x4_f32 v[106:109], v143, v87, v[106:109]
	v_pk_fma_f32 v[180:181], v[18:19], v[174:175], v[180:181] op_sel:[0,1,0]
	v_pk_fma_f32 v[192:193], v[20:21], v[174:175], v[192:193] op_sel:[0,1,0]
	v_pk_fma_f32 v[180:181], v[14:15], v[232:233], v[180:181] op_sel_hi:[1,0,1]
	v_pk_fma_f32 v[192:193], v[16:17], v[232:233], v[192:193] op_sel_hi:[1,0,1]
	v_mfma_f32_16x16x4_f32 v[102:105], v143, v88, v[102:105]
	v_pk_fma_f32 v[180:181], v[10:11], v[232:233], v[180:181] op_sel:[0,1,0]
	v_pk_fma_f32 v[192:193], v[12:13], v[232:233], v[192:193] op_sel:[0,1,0]
	v_pk_fma_f32 v[180:181], v[6:7], v[234:235], v[180:181] op_sel_hi:[1,0,1]
	v_pk_fma_f32 v[192:193], v[8:9], v[234:235], v[192:193] op_sel_hi:[1,0,1]
	v_mfma_f32_16x16x4_f32 v[98:101], v143, v89, v[98:101]
	v_pk_fma_f32 v[180:181], v[2:3], v[234:235], v[180:181] op_sel:[0,1,0]
	v_pk_fma_f32 v[192:193], v[4:5], v[234:235], v[192:193] op_sel:[0,1,0]
	v_pk_mul_f32 v[180:181], v[146:147], v[180:181]
	v_pk_mul_f32 v[192:193], v[146:147], v[192:193]
	v_pk_fma_f32 v[236:237], v[144:145], v[86:87], v[180:181]
	v_pk_fma_f32 v[238:239], v[144:145], v[88:89], v[192:193]
	global_store_dwordx4 v[150:151], v[236:239], off nt
	v_lshl_add_u64 v[150:151], v[150:151], 0, s[74:75]
	global_load_dwordx4 v[86:89], v[148:149], off nt
	v_lshl_add_u64 v[148:149], v[148:149], 0, s[74:75]
	ds_read_b32 v143, v160 offset:240
	ds_read_b128 v[172:175], v161 offset:1920
	ds_read_b128 v[232:235], v161 offset:1936
	s_waitcnt vmcnt(33)
	s_waitcnt lgkmcnt(3)
	v_cndmask_b32_e64 v141, 0, v141, s[8:9]
	v_pk_mul_f32 v[180:181], v[26:27], v[114:115] op_sel:[0,1]
	v_pk_mul_f32 v[192:193], v[28:29], v[114:115] op_sel:[0,1]
	v_mfma_f32_16x16x4_f32 v[110:113], v141, v90, v[110:113]
	v_pk_fma_f32 v[180:181], v[30:31], v[114:115], v[180:181] op_sel_hi:[1,0,1]
	v_pk_fma_f32 v[192:193], v[32:33], v[114:115], v[192:193] op_sel_hi:[1,0,1]
	v_pk_fma_f32 v[180:181], v[22:23], v[116:117], v[180:181] op_sel_hi:[1,0,1]
	v_pk_fma_f32 v[192:193], v[24:25], v[116:117], v[192:193] op_sel_hi:[1,0,1]
	v_mfma_f32_16x16x4_f32 v[106:109], v141, v91, v[106:109]
	v_pk_fma_f32 v[180:181], v[18:19], v[116:117], v[180:181] op_sel:[0,1,0]
	v_pk_fma_f32 v[192:193], v[20:21], v[116:117], v[192:193] op_sel:[0,1,0]
	v_pk_fma_f32 v[180:181], v[14:15], v[176:177], v[180:181] op_sel_hi:[1,0,1]
	v_pk_fma_f32 v[192:193], v[16:17], v[176:177], v[192:193] op_sel_hi:[1,0,1]
	v_mfma_f32_16x16x4_f32 v[102:105], v141, v92, v[102:105]
	v_pk_fma_f32 v[180:181], v[10:11], v[176:177], v[180:181] op_sel:[0,1,0]
	v_pk_fma_f32 v[192:193], v[12:13], v[176:177], v[192:193] op_sel:[0,1,0]
	v_pk_fma_f32 v[180:181], v[6:7], v[178:179], v[180:181] op_sel_hi:[1,0,1]
	v_pk_fma_f32 v[192:193], v[8:9], v[178:179], v[192:193] op_sel_hi:[1,0,1]
	v_mfma_f32_16x16x4_f32 v[98:101], v141, v93, v[98:101]
	v_pk_fma_f32 v[180:181], v[2:3], v[178:179], v[180:181] op_sel:[0,1,0]
	v_pk_fma_f32 v[192:193], v[4:5], v[178:179], v[192:193] op_sel:[0,1,0]
	v_pk_mul_f32 v[180:181], v[146:147], v[180:181]
	v_pk_mul_f32 v[192:193], v[146:147], v[192:193]
	v_pk_fma_f32 v[236:237], v[144:145], v[90:91], v[180:181]
	v_pk_fma_f32 v[238:239], v[144:145], v[92:93], v[192:193]
	global_store_dwordx4 v[150:151], v[236:239], off nt
	v_lshl_add_u64 v[150:151], v[150:151], 0, s[74:75]
	global_load_dwordx4 v[90:93], v[148:149], off nt
	v_lshl_add_u64 v[148:149], v[148:149], 0, s[74:75]
	ds_read_b32 v141, v160 offset:256
	ds_read_b128 v[114:117], v161 offset:2048
	ds_read_b128 v[176:179], v161 offset:2064
	s_waitcnt vmcnt(34)
	s_waitcnt lgkmcnt(3)
	v_cndmask_b32_e64 v143, 0, v143, s[8:9]
	v_pk_mul_f32 v[180:181], v[26:27], v[172:173] op_sel:[0,1]
	v_pk_mul_f32 v[192:193], v[28:29], v[172:173] op_sel:[0,1]
	v_mfma_f32_16x16x4_f32 v[110:113], v143, v94, v[110:113]
	v_pk_fma_f32 v[180:181], v[30:31], v[172:173], v[180:181] op_sel_hi:[1,0,1]
	v_pk_fma_f32 v[192:193], v[32:33], v[172:173], v[192:193] op_sel_hi:[1,0,1]
	v_pk_fma_f32 v[180:181], v[22:23], v[174:175], v[180:181] op_sel_hi:[1,0,1]
	v_pk_fma_f32 v[192:193], v[24:25], v[174:175], v[192:193] op_sel_hi:[1,0,1]
	v_mfma_f32_16x16x4_f32 v[106:109], v143, v95, v[106:109]
	v_pk_fma_f32 v[180:181], v[18:19], v[174:175], v[180:181] op_sel:[0,1,0]
	v_pk_fma_f32 v[192:193], v[20:21], v[174:175], v[192:193] op_sel:[0,1,0]
	v_pk_fma_f32 v[180:181], v[14:15], v[232:233], v[180:181] op_sel_hi:[1,0,1]
	v_pk_fma_f32 v[192:193], v[16:17], v[232:233], v[192:193] op_sel_hi:[1,0,1]
	v_mfma_f32_16x16x4_f32 v[102:105], v143, v96, v[102:105]
	v_pk_fma_f32 v[180:181], v[10:11], v[232:233], v[180:181] op_sel:[0,1,0]
	v_pk_fma_f32 v[192:193], v[12:13], v[232:233], v[192:193] op_sel:[0,1,0]
	v_pk_fma_f32 v[180:181], v[6:7], v[234:235], v[180:181] op_sel_hi:[1,0,1]
	v_pk_fma_f32 v[192:193], v[8:9], v[234:235], v[192:193] op_sel_hi:[1,0,1]
	v_mfma_f32_16x16x4_f32 v[98:101], v143, v97, v[98:101]
	v_pk_fma_f32 v[180:181], v[2:3], v[234:235], v[180:181] op_sel:[0,1,0]
	v_pk_fma_f32 v[192:193], v[4:5], v[234:235], v[192:193] op_sel:[0,1,0]
	v_pk_mul_f32 v[180:181], v[146:147], v[180:181]
	v_pk_mul_f32 v[192:193], v[146:147], v[192:193]
	v_pk_fma_f32 v[236:237], v[144:145], v[94:95], v[180:181]
	v_pk_fma_f32 v[238:239], v[144:145], v[96:97], v[192:193]
	global_store_dwordx4 v[150:151], v[236:239], off nt
	v_lshl_add_u64 v[150:151], v[150:151], 0, s[74:75]
	global_load_dwordx4 v[94:97], v[148:149], off nt
	v_lshl_add_u64 v[148:149], v[148:149], 0, s[74:75]
	ds_read_b32 v143, v160 offset:272
	ds_read_b128 v[172:175], v161 offset:2176
	ds_read_b128 v[232:235], v161 offset:2192
	s_waitcnt vmcnt(35)
; #define RS_LOAD(dst, it0) do { _Pragma("unroll") for (int u = 0; u < 8; ++u) dst[u] = __builtin_nontemporal_load((const f32x4*)(S0 + (size_t)(4 * ((it0) + u)) * DV)); } while (0)
; __device__ __forceinline__ void ret_sample_item(Frame& F, int item) {
;     ...
;     for (int it0 = 0; it0 < 64; it0 += 16) {
;         RS_LOAD(sb, it0 + 8);
;         RS_PROC(sa, it0);
;         { const int itn = it0 + 16 < 64 ? it0 + 16 : it0; RS_LOAD(sa, itn); }
	s_waitcnt lgkmcnt(3)
	v_cndmask_b32_e64 v141, 0, v141, s[8:9]
	v_pk_mul_f32 v[180:181], v[26:27], v[114:115] op_sel:[0,1]
	v_pk_mul_f32 v[192:193], v[28:29], v[114:115] op_sel:[0,1]
	v_mfma_f32_16x16x4_f32 v[110:113], v141, v212, v[110:113]
	v_pk_fma_f32 v[180:181], v[30:31], v[114:115], v[180:181] op_sel_hi:[1,0,1]
	v_pk_fma_f32 v[192:193], v[32:33], v[114:115], v[192:193] op_sel_hi:[1,0,1]
	v_pk_fma_f32 v[180:181], v[22:23], v[116:117], v[180:181] op_sel_hi:[1,0,1]
	v_pk_fma_f32 v[192:193], v[24:25], v[116:117], v[192:193] op_sel_hi:[1,0,1]
	v_mfma_f32_16x16x4_f32 v[106:109], v141, v213, v[106:109]
	v_pk_fma_f32 v[180:181], v[18:19], v[116:117], v[180:181] op_sel:[0,1,0]
	v_pk_fma_f32 v[192:193], v[20:21], v[116:117], v[192:193] op_sel:[0,1,0]
	v_pk_fma_f32 v[180:181], v[14:15], v[176:177], v[180:181] op_sel_hi:[1,0,1]
	v_pk_fma_f32 v[192:193], v[16:17], v[176:177], v[192:193] op_sel_hi:[1,0,1]
	v_mfma_f32_16x16x4_f32 v[102:105], v141, v214, v[102:105]
	v_pk_fma_f32 v[180:181], v[10:11], v[176:177], v[180:181] op_sel:[0,1,0]
	v_pk_fma_f32 v[192:193], v[12:13], v[176:177], v[192:193] op_sel:[0,1,0]
	v_pk_fma_f32 v[180:181], v[6:7], v[178:179], v[180:181] op_sel_hi:[1,0,1]
	v_pk_fma_f32 v[192:193], v[8:9], v[178:179], v[192:193] op_sel_hi:[1,0,1]
	v_mfma_f32_16x16x4_f32 v[98:101], v141, v215, v[98:101]
	v_pk_fma_f32 v[180:181], v[2:3], v[178:179], v[180:181] op_sel:[0,1,0]
	v_pk_fma_f32 v[192:193], v[4:5], v[178:179], v[192:193] op_sel:[0,1,0]
	v_pk_mul_f32 v[180:181], v[146:147], v[180:181]
	v_pk_mul_f32 v[192:193], v[146:147], v[192:193]
	v_pk_fma_f32 v[236:237], v[144:145], v[212:213], v[180:181]
	v_pk_fma_f32 v[238:239], v[144:145], v[214:215], v[192:193]
	global_store_dwordx4 v[150:151], v[236:239], off nt
	v_lshl_add_u64 v[150:151], v[150:151], 0, s[74:75]
	global_load_dwordx4 v[212:215], v[148:149], off nt
	v_lshl_add_u64 v[148:149], v[148:149], 0, s[74:75]
	ds_read_b32 v141, v160 offset:288
	ds_read_b128 v[114:117], v161 offset:2304
	ds_read_b128 v[176:179], v161 offset:2320
	s_waitcnt vmcnt(36)
	s_waitcnt lgkmcnt(3)
	v_cndmask_b32_e64 v143, 0, v143, s[8:9]
	v_pk_mul_f32 v[180:181], v[26:27], v[172:173] op_sel:[0,1]
	v_pk_mul_f32 v[192:193], v[28:29], v[172:173] op_sel:[0,1]
	v_mfma_f32_16x16x4_f32 v[110:113], v143, v216, v[110:113]
	v_pk_fma_f32 v[180:181], v[30:31], v[172:173], v[180:181] op_sel_hi:[1,0,1]
	v_pk_fma_f32 v[192:193], v[32:33], v[172:173], v[192:193] op_sel_hi:[1,0,1]
	v_pk_fma_f32 v[180:181], v[22:23], v[174:175], v[180:181] op_sel_hi:[1,0,1]
	v_pk_fma_f32 v[192:193], v[24:25], v[174:175], v[192:193] op_sel_hi:[1,0,1]
	v_mfma_f32_16x16x4_f32 v[106:109], v143, v217, v[106:109]
	v_pk_fma_f32 v[180:181], v[18:19], v[174:175], v[180:181] op_sel:[0,1,0]
	v_pk_fma_f32 v[192:193], v[20:21], v[174:175], v[192:193] op_sel:[0,1,0]
	v_pk_fma_f32 v[180:181], v[14:15], v[232:233], v[180:181] op_sel_hi:[1,0,1]
	v_pk_fma_f32 v[192:193], v[16:17], v[232:233], v[192:193] op_sel_hi:[1,0,1]
	v_mfma_f32_16x16x4_f32 v[102:105], v143, v218, v[102:105]
	v_pk_fma_f32 v[180:181], v[10:11], v[232:233], v[180:181] op_sel:[0,1,0]
	v_pk_fma_f32 v[192:193], v[12:13], v[232:233], v[192:193] op_sel:[0,1,0]
	v_pk_fma_f32 v[180:181], v[6:7], v[234:235], v[180:181] op_sel_hi:[1,0,1]
	v_pk_fma_f32 v[192:193], v[8:9], v[234:235], v[192:193] op_sel_hi:[1,0,1]
	v_mfma_f32_16x16x4_f32 v[98:101], v143, v219, v[98:101]
	v_pk_fma_f32 v[180:181], v[2:3], v[234:235], v[180:181] op_sel:[0,1,0]
	v_pk_fma_f32 v[192:193], v[4:5], v[234:235], v[192:193] op_sel:[0,1,0]
	v_pk_mul_f32 v[180:181], v[146:147], v[180:181]
	v_pk_mul_f32 v[192:193], v[146:147], v[192:193]
	v_pk_fma_f32 v[236:237], v[144:145], v[216:217], v[180:181]
	v_pk_fma_f32 v[238:239], v[144:145], v[218:219], v[192:193]
	global_store_dwordx4 v[150:151], v[236:239], off nt
	v_lshl_add_u64 v[150:151], v[150:151], 0, s[74:75]
	global_load_dwordx4 v[216:219], v[148:149], off nt
	v_lshl_add_u64 v[148:149], v[148:149], 0, s[74:75]
	ds_read_b32 v143, v160 offset:304
	ds_read_b128 v[172:175], v161 offset:2432
	ds_read_b128 v[232:235], v161 offset:2448
	s_waitcnt vmcnt(37)
	s_waitcnt lgkmcnt(3)
	v_cndmask_b32_e64 v141, 0, v141, s[8:9]
	v_pk_mul_f32 v[180:181], v[26:27], v[114:115] op_sel:[0,1]
	v_pk_mul_f32 v[192:193], v[28:29], v[114:115] op_sel:[0,1]
	v_mfma_f32_16x16x4_f32 v[110:113], v141, v224, v[110:113]
	v_pk_fma_f32 v[180:181], v[30:31], v[114:115], v[180:181] op_sel_hi:[1,0,1]
	v_pk_fma_f32 v[192:193], v[32:33], v[114:115], v[192:193] op_sel_hi:[1,0,1]
	v_pk_fma_f32 v[180:181], v[22:23], v[116:117], v[180:181] op_sel_hi:[1,0,1]
	v_pk_fma_f32 v[192:193], v[24:25], v[116:117], v[192:193] op_sel_hi:[1,0,1]
	v_mfma_f32_16x16x4_f32 v[106:109], v141, v225, v[106:109]
	v_pk_fma_f32 v[180:181], v[18:19], v[116:117], v[180:181] op_sel:[0,1,0]
	v_pk_fma_f32 v[192:193], v[20:21], v[116:117], v[192:193] op_sel:[0,1,0]
	v_pk_fma_f32 v[180:181], v[14:15], v[176:177], v[180:181] op_sel_hi:[1,0,1]
	v_pk_fma_f32 v[192:193], v[16:17], v[176:177], v[192:193] op_sel_hi:[1,0,1]
	v_mfma_f32_16x16x4_f32 v[102:105], v141, v226, v[102:105]
	v_pk_fma_f32 v[180:181], v[10:11], v[176:177], v[180:181] op_sel:[0,1,0]
	v_pk_fma_f32 v[192:193], v[12:13], v[176:177], v[192:193] op_sel:[0,1,0]
	v_pk_fma_f32 v[180:181], v[6:7], v[178:179], v[180:181] op_sel_hi:[1,0,1]
	v_pk_fma_f32 v[192:193], v[8:9], v[178:179], v[192:193] op_sel_hi:[1,0,1]
	v_mfma_f32_16x16x4_f32 v[98:101], v141, v227, v[98:101]
	v_pk_fma_f32 v[180:181], v[2:3], v[178:179], v[180:181] op_sel:[0,1,0]
	v_pk_fma_f32 v[192:193], v[4:5], v[178:179], v[192:193] op_sel:[0,1,0]
	v_pk_mul_f32 v[180:181], v[146:147], v[180:181]
	v_pk_mul_f32 v[192:193], v[146:147], v[192:193]
	v_pk_fma_f32 v[236:237], v[144:145], v[224:225], v[180:181]
	v_pk_fma_f32 v[238:239], v[144:145], v[226:227], v[192:193]
	global_store_dwordx4 v[150:151], v[236:239], off nt
	v_lshl_add_u64 v[150:151], v[150:151], 0, s[74:75]
	global_load_dwordx4 v[224:227], v[148:149], off nt
	v_lshl_add_u64 v[148:149], v[148:149], 0, s[74:75]
	ds_read_b32 v141, v160 offset:320
	ds_read_b128 v[114:117], v161 offset:2560
	ds_read_b128 v[176:179], v161 offset:2576
	s_waitcnt vmcnt(38)
; #define RS_LOAD(dst, it0) do { _Pragma("unroll") for (int u = 0; u < 8; ++u) dst[u] = __builtin_nontemporal_load((const f32x4*)(S0 + (size_t)(4 * ((it0) + u)) * DV)); } while (0)
; __device__ __forceinline__ void ret_sample_item(Frame& F, int item) {
;     ...
;     for (int it0 = 0; it0 < 64; it0 += 16) {
;         RS_LOAD(sb, it0 + 8);
;         RS_PROC(sa, it0);
;         { const int itn = it0 + 16 < 64 ? it0 + 16 : it0; RS_LOAD(sa, itn); }
	s_waitcnt lgkmcnt(3)
	v_cndmask_b32_e64 v143, 0, v143, s[8:9]
	v_pk_mul_f32 v[180:181], v[26:27], v[172:173] op_sel:[0,1]
	v_pk_mul_f32 v[192:193], v[28:29], v[172:173] op_sel:[0,1]
	v_mfma_f32_16x16x4_f32 v[110:113], v143, v228, v[110:113]
	v_pk_fma_f32 v[180:181], v[30:31], v[172:173], v[180:181] op_sel_hi:[1,0,1]
	v_pk_fma_f32 v[192:193], v[32:33], v[172:173], v[192:193] op_sel_hi:[1,0,1]
	v_pk_fma_f32 v[180:181], v[22:23], v[174:175], v[180:181] op_sel_hi:[1,0,1]
	v_pk_fma_f32 v[192:193], v[24:25], v[174:175], v[192:193] op_sel_hi:[1,0,1]
	v_mfma_f32_16x16x4_f32 v[106:109], v143, v229, v[106:109]
	v_pk_fma_f32 v[180:181], v[18:19], v[174:175], v[180:181] op_sel:[0,1,0]
	v_pk_fma_f32 v[192:193], v[20:21], v[174:175], v[192:193] op_sel:[0,1,0]
	v_pk_fma_f32 v[180:181], v[14:15], v[232:233], v[180:181] op_sel_hi:[1,0,1]
	v_pk_fma_f32 v[192:193], v[16:17], v[232:233], v[192:193] op_sel_hi:[1,0,1]
	v_mfma_f32_16x16x4_f32 v[102:105], v143, v230, v[102:105]
	v_pk_fma_f32 v[180:181], v[10:11], v[232:233], v[180:181] op_sel:[0,1,0]
	v_pk_fma_f32 v[192:193], v[12:13], v[232:233], v[192:193] op_sel:[0,1,0]
	v_pk_fma_f32 v[180:181], v[6:7], v[234:235], v[180:181] op_sel_hi:[1,0,1]
	v_pk_fma_f32 v[192:193], v[8:9], v[234:235], v[192:193] op_sel_hi:[1,0,1]
	v_mfma_f32_16x16x4_f32 v[98:101], v143, v231, v[98:101]
	v_pk_fma_f32 v[180:181], v[2:3], v[234:235], v[180:181] op_sel:[0,1,0]
	v_pk_fma_f32 v[192:193], v[4:5], v[234:235], v[192:193] op_sel:[0,1,0]
	v_pk_mul_f32 v[180:181], v[146:147], v[180:181]
	v_pk_mul_f32 v[192:193], v[146:147], v[192:193]
	v_pk_fma_f32 v[236:237], v[144:145], v[228:229], v[180:181]
	v_pk_fma_f32 v[238:239], v[144:145], v[230:231], v[192:193]
	global_store_dwordx4 v[150:151], v[236:239], off nt
	v_lshl_add_u64 v[150:151], v[150:151], 0, s[74:75]
	global_load_dwordx4 v[228:231], v[148:149], off nt
	v_lshl_add_u64 v[148:149], v[148:149], 0, s[74:75]
	ds_read_b32 v143, v160 offset:336
	ds_read_b128 v[172:175], v161 offset:2688
	ds_read_b128 v[232:235], v161 offset:2704
	s_waitcnt vmcnt(38)
	s_waitcnt lgkmcnt(3)
	v_cndmask_b32_e64 v141, 0, v141, s[8:9]
	v_pk_mul_f32 v[180:181], v[26:27], v[114:115] op_sel:[0,1]
	v_pk_mul_f32 v[192:193], v[28:29], v[114:115] op_sel:[0,1]
	v_mfma_f32_16x16x4_f32 v[110:113], v141, v70, v[110:113]
	v_pk_fma_f32 v[180:181], v[30:31], v[114:115], v[180:181] op_sel_hi:[1,0,1]
	v_pk_fma_f32 v[192:193], v[32:33], v[114:115], v[192:193] op_sel_hi:[1,0,1]
	v_pk_fma_f32 v[180:181], v[22:23], v[116:117], v[180:181] op_sel_hi:[1,0,1]
	v_pk_fma_f32 v[192:193], v[24:25], v[116:117], v[192:193] op_sel_hi:[1,0,1]
	v_mfma_f32_16x16x4_f32 v[106:109], v141, v71, v[106:109]
	v_pk_fma_f32 v[180:181], v[18:19], v[116:117], v[180:181] op_sel:[0,1,0]
	v_pk_fma_f32 v[192:193], v[20:21], v[116:117], v[192:193] op_sel:[0,1,0]
	v_pk_fma_f32 v[180:181], v[14:15], v[176:177], v[180:181] op_sel_hi:[1,0,1]
	v_pk_fma_f32 v[192:193], v[16:17], v[176:177], v[192:193] op_sel_hi:[1,0,1]
	v_mfma_f32_16x16x4_f32 v[102:105], v141, v72, v[102:105]
	v_pk_fma_f32 v[180:181], v[10:11], v[176:177], v[180:181] op_sel:[0,1,0]
	v_pk_fma_f32 v[192:193], v[12:13], v[176:177], v[192:193] op_sel:[0,1,0]
	v_pk_fma_f32 v[180:181], v[6:7], v[178:179], v[180:181] op_sel_hi:[1,0,1]
	v_pk_fma_f32 v[192:193], v[8:9], v[178:179], v[192:193] op_sel_hi:[1,0,1]
	v_mfma_f32_16x16x4_f32 v[98:101], v141, v73, v[98:101]
	v_pk_fma_f32 v[180:181], v[2:3], v[178:179], v[180:181] op_sel:[0,1,0]
	v_pk_fma_f32 v[192:193], v[4:5], v[178:179], v[192:193] op_sel:[0,1,0]
	v_pk_mul_f32 v[180:181], v[146:147], v[180:181]
	v_pk_mul_f32 v[192:193], v[146:147], v[192:193]
	v_pk_fma_f32 v[236:237], v[144:145], v[70:71], v[180:181]
	v_pk_fma_f32 v[238:239], v[144:145], v[72:73], v[192:193]
	global_store_dwordx4 v[150:151], v[236:239], off nt
	v_lshl_add_u64 v[150:151], v[150:151], 0, s[74:75]
	global_load_dwordx4 v[70:73], v[148:149], off nt
	v_lshl_add_u64 v[148:149], v[148:149], 0, s[74:75]
	ds_read_b32 v141, v160 offset:352
	ds_read_b128 v[114:117], v161 offset:2816
	ds_read_b128 v[176:179], v161 offset:2832
	s_waitcnt vmcnt(38)
	s_waitcnt lgkmcnt(3)
	v_cndmask_b32_e64 v143, 0, v143, s[8:9]
	v_pk_mul_f32 v[180:181], v[26:27], v[172:173] op_sel:[0,1]
	v_pk_mul_f32 v[192:193], v[28:29], v[172:173] op_sel:[0,1]
	v_mfma_f32_16x16x4_f32 v[110:113], v143, v62, v[110:113]
	v_pk_fma_f32 v[180:181], v[30:31], v[172:173], v[180:181] op_sel_hi:[1,0,1]
	v_pk_fma_f32 v[192:193], v[32:33], v[172:173], v[192:193] op_sel_hi:[1,0,1]
	v_pk_fma_f32 v[180:181], v[22:23], v[174:175], v[180:181] op_sel_hi:[1,0,1]
	v_pk_fma_f32 v[192:193], v[24:25], v[174:175], v[192:193] op_sel_hi:[1,0,1]
	v_mfma_f32_16x16x4_f32 v[106:109], v143, v63, v[106:109]
	v_pk_fma_f32 v[180:181], v[18:19], v[174:175], v[180:181] op_sel:[0,1,0]
	v_pk_fma_f32 v[192:193], v[20:21], v[174:175], v[192:193] op_sel:[0,1,0]
	v_pk_fma_f32 v[180:181], v[14:15], v[232:233], v[180:181] op_sel_hi:[1,0,1]
	v_pk_fma_f32 v[192:193], v[16:17], v[232:233], v[192:193] op_sel_hi:[1,0,1]
	v_mfma_f32_16x16x4_f32 v[102:105], v143, v64, v[102:105]
	v_pk_fma_f32 v[180:181], v[10:11], v[232:233], v[180:181] op_sel:[0,1,0]
	v_pk_fma_f32 v[192:193], v[12:13], v[232:233], v[192:193] op_sel:[0,1,0]
	v_pk_fma_f32 v[180:181], v[6:7], v[234:235], v[180:181] op_sel_hi:[1,0,1]
	v_pk_fma_f32 v[192:193], v[8:9], v[234:235], v[192:193] op_sel_hi:[1,0,1]
	v_mfma_f32_16x16x4_f32 v[98:101], v143, v65, v[98:101]
	v_pk_fma_f32 v[180:181], v[2:3], v[234:235], v[180:181] op_sel:[0,1,0]
	v_pk_fma_f32 v[192:193], v[4:5], v[234:235], v[192:193] op_sel:[0,1,0]
	v_pk_mul_f32 v[180:181], v[146:147], v[180:181]
	v_pk_mul_f32 v[192:193], v[146:147], v[192:193]
	v_pk_fma_f32 v[236:237], v[144:145], v[62:63], v[180:181]
	v_pk_fma_f32 v[238:239], v[144:145], v[64:65], v[192:193]
	global_store_dwordx4 v[150:151], v[236:239], off nt
	v_lshl_add_u64 v[150:151], v[150:151], 0, s[74:75]
	global_load_dwordx4 v[62:65], v[148:149], off nt
	v_lshl_add_u64 v[148:149], v[148:149], 0, s[74:75]
	ds_read_b32 v143, v160 offset:368
	ds_read_b128 v[172:175], v161 offset:2944
	ds_read_b128 v[232:235], v161 offset:2960
	s_waitcnt vmcnt(38)
; #define RS_LOAD(dst, it0) do { _Pragma("unroll") for (int u = 0; u < 8; ++u) dst[u] = __builtin_nontemporal_load((const f32x4*)(S0 + (size_t)(4 * ((it0) + u)) * DV)); } while (0)
; __device__ __forceinline__ void ret_sample_item(Frame& F, int item) {
;     ...
;     for (int it0 = 0; it0 < 64; it0 += 16) {
;         RS_LOAD(sb, it0 + 8);
;         RS_PROC(sa, it0);
;         { const int itn = it0 + 16 < 64 ? it0 + 16 : it0; RS_LOAD(sa, itn); }
	s_waitcnt lgkmcnt(3)
	v_cndmask_b32_e64 v141, 0, v141, s[8:9]
	v_pk_mul_f32 v[180:181], v[26:27], v[114:115] op_sel:[0,1]
	v_pk_mul_f32 v[192:193], v[28:29], v[114:115] op_sel:[0,1]
	v_mfma_f32_16x16x4_f32 v[110:113], v141, v54, v[110:113]
	v_pk_fma_f32 v[180:181], v[30:31], v[114:115], v[180:181] op_sel_hi:[1,0,1]
	v_pk_fma_f32 v[192:193], v[32:33], v[114:115], v[192:193] op_sel_hi:[1,0,1]
	v_pk_fma_f32 v[180:181], v[22:23], v[116:117], v[180:181] op_sel_hi:[1,0,1]
	v_pk_fma_f32 v[192:193], v[24:25], v[116:117], v[192:193] op_sel_hi:[1,0,1]
	v_mfma_f32_16x16x4_f32 v[106:109], v141, v55, v[106:109]
	v_pk_fma_f32 v[180:181], v[18:19], v[116:117], v[180:181] op_sel:[0,1,0]
	v_pk_fma_f32 v[192:193], v[20:21], v[116:117], v[192:193] op_sel:[0,1,0]
	v_pk_fma_f32 v[180:181], v[14:15], v[176:177], v[180:181] op_sel_hi:[1,0,1]
	v_pk_fma_f32 v[192:193], v[16:17], v[176:177], v[192:193] op_sel_hi:[1,0,1]
	v_mfma_f32_16x16x4_f32 v[102:105], v141, v56, v[102:105]
	v_pk_fma_f32 v[180:181], v[10:11], v[176:177], v[180:181] op_sel:[0,1,0]
	v_pk_fma_f32 v[192:193], v[12:13], v[176:177], v[192:193] op_sel:[0,1,0]
	v_pk_fma_f32 v[180:181], v[6:7], v[178:179], v[180:181] op_sel_hi:[1,0,1]
	v_pk_fma_f32 v[192:193], v[8:9], v[178:179], v[192:193] op_sel_hi:[1,0,1]
	v_mfma_f32_16x16x4_f32 v[98:101], v141, v57, v[98:101]
	v_pk_fma_f32 v[180:181], v[2:3], v[178:179], v[180:181] op_sel:[0,1,0]
	v_pk_fma_f32 v[192:193], v[4:5], v[178:179], v[192:193] op_sel:[0,1,0]
	v_pk_mul_f32 v[180:181], v[146:147], v[180:181]
	v_pk_mul_f32 v[192:193], v[146:147], v[192:193]
	v_pk_fma_f32 v[236:237], v[144:145], v[54:55], v[180:181]
	v_pk_fma_f32 v[238:239], v[144:145], v[56:57], v[192:193]
	global_store_dwordx4 v[150:151], v[236:239], off nt
	v_lshl_add_u64 v[150:151], v[150:151], 0, s[74:75]
	global_load_dwordx4 v[54:57], v[148:149], off nt
	v_lshl_add_u64 v[148:149], v[148:149], 0, s[74:75]
	ds_read_b32 v141, v160 offset:384
	ds_read_b128 v[114:117], v161 offset:3072
	ds_read_b128 v[176:179], v161 offset:3088
	s_waitcnt vmcnt(38)
	s_waitcnt lgkmcnt(3)
	v_cndmask_b32_e64 v143, 0, v143, s[8:9]
	v_pk_mul_f32 v[180:181], v[26:27], v[172:173] op_sel:[0,1]
	v_pk_mul_f32 v[192:193], v[28:29], v[172:173] op_sel:[0,1]
	v_mfma_f32_16x16x4_f32 v[110:113], v143, v50, v[110:113]
	v_pk_fma_f32 v[180:181], v[30:31], v[172:173], v[180:181] op_sel_hi:[1,0,1]
	v_pk_fma_f32 v[192:193], v[32:33], v[172:173], v[192:193] op_sel_hi:[1,0,1]
	v_pk_fma_f32 v[180:181], v[22:23], v[174:175], v[180:181] op_sel_hi:[1,0,1]
	v_pk_fma_f32 v[192:193], v[24:25], v[174:175], v[192:193] op_sel_hi:[1,0,1]
	v_mfma_f32_16x16x4_f32 v[106:109], v143, v51, v[106:109]
	v_pk_fma_f32 v[180:181], v[18:19], v[174:175], v[180:181] op_sel:[0,1,0]
	v_pk_fma_f32 v[192:193], v[20:21], v[174:175], v[192:193] op_sel:[0,1,0]
	v_pk_fma_f32 v[180:181], v[14:15], v[232:233], v[180:181] op_sel_hi:[1,0,1]
	v_pk_fma_f32 v[192:193], v[16:17], v[232:233], v[192:193] op_sel_hi:[1,0,1]
	v_mfma_f32_16x16x4_f32 v[102:105], v143, v52, v[102:105]
	v_pk_fma_f32 v[180:181], v[10:11], v[232:233], v[180:181] op_sel:[0,1,0]
	v_pk_fma_f32 v[192:193], v[12:13], v[232:233], v[192:193] op_sel:[0,1,0]
	v_pk_fma_f32 v[180:181], v[6:7], v[234:235], v[180:181] op_sel_hi:[1,0,1]
	v_pk_fma_f32 v[192:193], v[8:9], v[234:235], v[192:193] op_sel_hi:[1,0,1]
	v_mfma_f32_16x16x4_f32 v[98:101], v143, v53, v[98:101]
	v_pk_fma_f32 v[180:181], v[2:3], v[234:235], v[180:181] op_sel:[0,1,0]
	v_pk_fma_f32 v[192:193], v[4:5], v[234:235], v[192:193] op_sel:[0,1,0]
	v_pk_mul_f32 v[180:181], v[146:147], v[180:181]
	v_pk_mul_f32 v[192:193], v[146:147], v[192:193]
	v_pk_fma_f32 v[236:237], v[144:145], v[50:51], v[180:181]
	v_pk_fma_f32 v[238:239], v[144:145], v[52:53], v[192:193]
	global_store_dwordx4 v[150:151], v[236:239], off nt
	v_lshl_add_u64 v[150:151], v[150:151], 0, s[74:75]
	global_load_dwordx4 v[50:53], v[148:149], off nt
	v_lshl_add_u64 v[148:149], v[148:149], 0, s[74:75]
	ds_read_b32 v143, v160 offset:400
	ds_read_b128 v[172:175], v161 offset:3200
	ds_read_b128 v[232:235], v161 offset:3216
	s_waitcnt vmcnt(38)
	s_waitcnt lgkmcnt(3)
	v_cndmask_b32_e64 v141, 0, v141, s[8:9]
	v_pk_mul_f32 v[180:181], v[26:27], v[114:115] op_sel:[0,1]
	v_pk_mul_f32 v[192:193], v[28:29], v[114:115] op_sel:[0,1]
	v_mfma_f32_16x16x4_f32 v[110:113], v141, v46, v[110:113]
	v_pk_fma_f32 v[180:181], v[30:31], v[114:115], v[180:181] op_sel_hi:[1,0,1]
	v_pk_fma_f32 v[192:193], v[32:33], v[114:115], v[192:193] op_sel_hi:[1,0,1]
	v_pk_fma_f32 v[180:181], v[22:23], v[116:117], v[180:181] op_sel_hi:[1,0,1]
	v_pk_fma_f32 v[192:193], v[24:25], v[116:117], v[192:193] op_sel_hi:[1,0,1]
	v_mfma_f32_16x16x4_f32 v[106:109], v141, v47, v[106:109]
	v_pk_fma_f32 v[180:181], v[18:19], v[116:117], v[180:181] op_sel:[0,1,0]
	v_pk_fma_f32 v[192:193], v[20:21], v[116:117], v[192:193] op_sel:[0,1,0]
	v_pk_fma_f32 v[180:181], v[14:15], v[176:177], v[180:181] op_sel_hi:[1,0,1]
	v_pk_fma_f32 v[192:193], v[16:17], v[176:177], v[192:193] op_sel_hi:[1,0,1]
	v_mfma_f32_16x16x4_f32 v[102:105], v141, v48, v[102:105]
	v_pk_fma_f32 v[180:181], v[10:11], v[176:177], v[180:181] op_sel:[0,1,0]
	v_pk_fma_f32 v[192:193], v[12:13], v[176:177], v[192:193] op_sel:[0,1,0]
	v_pk_fma_f32 v[180:181], v[6:7], v[178:179], v[180:181] op_sel_hi:[1,0,1]
	v_pk_fma_f32 v[192:193], v[8:9], v[178:179], v[192:193] op_sel_hi:[1,0,1]
	v_mfma_f32_16x16x4_f32 v[98:101], v141, v49, v[98:101]
	v_pk_fma_f32 v[180:181], v[2:3], v[178:179], v[180:181] op_sel:[0,1,0]
	v_pk_fma_f32 v[192:193], v[4:5], v[178:179], v[192:193] op_sel:[0,1,0]
	v_pk_mul_f32 v[180:181], v[146:147], v[180:181]
	v_pk_mul_f32 v[192:193], v[146:147], v[192:193]
	v_pk_fma_f32 v[236:237], v[144:145], v[46:47], v[180:181]
	v_pk_fma_f32 v[238:239], v[144:145], v[48:49], v[192:193]
	global_store_dwordx4 v[150:151], v[236:239], off nt
	v_lshl_add_u64 v[150:151], v[150:151], 0, s[74:75]
	global_load_dwordx4 v[46:49], v[148:149], off nt
	v_lshl_add_u64 v[148:149], v[148:149], 0, s[74:75]
	ds_read_b32 v141, v160 offset:416
	ds_read_b128 v[114:117], v161 offset:3328
	ds_read_b128 v[176:179], v161 offset:3344
	s_waitcnt vmcnt(38)
; #define RS_LOAD(dst, it0) do { _Pragma("unroll") for (int u = 0; u < 8; ++u) dst[u] = __builtin_nontemporal_load((const f32x4*)(S0 + (size_t)(4 * ((it0) + u)) * DV)); } while (0)
; __device__ __forceinline__ void ret_sample_item(Frame& F, int item) {
;     ...
;     for (int it0 = 0; it0 < 64; it0 += 16) {
;         RS_LOAD(sb, it0 + 8);
;         RS_PROC(sa, it0);
;         { const int itn = it0 + 16 < 64 ? it0 + 16 : it0; RS_LOAD(sa, itn); }
	s_waitcnt lgkmcnt(3)
	v_cndmask_b32_e64 v143, 0, v143, s[8:9]
	v_pk_mul_f32 v[180:181], v[26:27], v[172:173] op_sel:[0,1]
	v_pk_mul_f32 v[192:193], v[28:29], v[172:173] op_sel:[0,1]
	v_mfma_f32_16x16x4_f32 v[110:113], v143, v42, v[110:113]
	v_pk_fma_f32 v[180:181], v[30:31], v[172:173], v[180:181] op_sel_hi:[1,0,1]
	v_pk_fma_f32 v[192:193], v[32:33], v[172:173], v[192:193] op_sel_hi:[1,0,1]
	v_pk_fma_f32 v[180:181], v[22:23], v[174:175], v[180:181] op_sel_hi:[1,0,1]
	v_pk_fma_f32 v[192:193], v[24:25], v[174:175], v[192:193] op_sel_hi:[1,0,1]
	v_mfma_f32_16x16x4_f32 v[106:109], v143, v43, v[106:109]
	v_pk_fma_f32 v[180:181], v[18:19], v[174:175], v[180:181] op_sel:[0,1,0]
	v_pk_fma_f32 v[192:193], v[20:21], v[174:175], v[192:193] op_sel:[0,1,0]
	v_pk_fma_f32 v[180:181], v[14:15], v[232:233], v[180:181] op_sel_hi:[1,0,1]
	v_pk_fma_f32 v[192:193], v[16:17], v[232:233], v[192:193] op_sel_hi:[1,0,1]
	v_mfma_f32_16x16x4_f32 v[102:105], v143, v44, v[102:105]
	v_pk_fma_f32 v[180:181], v[10:11], v[232:233], v[180:181] op_sel:[0,1,0]
	v_pk_fma_f32 v[192:193], v[12:13], v[232:233], v[192:193] op_sel:[0,1,0]
	v_pk_fma_f32 v[180:181], v[6:7], v[234:235], v[180:181] op_sel_hi:[1,0,1]
	v_pk_fma_f32 v[192:193], v[8:9], v[234:235], v[192:193] op_sel_hi:[1,0,1]
	v_mfma_f32_16x16x4_f32 v[98:101], v143, v45, v[98:101]
	v_pk_fma_f32 v[180:181], v[2:3], v[234:235], v[180:181] op_sel:[0,1,0]
	v_pk_fma_f32 v[192:193], v[4:5], v[234:235], v[192:193] op_sel:[0,1,0]
	v_pk_mul_f32 v[180:181], v[146:147], v[180:181]
	v_pk_mul_f32 v[192:193], v[146:147], v[192:193]
	v_pk_fma_f32 v[236:237], v[144:145], v[42:43], v[180:181]
	v_pk_fma_f32 v[238:239], v[144:145], v[44:45], v[192:193]
	global_store_dwordx4 v[150:151], v[236:239], off nt
	v_lshl_add_u64 v[150:151], v[150:151], 0, s[74:75]
	global_load_dwordx4 v[42:45], v[148:149], off nt
	v_lshl_add_u64 v[148:149], v[148:149], 0, s[74:75]
	ds_read_b32 v143, v160 offset:432
	ds_read_b128 v[172:175], v161 offset:3456
	ds_read_b128 v[232:235], v161 offset:3472
	s_waitcnt vmcnt(38)
	s_waitcnt lgkmcnt(3)
	v_cndmask_b32_e64 v141, 0, v141, s[8:9]
	v_pk_mul_f32 v[180:181], v[26:27], v[114:115] op_sel:[0,1]
	v_pk_mul_f32 v[192:193], v[28:29], v[114:115] op_sel:[0,1]
	v_mfma_f32_16x16x4_f32 v[110:113], v141, v38, v[110:113]
	v_pk_fma_f32 v[180:181], v[30:31], v[114:115], v[180:181] op_sel_hi:[1,0,1]
	v_pk_fma_f32 v[192:193], v[32:33], v[114:115], v[192:193] op_sel_hi:[1,0,1]
	v_pk_fma_f32 v[180:181], v[22:23], v[116:117], v[180:181] op_sel_hi:[1,0,1]
	v_pk_fma_f32 v[192:193], v[24:25], v[116:117], v[192:193] op_sel_hi:[1,0,1]
	v_mfma_f32_16x16x4_f32 v[106:109], v141, v39, v[106:109]
	v_pk_fma_f32 v[180:181], v[18:19], v[116:117], v[180:181] op_sel:[0,1,0]
	v_pk_fma_f32 v[192:193], v[20:21], v[116:117], v[192:193] op_sel:[0,1,0]
	v_pk_fma_f32 v[180:181], v[14:15], v[176:177], v[180:181] op_sel_hi:[1,0,1]
	v_pk_fma_f32 v[192:193], v[16:17], v[176:177], v[192:193] op_sel_hi:[1,0,1]
	v_mfma_f32_16x16x4_f32 v[102:105], v141, v40, v[102:105]
	v_pk_fma_f32 v[180:181], v[10:11], v[176:177], v[180:181] op_sel:[0,1,0]
	v_pk_fma_f32 v[192:193], v[12:13], v[176:177], v[192:193] op_sel:[0,1,0]
	v_pk_fma_f32 v[180:181], v[6:7], v[178:179], v[180:181] op_sel_hi:[1,0,1]
	v_pk_fma_f32 v[192:193], v[8:9], v[178:179], v[192:193] op_sel_hi:[1,0,1]
	v_mfma_f32_16x16x4_f32 v[98:101], v141, v41, v[98:101]
	v_pk_fma_f32 v[180:181], v[2:3], v[178:179], v[180:181] op_sel:[0,1,0]
	v_pk_fma_f32 v[192:193], v[4:5], v[178:179], v[192:193] op_sel:[0,1,0]
	v_pk_mul_f32 v[180:181], v[146:147], v[180:181]
	v_pk_mul_f32 v[192:193], v[146:147], v[192:193]
	v_pk_fma_f32 v[236:237], v[144:145], v[38:39], v[180:181]
	v_pk_fma_f32 v[238:239], v[144:145], v[40:41], v[192:193]
	global_store_dwordx4 v[150:151], v[236:239], off nt
	v_lshl_add_u64 v[150:151], v[150:151], 0, s[74:75]
	global_load_dwordx4 v[38:41], v[148:149], off nt
	v_lshl_add_u64 v[148:149], v[148:149], 0, s[74:75]
	ds_read_b32 v141, v160 offset:448
	ds_read_b128 v[114:117], v161 offset:3584
	ds_read_b128 v[176:179], v161 offset:3600
	s_waitcnt vmcnt(38)
	s_waitcnt lgkmcnt(3)
	v_cndmask_b32_e64 v143, 0, v143, s[8:9]
	v_pk_mul_f32 v[180:181], v[26:27], v[172:173] op_sel:[0,1]
	v_pk_mul_f32 v[192:193], v[28:29], v[172:173] op_sel:[0,1]
	v_mfma_f32_16x16x4_f32 v[110:113], v143, v34, v[110:113]
	v_pk_fma_f32 v[180:181], v[30:31], v[172:173], v[180:181] op_sel_hi:[1,0,1]
	v_pk_fma_f32 v[192:193], v[32:33], v[172:173], v[192:193] op_sel_hi:[1,0,1]
	v_pk_fma_f32 v[180:181], v[22:23], v[174:175], v[180:181] op_sel_hi:[1,0,1]
	v_pk_fma_f32 v[192:193], v[24:25], v[174:175], v[192:193] op_sel_hi:[1,0,1]
	v_mfma_f32_16x16x4_f32 v[106:109], v143, v35, v[106:109]
	v_pk_fma_f32 v[180:181], v[18:19], v[174:175], v[180:181] op_sel:[0,1,0]
	v_pk_fma_f32 v[192:193], v[20:21], v[174:175], v[192:193] op_sel:[0,1,0]
	v_pk_fma_f32 v[180:181], v[14:15], v[232:233], v[180:181] op_sel_hi:[1,0,1]
	v_pk_fma_f32 v[192:193], v[16:17], v[232:233], v[192:193] op_sel_hi:[1,0,1]
	v_mfma_f32_16x16x4_f32 v[102:105], v143, v36, v[102:105]
	v_pk_fma_f32 v[180:181], v[10:11], v[232:233], v[180:181] op_sel:[0,1,0]
	v_pk_fma_f32 v[192:193], v[12:13], v[232:233], v[192:193] op_sel:[0,1,0]
	v_pk_fma_f32 v[180:181], v[6:7], v[234:235], v[180:181] op_sel_hi:[1,0,1]
	v_pk_fma_f32 v[192:193], v[8:9], v[234:235], v[192:193] op_sel_hi:[1,0,1]
	v_mfma_f32_16x16x4_f32 v[98:101], v143, v37, v[98:101]
	v_pk_fma_f32 v[180:181], v[2:3], v[234:235], v[180:181] op_sel:[0,1,0]
	v_pk_fma_f32 v[192:193], v[4:5], v[234:235], v[192:193] op_sel:[0,1,0]
	v_pk_mul_f32 v[180:181], v[146:147], v[180:181]
	v_pk_mul_f32 v[192:193], v[146:147], v[192:193]
	v_pk_fma_f32 v[236:237], v[144:145], v[34:35], v[180:181]
	v_pk_fma_f32 v[238:239], v[144:145], v[36:37], v[192:193]
	global_store_dwordx4 v[150:151], v[236:239], off nt
	v_lshl_add_u64 v[150:151], v[150:151], 0, s[74:75]
	global_load_dwordx4 v[34:37], v[148:149], off nt
	v_lshl_add_u64 v[148:149], v[148:149], 0, s[74:75]
	ds_read_b32 v143, v160 offset:464
	ds_read_b128 v[172:175], v161 offset:3712
	ds_read_b128 v[232:235], v161 offset:3728
	s_waitcnt vmcnt(38)
; #define RS_LOAD(dst, it0) do { _Pragma("unroll") for (int u = 0; u < 8; ++u) dst[u] = __builtin_nontemporal_load((const f32x4*)(S0 + (size_t)(4 * ((it0) + u)) * DV)); } while (0)
; __device__ __forceinline__ void ret_sample_item(Frame& F, int item) {
;     ...
;     for (int it0 = 0; it0 < 64; it0 += 16) {
;         RS_LOAD(sb, it0 + 8);
;         RS_PROC(sa, it0);
;         { const int itn = it0 + 16 < 64 ? it0 + 16 : it0; RS_LOAD(sa, itn); }
	s_waitcnt lgkmcnt(3)
	v_cndmask_b32_e64 v141, 0, v141, s[8:9]
	v_pk_mul_f32 v[180:181], v[26:27], v[114:115] op_sel:[0,1]
	v_pk_mul_f32 v[192:193], v[28:29], v[114:115] op_sel:[0,1]
	v_mfma_f32_16x16x4_f32 v[110:113], v141, v58, v[110:113]
	v_pk_fma_f32 v[180:181], v[30:31], v[114:115], v[180:181] op_sel_hi:[1,0,1]
	v_pk_fma_f32 v[192:193], v[32:33], v[114:115], v[192:193] op_sel_hi:[1,0,1]
	v_pk_fma_f32 v[180:181], v[22:23], v[116:117], v[180:181] op_sel_hi:[1,0,1]
	v_pk_fma_f32 v[192:193], v[24:25], v[116:117], v[192:193] op_sel_hi:[1,0,1]
	v_mfma_f32_16x16x4_f32 v[106:109], v141, v59, v[106:109]
	v_pk_fma_f32 v[180:181], v[18:19], v[116:117], v[180:181] op_sel:[0,1,0]
	v_pk_fma_f32 v[192:193], v[20:21], v[116:117], v[192:193] op_sel:[0,1,0]
	v_pk_fma_f32 v[180:181], v[14:15], v[176:177], v[180:181] op_sel_hi:[1,0,1]
	v_pk_fma_f32 v[192:193], v[16:17], v[176:177], v[192:193] op_sel_hi:[1,0,1]
	v_mfma_f32_16x16x4_f32 v[102:105], v141, v60, v[102:105]
	v_pk_fma_f32 v[180:181], v[10:11], v[176:177], v[180:181] op_sel:[0,1,0]
	v_pk_fma_f32 v[192:193], v[12:13], v[176:177], v[192:193] op_sel:[0,1,0]
	v_pk_fma_f32 v[180:181], v[6:7], v[178:179], v[180:181] op_sel_hi:[1,0,1]
	v_pk_fma_f32 v[192:193], v[8:9], v[178:179], v[192:193] op_sel_hi:[1,0,1]
	v_mfma_f32_16x16x4_f32 v[98:101], v141, v61, v[98:101]
	v_pk_fma_f32 v[180:181], v[2:3], v[178:179], v[180:181] op_sel:[0,1,0]
	v_pk_fma_f32 v[192:193], v[4:5], v[178:179], v[192:193] op_sel:[0,1,0]
	v_pk_mul_f32 v[180:181], v[146:147], v[180:181]
	v_pk_mul_f32 v[192:193], v[146:147], v[192:193]
	v_pk_fma_f32 v[236:237], v[144:145], v[58:59], v[180:181]
	v_pk_fma_f32 v[238:239], v[144:145], v[60:61], v[192:193]
	global_store_dwordx4 v[150:151], v[236:239], off nt
	v_lshl_add_u64 v[150:151], v[150:151], 0, s[74:75]
	global_load_dwordx4 v[58:61], v[148:149], off nt
	v_lshl_add_u64 v[148:149], v[148:149], 0, s[74:75]
	ds_read_b32 v141, v160 offset:480
	ds_read_b128 v[114:117], v161 offset:3840
	ds_read_b128 v[176:179], v161 offset:3856
	s_waitcnt vmcnt(38)
	s_waitcnt lgkmcnt(3)
	v_cndmask_b32_e64 v143, 0, v143, s[8:9]
	v_pk_mul_f32 v[180:181], v[26:27], v[172:173] op_sel:[0,1]
	v_pk_mul_f32 v[192:193], v[28:29], v[172:173] op_sel:[0,1]
	v_mfma_f32_16x16x4_f32 v[110:113], v143, v66, v[110:113]
	v_pk_fma_f32 v[180:181], v[30:31], v[172:173], v[180:181] op_sel_hi:[1,0,1]
	v_pk_fma_f32 v[192:193], v[32:33], v[172:173], v[192:193] op_sel_hi:[1,0,1]
	v_pk_fma_f32 v[180:181], v[22:23], v[174:175], v[180:181] op_sel_hi:[1,0,1]
	v_pk_fma_f32 v[192:193], v[24:25], v[174:175], v[192:193] op_sel_hi:[1,0,1]
	v_mfma_f32_16x16x4_f32 v[106:109], v143, v67, v[106:109]
	v_pk_fma_f32 v[180:181], v[18:19], v[174:175], v[180:181] op_sel:[0,1,0]
	v_pk_fma_f32 v[192:193], v[20:21], v[174:175], v[192:193] op_sel:[0,1,0]
	v_pk_fma_f32 v[180:181], v[14:15], v[232:233], v[180:181] op_sel_hi:[1,0,1]
	v_pk_fma_f32 v[192:193], v[16:17], v[232:233], v[192:193] op_sel_hi:[1,0,1]
	v_mfma_f32_16x16x4_f32 v[102:105], v143, v68, v[102:105]
	v_pk_fma_f32 v[180:181], v[10:11], v[232:233], v[180:181] op_sel:[0,1,0]
	v_pk_fma_f32 v[192:193], v[12:13], v[232:233], v[192:193] op_sel:[0,1,0]
	v_pk_fma_f32 v[180:181], v[6:7], v[234:235], v[180:181] op_sel_hi:[1,0,1]
	v_pk_fma_f32 v[192:193], v[8:9], v[234:235], v[192:193] op_sel_hi:[1,0,1]
	v_mfma_f32_16x16x4_f32 v[98:101], v143, v69, v[98:101]
	v_pk_fma_f32 v[180:181], v[2:3], v[234:235], v[180:181] op_sel:[0,1,0]
	v_pk_fma_f32 v[192:193], v[4:5], v[234:235], v[192:193] op_sel:[0,1,0]
	v_pk_mul_f32 v[180:181], v[146:147], v[180:181]
	v_pk_mul_f32 v[192:193], v[146:147], v[192:193]
	v_pk_fma_f32 v[236:237], v[144:145], v[66:67], v[180:181]
	v_pk_fma_f32 v[238:239], v[144:145], v[68:69], v[192:193]
	global_store_dwordx4 v[150:151], v[236:239], off nt
	v_lshl_add_u64 v[150:151], v[150:151], 0, s[74:75]
	global_load_dwordx4 v[66:69], v[148:149], off nt
	v_lshl_add_u64 v[148:149], v[148:149], 0, s[74:75]
	ds_read_b32 v143, v160 offset:496
	ds_read_b128 v[172:175], v161 offset:3968
	ds_read_b128 v[232:235], v161 offset:3984
	s_waitcnt vmcnt(38)
	s_waitcnt lgkmcnt(3)
	v_cndmask_b32_e64 v141, 0, v141, s[8:9]
	v_pk_mul_f32 v[180:181], v[26:27], v[114:115] op_sel:[0,1]
	v_pk_mul_f32 v[192:193], v[28:29], v[114:115] op_sel:[0,1]
	v_mfma_f32_16x16x4_f32 v[110:113], v141, v74, v[110:113]
	v_pk_fma_f32 v[180:181], v[30:31], v[114:115], v[180:181] op_sel_hi:[1,0,1]
	v_pk_fma_f32 v[192:193], v[32:33], v[114:115], v[192:193] op_sel_hi:[1,0,1]
	v_pk_fma_f32 v[180:181], v[22:23], v[116:117], v[180:181] op_sel_hi:[1,0,1]
	v_pk_fma_f32 v[192:193], v[24:25], v[116:117], v[192:193] op_sel_hi:[1,0,1]
	v_mfma_f32_16x16x4_f32 v[106:109], v141, v75, v[106:109]
	v_pk_fma_f32 v[180:181], v[18:19], v[116:117], v[180:181] op_sel:[0,1,0]
	v_pk_fma_f32 v[192:193], v[20:21], v[116:117], v[192:193] op_sel:[0,1,0]
	v_pk_fma_f32 v[180:181], v[14:15], v[176:177], v[180:181] op_sel_hi:[1,0,1]
	v_pk_fma_f32 v[192:193], v[16:17], v[176:177], v[192:193] op_sel_hi:[1,0,1]
	v_mfma_f32_16x16x4_f32 v[102:105], v141, v76, v[102:105]
	v_pk_fma_f32 v[180:181], v[10:11], v[176:177], v[180:181] op_sel:[0,1,0]
	v_pk_fma_f32 v[192:193], v[12:13], v[176:177], v[192:193] op_sel:[0,1,0]
	v_pk_fma_f32 v[180:181], v[6:7], v[178:179], v[180:181] op_sel_hi:[1,0,1]
	v_pk_fma_f32 v[192:193], v[8:9], v[178:179], v[192:193] op_sel_hi:[1,0,1]
	v_mfma_f32_16x16x4_f32 v[98:101], v141, v77, v[98:101]
	v_pk_fma_f32 v[180:181], v[2:3], v[178:179], v[180:181] op_sel:[0,1,0]
	v_pk_fma_f32 v[192:193], v[4:5], v[178:179], v[192:193] op_sel:[0,1,0]
	v_pk_mul_f32 v[180:181], v[146:147], v[180:181]
	v_pk_mul_f32 v[192:193], v[146:147], v[192:193]
	v_pk_fma_f32 v[236:237], v[144:145], v[74:75], v[180:181]
	v_pk_fma_f32 v[238:239], v[144:145], v[76:77], v[192:193]
	global_store_dwordx4 v[150:151], v[236:239], off nt
	v_lshl_add_u64 v[150:151], v[150:151], 0, s[74:75]
	global_load_dwordx4 v[74:77], v[148:149], off nt
	v_lshl_add_u64 v[148:149], v[148:149], 0, s[74:75]
	ds_read_b32 v141, v160 offset:512
	ds_read_b128 v[114:117], v161 offset:4096
	ds_read_b128 v[176:179], v161 offset:4112
	s_waitcnt vmcnt(38)
; #define RS_LOAD(dst, it0) do { _Pragma("unroll") for (int u = 0; u < 8; ++u) dst[u] = __builtin_nontemporal_load((const f32x4*)(S0 + (size_t)(4 * ((it0) + u)) * DV)); } while (0)
; __device__ __forceinline__ void ret_sample_item(Frame& F, int item) {
;     ...
;     for (int it0 = 0; it0 < 64; it0 += 16) {
;         RS_LOAD(sb, it0 + 8);
;         RS_PROC(sa, it0);
;         { const int itn = it0 + 16 < 64 ? it0 + 16 : it0; RS_LOAD(sa, itn); }
	s_waitcnt lgkmcnt(3)
	v_cndmask_b32_e64 v143, 0, v143, s[8:9]
	v_pk_mul_f32 v[180:181], v[26:27], v[172:173] op_sel:[0,1]
	v_pk_mul_f32 v[192:193], v[28:29], v[172:173] op_sel:[0,1]
	v_mfma_f32_16x16x4_f32 v[110:113], v143, v78, v[110:113]
	v_pk_fma_f32 v[180:181], v[30:31], v[172:173], v[180:181] op_sel_hi:[1,0,1]
	v_pk_fma_f32 v[192:193], v[32:33], v[172:173], v[192:193] op_sel_hi:[1,0,1]
	v_pk_fma_f32 v[180:181], v[22:23], v[174:175], v[180:181] op_sel_hi:[1,0,1]
	v_pk_fma_f32 v[192:193], v[24:25], v[174:175], v[192:193] op_sel_hi:[1,0,1]
	v_mfma_f32_16x16x4_f32 v[106:109], v143, v79, v[106:109]
	v_pk_fma_f32 v[180:181], v[18:19], v[174:175], v[180:181] op_sel:[0,1,0]
	v_pk_fma_f32 v[192:193], v[20:21], v[174:175], v[192:193] op_sel:[0,1,0]
	v_pk_fma_f32 v[180:181], v[14:15], v[232:233], v[180:181] op_sel_hi:[1,0,1]
	v_pk_fma_f32 v[192:193], v[16:17], v[232:233], v[192:193] op_sel_hi:[1,0,1]
	v_mfma_f32_16x16x4_f32 v[102:105], v143, v80, v[102:105]
	v_pk_fma_f32 v[180:181], v[10:11], v[232:233], v[180:181] op_sel:[0,1,0]
	v_pk_fma_f32 v[192:193], v[12:13], v[232:233], v[192:193] op_sel:[0,1,0]
	v_pk_fma_f32 v[180:181], v[6:7], v[234:235], v[180:181] op_sel_hi:[1,0,1]
	v_pk_fma_f32 v[192:193], v[8:9], v[234:235], v[192:193] op_sel_hi:[1,0,1]
	v_mfma_f32_16x16x4_f32 v[98:101], v143, v81, v[98:101]
	v_pk_fma_f32 v[180:181], v[2:3], v[234:235], v[180:181] op_sel:[0,1,0]
	v_pk_fma_f32 v[192:193], v[4:5], v[234:235], v[192:193] op_sel:[0,1,0]
	v_pk_mul_f32 v[180:181], v[146:147], v[180:181]
	v_pk_mul_f32 v[192:193], v[146:147], v[192:193]
	v_pk_fma_f32 v[236:237], v[144:145], v[78:79], v[180:181]
	v_pk_fma_f32 v[238:239], v[144:145], v[80:81], v[192:193]
	global_store_dwordx4 v[150:151], v[236:239], off nt
	v_lshl_add_u64 v[150:151], v[150:151], 0, s[74:75]
	global_load_dwordx4 v[78:81], v[148:149], off nt
	v_lshl_add_u64 v[148:149], v[148:149], 0, s[74:75]
	ds_read_b32 v143, v160 offset:528
	ds_read_b128 v[172:175], v161 offset:4224
	ds_read_b128 v[232:235], v161 offset:4240
	s_waitcnt vmcnt(38)
	s_waitcnt lgkmcnt(3)
	v_cndmask_b32_e64 v141, 0, v141, s[8:9]
	v_pk_mul_f32 v[180:181], v[26:27], v[114:115] op_sel:[0,1]
	v_pk_mul_f32 v[192:193], v[28:29], v[114:115] op_sel:[0,1]
	v_mfma_f32_16x16x4_f32 v[110:113], v141, v82, v[110:113]
	v_pk_fma_f32 v[180:181], v[30:31], v[114:115], v[180:181] op_sel_hi:[1,0,1]
	v_pk_fma_f32 v[192:193], v[32:33], v[114:115], v[192:193] op_sel_hi:[1,0,1]
	v_pk_fma_f32 v[180:181], v[22:23], v[116:117], v[180:181] op_sel_hi:[1,0,1]
	v_pk_fma_f32 v[192:193], v[24:25], v[116:117], v[192:193] op_sel_hi:[1,0,1]
	v_mfma_f32_16x16x4_f32 v[106:109], v141, v83, v[106:109]
	v_pk_fma_f32 v[180:181], v[18:19], v[116:117], v[180:181] op_sel:[0,1,0]
	v_pk_fma_f32 v[192:193], v[20:21], v[116:117], v[192:193] op_sel:[0,1,0]
	v_pk_fma_f32 v[180:181], v[14:15], v[176:177], v[180:181] op_sel_hi:[1,0,1]
	v_pk_fma_f32 v[192:193], v[16:17], v[176:177], v[192:193] op_sel_hi:[1,0,1]
	v_mfma_f32_16x16x4_f32 v[102:105], v141, v84, v[102:105]
	v_pk_fma_f32 v[180:181], v[10:11], v[176:177], v[180:181] op_sel:[0,1,0]
	v_pk_fma_f32 v[192:193], v[12:13], v[176:177], v[192:193] op_sel:[0,1,0]
	v_pk_fma_f32 v[180:181], v[6:7], v[178:179], v[180:181] op_sel_hi:[1,0,1]
	v_pk_fma_f32 v[192:193], v[8:9], v[178:179], v[192:193] op_sel_hi:[1,0,1]
	v_mfma_f32_16x16x4_f32 v[98:101], v141, v85, v[98:101]
	v_pk_fma_f32 v[180:181], v[2:3], v[178:179], v[180:181] op_sel:[0,1,0]
	v_pk_fma_f32 v[192:193], v[4:5], v[178:179], v[192:193] op_sel:[0,1,0]
	v_pk_mul_f32 v[180:181], v[146:147], v[180:181]
	v_pk_mul_f32 v[192:193], v[146:147], v[192:193]
	v_pk_fma_f32 v[236:237], v[144:145], v[82:83], v[180:181]
	v_pk_fma_f32 v[238:239], v[144:145], v[84:85], v[192:193]
	global_store_dwordx4 v[150:151], v[236:239], off nt
	v_lshl_add_u64 v[150:151], v[150:151], 0, s[74:75]
	global_load_dwordx4 v[82:85], v[148:149], off nt
	v_lshl_add_u64 v[148:149], v[148:149], 0, s[74:75]
	ds_read_b32 v141, v160 offset:544
	ds_read_b128 v[114:117], v161 offset:4352
	ds_read_b128 v[176:179], v161 offset:4368
	s_waitcnt vmcnt(38)
	s_waitcnt lgkmcnt(3)
	v_cndmask_b32_e64 v143, 0, v143, s[8:9]
	v_pk_mul_f32 v[180:181], v[26:27], v[172:173] op_sel:[0,1]
	v_pk_mul_f32 v[192:193], v[28:29], v[172:173] op_sel:[0,1]
	v_mfma_f32_16x16x4_f32 v[110:113], v143, v86, v[110:113]
	v_pk_fma_f32 v[180:181], v[30:31], v[172:173], v[180:181] op_sel_hi:[1,0,1]
	v_pk_fma_f32 v[192:193], v[32:33], v[172:173], v[192:193] op_sel_hi:[1,0,1]
	v_pk_fma_f32 v[180:181], v[22:23], v[174:175], v[180:181] op_sel_hi:[1,0,1]
	v_pk_fma_f32 v[192:193], v[24:25], v[174:175], v[192:193] op_sel_hi:[1,0,1]
	v_mfma_f32_16x16x4_f32 v[106:109], v143, v87, v[106:109]
	v_pk_fma_f32 v[180:181], v[18:19], v[174:175], v[180:181] op_sel:[0,1,0]
	v_pk_fma_f32 v[192:193], v[20:21], v[174:175], v[192:193] op_sel:[0,1,0]
	v_pk_fma_f32 v[180:181], v[14:15], v[232:233], v[180:181] op_sel_hi:[1,0,1]
	v_pk_fma_f32 v[192:193], v[16:17], v[232:233], v[192:193] op_sel_hi:[1,0,1]
	v_mfma_f32_16x16x4_f32 v[102:105], v143, v88, v[102:105]
	v_pk_fma_f32 v[180:181], v[10:11], v[232:233], v[180:181] op_sel:[0,1,0]
	v_pk_fma_f32 v[192:193], v[12:13], v[232:233], v[192:193] op_sel:[0,1,0]
	v_pk_fma_f32 v[180:181], v[6:7], v[234:235], v[180:181] op_sel_hi:[1,0,1]
	v_pk_fma_f32 v[192:193], v[8:9], v[234:235], v[192:193] op_sel_hi:[1,0,1]
	v_mfma_f32_16x16x4_f32 v[98:101], v143, v89, v[98:101]
	v_pk_fma_f32 v[180:181], v[2:3], v[234:235], v[180:181] op_sel:[0,1,0]
	v_pk_fma_f32 v[192:193], v[4:5], v[234:235], v[192:193] op_sel:[0,1,0]
	v_pk_mul_f32 v[180:181], v[146:147], v[180:181]
	v_pk_mul_f32 v[192:193], v[146:147], v[192:193]
	v_pk_fma_f32 v[236:237], v[144:145], v[86:87], v[180:181]
	v_pk_fma_f32 v[238:239], v[144:145], v[88:89], v[192:193]
	global_store_dwordx4 v[150:151], v[236:239], off nt
	v_lshl_add_u64 v[150:151], v[150:151], 0, s[74:75]
	global_load_dwordx4 v[86:89], v[148:149], off nt
	v_lshl_add_u64 v[148:149], v[148:149], 0, s[74:75]
	ds_read_b32 v143, v160 offset:560
	ds_read_b128 v[172:175], v161 offset:4480
	ds_read_b128 v[232:235], v161 offset:4496
	s_waitcnt vmcnt(38)
	s_waitcnt lgkmcnt(3)
	v_cndmask_b32_e64 v141, 0, v141, s[8:9]
	v_pk_mul_f32 v[180:181], v[26:27], v[114:115] op_sel:[0,1]
	v_pk_mul_f32 v[192:193], v[28:29], v[114:115] op_sel:[0,1]
	v_mfma_f32_16x16x4_f32 v[110:113], v141, v90, v[110:113]
	v_pk_fma_f32 v[180:181], v[30:31], v[114:115], v[180:181] op_sel_hi:[1,0,1]
	v_pk_fma_f32 v[192:193], v[32:33], v[114:115], v[192:193] op_sel_hi:[1,0,1]
	v_pk_fma_f32 v[180:181], v[22:23], v[116:117], v[180:181] op_sel_hi:[1,0,1]
	v_pk_fma_f32 v[192:193], v[24:25], v[116:117], v[192:193] op_sel_hi:[1,0,1]
	v_mfma_f32_16x16x4_f32 v[106:109], v141, v91, v[106:109]
	v_pk_fma_f32 v[180:181], v[18:19], v[116:117], v[180:181] op_sel:[0,1,0]
	v_pk_fma_f32 v[192:193], v[20:21], v[116:117], v[192:193] op_sel:[0,1,0]
	v_pk_fma_f32 v[180:181], v[14:15], v[176:177], v[180:181] op_sel_hi:[1,0,1]
	v_pk_fma_f32 v[192:193], v[16:17], v[176:177], v[192:193] op_sel_hi:[1,0,1]
	v_mfma_f32_16x16x4_f32 v[102:105], v141, v92, v[102:105]
	v_pk_fma_f32 v[180:181], v[10:11], v[176:177], v[180:181] op_sel:[0,1,0]
	v_pk_fma_f32 v[192:193], v[12:13], v[176:177], v[192:193] op_sel:[0,1,0]
	v_pk_fma_f32 v[180:181], v[6:7], v[178:179], v[180:181] op_sel_hi:[1,0,1]
	v_pk_fma_f32 v[192:193], v[8:9], v[178:179], v[192:193] op_sel_hi:[1,0,1]
	v_mfma_f32_16x16x4_f32 v[98:101], v141, v93, v[98:101]
	v_pk_fma_f32 v[180:181], v[2:3], v[178:179], v[180:181] op_sel:[0,1,0]
	v_pk_fma_f32 v[192:193], v[4:5], v[178:179], v[192:193] op_sel:[0,1,0]
	v_pk_mul_f32 v[180:181], v[146:147], v[180:181]
	v_pk_mul_f32 v[192:193], v[146:147], v[192:193]
	v_pk_fma_f32 v[236:237], v[144:145], v[90:91], v[180:181]
	v_pk_fma_f32 v[238:239], v[144:145], v[92:93], v[192:193]
	global_store_dwordx4 v[150:151], v[236:239], off nt
	v_lshl_add_u64 v[150:151], v[150:151], 0, s[74:75]
	global_load_dwordx4 v[90:93], v[148:149], off nt
	v_lshl_add_u64 v[148:149], v[148:149], 0, s[74:75]
	ds_read_b32 v141, v160 offset:576
	ds_read_b128 v[114:117], v161 offset:4608
	ds_read_b128 v[176:179], v161 offset:4624
	s_waitcnt vmcnt(38)
	s_waitcnt lgkmcnt(3)
	v_cndmask_b32_e64 v143, 0, v143, s[8:9]
	v_pk_mul_f32 v[180:181], v[26:27], v[172:173] op_sel:[0,1]
	v_pk_mul_f32 v[192:193], v[28:29], v[172:173] op_sel:[0,1]
	v_mfma_f32_16x16x4_f32 v[110:113], v143, v94, v[110:113]
	v_pk_fma_f32 v[180:181], v[30:31], v[172:173], v[180:181] op_sel_hi:[1,0,1]
	v_pk_fma_f32 v[192:193], v[32:33], v[172:173], v[192:193] op_sel_hi:[1,0,1]
	v_pk_fma_f32 v[180:181], v[22:23], v[174:175], v[180:181] op_sel_hi:[1,0,1]
	v_pk_fma_f32 v[192:193], v[24:25], v[174:175], v[192:193] op_sel_hi:[1,0,1]
	v_mfma_f32_16x16x4_f32 v[106:109], v143, v95, v[106:109]
	v_pk_fma_f32 v[180:181], v[18:19], v[174:175], v[180:181] op_sel:[0,1,0]
	v_pk_fma_f32 v[192:193], v[20:21], v[174:175], v[192:193] op_sel:[0,1,0]
	v_pk_fma_f32 v[180:181], v[14:15], v[232:233], v[180:181] op_sel_hi:[1,0,1]
	v_pk_fma_f32 v[192:193], v[16:17], v[232:233], v[192:193] op_sel_hi:[1,0,1]
	v_mfma_f32_16x16x4_f32 v[102:105], v143, v96, v[102:105]
	v_pk_fma_f32 v[180:181], v[10:11], v[232:233], v[180:181] op_sel:[0,1,0]
	v_pk_fma_f32 v[192:193], v[12:13], v[232:233], v[192:193] op_sel:[0,1,0]
	v_pk_fma_f32 v[180:181], v[6:7], v[234:235], v[180:181] op_sel_hi:[1,0,1]
	v_pk_fma_f32 v[192:193], v[8:9], v[234:235], v[192:193] op_sel_hi:[1,0,1]
	v_mfma_f32_16x16x4_f32 v[98:101], v143, v97, v[98:101]
	v_pk_fma_f32 v[180:181], v[2:3], v[234:235], v[180:181] op_sel:[0,1,0]
	v_pk_fma_f32 v[192:193], v[4:5], v[234:235], v[192:193] op_sel:[0,1,0]
	v_pk_mul_f32 v[180:181], v[146:147], v[180:181]
	v_pk_mul_f32 v[192:193], v[146:147], v[192:193]
	v_pk_fma_f32 v[236:237], v[144:145], v[94:95], v[180:181]
	v_pk_fma_f32 v[238:239], v[144:145], v[96:97], v[192:193]
	global_store_dwordx4 v[150:151], v[236:239], off nt
	v_lshl_add_u64 v[150:151], v[150:151], 0, s[74:75]
	global_load_dwordx4 v[94:97], v[148:149], off nt
	v_lshl_add_u64 v[148:149], v[148:149], 0, s[74:75]
	ds_read_b32 v143, v160 offset:592
	ds_read_b128 v[172:175], v161 offset:4736
	ds_read_b128 v[232:235], v161 offset:4752
	s_waitcnt vmcnt(38)
	s_waitcnt lgkmcnt(3)
	v_cndmask_b32_e64 v141, 0, v141, s[8:9]
	v_pk_mul_f32 v[180:181], v[26:27], v[114:115] op_sel:[0,1]
	v_pk_mul_f32 v[192:193], v[28:29], v[114:115] op_sel:[0,1]
	v_mfma_f32_16x16x4_f32 v[110:113], v141, v212, v[110:113]
	v_pk_fma_f32 v[180:181], v[30:31], v[114:115], v[180:181] op_sel_hi:[1,0,1]
	v_pk_fma_f32 v[192:193], v[32:33], v[114:115], v[192:193] op_sel_hi:[1,0,1]
	v_pk_fma_f32 v[180:181], v[22:23], v[116:117], v[180:181] op_sel_hi:[1,0,1]
	v_pk_fma_f32 v[192:193], v[24:25], v[116:117], v[192:193] op_sel_hi:[1,0,1]
	v_mfma_f32_16x16x4_f32 v[106:109], v141, v213, v[106:109]
	v_pk_fma_f32 v[180:181], v[18:19], v[116:117], v[180:181] op_sel:[0,1,0]
	v_pk_fma_f32 v[192:193], v[20:21], v[116:117], v[192:193] op_sel:[0,1,0]
	v_pk_fma_f32 v[180:181], v[14:15], v[176:177], v[180:181] op_sel_hi:[1,0,1]
	v_pk_fma_f32 v[192:193], v[16:17], v[176:177], v[192:193] op_sel_hi:[1,0,1]
	v_mfma_f32_16x16x4_f32 v[102:105], v141, v214, v[102:105]
	v_pk_fma_f32 v[180:181], v[10:11], v[176:177], v[180:181] op_sel:[0,1,0]
	v_pk_fma_f32 v[192:193], v[12:13], v[176:177], v[192:193] op_sel:[0,1,0]
	v_pk_fma_f32 v[180:181], v[6:7], v[178:179], v[180:181] op_sel_hi:[1,0,1]
	v_pk_fma_f32 v[192:193], v[8:9], v[178:179], v[192:193] op_sel_hi:[1,0,1]
	v_mfma_f32_16x16x4_f32 v[98:101], v141, v215, v[98:101]
	v_pk_fma_f32 v[180:181], v[2:3], v[178:179], v[180:181] op_sel:[0,1,0]
	v_pk_fma_f32 v[192:193], v[4:5], v[178:179], v[192:193] op_sel:[0,1,0]
	v_pk_mul_f32 v[180:181], v[146:147], v[180:181]
	v_pk_mul_f32 v[192:193], v[146:147], v[192:193]
	v_pk_fma_f32 v[236:237], v[144:145], v[212:213], v[180:181]
	v_pk_fma_f32 v[238:239], v[144:145], v[214:215], v[192:193]
	global_store_dwordx4 v[150:151], v[236:239], off nt
	v_lshl_add_u64 v[150:151], v[150:151], 0, s[74:75]
	global_load_dwordx4 v[212:215], v[148:149], off nt
	v_lshl_add_u64 v[148:149], v[148:149], 0, s[74:75]
	ds_read_b32 v141, v160 offset:608
	ds_read_b128 v[114:117], v161 offset:4864
	ds_read_b128 v[176:179], v161 offset:4880
	s_waitcnt vmcnt(38)
; #define RS_LOAD(dst, it0) do { _Pragma("unroll") for (int u = 0; u < 8; ++u) dst[u] = __builtin_nontemporal_load((const f32x4*)(S0 + (size_t)(4 * ((it0) + u)) * DV)); } while (0)
; __device__ __forceinline__ void ret_sample_item(Frame& F, int item) {
;     ...
;     for (int it0 = 0; it0 < 64; it0 += 16) {
;         RS_LOAD(sb, it0 + 8);
;         RS_PROC(sa, it0);
;         { const int itn = it0 + 16 < 64 ? it0 + 16 : it0; RS_LOAD(sa, itn); }
	s_waitcnt lgkmcnt(3)
	v_cndmask_b32_e64 v143, 0, v143, s[8:9]
	v_pk_mul_f32 v[180:181], v[26:27], v[172:173] op_sel:[0,1]
	v_pk_mul_f32 v[192:193], v[28:29], v[172:173] op_sel:[0,1]
	v_mfma_f32_16x16x4_f32 v[110:113], v143, v216, v[110:113]
	v_pk_fma_f32 v[180:181], v[30:31], v[172:173], v[180:181] op_sel_hi:[1,0,1]
	v_pk_fma_f32 v[192:193], v[32:33], v[172:173], v[192:193] op_sel_hi:[1,0,1]
	v_pk_fma_f32 v[180:181], v[22:23], v[174:175], v[180:181] op_sel_hi:[1,0,1]
	v_pk_fma_f32 v[192:193], v[24:25], v[174:175], v[192:193] op_sel_hi:[1,0,1]
	v_mfma_f32_16x16x4_f32 v[106:109], v143, v217, v[106:109]
	v_pk_fma_f32 v[180:181], v[18:19], v[174:175], v[180:181] op_sel:[0,1,0]
	v_pk_fma_f32 v[192:193], v[20:21], v[174:175], v[192:193] op_sel:[0,1,0]
	v_pk_fma_f32 v[180:181], v[14:15], v[232:233], v[180:181] op_sel_hi:[1,0,1]
	v_pk_fma_f32 v[192:193], v[16:17], v[232:233], v[192:193] op_sel_hi:[1,0,1]
	v_mfma_f32_16x16x4_f32 v[102:105], v143, v218, v[102:105]
	v_pk_fma_f32 v[180:181], v[10:11], v[232:233], v[180:181] op_sel:[0,1,0]
	v_pk_fma_f32 v[192:193], v[12:13], v[232:233], v[192:193] op_sel:[0,1,0]
	v_pk_fma_f32 v[180:181], v[6:7], v[234:235], v[180:181] op_sel_hi:[1,0,1]
	v_pk_fma_f32 v[192:193], v[8:9], v[234:235], v[192:193] op_sel_hi:[1,0,1]
	v_mfma_f32_16x16x4_f32 v[98:101], v143, v219, v[98:101]
	v_pk_fma_f32 v[180:181], v[2:3], v[234:235], v[180:181] op_sel:[0,1,0]
	v_pk_fma_f32 v[192:193], v[4:5], v[234:235], v[192:193] op_sel:[0,1,0]
	v_pk_mul_f32 v[180:181], v[146:147], v[180:181]
	v_pk_mul_f32 v[192:193], v[146:147], v[192:193]
	v_pk_fma_f32 v[236:237], v[144:145], v[216:217], v[180:181]
	v_pk_fma_f32 v[238:239], v[144:145], v[218:219], v[192:193]
	global_store_dwordx4 v[150:151], v[236:239], off nt
	v_lshl_add_u64 v[150:151], v[150:151], 0, s[74:75]
	global_load_dwordx4 v[216:219], v[148:149], off nt
	v_lshl_add_u64 v[148:149], v[148:149], 0, s[74:75]
	ds_read_b32 v143, v160 offset:624
	ds_read_b128 v[172:175], v161 offset:4992
	ds_read_b128 v[232:235], v161 offset:5008
	s_waitcnt vmcnt(38)
	s_waitcnt lgkmcnt(3)
	v_cndmask_b32_e64 v141, 0, v141, s[8:9]
	v_pk_mul_f32 v[180:181], v[26:27], v[114:115] op_sel:[0,1]
	v_pk_mul_f32 v[192:193], v[28:29], v[114:115] op_sel:[0,1]
	v_mfma_f32_16x16x4_f32 v[110:113], v141, v224, v[110:113]
	v_pk_fma_f32 v[180:181], v[30:31], v[114:115], v[180:181] op_sel_hi:[1,0,1]
	v_pk_fma_f32 v[192:193], v[32:33], v[114:115], v[192:193] op_sel_hi:[1,0,1]
	v_pk_fma_f32 v[180:181], v[22:23], v[116:117], v[180:181] op_sel_hi:[1,0,1]
	v_pk_fma_f32 v[192:193], v[24:25], v[116:117], v[192:193] op_sel_hi:[1,0,1]
	v_mfma_f32_16x16x4_f32 v[106:109], v141, v225, v[106:109]
	v_pk_fma_f32 v[180:181], v[18:19], v[116:117], v[180:181] op_sel:[0,1,0]
	v_pk_fma_f32 v[192:193], v[20:21], v[116:117], v[192:193] op_sel:[0,1,0]
	v_pk_fma_f32 v[180:181], v[14:15], v[176:177], v[180:181] op_sel_hi:[1,0,1]
	v_pk_fma_f32 v[192:193], v[16:17], v[176:177], v[192:193] op_sel_hi:[1,0,1]
	v_mfma_f32_16x16x4_f32 v[102:105], v141, v226, v[102:105]
	v_pk_fma_f32 v[180:181], v[10:11], v[176:177], v[180:181] op_sel:[0,1,0]
	v_pk_fma_f32 v[192:193], v[12:13], v[176:177], v[192:193] op_sel:[0,1,0]
	v_pk_fma_f32 v[180:181], v[6:7], v[178:179], v[180:181] op_sel_hi:[1,0,1]
	v_pk_fma_f32 v[192:193], v[8:9], v[178:179], v[192:193] op_sel_hi:[1,0,1]
	v_mfma_f32_16x16x4_f32 v[98:101], v141, v227, v[98:101]
	v_pk_fma_f32 v[180:181], v[2:3], v[178:179], v[180:181] op_sel:[0,1,0]
	v_pk_fma_f32 v[192:193], v[4:5], v[178:179], v[192:193] op_sel:[0,1,0]
	v_pk_mul_f32 v[180:181], v[146:147], v[180:181]
	v_pk_mul_f32 v[192:193], v[146:147], v[192:193]
	v_pk_fma_f32 v[236:237], v[144:145], v[224:225], v[180:181]
	v_pk_fma_f32 v[238:239], v[144:145], v[226:227], v[192:193]
	global_store_dwordx4 v[150:151], v[236:239], off nt
	v_lshl_add_u64 v[150:151], v[150:151], 0, s[74:75]
	global_load_dwordx4 v[224:227], v[148:149], off nt
	v_lshl_add_u64 v[148:149], v[148:149], 0, s[74:75]
	ds_read_b32 v141, v160 offset:640
	ds_read_b128 v[114:117], v161 offset:5120
	ds_read_b128 v[176:179], v161 offset:5136
	s_waitcnt vmcnt(38)
	s_waitcnt lgkmcnt(3)
	v_cndmask_b32_e64 v143, 0, v143, s[8:9]
	v_pk_mul_f32 v[180:181], v[26:27], v[172:173] op_sel:[0,1]
	v_pk_mul_f32 v[192:193], v[28:29], v[172:173] op_sel:[0,1]
	v_mfma_f32_16x16x4_f32 v[110:113], v143, v228, v[110:113]
	v_pk_fma_f32 v[180:181], v[30:31], v[172:173], v[180:181] op_sel_hi:[1,0,1]
	v_pk_fma_f32 v[192:193], v[32:33], v[172:173], v[192:193] op_sel_hi:[1,0,1]
	v_pk_fma_f32 v[180:181], v[22:23], v[174:175], v[180:181] op_sel_hi:[1,0,1]
	v_pk_fma_f32 v[192:193], v[24:25], v[174:175], v[192:193] op_sel_hi:[1,0,1]
	v_mfma_f32_16x16x4_f32 v[106:109], v143, v229, v[106:109]
	v_pk_fma_f32 v[180:181], v[18:19], v[174:175], v[180:181] op_sel:[0,1,0]
	v_pk_fma_f32 v[192:193], v[20:21], v[174:175], v[192:193] op_sel:[0,1,0]
	v_pk_fma_f32 v[180:181], v[14:15], v[232:233], v[180:181] op_sel_hi:[1,0,1]
	v_pk_fma_f32 v[192:193], v[16:17], v[232:233], v[192:193] op_sel_hi:[1,0,1]
	v_mfma_f32_16x16x4_f32 v[102:105], v143, v230, v[102:105]
	v_pk_fma_f32 v[180:181], v[10:11], v[232:233], v[180:181] op_sel:[0,1,0]
	v_pk_fma_f32 v[192:193], v[12:13], v[232:233], v[192:193] op_sel:[0,1,0]
	v_pk_fma_f32 v[180:181], v[6:7], v[234:235], v[180:181] op_sel_hi:[1,0,1]
	v_pk_fma_f32 v[192:193], v[8:9], v[234:235], v[192:193] op_sel_hi:[1,0,1]
	v_mfma_f32_16x16x4_f32 v[98:101], v143, v231, v[98:101]
	v_pk_fma_f32 v[180:181], v[2:3], v[234:235], v[180:181] op_sel:[0,1,0]
	v_pk_fma_f32 v[192:193], v[4:5], v[234:235], v[192:193] op_sel:[0,1,0]
	v_pk_mul_f32 v[180:181], v[146:147], v[180:181]
	v_pk_mul_f32 v[192:193], v[146:147], v[192:193]
	v_pk_fma_f32 v[236:237], v[144:145], v[228:229], v[180:181]
	v_pk_fma_f32 v[238:239], v[144:145], v[230:231], v[192:193]
	global_store_dwordx4 v[150:151], v[236:239], off nt
	v_lshl_add_u64 v[150:151], v[150:151], 0, s[74:75]
	global_load_dwordx4 v[228:231], v[148:149], off nt
	v_lshl_add_u64 v[148:149], v[148:149], 0, s[74:75]
	ds_read_b32 v143, v160 offset:656
	ds_read_b128 v[172:175], v161 offset:5248
	ds_read_b128 v[232:235], v161 offset:5264
	s_waitcnt vmcnt(38)
; #define RS_LOAD(dst, it0) do { _Pragma("unroll") for (int u = 0; u < 8; ++u) dst[u] = __builtin_nontemporal_load((const f32x4*)(S0 + (size_t)(4 * ((it0) + u)) * DV)); } while (0)
; __device__ __forceinline__ void ret_sample_item(Frame& F, int item) {
;     ...
;     for (int it0 = 0; it0 < 64; it0 += 16) {
;         RS_LOAD(sb, it0 + 8);
;         RS_PROC(sa, it0);
;         { const int itn = it0 + 16 < 64 ? it0 + 16 : it0; RS_LOAD(sa, itn); }
;         RS_PROC(sb, it0 + 8);
;     }
	s_waitcnt lgkmcnt(3)
	v_cndmask_b32_e64 v141, 0, v141, s[8:9]
	v_pk_mul_f32 v[180:181], v[26:27], v[114:115] op_sel:[0,1]
	v_pk_mul_f32 v[192:193], v[28:29], v[114:115] op_sel:[0,1]
	v_mfma_f32_16x16x4_f32 v[110:113], v141, v70, v[110:113]
	v_pk_fma_f32 v[180:181], v[30:31], v[114:115], v[180:181] op_sel_hi:[1,0,1]
	v_pk_fma_f32 v[192:193], v[32:33], v[114:115], v[192:193] op_sel_hi:[1,0,1]
	v_pk_fma_f32 v[180:181], v[22:23], v[116:117], v[180:181] op_sel_hi:[1,0,1]
	v_pk_fma_f32 v[192:193], v[24:25], v[116:117], v[192:193] op_sel_hi:[1,0,1]
	v_mfma_f32_16x16x4_f32 v[106:109], v141, v71, v[106:109]
	v_pk_fma_f32 v[180:181], v[18:19], v[116:117], v[180:181] op_sel:[0,1,0]
	v_pk_fma_f32 v[192:193], v[20:21], v[116:117], v[192:193] op_sel:[0,1,0]
	v_pk_fma_f32 v[180:181], v[14:15], v[176:177], v[180:181] op_sel_hi:[1,0,1]
	v_pk_fma_f32 v[192:193], v[16:17], v[176:177], v[192:193] op_sel_hi:[1,0,1]
	v_mfma_f32_16x16x4_f32 v[102:105], v141, v72, v[102:105]
	v_pk_fma_f32 v[180:181], v[10:11], v[176:177], v[180:181] op_sel:[0,1,0]
	v_pk_fma_f32 v[192:193], v[12:13], v[176:177], v[192:193] op_sel:[0,1,0]
	v_pk_fma_f32 v[180:181], v[6:7], v[178:179], v[180:181] op_sel_hi:[1,0,1]
	v_pk_fma_f32 v[192:193], v[8:9], v[178:179], v[192:193] op_sel_hi:[1,0,1]
	v_mfma_f32_16x16x4_f32 v[98:101], v141, v73, v[98:101]
	v_pk_fma_f32 v[180:181], v[2:3], v[178:179], v[180:181] op_sel:[0,1,0]
	v_pk_fma_f32 v[192:193], v[4:5], v[178:179], v[192:193] op_sel:[0,1,0]
	v_pk_mul_f32 v[180:181], v[146:147], v[180:181]
	v_pk_mul_f32 v[192:193], v[146:147], v[192:193]
	v_pk_fma_f32 v[236:237], v[144:145], v[70:71], v[180:181]
	v_pk_fma_f32 v[238:239], v[144:145], v[72:73], v[192:193]
	global_store_dwordx4 v[150:151], v[236:239], off nt
	v_lshl_add_u64 v[150:151], v[150:151], 0, s[74:75]
	global_load_dwordx4 v[70:73], v[148:149], off nt
	v_lshl_add_u64 v[148:149], v[148:149], 0, s[74:75]
	ds_read_b32 v141, v160 offset:672
	ds_read_b128 v[114:117], v161 offset:5376
	ds_read_b128 v[176:179], v161 offset:5392
	s_waitcnt vmcnt(38)
	s_waitcnt lgkmcnt(3)
	v_cndmask_b32_e64 v143, 0, v143, s[8:9]
	v_pk_mul_f32 v[180:181], v[26:27], v[172:173] op_sel:[0,1]
	v_pk_mul_f32 v[192:193], v[28:29], v[172:173] op_sel:[0,1]
	v_mfma_f32_16x16x4_f32 v[110:113], v143, v62, v[110:113]
	v_pk_fma_f32 v[180:181], v[30:31], v[172:173], v[180:181] op_sel_hi:[1,0,1]
	v_pk_fma_f32 v[192:193], v[32:33], v[172:173], v[192:193] op_sel_hi:[1,0,1]
	v_pk_fma_f32 v[180:181], v[22:23], v[174:175], v[180:181] op_sel_hi:[1,0,1]
	v_pk_fma_f32 v[192:193], v[24:25], v[174:175], v[192:193] op_sel_hi:[1,0,1]
	v_mfma_f32_16x16x4_f32 v[106:109], v143, v63, v[106:109]
	v_pk_fma_f32 v[180:181], v[18:19], v[174:175], v[180:181] op_sel:[0,1,0]
	v_pk_fma_f32 v[192:193], v[20:21], v[174:175], v[192:193] op_sel:[0,1,0]
	v_pk_fma_f32 v[180:181], v[14:15], v[232:233], v[180:181] op_sel_hi:[1,0,1]
	v_pk_fma_f32 v[192:193], v[16:17], v[232:233], v[192:193] op_sel_hi:[1,0,1]
	v_mfma_f32_16x16x4_f32 v[102:105], v143, v64, v[102:105]
	v_pk_fma_f32 v[180:181], v[10:11], v[232:233], v[180:181] op_sel:[0,1,0]
	v_pk_fma_f32 v[192:193], v[12:13], v[232:233], v[192:193] op_sel:[0,1,0]
	v_pk_fma_f32 v[180:181], v[6:7], v[234:235], v[180:181] op_sel_hi:[1,0,1]
	v_pk_fma_f32 v[192:193], v[8:9], v[234:235], v[192:193] op_sel_hi:[1,0,1]
	v_mfma_f32_16x16x4_f32 v[98:101], v143, v65, v[98:101]
	v_pk_fma_f32 v[180:181], v[2:3], v[234:235], v[180:181] op_sel:[0,1,0]
	v_pk_fma_f32 v[192:193], v[4:5], v[234:235], v[192:193] op_sel:[0,1,0]
	v_pk_mul_f32 v[180:181], v[146:147], v[180:181]
	v_pk_mul_f32 v[192:193], v[146:147], v[192:193]
	v_pk_fma_f32 v[236:237], v[144:145], v[62:63], v[180:181]
	v_pk_fma_f32 v[238:239], v[144:145], v[64:65], v[192:193]
	global_store_dwordx4 v[150:151], v[236:239], off nt
	v_lshl_add_u64 v[150:151], v[150:151], 0, s[74:75]
	global_load_dwordx4 v[62:65], v[148:149], off nt
	v_lshl_add_u64 v[148:149], v[148:149], 0, s[74:75]
	ds_read_b32 v143, v160 offset:688
	ds_read_b128 v[172:175], v161 offset:5504
	ds_read_b128 v[232:235], v161 offset:5520
	s_waitcnt vmcnt(38)
	s_waitcnt lgkmcnt(3)
	v_cndmask_b32_e64 v141, 0, v141, s[8:9]
	v_pk_mul_f32 v[180:181], v[26:27], v[114:115] op_sel:[0,1]
	v_pk_mul_f32 v[192:193], v[28:29], v[114:115] op_sel:[0,1]
	v_mfma_f32_16x16x4_f32 v[110:113], v141, v54, v[110:113]
	v_pk_fma_f32 v[180:181], v[30:31], v[114:115], v[180:181] op_sel_hi:[1,0,1]
	v_pk_fma_f32 v[192:193], v[32:33], v[114:115], v[192:193] op_sel_hi:[1,0,1]
	v_pk_fma_f32 v[180:181], v[22:23], v[116:117], v[180:181] op_sel_hi:[1,0,1]
	v_pk_fma_f32 v[192:193], v[24:25], v[116:117], v[192:193] op_sel_hi:[1,0,1]
	v_mfma_f32_16x16x4_f32 v[106:109], v141, v55, v[106:109]
	v_pk_fma_f32 v[180:181], v[18:19], v[116:117], v[180:181] op_sel:[0,1,0]
	v_pk_fma_f32 v[192:193], v[20:21], v[116:117], v[192:193] op_sel:[0,1,0]
	v_pk_fma_f32 v[180:181], v[14:15], v[176:177], v[180:181] op_sel_hi:[1,0,1]
	v_pk_fma_f32 v[192:193], v[16:17], v[176:177], v[192:193] op_sel_hi:[1,0,1]
	v_mfma_f32_16x16x4_f32 v[102:105], v141, v56, v[102:105]
	v_pk_fma_f32 v[180:181], v[10:11], v[176:177], v[180:181] op_sel:[0,1,0]
	v_pk_fma_f32 v[192:193], v[12:13], v[176:177], v[192:193] op_sel:[0,1,0]
	v_pk_fma_f32 v[180:181], v[6:7], v[178:179], v[180:181] op_sel_hi:[1,0,1]
	v_pk_fma_f32 v[192:193], v[8:9], v[178:179], v[192:193] op_sel_hi:[1,0,1]
	v_mfma_f32_16x16x4_f32 v[98:101], v141, v57, v[98:101]
	v_pk_fma_f32 v[180:181], v[2:3], v[178:179], v[180:181] op_sel:[0,1,0]
	v_pk_fma_f32 v[192:193], v[4:5], v[178:179], v[192:193] op_sel:[0,1,0]
	v_pk_mul_f32 v[180:181], v[146:147], v[180:181]
	v_pk_mul_f32 v[192:193], v[146:147], v[192:193]
	v_pk_fma_f32 v[236:237], v[144:145], v[54:55], v[180:181]
	v_pk_fma_f32 v[238:239], v[144:145], v[56:57], v[192:193]
	global_store_dwordx4 v[150:151], v[236:239], off nt
	v_lshl_add_u64 v[150:151], v[150:151], 0, s[74:75]
	global_load_dwordx4 v[54:57], v[148:149], off nt
	v_lshl_add_u64 v[148:149], v[148:149], 0, s[74:75]
	ds_read_b32 v141, v160 offset:704
	ds_read_b128 v[114:117], v161 offset:5632
	ds_read_b128 v[176:179], v161 offset:5648
	s_waitcnt vmcnt(38)
; #define RS_LOAD(dst, it0) do { _Pragma("unroll") for (int u = 0; u < 8; ++u) dst[u] = __builtin_nontemporal_load((const f32x4*)(S0 + (size_t)(4 * ((it0) + u)) * DV)); } while (0)
; __device__ __forceinline__ void ret_sample_item(Frame& F, int item) {
;     ...
;     for (int it0 = 0; it0 < 64; it0 += 16) {
;         RS_LOAD(sb, it0 + 8);
;         RS_PROC(sa, it0);
;         { const int itn = it0 + 16 < 64 ? it0 + 16 : it0; RS_LOAD(sa, itn); }
;         RS_PROC(sb, it0 + 8);
;     }
	s_waitcnt lgkmcnt(3)
	v_cndmask_b32_e64 v143, 0, v143, s[8:9]
	v_pk_mul_f32 v[180:181], v[26:27], v[172:173] op_sel:[0,1]
	v_pk_mul_f32 v[192:193], v[28:29], v[172:173] op_sel:[0,1]
	v_mfma_f32_16x16x4_f32 v[110:113], v143, v50, v[110:113]
	v_pk_fma_f32 v[180:181], v[30:31], v[172:173], v[180:181] op_sel_hi:[1,0,1]
	v_pk_fma_f32 v[192:193], v[32:33], v[172:173], v[192:193] op_sel_hi:[1,0,1]
	v_pk_fma_f32 v[180:181], v[22:23], v[174:175], v[180:181] op_sel_hi:[1,0,1]
	v_pk_fma_f32 v[192:193], v[24:25], v[174:175], v[192:193] op_sel_hi:[1,0,1]
	v_mfma_f32_16x16x4_f32 v[106:109], v143, v51, v[106:109]
	v_pk_fma_f32 v[180:181], v[18:19], v[174:175], v[180:181] op_sel:[0,1,0]
	v_pk_fma_f32 v[192:193], v[20:21], v[174:175], v[192:193] op_sel:[0,1,0]
	v_pk_fma_f32 v[180:181], v[14:15], v[232:233], v[180:181] op_sel_hi:[1,0,1]
	v_pk_fma_f32 v[192:193], v[16:17], v[232:233], v[192:193] op_sel_hi:[1,0,1]
	v_mfma_f32_16x16x4_f32 v[102:105], v143, v52, v[102:105]
	v_pk_fma_f32 v[180:181], v[10:11], v[232:233], v[180:181] op_sel:[0,1,0]
	v_pk_fma_f32 v[192:193], v[12:13], v[232:233], v[192:193] op_sel:[0,1,0]
	v_pk_fma_f32 v[180:181], v[6:7], v[234:235], v[180:181] op_sel_hi:[1,0,1]
	v_pk_fma_f32 v[192:193], v[8:9], v[234:235], v[192:193] op_sel_hi:[1,0,1]
	v_mfma_f32_16x16x4_f32 v[98:101], v143, v53, v[98:101]
	v_pk_fma_f32 v[180:181], v[2:3], v[234:235], v[180:181] op_sel:[0,1,0]
	v_pk_fma_f32 v[192:193], v[4:5], v[234:235], v[192:193] op_sel:[0,1,0]
	v_pk_mul_f32 v[180:181], v[146:147], v[180:181]
	v_pk_mul_f32 v[192:193], v[146:147], v[192:193]
	v_pk_fma_f32 v[236:237], v[144:145], v[50:51], v[180:181]
	v_pk_fma_f32 v[238:239], v[144:145], v[52:53], v[192:193]
	global_store_dwordx4 v[150:151], v[236:239], off nt
	v_lshl_add_u64 v[150:151], v[150:151], 0, s[74:75]
	global_load_dwordx4 v[50:53], v[148:149], off nt
	v_lshl_add_u64 v[148:149], v[148:149], 0, s[74:75]
	ds_read_b32 v143, v160 offset:720
	ds_read_b128 v[172:175], v161 offset:5760
	ds_read_b128 v[232:235], v161 offset:5776
	s_waitcnt vmcnt(38)
	s_waitcnt lgkmcnt(3)
	v_cndmask_b32_e64 v141, 0, v141, s[8:9]
	v_pk_mul_f32 v[180:181], v[26:27], v[114:115] op_sel:[0,1]
	v_pk_mul_f32 v[192:193], v[28:29], v[114:115] op_sel:[0,1]
	v_mfma_f32_16x16x4_f32 v[110:113], v141, v46, v[110:113]
	v_pk_fma_f32 v[180:181], v[30:31], v[114:115], v[180:181] op_sel_hi:[1,0,1]
	v_pk_fma_f32 v[192:193], v[32:33], v[114:115], v[192:193] op_sel_hi:[1,0,1]
	v_pk_fma_f32 v[180:181], v[22:23], v[116:117], v[180:181] op_sel_hi:[1,0,1]
	v_pk_fma_f32 v[192:193], v[24:25], v[116:117], v[192:193] op_sel_hi:[1,0,1]
	v_mfma_f32_16x16x4_f32 v[106:109], v141, v47, v[106:109]
	v_pk_fma_f32 v[180:181], v[18:19], v[116:117], v[180:181] op_sel:[0,1,0]
	v_pk_fma_f32 v[192:193], v[20:21], v[116:117], v[192:193] op_sel:[0,1,0]
	v_pk_fma_f32 v[180:181], v[14:15], v[176:177], v[180:181] op_sel_hi:[1,0,1]
	v_pk_fma_f32 v[192:193], v[16:17], v[176:177], v[192:193] op_sel_hi:[1,0,1]
	v_mfma_f32_16x16x4_f32 v[102:105], v141, v48, v[102:105]
	v_pk_fma_f32 v[180:181], v[10:11], v[176:177], v[180:181] op_sel:[0,1,0]
	v_pk_fma_f32 v[192:193], v[12:13], v[176:177], v[192:193] op_sel:[0,1,0]
	v_pk_fma_f32 v[180:181], v[6:7], v[178:179], v[180:181] op_sel_hi:[1,0,1]
	v_pk_fma_f32 v[192:193], v[8:9], v[178:179], v[192:193] op_sel_hi:[1,0,1]
	v_mfma_f32_16x16x4_f32 v[98:101], v141, v49, v[98:101]
	v_pk_fma_f32 v[180:181], v[2:3], v[178:179], v[180:181] op_sel:[0,1,0]
	v_pk_fma_f32 v[192:193], v[4:5], v[178:179], v[192:193] op_sel:[0,1,0]
	v_pk_mul_f32 v[180:181], v[146:147], v[180:181]
	v_pk_mul_f32 v[192:193], v[146:147], v[192:193]
	v_pk_fma_f32 v[236:237], v[144:145], v[46:47], v[180:181]
	v_pk_fma_f32 v[238:239], v[144:145], v[48:49], v[192:193]
	global_store_dwordx4 v[150:151], v[236:239], off nt
	v_lshl_add_u64 v[150:151], v[150:151], 0, s[74:75]
	ds_read_b32 v141, v160 offset:736
	ds_read_b128 v[114:117], v161 offset:5888
	ds_read_b128 v[176:179], v161 offset:5904
	s_waitcnt vmcnt(37)
	s_waitcnt lgkmcnt(3)
	v_cndmask_b32_e64 v143, 0, v143, s[8:9]
	v_pk_mul_f32 v[180:181], v[26:27], v[172:173] op_sel:[0,1]
	v_pk_mul_f32 v[192:193], v[28:29], v[172:173] op_sel:[0,1]
	v_mfma_f32_16x16x4_f32 v[110:113], v143, v42, v[110:113]
	v_pk_fma_f32 v[180:181], v[30:31], v[172:173], v[180:181] op_sel_hi:[1,0,1]
	v_pk_fma_f32 v[192:193], v[32:33], v[172:173], v[192:193] op_sel_hi:[1,0,1]
	v_pk_fma_f32 v[180:181], v[22:23], v[174:175], v[180:181] op_sel_hi:[1,0,1]
	v_pk_fma_f32 v[192:193], v[24:25], v[174:175], v[192:193] op_sel_hi:[1,0,1]
	v_mfma_f32_16x16x4_f32 v[106:109], v143, v43, v[106:109]
	v_pk_fma_f32 v[180:181], v[18:19], v[174:175], v[180:181] op_sel:[0,1,0]
	v_pk_fma_f32 v[192:193], v[20:21], v[174:175], v[192:193] op_sel:[0,1,0]
	v_pk_fma_f32 v[180:181], v[14:15], v[232:233], v[180:181] op_sel_hi:[1,0,1]
	v_pk_fma_f32 v[192:193], v[16:17], v[232:233], v[192:193] op_sel_hi:[1,0,1]
	v_mfma_f32_16x16x4_f32 v[102:105], v143, v44, v[102:105]
	v_pk_fma_f32 v[180:181], v[10:11], v[232:233], v[180:181] op_sel:[0,1,0]
	v_pk_fma_f32 v[192:193], v[12:13], v[232:233], v[192:193] op_sel:[0,1,0]
	v_pk_fma_f32 v[180:181], v[6:7], v[234:235], v[180:181] op_sel_hi:[1,0,1]
	v_pk_fma_f32 v[192:193], v[8:9], v[234:235], v[192:193] op_sel_hi:[1,0,1]
	v_mfma_f32_16x16x4_f32 v[98:101], v143, v45, v[98:101]
	v_pk_fma_f32 v[180:181], v[2:3], v[234:235], v[180:181] op_sel:[0,1,0]
	v_pk_fma_f32 v[192:193], v[4:5], v[234:235], v[192:193] op_sel:[0,1,0]
	v_pk_mul_f32 v[180:181], v[146:147], v[180:181]
	v_pk_mul_f32 v[192:193], v[146:147], v[192:193]
	v_pk_fma_f32 v[236:237], v[144:145], v[42:43], v[180:181]
	v_pk_fma_f32 v[238:239], v[144:145], v[44:45], v[192:193]
	global_store_dwordx4 v[150:151], v[236:239], off nt
	v_lshl_add_u64 v[150:151], v[150:151], 0, s[74:75]
	ds_read_b32 v143, v160 offset:752
	ds_read_b128 v[172:175], v161 offset:6016
	ds_read_b128 v[232:235], v161 offset:6032
	s_waitcnt vmcnt(36)
; #define RS_LOAD(dst, it0) do { _Pragma("unroll") for (int u = 0; u < 8; ++u) dst[u] = __builtin_nontemporal_load((const f32x4*)(S0 + (size_t)(4 * ((it0) + u)) * DV)); } while (0)
; __device__ __forceinline__ void ret_sample_item(Frame& F, int item) {
;     ...
;     for (int it0 = 0; it0 < 64; it0 += 16) {
;         RS_LOAD(sb, it0 + 8);
;         RS_PROC(sa, it0);
;         { const int itn = it0 + 16 < 64 ? it0 + 16 : it0; RS_LOAD(sa, itn); }
;         RS_PROC(sb, it0 + 8);
;     }
	s_waitcnt lgkmcnt(3)
	v_cndmask_b32_e64 v141, 0, v141, s[8:9]
	v_pk_mul_f32 v[180:181], v[26:27], v[114:115] op_sel:[0,1]
	v_pk_mul_f32 v[192:193], v[28:29], v[114:115] op_sel:[0,1]
	v_mfma_f32_16x16x4_f32 v[110:113], v141, v38, v[110:113]
	v_pk_fma_f32 v[180:181], v[30:31], v[114:115], v[180:181] op_sel_hi:[1,0,1]
	v_pk_fma_f32 v[192:193], v[32:33], v[114:115], v[192:193] op_sel_hi:[1,0,1]
	v_pk_fma_f32 v[180:181], v[22:23], v[116:117], v[180:181] op_sel_hi:[1,0,1]
	v_pk_fma_f32 v[192:193], v[24:25], v[116:117], v[192:193] op_sel_hi:[1,0,1]
	v_mfma_f32_16x16x4_f32 v[106:109], v141, v39, v[106:109]
	v_pk_fma_f32 v[180:181], v[18:19], v[116:117], v[180:181] op_sel:[0,1,0]
	v_pk_fma_f32 v[192:193], v[20:21], v[116:117], v[192:193] op_sel:[0,1,0]
	v_pk_fma_f32 v[180:181], v[14:15], v[176:177], v[180:181] op_sel_hi:[1,0,1]
	v_pk_fma_f32 v[192:193], v[16:17], v[176:177], v[192:193] op_sel_hi:[1,0,1]
	v_mfma_f32_16x16x4_f32 v[102:105], v141, v40, v[102:105]
	v_pk_fma_f32 v[180:181], v[10:11], v[176:177], v[180:181] op_sel:[0,1,0]
	v_pk_fma_f32 v[192:193], v[12:13], v[176:177], v[192:193] op_sel:[0,1,0]
	v_pk_fma_f32 v[180:181], v[6:7], v[178:179], v[180:181] op_sel_hi:[1,0,1]
	v_pk_fma_f32 v[192:193], v[8:9], v[178:179], v[192:193] op_sel_hi:[1,0,1]
	v_mfma_f32_16x16x4_f32 v[98:101], v141, v41, v[98:101]
	v_pk_fma_f32 v[180:181], v[2:3], v[178:179], v[180:181] op_sel:[0,1,0]
	v_pk_fma_f32 v[192:193], v[4:5], v[178:179], v[192:193] op_sel:[0,1,0]
	v_pk_mul_f32 v[180:181], v[146:147], v[180:181]
	v_pk_mul_f32 v[192:193], v[146:147], v[192:193]
	v_pk_fma_f32 v[236:237], v[144:145], v[38:39], v[180:181]
	v_pk_fma_f32 v[238:239], v[144:145], v[40:41], v[192:193]
	global_store_dwordx4 v[150:151], v[236:239], off nt
	v_lshl_add_u64 v[150:151], v[150:151], 0, s[74:75]
	ds_read_b32 v141, v160 offset:768
	ds_read_b128 v[114:117], v161 offset:6144
	ds_read_b128 v[176:179], v161 offset:6160
	s_waitcnt vmcnt(35)
	s_waitcnt lgkmcnt(3)
	v_cndmask_b32_e64 v143, 0, v143, s[8:9]
	v_pk_mul_f32 v[180:181], v[26:27], v[172:173] op_sel:[0,1]
	v_pk_mul_f32 v[192:193], v[28:29], v[172:173] op_sel:[0,1]
	v_mfma_f32_16x16x4_f32 v[110:113], v143, v34, v[110:113]
	v_pk_fma_f32 v[180:181], v[30:31], v[172:173], v[180:181] op_sel_hi:[1,0,1]
	v_pk_fma_f32 v[192:193], v[32:33], v[172:173], v[192:193] op_sel_hi:[1,0,1]
	v_pk_fma_f32 v[180:181], v[22:23], v[174:175], v[180:181] op_sel_hi:[1,0,1]
	v_pk_fma_f32 v[192:193], v[24:25], v[174:175], v[192:193] op_sel_hi:[1,0,1]
	v_mfma_f32_16x16x4_f32 v[106:109], v143, v35, v[106:109]
	v_pk_fma_f32 v[180:181], v[18:19], v[174:175], v[180:181] op_sel:[0,1,0]
	v_pk_fma_f32 v[192:193], v[20:21], v[174:175], v[192:193] op_sel:[0,1,0]
	v_pk_fma_f32 v[180:181], v[14:15], v[232:233], v[180:181] op_sel_hi:[1,0,1]
	v_pk_fma_f32 v[192:193], v[16:17], v[232:233], v[192:193] op_sel_hi:[1,0,1]
	v_mfma_f32_16x16x4_f32 v[102:105], v143, v36, v[102:105]
	v_pk_fma_f32 v[180:181], v[10:11], v[232:233], v[180:181] op_sel:[0,1,0]
	v_pk_fma_f32 v[192:193], v[12:13], v[232:233], v[192:193] op_sel:[0,1,0]
	v_pk_fma_f32 v[180:181], v[6:7], v[234:235], v[180:181] op_sel_hi:[1,0,1]
	v_pk_fma_f32 v[192:193], v[8:9], v[234:235], v[192:193] op_sel_hi:[1,0,1]
	v_mfma_f32_16x16x4_f32 v[98:101], v143, v37, v[98:101]
	v_pk_fma_f32 v[180:181], v[2:3], v[234:235], v[180:181] op_sel:[0,1,0]
	v_pk_fma_f32 v[192:193], v[4:5], v[234:235], v[192:193] op_sel:[0,1,0]
	v_pk_mul_f32 v[180:181], v[146:147], v[180:181]
	v_pk_mul_f32 v[192:193], v[146:147], v[192:193]
	v_pk_fma_f32 v[236:237], v[144:145], v[34:35], v[180:181]
	v_pk_fma_f32 v[238:239], v[144:145], v[36:37], v[192:193]
	global_store_dwordx4 v[150:151], v[236:239], off nt
	v_lshl_add_u64 v[150:151], v[150:151], 0, s[74:75]
	ds_read_b32 v143, v160 offset:784
	ds_read_b128 v[172:175], v161 offset:6272
	ds_read_b128 v[232:235], v161 offset:6288
	s_waitcnt vmcnt(34)
	s_waitcnt lgkmcnt(3)
	v_cndmask_b32_e64 v141, 0, v141, s[8:9]
	v_pk_mul_f32 v[180:181], v[26:27], v[114:115] op_sel:[0,1]
	v_pk_mul_f32 v[192:193], v[28:29], v[114:115] op_sel:[0,1]
	v_mfma_f32_16x16x4_f32 v[110:113], v141, v58, v[110:113]
	v_pk_fma_f32 v[180:181], v[30:31], v[114:115], v[180:181] op_sel_hi:[1,0,1]
	v_pk_fma_f32 v[192:193], v[32:33], v[114:115], v[192:193] op_sel_hi:[1,0,1]
	v_pk_fma_f32 v[180:181], v[22:23], v[116:117], v[180:181] op_sel_hi:[1,0,1]
	v_pk_fma_f32 v[192:193], v[24:25], v[116:117], v[192:193] op_sel_hi:[1,0,1]
	v_mfma_f32_16x16x4_f32 v[106:109], v141, v59, v[106:109]
	v_pk_fma_f32 v[180:181], v[18:19], v[116:117], v[180:181] op_sel:[0,1,0]
	v_pk_fma_f32 v[192:193], v[20:21], v[116:117], v[192:193] op_sel:[0,1,0]
	v_pk_fma_f32 v[180:181], v[14:15], v[176:177], v[180:181] op_sel_hi:[1,0,1]
	v_pk_fma_f32 v[192:193], v[16:17], v[176:177], v[192:193] op_sel_hi:[1,0,1]
	v_mfma_f32_16x16x4_f32 v[102:105], v141, v60, v[102:105]
	v_pk_fma_f32 v[180:181], v[10:11], v[176:177], v[180:181] op_sel:[0,1,0]
	v_pk_fma_f32 v[192:193], v[12:13], v[176:177], v[192:193] op_sel:[0,1,0]
	v_pk_fma_f32 v[180:181], v[6:7], v[178:179], v[180:181] op_sel_hi:[1,0,1]
	v_pk_fma_f32 v[192:193], v[8:9], v[178:179], v[192:193] op_sel_hi:[1,0,1]
	v_mfma_f32_16x16x4_f32 v[98:101], v141, v61, v[98:101]
	v_pk_fma_f32 v[180:181], v[2:3], v[178:179], v[180:181] op_sel:[0,1,0]
	v_pk_fma_f32 v[192:193], v[4:5], v[178:179], v[192:193] op_sel:[0,1,0]
	v_pk_mul_f32 v[180:181], v[146:147], v[180:181]
	v_pk_mul_f32 v[192:193], v[146:147], v[192:193]
	v_pk_fma_f32 v[236:237], v[144:145], v[58:59], v[180:181]
	v_pk_fma_f32 v[238:239], v[144:145], v[60:61], v[192:193]
	global_store_dwordx4 v[150:151], v[236:239], off nt
	v_lshl_add_u64 v[150:151], v[150:151], 0, s[74:75]
	ds_read_b32 v141, v160 offset:800
	ds_read_b128 v[114:117], v161 offset:6400
	ds_read_b128 v[176:179], v161 offset:6416
	s_waitcnt vmcnt(33)
; #define RS_LOAD(dst, it0) do { _Pragma("unroll") for (int u = 0; u < 8; ++u) dst[u] = __builtin_nontemporal_load((const f32x4*)(S0 + (size_t)(4 * ((it0) + u)) * DV)); } while (0)
; __device__ __forceinline__ void ret_sample_item(Frame& F, int item) {
;     ...
;     for (int it0 = 0; it0 < 64; it0 += 16) {
;         RS_LOAD(sb, it0 + 8);
;         RS_PROC(sa, it0);
;         { const int itn = it0 + 16 < 64 ? it0 + 16 : it0; RS_LOAD(sa, itn); }
;         RS_PROC(sb, it0 + 8);
;     }
	s_waitcnt lgkmcnt(3)
	v_cndmask_b32_e64 v143, 0, v143, s[8:9]
	v_pk_mul_f32 v[180:181], v[26:27], v[172:173] op_sel:[0,1]
	v_pk_mul_f32 v[192:193], v[28:29], v[172:173] op_sel:[0,1]
	v_mfma_f32_16x16x4_f32 v[110:113], v143, v66, v[110:113]
	v_pk_fma_f32 v[180:181], v[30:31], v[172:173], v[180:181] op_sel_hi:[1,0,1]
	v_pk_fma_f32 v[192:193], v[32:33], v[172:173], v[192:193] op_sel_hi:[1,0,1]
	v_pk_fma_f32 v[180:181], v[22:23], v[174:175], v[180:181] op_sel_hi:[1,0,1]
	v_pk_fma_f32 v[192:193], v[24:25], v[174:175], v[192:193] op_sel_hi:[1,0,1]
	v_mfma_f32_16x16x4_f32 v[106:109], v143, v67, v[106:109]
	v_pk_fma_f32 v[180:181], v[18:19], v[174:175], v[180:181] op_sel:[0,1,0]
	v_pk_fma_f32 v[192:193], v[20:21], v[174:175], v[192:193] op_sel:[0,1,0]
	v_pk_fma_f32 v[180:181], v[14:15], v[232:233], v[180:181] op_sel_hi:[1,0,1]
	v_pk_fma_f32 v[192:193], v[16:17], v[232:233], v[192:193] op_sel_hi:[1,0,1]
	v_mfma_f32_16x16x4_f32 v[102:105], v143, v68, v[102:105]
	v_pk_fma_f32 v[180:181], v[10:11], v[232:233], v[180:181] op_sel:[0,1,0]
	v_pk_fma_f32 v[192:193], v[12:13], v[232:233], v[192:193] op_sel:[0,1,0]
	v_pk_fma_f32 v[180:181], v[6:7], v[234:235], v[180:181] op_sel_hi:[1,0,1]
	v_pk_fma_f32 v[192:193], v[8:9], v[234:235], v[192:193] op_sel_hi:[1,0,1]
	v_mfma_f32_16x16x4_f32 v[98:101], v143, v69, v[98:101]
	v_pk_fma_f32 v[180:181], v[2:3], v[234:235], v[180:181] op_sel:[0,1,0]
	v_pk_fma_f32 v[192:193], v[4:5], v[234:235], v[192:193] op_sel:[0,1,0]
	v_pk_mul_f32 v[180:181], v[146:147], v[180:181]
	v_pk_mul_f32 v[192:193], v[146:147], v[192:193]
	v_pk_fma_f32 v[236:237], v[144:145], v[66:67], v[180:181]
	v_pk_fma_f32 v[238:239], v[144:145], v[68:69], v[192:193]
	global_store_dwordx4 v[150:151], v[236:239], off nt
	v_lshl_add_u64 v[150:151], v[150:151], 0, s[74:75]
	ds_read_b32 v143, v160 offset:816
	ds_read_b128 v[172:175], v161 offset:6528
	ds_read_b128 v[232:235], v161 offset:6544
	s_waitcnt vmcnt(32)
	s_waitcnt lgkmcnt(3)
	v_cndmask_b32_e64 v141, 0, v141, s[8:9]
	v_pk_mul_f32 v[180:181], v[26:27], v[114:115] op_sel:[0,1]
	v_pk_mul_f32 v[192:193], v[28:29], v[114:115] op_sel:[0,1]
	v_mfma_f32_16x16x4_f32 v[110:113], v141, v74, v[110:113]
	v_pk_fma_f32 v[180:181], v[30:31], v[114:115], v[180:181] op_sel_hi:[1,0,1]
	v_pk_fma_f32 v[192:193], v[32:33], v[114:115], v[192:193] op_sel_hi:[1,0,1]
	v_pk_fma_f32 v[180:181], v[22:23], v[116:117], v[180:181] op_sel_hi:[1,0,1]
	v_pk_fma_f32 v[192:193], v[24:25], v[116:117], v[192:193] op_sel_hi:[1,0,1]
	v_mfma_f32_16x16x4_f32 v[106:109], v141, v75, v[106:109]
	v_pk_fma_f32 v[180:181], v[18:19], v[116:117], v[180:181] op_sel:[0,1,0]
	v_pk_fma_f32 v[192:193], v[20:21], v[116:117], v[192:193] op_sel:[0,1,0]
	v_pk_fma_f32 v[180:181], v[14:15], v[176:177], v[180:181] op_sel_hi:[1,0,1]
	v_pk_fma_f32 v[192:193], v[16:17], v[176:177], v[192:193] op_sel_hi:[1,0,1]
	v_mfma_f32_16x16x4_f32 v[102:105], v141, v76, v[102:105]
	v_pk_fma_f32 v[180:181], v[10:11], v[176:177], v[180:181] op_sel:[0,1,0]
	v_pk_fma_f32 v[192:193], v[12:13], v[176:177], v[192:193] op_sel:[0,1,0]
	v_pk_fma_f32 v[180:181], v[6:7], v[178:179], v[180:181] op_sel_hi:[1,0,1]
	v_pk_fma_f32 v[192:193], v[8:9], v[178:179], v[192:193] op_sel_hi:[1,0,1]
	v_mfma_f32_16x16x4_f32 v[98:101], v141, v77, v[98:101]
	v_pk_fma_f32 v[180:181], v[2:3], v[178:179], v[180:181] op_sel:[0,1,0]
	v_pk_fma_f32 v[192:193], v[4:5], v[178:179], v[192:193] op_sel:[0,1,0]
	v_pk_mul_f32 v[180:181], v[146:147], v[180:181]
	v_pk_mul_f32 v[192:193], v[146:147], v[192:193]
	v_pk_fma_f32 v[236:237], v[144:145], v[74:75], v[180:181]
	v_pk_fma_f32 v[238:239], v[144:145], v[76:77], v[192:193]
	global_store_dwordx4 v[150:151], v[236:239], off nt
	v_lshl_add_u64 v[150:151], v[150:151], 0, s[74:75]
	ds_read_b32 v141, v160 offset:832
	ds_read_b128 v[114:117], v161 offset:6656
	ds_read_b128 v[176:179], v161 offset:6672
	s_waitcnt vmcnt(31)
	s_waitcnt lgkmcnt(3)
	v_cndmask_b32_e64 v143, 0, v143, s[8:9]
	v_pk_mul_f32 v[180:181], v[26:27], v[172:173] op_sel:[0,1]
	v_pk_mul_f32 v[192:193], v[28:29], v[172:173] op_sel:[0,1]
	v_mfma_f32_16x16x4_f32 v[110:113], v143, v78, v[110:113]
	v_pk_fma_f32 v[180:181], v[30:31], v[172:173], v[180:181] op_sel_hi:[1,0,1]
	v_pk_fma_f32 v[192:193], v[32:33], v[172:173], v[192:193] op_sel_hi:[1,0,1]
	v_pk_fma_f32 v[180:181], v[22:23], v[174:175], v[180:181] op_sel_hi:[1,0,1]
	v_pk_fma_f32 v[192:193], v[24:25], v[174:175], v[192:193] op_sel_hi:[1,0,1]
	v_mfma_f32_16x16x4_f32 v[106:109], v143, v79, v[106:109]
	v_pk_fma_f32 v[180:181], v[18:19], v[174:175], v[180:181] op_sel:[0,1,0]
	v_pk_fma_f32 v[192:193], v[20:21], v[174:175], v[192:193] op_sel:[0,1,0]
	v_pk_fma_f32 v[180:181], v[14:15], v[232:233], v[180:181] op_sel_hi:[1,0,1]
	v_pk_fma_f32 v[192:193], v[16:17], v[232:233], v[192:193] op_sel_hi:[1,0,1]
	v_mfma_f32_16x16x4_f32 v[102:105], v143, v80, v[102:105]
	v_pk_fma_f32 v[180:181], v[10:11], v[232:233], v[180:181] op_sel:[0,1,0]
	v_pk_fma_f32 v[192:193], v[12:13], v[232:233], v[192:193] op_sel:[0,1,0]
	v_pk_fma_f32 v[180:181], v[6:7], v[234:235], v[180:181] op_sel_hi:[1,0,1]
	v_pk_fma_f32 v[192:193], v[8:9], v[234:235], v[192:193] op_sel_hi:[1,0,1]
	v_mfma_f32_16x16x4_f32 v[98:101], v143, v81, v[98:101]
	v_pk_fma_f32 v[180:181], v[2:3], v[234:235], v[180:181] op_sel:[0,1,0]
	v_pk_fma_f32 v[192:193], v[4:5], v[234:235], v[192:193] op_sel:[0,1,0]
	v_pk_mul_f32 v[180:181], v[146:147], v[180:181]
	v_pk_mul_f32 v[192:193], v[146:147], v[192:193]
	v_pk_fma_f32 v[236:237], v[144:145], v[78:79], v[180:181]
	v_pk_fma_f32 v[238:239], v[144:145], v[80:81], v[192:193]
	global_store_dwordx4 v[150:151], v[236:239], off nt
	v_lshl_add_u64 v[150:151], v[150:151], 0, s[74:75]
	ds_read_b32 v143, v160 offset:848
	ds_read_b128 v[172:175], v161 offset:6784
	ds_read_b128 v[232:235], v161 offset:6800
	s_waitcnt vmcnt(30)
; #define RS_LOAD(dst, it0) do { _Pragma("unroll") for (int u = 0; u < 8; ++u) dst[u] = __builtin_nontemporal_load((const f32x4*)(S0 + (size_t)(4 * ((it0) + u)) * DV)); } while (0)
; __device__ __forceinline__ void ret_sample_item(Frame& F, int item) {
;     ...
;     for (int it0 = 0; it0 < 64; it0 += 16) {
;         RS_LOAD(sb, it0 + 8);
;         RS_PROC(sa, it0);
;         { const int itn = it0 + 16 < 64 ? it0 + 16 : it0; RS_LOAD(sa, itn); }
;         RS_PROC(sb, it0 + 8);
;     }
	s_waitcnt lgkmcnt(3)
	v_cndmask_b32_e64 v141, 0, v141, s[8:9]
	v_pk_mul_f32 v[180:181], v[26:27], v[114:115] op_sel:[0,1]
	v_pk_mul_f32 v[192:193], v[28:29], v[114:115] op_sel:[0,1]
	v_mfma_f32_16x16x4_f32 v[110:113], v141, v82, v[110:113]
	v_pk_fma_f32 v[180:181], v[30:31], v[114:115], v[180:181] op_sel_hi:[1,0,1]
	v_pk_fma_f32 v[192:193], v[32:33], v[114:115], v[192:193] op_sel_hi:[1,0,1]
	v_pk_fma_f32 v[180:181], v[22:23], v[116:117], v[180:181] op_sel_hi:[1,0,1]
	v_pk_fma_f32 v[192:193], v[24:25], v[116:117], v[192:193] op_sel_hi:[1,0,1]
	v_mfma_f32_16x16x4_f32 v[106:109], v141, v83, v[106:109]
	v_pk_fma_f32 v[180:181], v[18:19], v[116:117], v[180:181] op_sel:[0,1,0]
	v_pk_fma_f32 v[192:193], v[20:21], v[116:117], v[192:193] op_sel:[0,1,0]
	v_pk_fma_f32 v[180:181], v[14:15], v[176:177], v[180:181] op_sel_hi:[1,0,1]
	v_pk_fma_f32 v[192:193], v[16:17], v[176:177], v[192:193] op_sel_hi:[1,0,1]
	v_mfma_f32_16x16x4_f32 v[102:105], v141, v84, v[102:105]
	v_pk_fma_f32 v[180:181], v[10:11], v[176:177], v[180:181] op_sel:[0,1,0]
	v_pk_fma_f32 v[192:193], v[12:13], v[176:177], v[192:193] op_sel:[0,1,0]
	v_pk_fma_f32 v[180:181], v[6:7], v[178:179], v[180:181] op_sel_hi:[1,0,1]
	v_pk_fma_f32 v[192:193], v[8:9], v[178:179], v[192:193] op_sel_hi:[1,0,1]
	v_mfma_f32_16x16x4_f32 v[98:101], v141, v85, v[98:101]
	v_pk_fma_f32 v[180:181], v[2:3], v[178:179], v[180:181] op_sel:[0,1,0]
	v_pk_fma_f32 v[192:193], v[4:5], v[178:179], v[192:193] op_sel:[0,1,0]
	v_pk_mul_f32 v[180:181], v[146:147], v[180:181]
	v_pk_mul_f32 v[192:193], v[146:147], v[192:193]
	v_pk_fma_f32 v[236:237], v[144:145], v[82:83], v[180:181]
	v_pk_fma_f32 v[238:239], v[144:145], v[84:85], v[192:193]
	global_store_dwordx4 v[150:151], v[236:239], off nt
	v_lshl_add_u64 v[150:151], v[150:151], 0, s[74:75]
	ds_read_b32 v141, v160 offset:864
	ds_read_b128 v[114:117], v161 offset:6912
	ds_read_b128 v[176:179], v161 offset:6928
	s_waitcnt vmcnt(29)
	s_waitcnt lgkmcnt(3)
	v_cndmask_b32_e64 v143, 0, v143, s[8:9]
	v_pk_mul_f32 v[180:181], v[26:27], v[172:173] op_sel:[0,1]
	v_pk_mul_f32 v[192:193], v[28:29], v[172:173] op_sel:[0,1]
	v_mfma_f32_16x16x4_f32 v[110:113], v143, v86, v[110:113]
	v_pk_fma_f32 v[180:181], v[30:31], v[172:173], v[180:181] op_sel_hi:[1,0,1]
	v_pk_fma_f32 v[192:193], v[32:33], v[172:173], v[192:193] op_sel_hi:[1,0,1]
	v_pk_fma_f32 v[180:181], v[22:23], v[174:175], v[180:181] op_sel_hi:[1,0,1]
	v_pk_fma_f32 v[192:193], v[24:25], v[174:175], v[192:193] op_sel_hi:[1,0,1]
	v_mfma_f32_16x16x4_f32 v[106:109], v143, v87, v[106:109]
	v_pk_fma_f32 v[180:181], v[18:19], v[174:175], v[180:181] op_sel:[0,1,0]
	v_pk_fma_f32 v[192:193], v[20:21], v[174:175], v[192:193] op_sel:[0,1,0]
	v_pk_fma_f32 v[180:181], v[14:15], v[232:233], v[180:181] op_sel_hi:[1,0,1]
	v_pk_fma_f32 v[192:193], v[16:17], v[232:233], v[192:193] op_sel_hi:[1,0,1]
	v_mfma_f32_16x16x4_f32 v[102:105], v143, v88, v[102:105]
	v_pk_fma_f32 v[180:181], v[10:11], v[232:233], v[180:181] op_sel:[0,1,0]
	v_pk_fma_f32 v[192:193], v[12:13], v[232:233], v[192:193] op_sel:[0,1,0]
	v_pk_fma_f32 v[180:181], v[6:7], v[234:235], v[180:181] op_sel_hi:[1,0,1]
	v_pk_fma_f32 v[192:193], v[8:9], v[234:235], v[192:193] op_sel_hi:[1,0,1]
	v_mfma_f32_16x16x4_f32 v[98:101], v143, v89, v[98:101]
	v_pk_fma_f32 v[180:181], v[2:3], v[234:235], v[180:181] op_sel:[0,1,0]
	v_pk_fma_f32 v[192:193], v[4:5], v[234:235], v[192:193] op_sel:[0,1,0]
	v_pk_mul_f32 v[180:181], v[146:147], v[180:181]
	v_pk_mul_f32 v[192:193], v[146:147], v[192:193]
	v_pk_fma_f32 v[236:237], v[144:145], v[86:87], v[180:181]
	v_pk_fma_f32 v[238:239], v[144:145], v[88:89], v[192:193]
	global_store_dwordx4 v[150:151], v[236:239], off nt
	v_lshl_add_u64 v[150:151], v[150:151], 0, s[74:75]
	ds_read_b32 v143, v160 offset:880
	ds_read_b128 v[172:175], v161 offset:7040
	ds_read_b128 v[232:235], v161 offset:7056
	s_waitcnt vmcnt(28)
	s_waitcnt lgkmcnt(3)
	v_cndmask_b32_e64 v141, 0, v141, s[8:9]
	v_pk_mul_f32 v[180:181], v[26:27], v[114:115] op_sel:[0,1]
	v_pk_mul_f32 v[192:193], v[28:29], v[114:115] op_sel:[0,1]
	v_mfma_f32_16x16x4_f32 v[110:113], v141, v90, v[110:113]
	v_pk_fma_f32 v[180:181], v[30:31], v[114:115], v[180:181] op_sel_hi:[1,0,1]
	v_pk_fma_f32 v[192:193], v[32:33], v[114:115], v[192:193] op_sel_hi:[1,0,1]
	v_pk_fma_f32 v[180:181], v[22:23], v[116:117], v[180:181] op_sel_hi:[1,0,1]
	v_pk_fma_f32 v[192:193], v[24:25], v[116:117], v[192:193] op_sel_hi:[1,0,1]
	v_mfma_f32_16x16x4_f32 v[106:109], v141, v91, v[106:109]
	v_pk_fma_f32 v[180:181], v[18:19], v[116:117], v[180:181] op_sel:[0,1,0]
	v_pk_fma_f32 v[192:193], v[20:21], v[116:117], v[192:193] op_sel:[0,1,0]
	v_pk_fma_f32 v[180:181], v[14:15], v[176:177], v[180:181] op_sel_hi:[1,0,1]
	v_pk_fma_f32 v[192:193], v[16:17], v[176:177], v[192:193] op_sel_hi:[1,0,1]
	v_mfma_f32_16x16x4_f32 v[102:105], v141, v92, v[102:105]
	v_pk_fma_f32 v[180:181], v[10:11], v[176:177], v[180:181] op_sel:[0,1,0]
	v_pk_fma_f32 v[192:193], v[12:13], v[176:177], v[192:193] op_sel:[0,1,0]
	v_pk_fma_f32 v[180:181], v[6:7], v[178:179], v[180:181] op_sel_hi:[1,0,1]
	v_pk_fma_f32 v[192:193], v[8:9], v[178:179], v[192:193] op_sel_hi:[1,0,1]
	v_mfma_f32_16x16x4_f32 v[98:101], v141, v93, v[98:101]
	v_pk_fma_f32 v[180:181], v[2:3], v[178:179], v[180:181] op_sel:[0,1,0]
	v_pk_fma_f32 v[192:193], v[4:5], v[178:179], v[192:193] op_sel:[0,1,0]
	v_pk_mul_f32 v[180:181], v[146:147], v[180:181]
	v_pk_mul_f32 v[192:193], v[146:147], v[192:193]
	v_pk_fma_f32 v[236:237], v[144:145], v[90:91], v[180:181]
	v_pk_fma_f32 v[238:239], v[144:145], v[92:93], v[192:193]
	global_store_dwordx4 v[150:151], v[236:239], off nt
	v_lshl_add_u64 v[150:151], v[150:151], 0, s[74:75]
	ds_read_b32 v141, v160 offset:896
	ds_read_b128 v[114:117], v161 offset:7168
	ds_read_b128 v[176:179], v161 offset:7184
	s_waitcnt vmcnt(27)
; #define RS_LOAD(dst, it0) do { _Pragma("unroll") for (int u = 0; u < 8; ++u) dst[u] = __builtin_nontemporal_load((const f32x4*)(S0 + (size_t)(4 * ((it0) + u)) * DV)); } while (0)
; __device__ __forceinline__ void ret_sample_item(Frame& F, int item) {
;     ...
;     for (int it0 = 0; it0 < 64; it0 += 16) {
;         RS_LOAD(sb, it0 + 8);
;         RS_PROC(sa, it0);
;         { const int itn = it0 + 16 < 64 ? it0 + 16 : it0; RS_LOAD(sa, itn); }
;         RS_PROC(sb, it0 + 8);
;     }
	s_waitcnt lgkmcnt(3)
	v_cndmask_b32_e64 v143, 0, v143, s[8:9]
	v_pk_mul_f32 v[180:181], v[26:27], v[172:173] op_sel:[0,1]
	v_pk_mul_f32 v[192:193], v[28:29], v[172:173] op_sel:[0,1]
	v_mfma_f32_16x16x4_f32 v[110:113], v143, v94, v[110:113]
	v_pk_fma_f32 v[180:181], v[30:31], v[172:173], v[180:181] op_sel_hi:[1,0,1]
	v_pk_fma_f32 v[192:193], v[32:33], v[172:173], v[192:193] op_sel_hi:[1,0,1]
	v_pk_fma_f32 v[180:181], v[22:23], v[174:175], v[180:181] op_sel_hi:[1,0,1]
	v_pk_fma_f32 v[192:193], v[24:25], v[174:175], v[192:193] op_sel_hi:[1,0,1]
	v_mfma_f32_16x16x4_f32 v[106:109], v143, v95, v[106:109]
	v_pk_fma_f32 v[180:181], v[18:19], v[174:175], v[180:181] op_sel:[0,1,0]
	v_pk_fma_f32 v[192:193], v[20:21], v[174:175], v[192:193] op_sel:[0,1,0]
	v_pk_fma_f32 v[180:181], v[14:15], v[232:233], v[180:181] op_sel_hi:[1,0,1]
	v_pk_fma_f32 v[192:193], v[16:17], v[232:233], v[192:193] op_sel_hi:[1,0,1]
	v_mfma_f32_16x16x4_f32 v[102:105], v143, v96, v[102:105]
	v_pk_fma_f32 v[180:181], v[10:11], v[232:233], v[180:181] op_sel:[0,1,0]
	v_pk_fma_f32 v[192:193], v[12:13], v[232:233], v[192:193] op_sel:[0,1,0]
	v_pk_fma_f32 v[180:181], v[6:7], v[234:235], v[180:181] op_sel_hi:[1,0,1]
	v_pk_fma_f32 v[192:193], v[8:9], v[234:235], v[192:193] op_sel_hi:[1,0,1]
	v_mfma_f32_16x16x4_f32 v[98:101], v143, v97, v[98:101]
	v_pk_fma_f32 v[180:181], v[2:3], v[234:235], v[180:181] op_sel:[0,1,0]
	v_pk_fma_f32 v[192:193], v[4:5], v[234:235], v[192:193] op_sel:[0,1,0]
	v_pk_mul_f32 v[180:181], v[146:147], v[180:181]
	v_pk_mul_f32 v[192:193], v[146:147], v[192:193]
	v_pk_fma_f32 v[236:237], v[144:145], v[94:95], v[180:181]
	v_pk_fma_f32 v[238:239], v[144:145], v[96:97], v[192:193]
	global_store_dwordx4 v[150:151], v[236:239], off nt
	v_lshl_add_u64 v[150:151], v[150:151], 0, s[74:75]
	ds_read_b32 v143, v160 offset:912
	ds_read_b128 v[172:175], v161 offset:7296
	ds_read_b128 v[232:235], v161 offset:7312
	s_waitcnt vmcnt(26)
	s_waitcnt lgkmcnt(3)
	v_cndmask_b32_e64 v141, 0, v141, s[8:9]
	v_pk_mul_f32 v[180:181], v[26:27], v[114:115] op_sel:[0,1]
	v_pk_mul_f32 v[192:193], v[28:29], v[114:115] op_sel:[0,1]
	v_mfma_f32_16x16x4_f32 v[110:113], v141, v212, v[110:113]
	v_pk_fma_f32 v[180:181], v[30:31], v[114:115], v[180:181] op_sel_hi:[1,0,1]
	v_pk_fma_f32 v[192:193], v[32:33], v[114:115], v[192:193] op_sel_hi:[1,0,1]
	v_pk_fma_f32 v[180:181], v[22:23], v[116:117], v[180:181] op_sel_hi:[1,0,1]
	v_pk_fma_f32 v[192:193], v[24:25], v[116:117], v[192:193] op_sel_hi:[1,0,1]
	v_mfma_f32_16x16x4_f32 v[106:109], v141, v213, v[106:109]
	v_pk_fma_f32 v[180:181], v[18:19], v[116:117], v[180:181] op_sel:[0,1,0]
	v_pk_fma_f32 v[192:193], v[20:21], v[116:117], v[192:193] op_sel:[0,1,0]
	v_pk_fma_f32 v[180:181], v[14:15], v[176:177], v[180:181] op_sel_hi:[1,0,1]
	v_pk_fma_f32 v[192:193], v[16:17], v[176:177], v[192:193] op_sel_hi:[1,0,1]
	v_mfma_f32_16x16x4_f32 v[102:105], v141, v214, v[102:105]
	v_pk_fma_f32 v[180:181], v[10:11], v[176:177], v[180:181] op_sel:[0,1,0]
	v_pk_fma_f32 v[192:193], v[12:13], v[176:177], v[192:193] op_sel:[0,1,0]
	v_pk_fma_f32 v[180:181], v[6:7], v[178:179], v[180:181] op_sel_hi:[1,0,1]
	v_pk_fma_f32 v[192:193], v[8:9], v[178:179], v[192:193] op_sel_hi:[1,0,1]
	v_mfma_f32_16x16x4_f32 v[98:101], v141, v215, v[98:101]
	v_pk_fma_f32 v[180:181], v[2:3], v[178:179], v[180:181] op_sel:[0,1,0]
	v_pk_fma_f32 v[192:193], v[4:5], v[178:179], v[192:193] op_sel:[0,1,0]
	v_pk_mul_f32 v[180:181], v[146:147], v[180:181]
	v_pk_mul_f32 v[192:193], v[146:147], v[192:193]
	v_pk_fma_f32 v[236:237], v[144:145], v[212:213], v[180:181]
	v_pk_fma_f32 v[238:239], v[144:145], v[214:215], v[192:193]
	global_store_dwordx4 v[150:151], v[236:239], off nt
	v_lshl_add_u64 v[150:151], v[150:151], 0, s[74:75]
	ds_read_b32 v141, v160 offset:928
	ds_read_b128 v[114:117], v161 offset:7424
	ds_read_b128 v[176:179], v161 offset:7440
	s_waitcnt vmcnt(25)
	s_waitcnt lgkmcnt(3)
	v_cndmask_b32_e64 v143, 0, v143, s[8:9]
	v_pk_mul_f32 v[180:181], v[26:27], v[172:173] op_sel:[0,1]
	v_pk_mul_f32 v[192:193], v[28:29], v[172:173] op_sel:[0,1]
	v_mfma_f32_16x16x4_f32 v[110:113], v143, v216, v[110:113]
	v_pk_fma_f32 v[180:181], v[30:31], v[172:173], v[180:181] op_sel_hi:[1,0,1]
	v_pk_fma_f32 v[192:193], v[32:33], v[172:173], v[192:193] op_sel_hi:[1,0,1]
	v_pk_fma_f32 v[180:181], v[22:23], v[174:175], v[180:181] op_sel_hi:[1,0,1]
	v_pk_fma_f32 v[192:193], v[24:25], v[174:175], v[192:193] op_sel_hi:[1,0,1]
	v_mfma_f32_16x16x4_f32 v[106:109], v143, v217, v[106:109]
	v_pk_fma_f32 v[180:181], v[18:19], v[174:175], v[180:181] op_sel:[0,1,0]
	v_pk_fma_f32 v[192:193], v[20:21], v[174:175], v[192:193] op_sel:[0,1,0]
	v_pk_fma_f32 v[180:181], v[14:15], v[232:233], v[180:181] op_sel_hi:[1,0,1]
	v_pk_fma_f32 v[192:193], v[16:17], v[232:233], v[192:193] op_sel_hi:[1,0,1]
	v_mfma_f32_16x16x4_f32 v[102:105], v143, v218, v[102:105]
	v_pk_fma_f32 v[180:181], v[10:11], v[232:233], v[180:181] op_sel:[0,1,0]
	v_pk_fma_f32 v[192:193], v[12:13], v[232:233], v[192:193] op_sel:[0,1,0]
	v_pk_fma_f32 v[180:181], v[6:7], v[234:235], v[180:181] op_sel_hi:[1,0,1]
	v_pk_fma_f32 v[192:193], v[8:9], v[234:235], v[192:193] op_sel_hi:[1,0,1]
	v_mfma_f32_16x16x4_f32 v[98:101], v143, v219, v[98:101]
	v_pk_fma_f32 v[180:181], v[2:3], v[234:235], v[180:181] op_sel:[0,1,0]
	v_pk_fma_f32 v[192:193], v[4:5], v[234:235], v[192:193] op_sel:[0,1,0]
	v_pk_mul_f32 v[180:181], v[146:147], v[180:181]
	v_pk_mul_f32 v[192:193], v[146:147], v[192:193]
	v_pk_fma_f32 v[236:237], v[144:145], v[216:217], v[180:181]
	v_pk_fma_f32 v[238:239], v[144:145], v[218:219], v[192:193]
	global_store_dwordx4 v[150:151], v[236:239], off nt
	v_lshl_add_u64 v[150:151], v[150:151], 0, s[74:75]
	ds_read_b32 v143, v160 offset:944
	ds_read_b128 v[172:175], v161 offset:7552
	ds_read_b128 v[232:235], v161 offset:7568
	s_waitcnt vmcnt(24)
; #define RS_LOAD(dst, it0) do { _Pragma("unroll") for (int u = 0; u < 8; ++u) dst[u] = __builtin_nontemporal_load((const f32x4*)(S0 + (size_t)(4 * ((it0) + u)) * DV)); } while (0)
; __device__ __forceinline__ void ret_sample_item(Frame& F, int item) {
;     ...
;     for (int it0 = 0; it0 < 64; it0 += 16) {
;         RS_LOAD(sb, it0 + 8);
;         RS_PROC(sa, it0);
;         { const int itn = it0 + 16 < 64 ? it0 + 16 : it0; RS_LOAD(sa, itn); }
;         RS_PROC(sb, it0 + 8);
;     }
	s_waitcnt lgkmcnt(3)
	v_cndmask_b32_e64 v141, 0, v141, s[8:9]
	v_pk_mul_f32 v[180:181], v[26:27], v[114:115] op_sel:[0,1]
	v_pk_mul_f32 v[192:193], v[28:29], v[114:115] op_sel:[0,1]
	v_mfma_f32_16x16x4_f32 v[110:113], v141, v224, v[110:113]
	v_pk_fma_f32 v[180:181], v[30:31], v[114:115], v[180:181] op_sel_hi:[1,0,1]
	v_pk_fma_f32 v[192:193], v[32:33], v[114:115], v[192:193] op_sel_hi:[1,0,1]
	v_pk_fma_f32 v[180:181], v[22:23], v[116:117], v[180:181] op_sel_hi:[1,0,1]
	v_pk_fma_f32 v[192:193], v[24:25], v[116:117], v[192:193] op_sel_hi:[1,0,1]
	v_mfma_f32_16x16x4_f32 v[106:109], v141, v225, v[106:109]
	v_pk_fma_f32 v[180:181], v[18:19], v[116:117], v[180:181] op_sel:[0,1,0]
	v_pk_fma_f32 v[192:193], v[20:21], v[116:117], v[192:193] op_sel:[0,1,0]
	v_pk_fma_f32 v[180:181], v[14:15], v[176:177], v[180:181] op_sel_hi:[1,0,1]
	v_pk_fma_f32 v[192:193], v[16:17], v[176:177], v[192:193] op_sel_hi:[1,0,1]
	v_mfma_f32_16x16x4_f32 v[102:105], v141, v226, v[102:105]
	v_pk_fma_f32 v[180:181], v[10:11], v[176:177], v[180:181] op_sel:[0,1,0]
	v_pk_fma_f32 v[192:193], v[12:13], v[176:177], v[192:193] op_sel:[0,1,0]
	v_pk_fma_f32 v[180:181], v[6:7], v[178:179], v[180:181] op_sel_hi:[1,0,1]
	v_pk_fma_f32 v[192:193], v[8:9], v[178:179], v[192:193] op_sel_hi:[1,0,1]
	v_mfma_f32_16x16x4_f32 v[98:101], v141, v227, v[98:101]
	v_pk_fma_f32 v[180:181], v[2:3], v[178:179], v[180:181] op_sel:[0,1,0]
	v_pk_fma_f32 v[192:193], v[4:5], v[178:179], v[192:193] op_sel:[0,1,0]
	v_pk_mul_f32 v[180:181], v[146:147], v[180:181]
	v_pk_mul_f32 v[192:193], v[146:147], v[192:193]
	v_pk_fma_f32 v[236:237], v[144:145], v[224:225], v[180:181]
	v_pk_fma_f32 v[238:239], v[144:145], v[226:227], v[192:193]
	global_store_dwordx4 v[150:151], v[236:239], off nt
	v_lshl_add_u64 v[150:151], v[150:151], 0, s[74:75]
	ds_read_b32 v141, v160 offset:960
	ds_read_b128 v[114:117], v161 offset:7680
	ds_read_b128 v[176:179], v161 offset:7696
	s_waitcnt vmcnt(23)
	s_waitcnt lgkmcnt(3)
	v_cndmask_b32_e64 v143, 0, v143, s[8:9]
	v_pk_mul_f32 v[180:181], v[26:27], v[172:173] op_sel:[0,1]
	v_pk_mul_f32 v[192:193], v[28:29], v[172:173] op_sel:[0,1]
	v_mfma_f32_16x16x4_f32 v[110:113], v143, v228, v[110:113]
	v_pk_fma_f32 v[180:181], v[30:31], v[172:173], v[180:181] op_sel_hi:[1,0,1]
	v_pk_fma_f32 v[192:193], v[32:33], v[172:173], v[192:193] op_sel_hi:[1,0,1]
	v_pk_fma_f32 v[180:181], v[22:23], v[174:175], v[180:181] op_sel_hi:[1,0,1]
	v_pk_fma_f32 v[192:193], v[24:25], v[174:175], v[192:193] op_sel_hi:[1,0,1]
	v_mfma_f32_16x16x4_f32 v[106:109], v143, v229, v[106:109]
	v_pk_fma_f32 v[180:181], v[18:19], v[174:175], v[180:181] op_sel:[0,1,0]
	v_pk_fma_f32 v[192:193], v[20:21], v[174:175], v[192:193] op_sel:[0,1,0]
	v_pk_fma_f32 v[180:181], v[14:15], v[232:233], v[180:181] op_sel_hi:[1,0,1]
	v_pk_fma_f32 v[192:193], v[16:17], v[232:233], v[192:193] op_sel_hi:[1,0,1]
	v_mfma_f32_16x16x4_f32 v[102:105], v143, v230, v[102:105]
	v_pk_fma_f32 v[180:181], v[10:11], v[232:233], v[180:181] op_sel:[0,1,0]
	v_pk_fma_f32 v[192:193], v[12:13], v[232:233], v[192:193] op_sel:[0,1,0]
	v_pk_fma_f32 v[180:181], v[6:7], v[234:235], v[180:181] op_sel_hi:[1,0,1]
	v_pk_fma_f32 v[192:193], v[8:9], v[234:235], v[192:193] op_sel_hi:[1,0,1]
	v_mfma_f32_16x16x4_f32 v[98:101], v143, v231, v[98:101]
	v_pk_fma_f32 v[180:181], v[2:3], v[234:235], v[180:181] op_sel:[0,1,0]
	v_pk_fma_f32 v[192:193], v[4:5], v[234:235], v[192:193] op_sel:[0,1,0]
	v_pk_mul_f32 v[180:181], v[146:147], v[180:181]
	v_pk_mul_f32 v[192:193], v[146:147], v[192:193]
	v_pk_fma_f32 v[236:237], v[144:145], v[228:229], v[180:181]
	v_pk_fma_f32 v[238:239], v[144:145], v[230:231], v[192:193]
	global_store_dwordx4 v[150:151], v[236:239], off nt
	v_lshl_add_u64 v[150:151], v[150:151], 0, s[74:75]
	ds_read_b32 v143, v160 offset:976
	ds_read_b128 v[172:175], v161 offset:7808
	ds_read_b128 v[232:235], v161 offset:7824
	s_waitcnt vmcnt(22)
	s_waitcnt lgkmcnt(3)
	v_cndmask_b32_e64 v141, 0, v141, s[8:9]
	v_pk_mul_f32 v[180:181], v[26:27], v[114:115] op_sel:[0,1]
	v_pk_mul_f32 v[192:193], v[28:29], v[114:115] op_sel:[0,1]
	v_mfma_f32_16x16x4_f32 v[110:113], v141, v70, v[110:113]
	v_pk_fma_f32 v[180:181], v[30:31], v[114:115], v[180:181] op_sel_hi:[1,0,1]
	v_pk_fma_f32 v[192:193], v[32:33], v[114:115], v[192:193] op_sel_hi:[1,0,1]
	v_pk_fma_f32 v[180:181], v[22:23], v[116:117], v[180:181] op_sel_hi:[1,0,1]
	v_pk_fma_f32 v[192:193], v[24:25], v[116:117], v[192:193] op_sel_hi:[1,0,1]
	v_mfma_f32_16x16x4_f32 v[106:109], v141, v71, v[106:109]
	v_pk_fma_f32 v[180:181], v[18:19], v[116:117], v[180:181] op_sel:[0,1,0]
	v_pk_fma_f32 v[192:193], v[20:21], v[116:117], v[192:193] op_sel:[0,1,0]
	v_pk_fma_f32 v[180:181], v[14:15], v[176:177], v[180:181] op_sel_hi:[1,0,1]
	v_pk_fma_f32 v[192:193], v[16:17], v[176:177], v[192:193] op_sel_hi:[1,0,1]
	v_mfma_f32_16x16x4_f32 v[102:105], v141, v72, v[102:105]
	v_pk_fma_f32 v[180:181], v[10:11], v[176:177], v[180:181] op_sel:[0,1,0]
	v_pk_fma_f32 v[192:193], v[12:13], v[176:177], v[192:193] op_sel:[0,1,0]
	v_pk_fma_f32 v[180:181], v[6:7], v[178:179], v[180:181] op_sel_hi:[1,0,1]
	v_pk_fma_f32 v[192:193], v[8:9], v[178:179], v[192:193] op_sel_hi:[1,0,1]
	v_mfma_f32_16x16x4_f32 v[98:101], v141, v73, v[98:101]
	v_pk_fma_f32 v[180:181], v[2:3], v[178:179], v[180:181] op_sel:[0,1,0]
	v_pk_fma_f32 v[192:193], v[4:5], v[178:179], v[192:193] op_sel:[0,1,0]
	v_pk_mul_f32 v[180:181], v[146:147], v[180:181]
	v_pk_mul_f32 v[192:193], v[146:147], v[192:193]
	v_pk_fma_f32 v[236:237], v[144:145], v[70:71], v[180:181]
	v_pk_fma_f32 v[238:239], v[144:145], v[72:73], v[192:193]
	global_store_dwordx4 v[150:151], v[236:239], off nt
	v_lshl_add_u64 v[150:151], v[150:151], 0, s[74:75]
	ds_read_b32 v141, v160 offset:992
	ds_read_b128 v[114:117], v161 offset:7936
	ds_read_b128 v[176:179], v161 offset:7952
	s_waitcnt vmcnt(21)
; #define RS_LOAD(dst, it0) do { _Pragma("unroll") for (int u = 0; u < 8; ++u) dst[u] = __builtin_nontemporal_load((const f32x4*)(S0 + (size_t)(4 * ((it0) + u)) * DV)); } while (0)
; __device__ __forceinline__ void ret_sample_item(Frame& F, int item) {
;     ...
;     for (int it0 = 0; it0 < 64; it0 += 16) {
;         RS_LOAD(sb, it0 + 8);
;         RS_PROC(sa, it0);
;         { const int itn = it0 + 16 < 64 ? it0 + 16 : it0; RS_LOAD(sa, itn); }
;         RS_PROC(sb, it0 + 8);
;     }
	s_waitcnt lgkmcnt(3)
	v_cndmask_b32_e64 v143, 0, v143, s[8:9]
	v_pk_mul_f32 v[180:181], v[26:27], v[172:173] op_sel:[0,1]
	v_pk_mul_f32 v[192:193], v[28:29], v[172:173] op_sel:[0,1]
	v_mfma_f32_16x16x4_f32 v[110:113], v143, v62, v[110:113]
	v_pk_fma_f32 v[180:181], v[30:31], v[172:173], v[180:181] op_sel_hi:[1,0,1]
	v_pk_fma_f32 v[192:193], v[32:33], v[172:173], v[192:193] op_sel_hi:[1,0,1]
	v_pk_fma_f32 v[180:181], v[22:23], v[174:175], v[180:181] op_sel_hi:[1,0,1]
	v_pk_fma_f32 v[192:193], v[24:25], v[174:175], v[192:193] op_sel_hi:[1,0,1]
	v_mfma_f32_16x16x4_f32 v[106:109], v143, v63, v[106:109]
	v_pk_fma_f32 v[180:181], v[18:19], v[174:175], v[180:181] op_sel:[0,1,0]
	v_pk_fma_f32 v[192:193], v[20:21], v[174:175], v[192:193] op_sel:[0,1,0]
	v_pk_fma_f32 v[180:181], v[14:15], v[232:233], v[180:181] op_sel_hi:[1,0,1]
	v_pk_fma_f32 v[192:193], v[16:17], v[232:233], v[192:193] op_sel_hi:[1,0,1]
	v_mfma_f32_16x16x4_f32 v[102:105], v143, v64, v[102:105]
	v_pk_fma_f32 v[180:181], v[10:11], v[232:233], v[180:181] op_sel:[0,1,0]
	v_pk_fma_f32 v[192:193], v[12:13], v[232:233], v[192:193] op_sel:[0,1,0]
	v_pk_fma_f32 v[180:181], v[6:7], v[234:235], v[180:181] op_sel_hi:[1,0,1]
	v_pk_fma_f32 v[192:193], v[8:9], v[234:235], v[192:193] op_sel_hi:[1,0,1]
	v_mfma_f32_16x16x4_f32 v[98:101], v143, v65, v[98:101]
	v_pk_fma_f32 v[180:181], v[2:3], v[234:235], v[180:181] op_sel:[0,1,0]
	v_pk_fma_f32 v[192:193], v[4:5], v[234:235], v[192:193] op_sel:[0,1,0]
	v_pk_mul_f32 v[180:181], v[146:147], v[180:181]
	v_pk_mul_f32 v[192:193], v[146:147], v[192:193]
	v_pk_fma_f32 v[236:237], v[144:145], v[62:63], v[180:181]
	v_pk_fma_f32 v[238:239], v[144:145], v[64:65], v[192:193]
	global_store_dwordx4 v[150:151], v[236:239], off nt
	v_lshl_add_u64 v[150:151], v[150:151], 0, s[74:75]
	ds_read_b32 v143, v160 offset:1008
	ds_read_b128 v[172:175], v161 offset:8064
	ds_read_b128 v[232:235], v161 offset:8080
	s_waitcnt vmcnt(20)
	s_waitcnt lgkmcnt(3)
	v_cndmask_b32_e64 v141, 0, v141, s[8:9]
	v_pk_mul_f32 v[180:181], v[26:27], v[114:115] op_sel:[0,1]
	v_pk_mul_f32 v[192:193], v[28:29], v[114:115] op_sel:[0,1]
	v_mfma_f32_16x16x4_f32 v[110:113], v141, v54, v[110:113]
	v_pk_fma_f32 v[180:181], v[30:31], v[114:115], v[180:181] op_sel_hi:[1,0,1]
	v_pk_fma_f32 v[192:193], v[32:33], v[114:115], v[192:193] op_sel_hi:[1,0,1]
	v_pk_fma_f32 v[180:181], v[22:23], v[116:117], v[180:181] op_sel_hi:[1,0,1]
	v_pk_fma_f32 v[192:193], v[24:25], v[116:117], v[192:193] op_sel_hi:[1,0,1]
	v_mfma_f32_16x16x4_f32 v[106:109], v141, v55, v[106:109]
	v_pk_fma_f32 v[180:181], v[18:19], v[116:117], v[180:181] op_sel:[0,1,0]
	v_pk_fma_f32 v[192:193], v[20:21], v[116:117], v[192:193] op_sel:[0,1,0]
	v_pk_fma_f32 v[180:181], v[14:15], v[176:177], v[180:181] op_sel_hi:[1,0,1]
	v_pk_fma_f32 v[192:193], v[16:17], v[176:177], v[192:193] op_sel_hi:[1,0,1]
	v_mfma_f32_16x16x4_f32 v[102:105], v141, v56, v[102:105]
	v_pk_fma_f32 v[180:181], v[10:11], v[176:177], v[180:181] op_sel:[0,1,0]
	v_pk_fma_f32 v[192:193], v[12:13], v[176:177], v[192:193] op_sel:[0,1,0]
	v_pk_fma_f32 v[180:181], v[6:7], v[178:179], v[180:181] op_sel_hi:[1,0,1]
	v_pk_fma_f32 v[192:193], v[8:9], v[178:179], v[192:193] op_sel_hi:[1,0,1]
	v_mfma_f32_16x16x4_f32 v[98:101], v141, v57, v[98:101]
	v_pk_fma_f32 v[180:181], v[2:3], v[178:179], v[180:181] op_sel:[0,1,0]
	v_pk_fma_f32 v[192:193], v[4:5], v[178:179], v[192:193] op_sel:[0,1,0]
	v_pk_mul_f32 v[180:181], v[146:147], v[180:181]
	v_pk_mul_f32 v[192:193], v[146:147], v[192:193]
	v_pk_fma_f32 v[236:237], v[144:145], v[54:55], v[180:181]
	v_pk_fma_f32 v[238:239], v[144:145], v[56:57], v[192:193]
	global_store_dwordx4 v[150:151], v[236:239], off nt
	v_lshl_add_u64 v[150:151], v[150:151], 0, s[74:75]
	s_waitcnt vmcnt(19)
	s_waitcnt lgkmcnt(0)
	v_cndmask_b32_e64 v143, 0, v143, s[8:9]
	v_pk_mul_f32 v[180:181], v[26:27], v[172:173] op_sel:[0,1]
	v_pk_mul_f32 v[192:193], v[28:29], v[172:173] op_sel:[0,1]
	v_mfma_f32_16x16x4_f32 v[110:113], v143, v50, v[110:113]
	v_pk_fma_f32 v[180:181], v[30:31], v[172:173], v[180:181] op_sel_hi:[1,0,1]
	v_pk_fma_f32 v[192:193], v[32:33], v[172:173], v[192:193] op_sel_hi:[1,0,1]
	v_pk_fma_f32 v[180:181], v[22:23], v[174:175], v[180:181] op_sel_hi:[1,0,1]
	v_pk_fma_f32 v[192:193], v[24:25], v[174:175], v[192:193] op_sel_hi:[1,0,1]
	v_mfma_f32_16x16x4_f32 v[106:109], v143, v51, v[106:109]
	v_pk_fma_f32 v[180:181], v[18:19], v[174:175], v[180:181] op_sel:[0,1,0]
	v_pk_fma_f32 v[192:193], v[20:21], v[174:175], v[192:193] op_sel:[0,1,0]
	v_pk_fma_f32 v[180:181], v[14:15], v[232:233], v[180:181] op_sel_hi:[1,0,1]
	v_pk_fma_f32 v[192:193], v[16:17], v[232:233], v[192:193] op_sel_hi:[1,0,1]
	v_mfma_f32_16x16x4_f32 v[102:105], v143, v52, v[102:105]
	v_pk_fma_f32 v[180:181], v[10:11], v[232:233], v[180:181] op_sel:[0,1,0]
	v_pk_fma_f32 v[192:193], v[12:13], v[232:233], v[192:193] op_sel:[0,1,0]
	v_pk_fma_f32 v[180:181], v[6:7], v[234:235], v[180:181] op_sel_hi:[1,0,1]
	v_pk_fma_f32 v[192:193], v[8:9], v[234:235], v[192:193] op_sel_hi:[1,0,1]
	v_mfma_f32_16x16x4_f32 v[98:101], v143, v53, v[98:101]
	v_pk_fma_f32 v[180:181], v[2:3], v[234:235], v[180:181] op_sel:[0,1,0]
	v_pk_fma_f32 v[192:193], v[4:5], v[234:235], v[192:193] op_sel:[0,1,0]
	v_pk_mul_f32 v[180:181], v[146:147], v[180:181]
	v_pk_mul_f32 v[192:193], v[146:147], v[192:193]
	v_pk_fma_f32 v[236:237], v[144:145], v[50:51], v[180:181]
	v_pk_fma_f32 v[238:239], v[144:145], v[52:53], v[192:193]
	global_store_dwordx4 v[150:151], v[236:239], off nt
	v_lshl_add_u64 v[150:151], v[150:151], 0, s[74:75]
	s_nop 7
	s_nop 3
	s_branch .LBB0_618
	s_nop 0
	s_nop 0
	s_nop 0
	s_nop 0
	s_nop 0
	s_nop 0

; #define LAS __attribute__((address_space(3)))
; #define RS_LOAD(dst, it0) do { _Pragma("unroll") for (int u = 0; u < 8; ++u) dst[u] = __builtin_nontemporal_load((const f32x4*)(S0 + (size_t)(4 * ((it0) + u)) * DV)); } while (0)
; __device__ __forceinline__ void ret_sample_item(Frame& F, int item) {
;     ...
;     const float gam = 1.0f - exp2f(-5.0f - (float)h);
;     const float g7 = exp2f(7.0f * log2f(gam)), g8 = g7 * gam;
;     ...
;     f32x4 v4[8];
; #pragma unroll
;     for (int m = 0; m < 8; ++m) v4[m] = *(const LAS f32x4*)(vs + m * 512 + e4);
;     f32x4 oacc[4];
; #pragma unroll
;     for (int i = 0; i < 4; ++i) oacc[i] = (f32x4){0.f, 0.f, 0.f, 0.f};
;     ...
;     for (int it0 = 0; it0 < 64; it0 += 16) {
;         RS_LOAD(sb, it0 + 8);
;         RS_PROC(sa, it0);
;         { const int itn = it0 + 16 < 64 ? it0 + 16 : it0; RS_LOAD(sa, itn); }
;         RS_PROC(sb, it0 + 8);
;     }
.LBB0_643:
	s_or_b64 exec, exec, s[58:59]
	v_cvt_f32_ubyte0_e32 v2, s10
	v_sub_f32_e32 v2, 0xc0a00000, v2
	v_cmp_gt_f32_e32 vcc, s75, v2
	s_and_b64 s[58:59], vcc, exec
	s_cselect_b32 s10, 0xffffffc0, 0
	v_cndmask_b32_e32 v3, 0, v169, vcc
	v_add_f32_e32 v2, v2, v3
	v_exp_f32_e32 v2, v2
	s_waitcnt lgkmcnt(0)
	s_barrier
	v_ldexp_f32 v2, v2, s10
	v_sub_f32_e32 v138, 1.0, v2
	v_cmp_gt_f32_e32 vcc, s76, v138
	s_and_b64 s[58:59], vcc, exec
	s_cselect_b32 s10, 32, 0
	v_ldexp_f32 v3, v138, s10
	v_log_f32_e32 v3, v3
	v_cndmask_b32_e32 v2, 0, v170, vcc
	v_mov_b32_e32 v98, 0
	s_mov_b32 s10, 0
	v_sub_f32_e32 v2, v3, v2
	v_mul_f32_e32 v3, 0x40e00000, v2
	v_cmp_gt_f32_e32 vcc, s75, v3
	s_and_b64 s[58:59], vcc, exec
	s_cselect_b32 s18, 0xffffffc0, 0
	v_cndmask_b32_e32 v3, 0, v169, vcc
	v_fmac_f32_e32 v3, 0x40e00000, v2
	v_exp_f32_e32 v2, v3
	v_mov_b64_e32 v[148:149], v[130:131]
	v_mov_b64_e32 v[150:151], v[128:129]
	v_mov_b32_e32 v171, v161
	v_ldexp_f32 v140, v2, s18
	ds_read_b128 v[30:33], v139 offset:16512
	ds_read_b128 v[26:29], v139 offset:18560
	ds_read_b128 v[22:25], v139 offset:20608
	ds_read_b128 v[18:21], v139 offset:22656
	ds_read_b128 v[14:17], v139 offset:24704
	ds_read_b128 v[10:13], v139 offset:26752
	ds_read_b128 v[6:9], v139 offset:28800
	ds_read_b128 v[2:5], v139 offset:30848
	v_mul_f32_e32 v142, v138, v140
	v_mov_b32_e32 v144, v142
	v_mov_b32_e32 v145, v142
	v_mov_b32_e32 v146, v140
	v_mov_b32_e32 v147, v140
	v_mov_b32_e32 v172, v160
	v_mov_b32_e32 v99, v98
	v_mov_b32_e32 v100, v98
	v_mov_b32_e32 v101, v98
	v_mov_b32_e32 v102, v98
	v_mov_b32_e32 v103, v98
	v_mov_b32_e32 v104, v98
	v_mov_b32_e32 v105, v98
	v_mov_b32_e32 v106, v98
	v_mov_b32_e32 v107, v98
	v_mov_b32_e32 v108, v98
	v_mov_b32_e32 v109, v98
	v_mov_b32_e32 v110, v98
	v_mov_b32_e32 v111, v98
	v_mov_b32_e32 v112, v98
	v_mov_b32_e32 v113, v98
	v_lshl_add_u64 v[148:149], v[130:131], 0, v[122:123]
	v_lshl_add_u64 v[150:151], v[128:129], 0, v[122:123]
	s_mov_b32 s58, 0x10000
	s_mov_b32 s59, 0
	v_add_co_u32_e32 v150, vcc, 0x5878000, v150
	v_lshl_add_u64 v[148:149], v[148:149], 0, s[58:59]
	s_mov_b32 s58, 0x2000
	v_addc_co_u32_e32 v151, vcc, 0, v151, vcc
	ds_read_b32 v141, v160
	ds_read_b128 v[114:117], v161
	ds_read_b128 v[176:179], v161 offset:16
	global_load_dwordx4 v[58:61], v[148:149], off nt
	v_lshl_add_u64 v[148:149], v[148:149], 0, s[58:59]
	global_load_dwordx4 v[66:69], v[148:149], off nt
	v_lshl_add_u64 v[148:149], v[148:149], 0, s[58:59]
	global_load_dwordx4 v[74:77], v[148:149], off nt
	v_lshl_add_u64 v[148:149], v[148:149], 0, s[58:59]
	global_load_dwordx4 v[78:81], v[148:149], off nt
	v_lshl_add_u64 v[148:149], v[148:149], 0, s[58:59]
	global_load_dwordx4 v[82:85], v[148:149], off nt
	v_lshl_add_u64 v[148:149], v[148:149], 0, s[58:59]
	global_load_dwordx4 v[86:89], v[148:149], off nt
	v_lshl_add_u64 v[148:149], v[148:149], 0, s[58:59]
	global_load_dwordx4 v[90:93], v[148:149], off nt
	v_lshl_add_u64 v[148:149], v[148:149], 0, s[58:59]
	global_load_dwordx4 v[94:97], v[148:149], off nt
	v_lshl_add_u64 v[148:149], v[148:149], 0, s[58:59]
	global_load_dwordx4 v[212:215], v[148:149], off nt
	v_lshl_add_u64 v[148:149], v[148:149], 0, s[58:59]
	global_load_dwordx4 v[216:219], v[148:149], off nt
	v_lshl_add_u64 v[148:149], v[148:149], 0, s[58:59]
	global_load_dwordx4 v[224:227], v[148:149], off nt
	v_lshl_add_u64 v[148:149], v[148:149], 0, s[58:59]
	global_load_dwordx4 v[228:231], v[148:149], off nt
	v_lshl_add_u64 v[148:149], v[148:149], 0, s[58:59]
	ds_read_b32 v143, v160 offset:16
	ds_read_b128 v[172:175], v161 offset:128
	ds_read_b128 v[232:235], v161 offset:144
	s_waitcnt lgkmcnt(3)
	v_cndmask_b32_e64 v141, 0, v141, s[6:7]
	v_pk_mul_f32 v[180:181], v[26:27], v[114:115] op_sel:[0,1]
	v_pk_mul_f32 v[192:193], v[28:29], v[114:115] op_sel:[0,1]
	v_mfma_f32_16x16x4_f32 v[110:113], v141, v70, v[110:113]
	v_pk_fma_f32 v[180:181], v[30:31], v[114:115], v[180:181] op_sel_hi:[1,0,1]
	v_pk_fma_f32 v[192:193], v[32:33], v[114:115], v[192:193] op_sel_hi:[1,0,1]
	v_pk_fma_f32 v[180:181], v[22:23], v[116:117], v[180:181] op_sel_hi:[1,0,1]
	v_pk_fma_f32 v[192:193], v[24:25], v[116:117], v[192:193] op_sel_hi:[1,0,1]
	v_mfma_f32_16x16x4_f32 v[106:109], v141, v71, v[106:109]
	v_pk_fma_f32 v[180:181], v[18:19], v[116:117], v[180:181] op_sel:[0,1,0]
	v_pk_fma_f32 v[192:193], v[20:21], v[116:117], v[192:193] op_sel:[0,1,0]
	v_pk_fma_f32 v[180:181], v[14:15], v[176:177], v[180:181] op_sel_hi:[1,0,1]
	v_pk_fma_f32 v[192:193], v[16:17], v[176:177], v[192:193] op_sel_hi:[1,0,1]
	v_mfma_f32_16x16x4_f32 v[102:105], v141, v72, v[102:105]
	v_pk_fma_f32 v[180:181], v[10:11], v[176:177], v[180:181] op_sel:[0,1,0]
	v_pk_fma_f32 v[192:193], v[12:13], v[176:177], v[192:193] op_sel:[0,1,0]
	v_pk_fma_f32 v[180:181], v[6:7], v[178:179], v[180:181] op_sel_hi:[1,0,1]
	v_pk_fma_f32 v[192:193], v[8:9], v[178:179], v[192:193] op_sel_hi:[1,0,1]
	v_mfma_f32_16x16x4_f32 v[98:101], v141, v73, v[98:101]
	v_pk_fma_f32 v[180:181], v[2:3], v[178:179], v[180:181] op_sel:[0,1,0]
	v_pk_fma_f32 v[192:193], v[4:5], v[178:179], v[192:193] op_sel:[0,1,0]
	v_pk_mul_f32 v[180:181], v[146:147], v[180:181]
	v_pk_mul_f32 v[192:193], v[146:147], v[192:193]
	v_pk_fma_f32 v[236:237], v[144:145], v[70:71], v[180:181]
	v_pk_fma_f32 v[238:239], v[144:145], v[72:73], v[192:193]
	global_store_dwordx4 v[150:151], v[236:239], off nt
	v_lshl_add_u64 v[150:151], v[150:151], 0, s[58:59]
	global_load_dwordx4 v[70:73], v[148:149], off nt
	v_lshl_add_u64 v[148:149], v[148:149], 0, s[58:59]
	ds_read_b32 v141, v160 offset:32
	ds_read_b128 v[114:117], v161 offset:256
	ds_read_b128 v[176:179], v161 offset:272
	s_waitcnt lgkmcnt(3)
; #define RS_LOAD(dst, it0) do { _Pragma("unroll") for (int u = 0; u < 8; ++u) dst[u] = __builtin_nontemporal_load((const f32x4*)(S0 + (size_t)(4 * ((it0) + u)) * DV)); } while (0)
; __device__ __forceinline__ void ret_sample_item(Frame& F, int item) {
;     ...
;     for (int it0 = 0; it0 < 64; it0 += 16) {
;         RS_LOAD(sb, it0 + 8);
;         RS_PROC(sa, it0);
;         { const int itn = it0 + 16 < 64 ? it0 + 16 : it0; RS_LOAD(sa, itn); }
;         RS_PROC(sb, it0 + 8);
;     }
	v_cndmask_b32_e64 v143, 0, v143, s[6:7]
	v_pk_mul_f32 v[180:181], v[26:27], v[172:173] op_sel:[0,1]
	v_pk_mul_f32 v[192:193], v[28:29], v[172:173] op_sel:[0,1]
	v_mfma_f32_16x16x4_f32 v[110:113], v143, v62, v[110:113]
	v_pk_fma_f32 v[180:181], v[30:31], v[172:173], v[180:181] op_sel_hi:[1,0,1]
	v_pk_fma_f32 v[192:193], v[32:33], v[172:173], v[192:193] op_sel_hi:[1,0,1]
	v_pk_fma_f32 v[180:181], v[22:23], v[174:175], v[180:181] op_sel_hi:[1,0,1]
	v_pk_fma_f32 v[192:193], v[24:25], v[174:175], v[192:193] op_sel_hi:[1,0,1]
	v_mfma_f32_16x16x4_f32 v[106:109], v143, v63, v[106:109]
	v_pk_fma_f32 v[180:181], v[18:19], v[174:175], v[180:181] op_sel:[0,1,0]
	v_pk_fma_f32 v[192:193], v[20:21], v[174:175], v[192:193] op_sel:[0,1,0]
	v_pk_fma_f32 v[180:181], v[14:15], v[232:233], v[180:181] op_sel_hi:[1,0,1]
	v_pk_fma_f32 v[192:193], v[16:17], v[232:233], v[192:193] op_sel_hi:[1,0,1]
	v_mfma_f32_16x16x4_f32 v[102:105], v143, v64, v[102:105]
	v_pk_fma_f32 v[180:181], v[10:11], v[232:233], v[180:181] op_sel:[0,1,0]
	v_pk_fma_f32 v[192:193], v[12:13], v[232:233], v[192:193] op_sel:[0,1,0]
	v_pk_fma_f32 v[180:181], v[6:7], v[234:235], v[180:181] op_sel_hi:[1,0,1]
	v_pk_fma_f32 v[192:193], v[8:9], v[234:235], v[192:193] op_sel_hi:[1,0,1]
	v_mfma_f32_16x16x4_f32 v[98:101], v143, v65, v[98:101]
	v_pk_fma_f32 v[180:181], v[2:3], v[234:235], v[180:181] op_sel:[0,1,0]
	v_pk_fma_f32 v[192:193], v[4:5], v[234:235], v[192:193] op_sel:[0,1,0]
	v_pk_mul_f32 v[180:181], v[146:147], v[180:181]
	v_pk_mul_f32 v[192:193], v[146:147], v[192:193]
	v_pk_fma_f32 v[236:237], v[144:145], v[62:63], v[180:181]
	v_pk_fma_f32 v[238:239], v[144:145], v[64:65], v[192:193]
	global_store_dwordx4 v[150:151], v[236:239], off nt
	v_lshl_add_u64 v[150:151], v[150:151], 0, s[58:59]
	global_load_dwordx4 v[62:65], v[148:149], off nt
	v_lshl_add_u64 v[148:149], v[148:149], 0, s[58:59]
	ds_read_b32 v143, v160 offset:48
	ds_read_b128 v[172:175], v161 offset:384
	ds_read_b128 v[232:235], v161 offset:400
	s_waitcnt lgkmcnt(3)
	v_cndmask_b32_e64 v141, 0, v141, s[6:7]
	v_pk_mul_f32 v[180:181], v[26:27], v[114:115] op_sel:[0,1]
	v_pk_mul_f32 v[192:193], v[28:29], v[114:115] op_sel:[0,1]
	v_mfma_f32_16x16x4_f32 v[110:113], v141, v54, v[110:113]
	v_pk_fma_f32 v[180:181], v[30:31], v[114:115], v[180:181] op_sel_hi:[1,0,1]
	v_pk_fma_f32 v[192:193], v[32:33], v[114:115], v[192:193] op_sel_hi:[1,0,1]
	v_pk_fma_f32 v[180:181], v[22:23], v[116:117], v[180:181] op_sel_hi:[1,0,1]
	v_pk_fma_f32 v[192:193], v[24:25], v[116:117], v[192:193] op_sel_hi:[1,0,1]
	v_mfma_f32_16x16x4_f32 v[106:109], v141, v55, v[106:109]
	v_pk_fma_f32 v[180:181], v[18:19], v[116:117], v[180:181] op_sel:[0,1,0]
	v_pk_fma_f32 v[192:193], v[20:21], v[116:117], v[192:193] op_sel:[0,1,0]
	v_pk_fma_f32 v[180:181], v[14:15], v[176:177], v[180:181] op_sel_hi:[1,0,1]
	v_pk_fma_f32 v[192:193], v[16:17], v[176:177], v[192:193] op_sel_hi:[1,0,1]
	v_mfma_f32_16x16x4_f32 v[102:105], v141, v56, v[102:105]
	v_pk_fma_f32 v[180:181], v[10:11], v[176:177], v[180:181] op_sel:[0,1,0]
	v_pk_fma_f32 v[192:193], v[12:13], v[176:177], v[192:193] op_sel:[0,1,0]
	v_pk_fma_f32 v[180:181], v[6:7], v[178:179], v[180:181] op_sel_hi:[1,0,1]
	v_pk_fma_f32 v[192:193], v[8:9], v[178:179], v[192:193] op_sel_hi:[1,0,1]
	v_mfma_f32_16x16x4_f32 v[98:101], v141, v57, v[98:101]
	v_pk_fma_f32 v[180:181], v[2:3], v[178:179], v[180:181] op_sel:[0,1,0]
	v_pk_fma_f32 v[192:193], v[4:5], v[178:179], v[192:193] op_sel:[0,1,0]
	v_pk_mul_f32 v[180:181], v[146:147], v[180:181]
	v_pk_mul_f32 v[192:193], v[146:147], v[192:193]
	v_pk_fma_f32 v[236:237], v[144:145], v[54:55], v[180:181]
	v_pk_fma_f32 v[238:239], v[144:145], v[56:57], v[192:193]
	global_store_dwordx4 v[150:151], v[236:239], off nt
	v_lshl_add_u64 v[150:151], v[150:151], 0, s[58:59]
	global_load_dwordx4 v[54:57], v[148:149], off nt
	v_lshl_add_u64 v[148:149], v[148:149], 0, s[58:59]
	ds_read_b32 v141, v160 offset:64
	ds_read_b128 v[114:117], v161 offset:512
	ds_read_b128 v[176:179], v161 offset:528
	s_waitcnt lgkmcnt(3)
	v_cndmask_b32_e64 v143, 0, v143, s[6:7]
	v_pk_mul_f32 v[180:181], v[26:27], v[172:173] op_sel:[0,1]
	v_pk_mul_f32 v[192:193], v[28:29], v[172:173] op_sel:[0,1]
	v_mfma_f32_16x16x4_f32 v[110:113], v143, v50, v[110:113]
	v_pk_fma_f32 v[180:181], v[30:31], v[172:173], v[180:181] op_sel_hi:[1,0,1]
	v_pk_fma_f32 v[192:193], v[32:33], v[172:173], v[192:193] op_sel_hi:[1,0,1]
	v_pk_fma_f32 v[180:181], v[22:23], v[174:175], v[180:181] op_sel_hi:[1,0,1]
	v_pk_fma_f32 v[192:193], v[24:25], v[174:175], v[192:193] op_sel_hi:[1,0,1]
	v_mfma_f32_16x16x4_f32 v[106:109], v143, v51, v[106:109]
	v_pk_fma_f32 v[180:181], v[18:19], v[174:175], v[180:181] op_sel:[0,1,0]
	v_pk_fma_f32 v[192:193], v[20:21], v[174:175], v[192:193] op_sel:[0,1,0]
	v_pk_fma_f32 v[180:181], v[14:15], v[232:233], v[180:181] op_sel_hi:[1,0,1]
	v_pk_fma_f32 v[192:193], v[16:17], v[232:233], v[192:193] op_sel_hi:[1,0,1]
	v_mfma_f32_16x16x4_f32 v[102:105], v143, v52, v[102:105]
	v_pk_fma_f32 v[180:181], v[10:11], v[232:233], v[180:181] op_sel:[0,1,0]
	v_pk_fma_f32 v[192:193], v[12:13], v[232:233], v[192:193] op_sel:[0,1,0]
	v_pk_fma_f32 v[180:181], v[6:7], v[234:235], v[180:181] op_sel_hi:[1,0,1]
	v_pk_fma_f32 v[192:193], v[8:9], v[234:235], v[192:193] op_sel_hi:[1,0,1]
	v_mfma_f32_16x16x4_f32 v[98:101], v143, v53, v[98:101]
	v_pk_fma_f32 v[180:181], v[2:3], v[234:235], v[180:181] op_sel:[0,1,0]
	v_pk_fma_f32 v[192:193], v[4:5], v[234:235], v[192:193] op_sel:[0,1,0]
	v_pk_mul_f32 v[180:181], v[146:147], v[180:181]
	v_pk_mul_f32 v[192:193], v[146:147], v[192:193]
	v_pk_fma_f32 v[236:237], v[144:145], v[50:51], v[180:181]
	v_pk_fma_f32 v[238:239], v[144:145], v[52:53], v[192:193]
	global_store_dwordx4 v[150:151], v[236:239], off nt
	v_lshl_add_u64 v[150:151], v[150:151], 0, s[58:59]
	global_load_dwordx4 v[50:53], v[148:149], off nt
	v_lshl_add_u64 v[148:149], v[148:149], 0, s[58:59]
	ds_read_b32 v143, v160 offset:80
	ds_read_b128 v[172:175], v161 offset:640
	ds_read_b128 v[232:235], v161 offset:656
	s_waitcnt lgkmcnt(3)
; #define RS_LOAD(dst, it0) do { _Pragma("unroll") for (int u = 0; u < 8; ++u) dst[u] = __builtin_nontemporal_load((const f32x4*)(S0 + (size_t)(4 * ((it0) + u)) * DV)); } while (0)
; __device__ __forceinline__ void ret_sample_item(Frame& F, int item) {
;     ...
;     for (int it0 = 0; it0 < 64; it0 += 16) {
;         RS_LOAD(sb, it0 + 8);
;         RS_PROC(sa, it0);
;         { const int itn = it0 + 16 < 64 ? it0 + 16 : it0; RS_LOAD(sa, itn); }
;         RS_PROC(sb, it0 + 8);
;     }
	v_cndmask_b32_e64 v141, 0, v141, s[6:7]
	v_pk_mul_f32 v[180:181], v[26:27], v[114:115] op_sel:[0,1]
	v_pk_mul_f32 v[192:193], v[28:29], v[114:115] op_sel:[0,1]
	v_mfma_f32_16x16x4_f32 v[110:113], v141, v46, v[110:113]
	v_pk_fma_f32 v[180:181], v[30:31], v[114:115], v[180:181] op_sel_hi:[1,0,1]
	v_pk_fma_f32 v[192:193], v[32:33], v[114:115], v[192:193] op_sel_hi:[1,0,1]
	v_pk_fma_f32 v[180:181], v[22:23], v[116:117], v[180:181] op_sel_hi:[1,0,1]
	v_pk_fma_f32 v[192:193], v[24:25], v[116:117], v[192:193] op_sel_hi:[1,0,1]
	v_mfma_f32_16x16x4_f32 v[106:109], v141, v47, v[106:109]
	v_pk_fma_f32 v[180:181], v[18:19], v[116:117], v[180:181] op_sel:[0,1,0]
	v_pk_fma_f32 v[192:193], v[20:21], v[116:117], v[192:193] op_sel:[0,1,0]
	v_pk_fma_f32 v[180:181], v[14:15], v[176:177], v[180:181] op_sel_hi:[1,0,1]
	v_pk_fma_f32 v[192:193], v[16:17], v[176:177], v[192:193] op_sel_hi:[1,0,1]
	v_mfma_f32_16x16x4_f32 v[102:105], v141, v48, v[102:105]
	v_pk_fma_f32 v[180:181], v[10:11], v[176:177], v[180:181] op_sel:[0,1,0]
	v_pk_fma_f32 v[192:193], v[12:13], v[176:177], v[192:193] op_sel:[0,1,0]
	v_pk_fma_f32 v[180:181], v[6:7], v[178:179], v[180:181] op_sel_hi:[1,0,1]
	v_pk_fma_f32 v[192:193], v[8:9], v[178:179], v[192:193] op_sel_hi:[1,0,1]
	v_mfma_f32_16x16x4_f32 v[98:101], v141, v49, v[98:101]
	v_pk_fma_f32 v[180:181], v[2:3], v[178:179], v[180:181] op_sel:[0,1,0]
	v_pk_fma_f32 v[192:193], v[4:5], v[178:179], v[192:193] op_sel:[0,1,0]
	v_pk_mul_f32 v[180:181], v[146:147], v[180:181]
	v_pk_mul_f32 v[192:193], v[146:147], v[192:193]
	v_pk_fma_f32 v[236:237], v[144:145], v[46:47], v[180:181]
	v_pk_fma_f32 v[238:239], v[144:145], v[48:49], v[192:193]
	global_store_dwordx4 v[150:151], v[236:239], off nt
	v_lshl_add_u64 v[150:151], v[150:151], 0, s[58:59]
	global_load_dwordx4 v[46:49], v[148:149], off nt
	v_lshl_add_u64 v[148:149], v[148:149], 0, s[58:59]
	ds_read_b32 v141, v160 offset:96
	ds_read_b128 v[114:117], v161 offset:768
	ds_read_b128 v[176:179], v161 offset:784
	s_waitcnt lgkmcnt(3)
	v_cndmask_b32_e64 v143, 0, v143, s[6:7]
	v_pk_mul_f32 v[180:181], v[26:27], v[172:173] op_sel:[0,1]
	v_pk_mul_f32 v[192:193], v[28:29], v[172:173] op_sel:[0,1]
	v_mfma_f32_16x16x4_f32 v[110:113], v143, v42, v[110:113]
	v_pk_fma_f32 v[180:181], v[30:31], v[172:173], v[180:181] op_sel_hi:[1,0,1]
	v_pk_fma_f32 v[192:193], v[32:33], v[172:173], v[192:193] op_sel_hi:[1,0,1]
	v_pk_fma_f32 v[180:181], v[22:23], v[174:175], v[180:181] op_sel_hi:[1,0,1]
	v_pk_fma_f32 v[192:193], v[24:25], v[174:175], v[192:193] op_sel_hi:[1,0,1]
	v_mfma_f32_16x16x4_f32 v[106:109], v143, v43, v[106:109]
	v_pk_fma_f32 v[180:181], v[18:19], v[174:175], v[180:181] op_sel:[0,1,0]
	v_pk_fma_f32 v[192:193], v[20:21], v[174:175], v[192:193] op_sel:[0,1,0]
	v_pk_fma_f32 v[180:181], v[14:15], v[232:233], v[180:181] op_sel_hi:[1,0,1]
	v_pk_fma_f32 v[192:193], v[16:17], v[232:233], v[192:193] op_sel_hi:[1,0,1]
	v_mfma_f32_16x16x4_f32 v[102:105], v143, v44, v[102:105]
	v_pk_fma_f32 v[180:181], v[10:11], v[232:233], v[180:181] op_sel:[0,1,0]
	v_pk_fma_f32 v[192:193], v[12:13], v[232:233], v[192:193] op_sel:[0,1,0]
	v_pk_fma_f32 v[180:181], v[6:7], v[234:235], v[180:181] op_sel_hi:[1,0,1]
	v_pk_fma_f32 v[192:193], v[8:9], v[234:235], v[192:193] op_sel_hi:[1,0,1]
	v_mfma_f32_16x16x4_f32 v[98:101], v143, v45, v[98:101]
	v_pk_fma_f32 v[180:181], v[2:3], v[234:235], v[180:181] op_sel:[0,1,0]
	v_pk_fma_f32 v[192:193], v[4:5], v[234:235], v[192:193] op_sel:[0,1,0]
	v_pk_mul_f32 v[180:181], v[146:147], v[180:181]
	v_pk_mul_f32 v[192:193], v[146:147], v[192:193]
	v_pk_fma_f32 v[236:237], v[144:145], v[42:43], v[180:181]
	v_pk_fma_f32 v[238:239], v[144:145], v[44:45], v[192:193]
	global_store_dwordx4 v[150:151], v[236:239], off nt
	v_lshl_add_u64 v[150:151], v[150:151], 0, s[58:59]
	global_load_dwordx4 v[42:45], v[148:149], off nt
	v_lshl_add_u64 v[148:149], v[148:149], 0, s[58:59]
	ds_read_b32 v143, v160 offset:112
	ds_read_b128 v[172:175], v161 offset:896
	ds_read_b128 v[232:235], v161 offset:912
	s_waitcnt lgkmcnt(3)
	v_cndmask_b32_e64 v141, 0, v141, s[6:7]
	v_pk_mul_f32 v[180:181], v[26:27], v[114:115] op_sel:[0,1]
	v_pk_mul_f32 v[192:193], v[28:29], v[114:115] op_sel:[0,1]
	v_mfma_f32_16x16x4_f32 v[110:113], v141, v38, v[110:113]
	v_pk_fma_f32 v[180:181], v[30:31], v[114:115], v[180:181] op_sel_hi:[1,0,1]
	v_pk_fma_f32 v[192:193], v[32:33], v[114:115], v[192:193] op_sel_hi:[1,0,1]
	v_pk_fma_f32 v[180:181], v[22:23], v[116:117], v[180:181] op_sel_hi:[1,0,1]
	v_pk_fma_f32 v[192:193], v[24:25], v[116:117], v[192:193] op_sel_hi:[1,0,1]
	v_mfma_f32_16x16x4_f32 v[106:109], v141, v39, v[106:109]
	v_pk_fma_f32 v[180:181], v[18:19], v[116:117], v[180:181] op_sel:[0,1,0]
	v_pk_fma_f32 v[192:193], v[20:21], v[116:117], v[192:193] op_sel:[0,1,0]
	v_pk_fma_f32 v[180:181], v[14:15], v[176:177], v[180:181] op_sel_hi:[1,0,1]
	v_pk_fma_f32 v[192:193], v[16:17], v[176:177], v[192:193] op_sel_hi:[1,0,1]
	v_mfma_f32_16x16x4_f32 v[102:105], v141, v40, v[102:105]
	v_pk_fma_f32 v[180:181], v[10:11], v[176:177], v[180:181] op_sel:[0,1,0]
	v_pk_fma_f32 v[192:193], v[12:13], v[176:177], v[192:193] op_sel:[0,1,0]
	v_pk_fma_f32 v[180:181], v[6:7], v[178:179], v[180:181] op_sel_hi:[1,0,1]
	v_pk_fma_f32 v[192:193], v[8:9], v[178:179], v[192:193] op_sel_hi:[1,0,1]
	v_mfma_f32_16x16x4_f32 v[98:101], v141, v41, v[98:101]
	v_pk_fma_f32 v[180:181], v[2:3], v[178:179], v[180:181] op_sel:[0,1,0]
	v_pk_fma_f32 v[192:193], v[4:5], v[178:179], v[192:193] op_sel:[0,1,0]
	v_pk_mul_f32 v[180:181], v[146:147], v[180:181]
	v_pk_mul_f32 v[192:193], v[146:147], v[192:193]
	v_pk_fma_f32 v[236:237], v[144:145], v[38:39], v[180:181]
	v_pk_fma_f32 v[238:239], v[144:145], v[40:41], v[192:193]
	global_store_dwordx4 v[150:151], v[236:239], off nt
	v_lshl_add_u64 v[150:151], v[150:151], 0, s[58:59]
	global_load_dwordx4 v[38:41], v[148:149], off nt
	v_lshl_add_u64 v[148:149], v[148:149], 0, s[58:59]
	ds_read_b32 v141, v160 offset:128
	ds_read_b128 v[114:117], v161 offset:1024
	ds_read_b128 v[176:179], v161 offset:1040
	s_waitcnt lgkmcnt(3)
; #define RS_LOAD(dst, it0) do { _Pragma("unroll") for (int u = 0; u < 8; ++u) dst[u] = __builtin_nontemporal_load((const f32x4*)(S0 + (size_t)(4 * ((it0) + u)) * DV)); } while (0)
; __device__ __forceinline__ void ret_sample_item(Frame& F, int item) {
;     ...
;     for (int it0 = 0; it0 < 64; it0 += 16) {
;         RS_LOAD(sb, it0 + 8);
;         RS_PROC(sa, it0);
;         { const int itn = it0 + 16 < 64 ? it0 + 16 : it0; RS_LOAD(sa, itn); }
;         RS_PROC(sb, it0 + 8);
;     }
	v_cndmask_b32_e64 v143, 0, v143, s[6:7]
	v_pk_mul_f32 v[180:181], v[26:27], v[172:173] op_sel:[0,1]
	v_pk_mul_f32 v[192:193], v[28:29], v[172:173] op_sel:[0,1]
	v_mfma_f32_16x16x4_f32 v[110:113], v143, v34, v[110:113]
	v_pk_fma_f32 v[180:181], v[30:31], v[172:173], v[180:181] op_sel_hi:[1,0,1]
	v_pk_fma_f32 v[192:193], v[32:33], v[172:173], v[192:193] op_sel_hi:[1,0,1]
	v_pk_fma_f32 v[180:181], v[22:23], v[174:175], v[180:181] op_sel_hi:[1,0,1]
	v_pk_fma_f32 v[192:193], v[24:25], v[174:175], v[192:193] op_sel_hi:[1,0,1]
	v_mfma_f32_16x16x4_f32 v[106:109], v143, v35, v[106:109]
	v_pk_fma_f32 v[180:181], v[18:19], v[174:175], v[180:181] op_sel:[0,1,0]
	v_pk_fma_f32 v[192:193], v[20:21], v[174:175], v[192:193] op_sel:[0,1,0]
	v_pk_fma_f32 v[180:181], v[14:15], v[232:233], v[180:181] op_sel_hi:[1,0,1]
	v_pk_fma_f32 v[192:193], v[16:17], v[232:233], v[192:193] op_sel_hi:[1,0,1]
	v_mfma_f32_16x16x4_f32 v[102:105], v143, v36, v[102:105]
	v_pk_fma_f32 v[180:181], v[10:11], v[232:233], v[180:181] op_sel:[0,1,0]
	v_pk_fma_f32 v[192:193], v[12:13], v[232:233], v[192:193] op_sel:[0,1,0]
	v_pk_fma_f32 v[180:181], v[6:7], v[234:235], v[180:181] op_sel_hi:[1,0,1]
	v_pk_fma_f32 v[192:193], v[8:9], v[234:235], v[192:193] op_sel_hi:[1,0,1]
	v_mfma_f32_16x16x4_f32 v[98:101], v143, v37, v[98:101]
	v_pk_fma_f32 v[180:181], v[2:3], v[234:235], v[180:181] op_sel:[0,1,0]
	v_pk_fma_f32 v[192:193], v[4:5], v[234:235], v[192:193] op_sel:[0,1,0]
	v_pk_mul_f32 v[180:181], v[146:147], v[180:181]
	v_pk_mul_f32 v[192:193], v[146:147], v[192:193]
	v_pk_fma_f32 v[236:237], v[144:145], v[34:35], v[180:181]
	v_pk_fma_f32 v[238:239], v[144:145], v[36:37], v[192:193]
	global_store_dwordx4 v[150:151], v[236:239], off nt
	v_lshl_add_u64 v[150:151], v[150:151], 0, s[58:59]
	global_load_dwordx4 v[34:37], v[148:149], off nt
	v_lshl_add_u64 v[148:149], v[148:149], 0, s[58:59]
	ds_read_b32 v143, v160 offset:144
	ds_read_b128 v[172:175], v161 offset:1152
	ds_read_b128 v[232:235], v161 offset:1168
	s_waitcnt vmcnt(27)
	s_waitcnt lgkmcnt(3)
	v_cndmask_b32_e64 v141, 0, v141, s[6:7]
	v_pk_mul_f32 v[180:181], v[26:27], v[114:115] op_sel:[0,1]
	v_pk_mul_f32 v[192:193], v[28:29], v[114:115] op_sel:[0,1]
	v_mfma_f32_16x16x4_f32 v[110:113], v141, v58, v[110:113]
	v_pk_fma_f32 v[180:181], v[30:31], v[114:115], v[180:181] op_sel_hi:[1,0,1]
	v_pk_fma_f32 v[192:193], v[32:33], v[114:115], v[192:193] op_sel_hi:[1,0,1]
	v_pk_fma_f32 v[180:181], v[22:23], v[116:117], v[180:181] op_sel_hi:[1,0,1]
	v_pk_fma_f32 v[192:193], v[24:25], v[116:117], v[192:193] op_sel_hi:[1,0,1]
	v_mfma_f32_16x16x4_f32 v[106:109], v141, v59, v[106:109]
	v_pk_fma_f32 v[180:181], v[18:19], v[116:117], v[180:181] op_sel:[0,1,0]
	v_pk_fma_f32 v[192:193], v[20:21], v[116:117], v[192:193] op_sel:[0,1,0]
	v_pk_fma_f32 v[180:181], v[14:15], v[176:177], v[180:181] op_sel_hi:[1,0,1]
	v_pk_fma_f32 v[192:193], v[16:17], v[176:177], v[192:193] op_sel_hi:[1,0,1]
	v_mfma_f32_16x16x4_f32 v[102:105], v141, v60, v[102:105]
	v_pk_fma_f32 v[180:181], v[10:11], v[176:177], v[180:181] op_sel:[0,1,0]
	v_pk_fma_f32 v[192:193], v[12:13], v[176:177], v[192:193] op_sel:[0,1,0]
	v_pk_fma_f32 v[180:181], v[6:7], v[178:179], v[180:181] op_sel_hi:[1,0,1]
	v_pk_fma_f32 v[192:193], v[8:9], v[178:179], v[192:193] op_sel_hi:[1,0,1]
	v_mfma_f32_16x16x4_f32 v[98:101], v141, v61, v[98:101]
	v_pk_fma_f32 v[180:181], v[2:3], v[178:179], v[180:181] op_sel:[0,1,0]
	v_pk_fma_f32 v[192:193], v[4:5], v[178:179], v[192:193] op_sel:[0,1,0]
	v_pk_mul_f32 v[180:181], v[146:147], v[180:181]
	v_pk_mul_f32 v[192:193], v[146:147], v[192:193]
	v_pk_fma_f32 v[236:237], v[144:145], v[58:59], v[180:181]
	v_pk_fma_f32 v[238:239], v[144:145], v[60:61], v[192:193]
	global_store_dwordx4 v[150:151], v[236:239], off nt
	v_lshl_add_u64 v[150:151], v[150:151], 0, s[58:59]
	global_load_dwordx4 v[58:61], v[148:149], off nt
	v_lshl_add_u64 v[148:149], v[148:149], 0, s[58:59]
	ds_read_b32 v141, v160 offset:160
	ds_read_b128 v[114:117], v161 offset:1280
	ds_read_b128 v[176:179], v161 offset:1296
	s_waitcnt vmcnt(28)
	s_waitcnt lgkmcnt(3)
	v_cndmask_b32_e64 v143, 0, v143, s[6:7]
	v_pk_mul_f32 v[180:181], v[26:27], v[172:173] op_sel:[0,1]
	v_pk_mul_f32 v[192:193], v[28:29], v[172:173] op_sel:[0,1]
	v_mfma_f32_16x16x4_f32 v[110:113], v143, v66, v[110:113]
	v_pk_fma_f32 v[180:181], v[30:31], v[172:173], v[180:181] op_sel_hi:[1,0,1]
	v_pk_fma_f32 v[192:193], v[32:33], v[172:173], v[192:193] op_sel_hi:[1,0,1]
	v_pk_fma_f32 v[180:181], v[22:23], v[174:175], v[180:181] op_sel_hi:[1,0,1]
	v_pk_fma_f32 v[192:193], v[24:25], v[174:175], v[192:193] op_sel_hi:[1,0,1]
	v_mfma_f32_16x16x4_f32 v[106:109], v143, v67, v[106:109]
	v_pk_fma_f32 v[180:181], v[18:19], v[174:175], v[180:181] op_sel:[0,1,0]
	v_pk_fma_f32 v[192:193], v[20:21], v[174:175], v[192:193] op_sel:[0,1,0]
	v_pk_fma_f32 v[180:181], v[14:15], v[232:233], v[180:181] op_sel_hi:[1,0,1]
	v_pk_fma_f32 v[192:193], v[16:17], v[232:233], v[192:193] op_sel_hi:[1,0,1]
	v_mfma_f32_16x16x4_f32 v[102:105], v143, v68, v[102:105]
	v_pk_fma_f32 v[180:181], v[10:11], v[232:233], v[180:181] op_sel:[0,1,0]
	v_pk_fma_f32 v[192:193], v[12:13], v[232:233], v[192:193] op_sel:[0,1,0]
	v_pk_fma_f32 v[180:181], v[6:7], v[234:235], v[180:181] op_sel_hi:[1,0,1]
	v_pk_fma_f32 v[192:193], v[8:9], v[234:235], v[192:193] op_sel_hi:[1,0,1]
	v_mfma_f32_16x16x4_f32 v[98:101], v143, v69, v[98:101]
	v_pk_fma_f32 v[180:181], v[2:3], v[234:235], v[180:181] op_sel:[0,1,0]
	v_pk_fma_f32 v[192:193], v[4:5], v[234:235], v[192:193] op_sel:[0,1,0]
	v_pk_mul_f32 v[180:181], v[146:147], v[180:181]
	v_pk_mul_f32 v[192:193], v[146:147], v[192:193]
	v_pk_fma_f32 v[236:237], v[144:145], v[66:67], v[180:181]
	v_pk_fma_f32 v[238:239], v[144:145], v[68:69], v[192:193]
	global_store_dwordx4 v[150:151], v[236:239], off nt
	v_lshl_add_u64 v[150:151], v[150:151], 0, s[58:59]
	global_load_dwordx4 v[66:69], v[148:149], off nt
	v_lshl_add_u64 v[148:149], v[148:149], 0, s[58:59]
	ds_read_b32 v143, v160 offset:176
	ds_read_b128 v[172:175], v161 offset:1408
	ds_read_b128 v[232:235], v161 offset:1424
	s_waitcnt vmcnt(29)
; #define RS_LOAD(dst, it0) do { _Pragma("unroll") for (int u = 0; u < 8; ++u) dst[u] = __builtin_nontemporal_load((const f32x4*)(S0 + (size_t)(4 * ((it0) + u)) * DV)); } while (0)
; __device__ __forceinline__ void ret_sample_item(Frame& F, int item) {
;     ...
;     for (int it0 = 0; it0 < 64; it0 += 16) {
;         RS_LOAD(sb, it0 + 8);
;         RS_PROC(sa, it0);
;         { const int itn = it0 + 16 < 64 ? it0 + 16 : it0; RS_LOAD(sa, itn); }
;         RS_PROC(sb, it0 + 8);
;     }
	s_waitcnt lgkmcnt(3)
	v_cndmask_b32_e64 v141, 0, v141, s[6:7]
	v_pk_mul_f32 v[180:181], v[26:27], v[114:115] op_sel:[0,1]
	v_pk_mul_f32 v[192:193], v[28:29], v[114:115] op_sel:[0,1]
	v_mfma_f32_16x16x4_f32 v[110:113], v141, v74, v[110:113]
	v_pk_fma_f32 v[180:181], v[30:31], v[114:115], v[180:181] op_sel_hi:[1,0,1]
	v_pk_fma_f32 v[192:193], v[32:33], v[114:115], v[192:193] op_sel_hi:[1,0,1]
	v_pk_fma_f32 v[180:181], v[22:23], v[116:117], v[180:181] op_sel_hi:[1,0,1]
	v_pk_fma_f32 v[192:193], v[24:25], v[116:117], v[192:193] op_sel_hi:[1,0,1]
	v_mfma_f32_16x16x4_f32 v[106:109], v141, v75, v[106:109]
	v_pk_fma_f32 v[180:181], v[18:19], v[116:117], v[180:181] op_sel:[0,1,0]
	v_pk_fma_f32 v[192:193], v[20:21], v[116:117], v[192:193] op_sel:[0,1,0]
	v_pk_fma_f32 v[180:181], v[14:15], v[176:177], v[180:181] op_sel_hi:[1,0,1]
	v_pk_fma_f32 v[192:193], v[16:17], v[176:177], v[192:193] op_sel_hi:[1,0,1]
	v_mfma_f32_16x16x4_f32 v[102:105], v141, v76, v[102:105]
	v_pk_fma_f32 v[180:181], v[10:11], v[176:177], v[180:181] op_sel:[0,1,0]
	v_pk_fma_f32 v[192:193], v[12:13], v[176:177], v[192:193] op_sel:[0,1,0]
	v_pk_fma_f32 v[180:181], v[6:7], v[178:179], v[180:181] op_sel_hi:[1,0,1]
	v_pk_fma_f32 v[192:193], v[8:9], v[178:179], v[192:193] op_sel_hi:[1,0,1]
	v_mfma_f32_16x16x4_f32 v[98:101], v141, v77, v[98:101]
	v_pk_fma_f32 v[180:181], v[2:3], v[178:179], v[180:181] op_sel:[0,1,0]
	v_pk_fma_f32 v[192:193], v[4:5], v[178:179], v[192:193] op_sel:[0,1,0]
	v_pk_mul_f32 v[180:181], v[146:147], v[180:181]
	v_pk_mul_f32 v[192:193], v[146:147], v[192:193]
	v_pk_fma_f32 v[236:237], v[144:145], v[74:75], v[180:181]
	v_pk_fma_f32 v[238:239], v[144:145], v[76:77], v[192:193]
	global_store_dwordx4 v[150:151], v[236:239], off nt
	v_lshl_add_u64 v[150:151], v[150:151], 0, s[58:59]
	global_load_dwordx4 v[74:77], v[148:149], off nt
	v_lshl_add_u64 v[148:149], v[148:149], 0, s[58:59]
	ds_read_b32 v141, v160 offset:192
	ds_read_b128 v[114:117], v161 offset:1536
	ds_read_b128 v[176:179], v161 offset:1552
	s_waitcnt vmcnt(30)
	s_waitcnt lgkmcnt(3)
	v_cndmask_b32_e64 v143, 0, v143, s[6:7]
	v_pk_mul_f32 v[180:181], v[26:27], v[172:173] op_sel:[0,1]
	v_pk_mul_f32 v[192:193], v[28:29], v[172:173] op_sel:[0,1]
	v_mfma_f32_16x16x4_f32 v[110:113], v143, v78, v[110:113]
	v_pk_fma_f32 v[180:181], v[30:31], v[172:173], v[180:181] op_sel_hi:[1,0,1]
	v_pk_fma_f32 v[192:193], v[32:33], v[172:173], v[192:193] op_sel_hi:[1,0,1]
	v_pk_fma_f32 v[180:181], v[22:23], v[174:175], v[180:181] op_sel_hi:[1,0,1]
	v_pk_fma_f32 v[192:193], v[24:25], v[174:175], v[192:193] op_sel_hi:[1,0,1]
	v_mfma_f32_16x16x4_f32 v[106:109], v143, v79, v[106:109]
	v_pk_fma_f32 v[180:181], v[18:19], v[174:175], v[180:181] op_sel:[0,1,0]
	v_pk_fma_f32 v[192:193], v[20:21], v[174:175], v[192:193] op_sel:[0,1,0]
	v_pk_fma_f32 v[180:181], v[14:15], v[232:233], v[180:181] op_sel_hi:[1,0,1]
	v_pk_fma_f32 v[192:193], v[16:17], v[232:233], v[192:193] op_sel_hi:[1,0,1]
	v_mfma_f32_16x16x4_f32 v[102:105], v143, v80, v[102:105]
	v_pk_fma_f32 v[180:181], v[10:11], v[232:233], v[180:181] op_sel:[0,1,0]
	v_pk_fma_f32 v[192:193], v[12:13], v[232:233], v[192:193] op_sel:[0,1,0]
	v_pk_fma_f32 v[180:181], v[6:7], v[234:235], v[180:181] op_sel_hi:[1,0,1]
	v_pk_fma_f32 v[192:193], v[8:9], v[234:235], v[192:193] op_sel_hi:[1,0,1]
	v_mfma_f32_16x16x4_f32 v[98:101], v143, v81, v[98:101]
	v_pk_fma_f32 v[180:181], v[2:3], v[234:235], v[180:181] op_sel:[0,1,0]
	v_pk_fma_f32 v[192:193], v[4:5], v[234:235], v[192:193] op_sel:[0,1,0]
	v_pk_mul_f32 v[180:181], v[146:147], v[180:181]
	v_pk_mul_f32 v[192:193], v[146:147], v[192:193]
	v_pk_fma_f32 v[236:237], v[144:145], v[78:79], v[180:181]
	v_pk_fma_f32 v[238:239], v[144:145], v[80:81], v[192:193]
	global_store_dwordx4 v[150:151], v[236:239], off nt
	v_lshl_add_u64 v[150:151], v[150:151], 0, s[58:59]
	global_load_dwordx4 v[78:81], v[148:149], off nt
	v_lshl_add_u64 v[148:149], v[148:149], 0, s[58:59]
	ds_read_b32 v143, v160 offset:208
	ds_read_b128 v[172:175], v161 offset:1664
	ds_read_b128 v[232:235], v161 offset:1680
	s_waitcnt vmcnt(31)
	s_waitcnt lgkmcnt(3)
	v_cndmask_b32_e64 v141, 0, v141, s[6:7]
	v_pk_mul_f32 v[180:181], v[26:27], v[114:115] op_sel:[0,1]
	v_pk_mul_f32 v[192:193], v[28:29], v[114:115] op_sel:[0,1]
	v_mfma_f32_16x16x4_f32 v[110:113], v141, v82, v[110:113]
	v_pk_fma_f32 v[180:181], v[30:31], v[114:115], v[180:181] op_sel_hi:[1,0,1]
	v_pk_fma_f32 v[192:193], v[32:33], v[114:115], v[192:193] op_sel_hi:[1,0,1]
	v_pk_fma_f32 v[180:181], v[22:23], v[116:117], v[180:181] op_sel_hi:[1,0,1]
	v_pk_fma_f32 v[192:193], v[24:25], v[116:117], v[192:193] op_sel_hi:[1,0,1]
	v_mfma_f32_16x16x4_f32 v[106:109], v141, v83, v[106:109]
	v_pk_fma_f32 v[180:181], v[18:19], v[116:117], v[180:181] op_sel:[0,1,0]
	v_pk_fma_f32 v[192:193], v[20:21], v[116:117], v[192:193] op_sel:[0,1,0]
	v_pk_fma_f32 v[180:181], v[14:15], v[176:177], v[180:181] op_sel_hi:[1,0,1]
	v_pk_fma_f32 v[192:193], v[16:17], v[176:177], v[192:193] op_sel_hi:[1,0,1]
	v_mfma_f32_16x16x4_f32 v[102:105], v141, v84, v[102:105]
	v_pk_fma_f32 v[180:181], v[10:11], v[176:177], v[180:181] op_sel:[0,1,0]
	v_pk_fma_f32 v[192:193], v[12:13], v[176:177], v[192:193] op_sel:[0,1,0]
	v_pk_fma_f32 v[180:181], v[6:7], v[178:179], v[180:181] op_sel_hi:[1,0,1]
	v_pk_fma_f32 v[192:193], v[8:9], v[178:179], v[192:193] op_sel_hi:[1,0,1]
	v_mfma_f32_16x16x4_f32 v[98:101], v141, v85, v[98:101]
	v_pk_fma_f32 v[180:181], v[2:3], v[178:179], v[180:181] op_sel:[0,1,0]
	v_pk_fma_f32 v[192:193], v[4:5], v[178:179], v[192:193] op_sel:[0,1,0]
	v_pk_mul_f32 v[180:181], v[146:147], v[180:181]
	v_pk_mul_f32 v[192:193], v[146:147], v[192:193]
	v_pk_fma_f32 v[236:237], v[144:145], v[82:83], v[180:181]
	v_pk_fma_f32 v[238:239], v[144:145], v[84:85], v[192:193]
	global_store_dwordx4 v[150:151], v[236:239], off nt
	v_lshl_add_u64 v[150:151], v[150:151], 0, s[58:59]
	global_load_dwordx4 v[82:85], v[148:149], off nt
	v_lshl_add_u64 v[148:149], v[148:149], 0, s[58:59]
	ds_read_b32 v141, v160 offset:224
	ds_read_b128 v[114:117], v161 offset:1792
	ds_read_b128 v[176:179], v161 offset:1808
	s_waitcnt vmcnt(32)
; #define RS_LOAD(dst, it0) do { _Pragma("unroll") for (int u = 0; u < 8; ++u) dst[u] = __builtin_nontemporal_load((const f32x4*)(S0 + (size_t)(4 * ((it0) + u)) * DV)); } while (0)
; __device__ __forceinline__ void ret_sample_item(Frame& F, int item) {
;     ...
;     for (int it0 = 0; it0 < 64; it0 += 16) {
;         RS_LOAD(sb, it0 + 8);
;         RS_PROC(sa, it0);
;         { const int itn = it0 + 16 < 64 ? it0 + 16 : it0; RS_LOAD(sa, itn); }
;         RS_PROC(sb, it0 + 8);
;     }
	s_waitcnt lgkmcnt(3)
	v_cndmask_b32_e64 v143, 0, v143, s[6:7]
	v_pk_mul_f32 v[180:181], v[26:27], v[172:173] op_sel:[0,1]
	v_pk_mul_f32 v[192:193], v[28:29], v[172:173] op_sel:[0,1]
	v_mfma_f32_16x16x4_f32 v[110:113], v143, v86, v[110:113]
	v_pk_fma_f32 v[180:181], v[30:31], v[172:173], v[180:181] op_sel_hi:[1,0,1]
	v_pk_fma_f32 v[192:193], v[32:33], v[172:173], v[192:193] op_sel_hi:[1,0,1]
	v_pk_fma_f32 v[180:181], v[22:23], v[174:175], v[180:181] op_sel_hi:[1,0,1]
	v_pk_fma_f32 v[192:193], v[24:25], v[174:175], v[192:193] op_sel_hi:[1,0,1]
	v_mfma_f32_16x16x4_f32 v[106:109], v143, v87, v[106:109]
	v_pk_fma_f32 v[180:181], v[18:19], v[174:175], v[180:181] op_sel:[0,1,0]
	v_pk_fma_f32 v[192:193], v[20:21], v[174:175], v[192:193] op_sel:[0,1,0]
	v_pk_fma_f32 v[180:181], v[14:15], v[232:233], v[180:181] op_sel_hi:[1,0,1]
	v_pk_fma_f32 v[192:193], v[16:17], v[232:233], v[192:193] op_sel_hi:[1,0,1]
	v_mfma_f32_16x16x4_f32 v[102:105], v143, v88, v[102:105]
	v_pk_fma_f32 v[180:181], v[10:11], v[232:233], v[180:181] op_sel:[0,1,0]
	v_pk_fma_f32 v[192:193], v[12:13], v[232:233], v[192:193] op_sel:[0,1,0]
	v_pk_fma_f32 v[180:181], v[6:7], v[234:235], v[180:181] op_sel_hi:[1,0,1]
	v_pk_fma_f32 v[192:193], v[8:9], v[234:235], v[192:193] op_sel_hi:[1,0,1]
	v_mfma_f32_16x16x4_f32 v[98:101], v143, v89, v[98:101]
	v_pk_fma_f32 v[180:181], v[2:3], v[234:235], v[180:181] op_sel:[0,1,0]
	v_pk_fma_f32 v[192:193], v[4:5], v[234:235], v[192:193] op_sel:[0,1,0]
	v_pk_mul_f32 v[180:181], v[146:147], v[180:181]
	v_pk_mul_f32 v[192:193], v[146:147], v[192:193]
	v_pk_fma_f32 v[236:237], v[144:145], v[86:87], v[180:181]
	v_pk_fma_f32 v[238:239], v[144:145], v[88:89], v[192:193]
	global_store_dwordx4 v[150:151], v[236:239], off nt
	v_lshl_add_u64 v[150:151], v[150:151], 0, s[58:59]
	global_load_dwordx4 v[86:89], v[148:149], off nt
	v_lshl_add_u64 v[148:149], v[148:149], 0, s[58:59]
	ds_read_b32 v143, v160 offset:240
	ds_read_b128 v[172:175], v161 offset:1920
	ds_read_b128 v[232:235], v161 offset:1936
	s_waitcnt vmcnt(33)
	s_waitcnt lgkmcnt(3)
	v_cndmask_b32_e64 v141, 0, v141, s[6:7]
	v_pk_mul_f32 v[180:181], v[26:27], v[114:115] op_sel:[0,1]
	v_pk_mul_f32 v[192:193], v[28:29], v[114:115] op_sel:[0,1]
	v_mfma_f32_16x16x4_f32 v[110:113], v141, v90, v[110:113]
	v_pk_fma_f32 v[180:181], v[30:31], v[114:115], v[180:181] op_sel_hi:[1,0,1]
	v_pk_fma_f32 v[192:193], v[32:33], v[114:115], v[192:193] op_sel_hi:[1,0,1]
	v_pk_fma_f32 v[180:181], v[22:23], v[116:117], v[180:181] op_sel_hi:[1,0,1]
	v_pk_fma_f32 v[192:193], v[24:25], v[116:117], v[192:193] op_sel_hi:[1,0,1]
	v_mfma_f32_16x16x4_f32 v[106:109], v141, v91, v[106:109]
	v_pk_fma_f32 v[180:181], v[18:19], v[116:117], v[180:181] op_sel:[0,1,0]
	v_pk_fma_f32 v[192:193], v[20:21], v[116:117], v[192:193] op_sel:[0,1,0]
	v_pk_fma_f32 v[180:181], v[14:15], v[176:177], v[180:181] op_sel_hi:[1,0,1]
	v_pk_fma_f32 v[192:193], v[16:17], v[176:177], v[192:193] op_sel_hi:[1,0,1]
	v_mfma_f32_16x16x4_f32 v[102:105], v141, v92, v[102:105]
	v_pk_fma_f32 v[180:181], v[10:11], v[176:177], v[180:181] op_sel:[0,1,0]
	v_pk_fma_f32 v[192:193], v[12:13], v[176:177], v[192:193] op_sel:[0,1,0]
	v_pk_fma_f32 v[180:181], v[6:7], v[178:179], v[180:181] op_sel_hi:[1,0,1]
	v_pk_fma_f32 v[192:193], v[8:9], v[178:179], v[192:193] op_sel_hi:[1,0,1]
	v_mfma_f32_16x16x4_f32 v[98:101], v141, v93, v[98:101]
	v_pk_fma_f32 v[180:181], v[2:3], v[178:179], v[180:181] op_sel:[0,1,0]
	v_pk_fma_f32 v[192:193], v[4:5], v[178:179], v[192:193] op_sel:[0,1,0]
	v_pk_mul_f32 v[180:181], v[146:147], v[180:181]
	v_pk_mul_f32 v[192:193], v[146:147], v[192:193]
	v_pk_fma_f32 v[236:237], v[144:145], v[90:91], v[180:181]
	v_pk_fma_f32 v[238:239], v[144:145], v[92:93], v[192:193]
	global_store_dwordx4 v[150:151], v[236:239], off nt
	v_lshl_add_u64 v[150:151], v[150:151], 0, s[58:59]
	global_load_dwordx4 v[90:93], v[148:149], off nt
	v_lshl_add_u64 v[148:149], v[148:149], 0, s[58:59]
	ds_read_b32 v141, v160 offset:256
	ds_read_b128 v[114:117], v161 offset:2048
	ds_read_b128 v[176:179], v161 offset:2064
	s_waitcnt vmcnt(34)
	s_waitcnt lgkmcnt(3)
	v_cndmask_b32_e64 v143, 0, v143, s[6:7]
	v_pk_mul_f32 v[180:181], v[26:27], v[172:173] op_sel:[0,1]
	v_pk_mul_f32 v[192:193], v[28:29], v[172:173] op_sel:[0,1]
	v_mfma_f32_16x16x4_f32 v[110:113], v143, v94, v[110:113]
	v_pk_fma_f32 v[180:181], v[30:31], v[172:173], v[180:181] op_sel_hi:[1,0,1]
	v_pk_fma_f32 v[192:193], v[32:33], v[172:173], v[192:193] op_sel_hi:[1,0,1]
	v_pk_fma_f32 v[180:181], v[22:23], v[174:175], v[180:181] op_sel_hi:[1,0,1]
	v_pk_fma_f32 v[192:193], v[24:25], v[174:175], v[192:193] op_sel_hi:[1,0,1]
	v_mfma_f32_16x16x4_f32 v[106:109], v143, v95, v[106:109]
	v_pk_fma_f32 v[180:181], v[18:19], v[174:175], v[180:181] op_sel:[0,1,0]
	v_pk_fma_f32 v[192:193], v[20:21], v[174:175], v[192:193] op_sel:[0,1,0]
	v_pk_fma_f32 v[180:181], v[14:15], v[232:233], v[180:181] op_sel_hi:[1,0,1]
	v_pk_fma_f32 v[192:193], v[16:17], v[232:233], v[192:193] op_sel_hi:[1,0,1]
	v_mfma_f32_16x16x4_f32 v[102:105], v143, v96, v[102:105]
	v_pk_fma_f32 v[180:181], v[10:11], v[232:233], v[180:181] op_sel:[0,1,0]
	v_pk_fma_f32 v[192:193], v[12:13], v[232:233], v[192:193] op_sel:[0,1,0]
	v_pk_fma_f32 v[180:181], v[6:7], v[234:235], v[180:181] op_sel_hi:[1,0,1]
	v_pk_fma_f32 v[192:193], v[8:9], v[234:235], v[192:193] op_sel_hi:[1,0,1]
	v_mfma_f32_16x16x4_f32 v[98:101], v143, v97, v[98:101]
	v_pk_fma_f32 v[180:181], v[2:3], v[234:235], v[180:181] op_sel:[0,1,0]
	v_pk_fma_f32 v[192:193], v[4:5], v[234:235], v[192:193] op_sel:[0,1,0]
	v_pk_mul_f32 v[180:181], v[146:147], v[180:181]
	v_pk_mul_f32 v[192:193], v[146:147], v[192:193]
	v_pk_fma_f32 v[236:237], v[144:145], v[94:95], v[180:181]
	v_pk_fma_f32 v[238:239], v[144:145], v[96:97], v[192:193]
	global_store_dwordx4 v[150:151], v[236:239], off nt
	v_lshl_add_u64 v[150:151], v[150:151], 0, s[58:59]
	global_load_dwordx4 v[94:97], v[148:149], off nt
	v_lshl_add_u64 v[148:149], v[148:149], 0, s[58:59]
	ds_read_b32 v143, v160 offset:272
	ds_read_b128 v[172:175], v161 offset:2176
	ds_read_b128 v[232:235], v161 offset:2192
	s_waitcnt vmcnt(35)
; #define RS_LOAD(dst, it0) do { _Pragma("unroll") for (int u = 0; u < 8; ++u) dst[u] = __builtin_nontemporal_load((const f32x4*)(S0 + (size_t)(4 * ((it0) + u)) * DV)); } while (0)
; __device__ __forceinline__ void ret_sample_item(Frame& F, int item) {
;     ...
;     for (int it0 = 0; it0 < 64; it0 += 16) {
;         RS_LOAD(sb, it0 + 8);
;         RS_PROC(sa, it0);
;         { const int itn = it0 + 16 < 64 ? it0 + 16 : it0; RS_LOAD(sa, itn); }
;         RS_PROC(sb, it0 + 8);
;     }
	s_waitcnt lgkmcnt(3)
	v_cndmask_b32_e64 v141, 0, v141, s[6:7]
	v_pk_mul_f32 v[180:181], v[26:27], v[114:115] op_sel:[0,1]
	v_pk_mul_f32 v[192:193], v[28:29], v[114:115] op_sel:[0,1]
	v_mfma_f32_16x16x4_f32 v[110:113], v141, v212, v[110:113]
	v_pk_fma_f32 v[180:181], v[30:31], v[114:115], v[180:181] op_sel_hi:[1,0,1]
	v_pk_fma_f32 v[192:193], v[32:33], v[114:115], v[192:193] op_sel_hi:[1,0,1]
	v_pk_fma_f32 v[180:181], v[22:23], v[116:117], v[180:181] op_sel_hi:[1,0,1]
	v_pk_fma_f32 v[192:193], v[24:25], v[116:117], v[192:193] op_sel_hi:[1,0,1]
	v_mfma_f32_16x16x4_f32 v[106:109], v141, v213, v[106:109]
	v_pk_fma_f32 v[180:181], v[18:19], v[116:117], v[180:181] op_sel:[0,1,0]
	v_pk_fma_f32 v[192:193], v[20:21], v[116:117], v[192:193] op_sel:[0,1,0]
	v_pk_fma_f32 v[180:181], v[14:15], v[176:177], v[180:181] op_sel_hi:[1,0,1]
	v_pk_fma_f32 v[192:193], v[16:17], v[176:177], v[192:193] op_sel_hi:[1,0,1]
	v_mfma_f32_16x16x4_f32 v[102:105], v141, v214, v[102:105]
	v_pk_fma_f32 v[180:181], v[10:11], v[176:177], v[180:181] op_sel:[0,1,0]
	v_pk_fma_f32 v[192:193], v[12:13], v[176:177], v[192:193] op_sel:[0,1,0]
	v_pk_fma_f32 v[180:181], v[6:7], v[178:179], v[180:181] op_sel_hi:[1,0,1]
	v_pk_fma_f32 v[192:193], v[8:9], v[178:179], v[192:193] op_sel_hi:[1,0,1]
	v_mfma_f32_16x16x4_f32 v[98:101], v141, v215, v[98:101]
	v_pk_fma_f32 v[180:181], v[2:3], v[178:179], v[180:181] op_sel:[0,1,0]
	v_pk_fma_f32 v[192:193], v[4:5], v[178:179], v[192:193] op_sel:[0,1,0]
	v_pk_mul_f32 v[180:181], v[146:147], v[180:181]
	v_pk_mul_f32 v[192:193], v[146:147], v[192:193]
	v_pk_fma_f32 v[236:237], v[144:145], v[212:213], v[180:181]
	v_pk_fma_f32 v[238:239], v[144:145], v[214:215], v[192:193]
	global_store_dwordx4 v[150:151], v[236:239], off nt
	v_lshl_add_u64 v[150:151], v[150:151], 0, s[58:59]
	global_load_dwordx4 v[212:215], v[148:149], off nt
	v_lshl_add_u64 v[148:149], v[148:149], 0, s[58:59]
	ds_read_b32 v141, v160 offset:288
	ds_read_b128 v[114:117], v161 offset:2304
	ds_read_b128 v[176:179], v161 offset:2320
	s_waitcnt vmcnt(36)
	s_waitcnt lgkmcnt(3)
	v_cndmask_b32_e64 v143, 0, v143, s[6:7]
	v_pk_mul_f32 v[180:181], v[26:27], v[172:173] op_sel:[0,1]
	v_pk_mul_f32 v[192:193], v[28:29], v[172:173] op_sel:[0,1]
	v_mfma_f32_16x16x4_f32 v[110:113], v143, v216, v[110:113]
	v_pk_fma_f32 v[180:181], v[30:31], v[172:173], v[180:181] op_sel_hi:[1,0,1]
	v_pk_fma_f32 v[192:193], v[32:33], v[172:173], v[192:193] op_sel_hi:[1,0,1]
	v_pk_fma_f32 v[180:181], v[22:23], v[174:175], v[180:181] op_sel_hi:[1,0,1]
	v_pk_fma_f32 v[192:193], v[24:25], v[174:175], v[192:193] op_sel_hi:[1,0,1]
	v_mfma_f32_16x16x4_f32 v[106:109], v143, v217, v[106:109]
	v_pk_fma_f32 v[180:181], v[18:19], v[174:175], v[180:181] op_sel:[0,1,0]
	v_pk_fma_f32 v[192:193], v[20:21], v[174:175], v[192:193] op_sel:[0,1,0]
	v_pk_fma_f32 v[180:181], v[14:15], v[232:233], v[180:181] op_sel_hi:[1,0,1]
	v_pk_fma_f32 v[192:193], v[16:17], v[232:233], v[192:193] op_sel_hi:[1,0,1]
	v_mfma_f32_16x16x4_f32 v[102:105], v143, v218, v[102:105]
	v_pk_fma_f32 v[180:181], v[10:11], v[232:233], v[180:181] op_sel:[0,1,0]
	v_pk_fma_f32 v[192:193], v[12:13], v[232:233], v[192:193] op_sel:[0,1,0]
	v_pk_fma_f32 v[180:181], v[6:7], v[234:235], v[180:181] op_sel_hi:[1,0,1]
	v_pk_fma_f32 v[192:193], v[8:9], v[234:235], v[192:193] op_sel_hi:[1,0,1]
	v_mfma_f32_16x16x4_f32 v[98:101], v143, v219, v[98:101]
	v_pk_fma_f32 v[180:181], v[2:3], v[234:235], v[180:181] op_sel:[0,1,0]
	v_pk_fma_f32 v[192:193], v[4:5], v[234:235], v[192:193] op_sel:[0,1,0]
	v_pk_mul_f32 v[180:181], v[146:147], v[180:181]
	v_pk_mul_f32 v[192:193], v[146:147], v[192:193]
	v_pk_fma_f32 v[236:237], v[144:145], v[216:217], v[180:181]
	v_pk_fma_f32 v[238:239], v[144:145], v[218:219], v[192:193]
	global_store_dwordx4 v[150:151], v[236:239], off nt
	v_lshl_add_u64 v[150:151], v[150:151], 0, s[58:59]
	global_load_dwordx4 v[216:219], v[148:149], off nt
	v_lshl_add_u64 v[148:149], v[148:149], 0, s[58:59]
	ds_read_b32 v143, v160 offset:304
	ds_read_b128 v[172:175], v161 offset:2432
	ds_read_b128 v[232:235], v161 offset:2448
	s_waitcnt vmcnt(37)
	s_waitcnt lgkmcnt(3)
	v_cndmask_b32_e64 v141, 0, v141, s[6:7]
	v_pk_mul_f32 v[180:181], v[26:27], v[114:115] op_sel:[0,1]
	v_pk_mul_f32 v[192:193], v[28:29], v[114:115] op_sel:[0,1]
	v_mfma_f32_16x16x4_f32 v[110:113], v141, v224, v[110:113]
	v_pk_fma_f32 v[180:181], v[30:31], v[114:115], v[180:181] op_sel_hi:[1,0,1]
	v_pk_fma_f32 v[192:193], v[32:33], v[114:115], v[192:193] op_sel_hi:[1,0,1]
	v_pk_fma_f32 v[180:181], v[22:23], v[116:117], v[180:181] op_sel_hi:[1,0,1]
	v_pk_fma_f32 v[192:193], v[24:25], v[116:117], v[192:193] op_sel_hi:[1,0,1]
	v_mfma_f32_16x16x4_f32 v[106:109], v141, v225, v[106:109]
	v_pk_fma_f32 v[180:181], v[18:19], v[116:117], v[180:181] op_sel:[0,1,0]
	v_pk_fma_f32 v[192:193], v[20:21], v[116:117], v[192:193] op_sel:[0,1,0]
	v_pk_fma_f32 v[180:181], v[14:15], v[176:177], v[180:181] op_sel_hi:[1,0,1]
	v_pk_fma_f32 v[192:193], v[16:17], v[176:177], v[192:193] op_sel_hi:[1,0,1]
	v_mfma_f32_16x16x4_f32 v[102:105], v141, v226, v[102:105]
	v_pk_fma_f32 v[180:181], v[10:11], v[176:177], v[180:181] op_sel:[0,1,0]
	v_pk_fma_f32 v[192:193], v[12:13], v[176:177], v[192:193] op_sel:[0,1,0]
	v_pk_fma_f32 v[180:181], v[6:7], v[178:179], v[180:181] op_sel_hi:[1,0,1]
	v_pk_fma_f32 v[192:193], v[8:9], v[178:179], v[192:193] op_sel_hi:[1,0,1]
	v_mfma_f32_16x16x4_f32 v[98:101], v141, v227, v[98:101]
	v_pk_fma_f32 v[180:181], v[2:3], v[178:179], v[180:181] op_sel:[0,1,0]
	v_pk_fma_f32 v[192:193], v[4:5], v[178:179], v[192:193] op_sel:[0,1,0]
	v_pk_mul_f32 v[180:181], v[146:147], v[180:181]
	v_pk_mul_f32 v[192:193], v[146:147], v[192:193]
	v_pk_fma_f32 v[236:237], v[144:145], v[224:225], v[180:181]
	v_pk_fma_f32 v[238:239], v[144:145], v[226:227], v[192:193]
	global_store_dwordx4 v[150:151], v[236:239], off nt
	v_lshl_add_u64 v[150:151], v[150:151], 0, s[58:59]
	global_load_dwordx4 v[224:227], v[148:149], off nt
	v_lshl_add_u64 v[148:149], v[148:149], 0, s[58:59]
	ds_read_b32 v141, v160 offset:320
	ds_read_b128 v[114:117], v161 offset:2560
	ds_read_b128 v[176:179], v161 offset:2576
	s_waitcnt vmcnt(38)
; #define RS_LOAD(dst, it0) do { _Pragma("unroll") for (int u = 0; u < 8; ++u) dst[u] = __builtin_nontemporal_load((const f32x4*)(S0 + (size_t)(4 * ((it0) + u)) * DV)); } while (0)
; __device__ __forceinline__ void ret_sample_item(Frame& F, int item) {
;     ...
;     for (int it0 = 0; it0 < 64; it0 += 16) {
;         RS_LOAD(sb, it0 + 8);
;         RS_PROC(sa, it0);
;         { const int itn = it0 + 16 < 64 ? it0 + 16 : it0; RS_LOAD(sa, itn); }
;         RS_PROC(sb, it0 + 8);
;     }
	s_waitcnt lgkmcnt(3)
	v_cndmask_b32_e64 v143, 0, v143, s[6:7]
	v_pk_mul_f32 v[180:181], v[26:27], v[172:173] op_sel:[0,1]
	v_pk_mul_f32 v[192:193], v[28:29], v[172:173] op_sel:[0,1]
	v_mfma_f32_16x16x4_f32 v[110:113], v143, v228, v[110:113]
	v_pk_fma_f32 v[180:181], v[30:31], v[172:173], v[180:181] op_sel_hi:[1,0,1]
	v_pk_fma_f32 v[192:193], v[32:33], v[172:173], v[192:193] op_sel_hi:[1,0,1]
	v_pk_fma_f32 v[180:181], v[22:23], v[174:175], v[180:181] op_sel_hi:[1,0,1]
	v_pk_fma_f32 v[192:193], v[24:25], v[174:175], v[192:193] op_sel_hi:[1,0,1]
	v_mfma_f32_16x16x4_f32 v[106:109], v143, v229, v[106:109]
	v_pk_fma_f32 v[180:181], v[18:19], v[174:175], v[180:181] op_sel:[0,1,0]
	v_pk_fma_f32 v[192:193], v[20:21], v[174:175], v[192:193] op_sel:[0,1,0]
	v_pk_fma_f32 v[180:181], v[14:15], v[232:233], v[180:181] op_sel_hi:[1,0,1]
	v_pk_fma_f32 v[192:193], v[16:17], v[232:233], v[192:193] op_sel_hi:[1,0,1]
	v_mfma_f32_16x16x4_f32 v[102:105], v143, v230, v[102:105]
	v_pk_fma_f32 v[180:181], v[10:11], v[232:233], v[180:181] op_sel:[0,1,0]
	v_pk_fma_f32 v[192:193], v[12:13], v[232:233], v[192:193] op_sel:[0,1,0]
	v_pk_fma_f32 v[180:181], v[6:7], v[234:235], v[180:181] op_sel_hi:[1,0,1]
	v_pk_fma_f32 v[192:193], v[8:9], v[234:235], v[192:193] op_sel_hi:[1,0,1]
	v_mfma_f32_16x16x4_f32 v[98:101], v143, v231, v[98:101]
	v_pk_fma_f32 v[180:181], v[2:3], v[234:235], v[180:181] op_sel:[0,1,0]
	v_pk_fma_f32 v[192:193], v[4:5], v[234:235], v[192:193] op_sel:[0,1,0]
	v_pk_mul_f32 v[180:181], v[146:147], v[180:181]
	v_pk_mul_f32 v[192:193], v[146:147], v[192:193]
	v_pk_fma_f32 v[236:237], v[144:145], v[228:229], v[180:181]
	v_pk_fma_f32 v[238:239], v[144:145], v[230:231], v[192:193]
	global_store_dwordx4 v[150:151], v[236:239], off nt
	v_lshl_add_u64 v[150:151], v[150:151], 0, s[58:59]
	global_load_dwordx4 v[228:231], v[148:149], off nt
	v_lshl_add_u64 v[148:149], v[148:149], 0, s[58:59]
	ds_read_b32 v143, v160 offset:336
	ds_read_b128 v[172:175], v161 offset:2688
	ds_read_b128 v[232:235], v161 offset:2704
	s_waitcnt vmcnt(38)
	s_waitcnt lgkmcnt(3)
	v_cndmask_b32_e64 v141, 0, v141, s[6:7]
	v_pk_mul_f32 v[180:181], v[26:27], v[114:115] op_sel:[0,1]
	v_pk_mul_f32 v[192:193], v[28:29], v[114:115] op_sel:[0,1]
	v_mfma_f32_16x16x4_f32 v[110:113], v141, v70, v[110:113]
	v_pk_fma_f32 v[180:181], v[30:31], v[114:115], v[180:181] op_sel_hi:[1,0,1]
	v_pk_fma_f32 v[192:193], v[32:33], v[114:115], v[192:193] op_sel_hi:[1,0,1]
	v_pk_fma_f32 v[180:181], v[22:23], v[116:117], v[180:181] op_sel_hi:[1,0,1]
	v_pk_fma_f32 v[192:193], v[24:25], v[116:117], v[192:193] op_sel_hi:[1,0,1]
	v_mfma_f32_16x16x4_f32 v[106:109], v141, v71, v[106:109]
	v_pk_fma_f32 v[180:181], v[18:19], v[116:117], v[180:181] op_sel:[0,1,0]
	v_pk_fma_f32 v[192:193], v[20:21], v[116:117], v[192:193] op_sel:[0,1,0]
	v_pk_fma_f32 v[180:181], v[14:15], v[176:177], v[180:181] op_sel_hi:[1,0,1]
	v_pk_fma_f32 v[192:193], v[16:17], v[176:177], v[192:193] op_sel_hi:[1,0,1]
	v_mfma_f32_16x16x4_f32 v[102:105], v141, v72, v[102:105]
	v_pk_fma_f32 v[180:181], v[10:11], v[176:177], v[180:181] op_sel:[0,1,0]
	v_pk_fma_f32 v[192:193], v[12:13], v[176:177], v[192:193] op_sel:[0,1,0]
	v_pk_fma_f32 v[180:181], v[6:7], v[178:179], v[180:181] op_sel_hi:[1,0,1]
	v_pk_fma_f32 v[192:193], v[8:9], v[178:179], v[192:193] op_sel_hi:[1,0,1]
	v_mfma_f32_16x16x4_f32 v[98:101], v141, v73, v[98:101]
	v_pk_fma_f32 v[180:181], v[2:3], v[178:179], v[180:181] op_sel:[0,1,0]
	v_pk_fma_f32 v[192:193], v[4:5], v[178:179], v[192:193] op_sel:[0,1,0]
	v_pk_mul_f32 v[180:181], v[146:147], v[180:181]
	v_pk_mul_f32 v[192:193], v[146:147], v[192:193]
	v_pk_fma_f32 v[236:237], v[144:145], v[70:71], v[180:181]
	v_pk_fma_f32 v[238:239], v[144:145], v[72:73], v[192:193]
	global_store_dwordx4 v[150:151], v[236:239], off nt
	v_lshl_add_u64 v[150:151], v[150:151], 0, s[58:59]
	global_load_dwordx4 v[70:73], v[148:149], off nt
	v_lshl_add_u64 v[148:149], v[148:149], 0, s[58:59]
	ds_read_b32 v141, v160 offset:352
	ds_read_b128 v[114:117], v161 offset:2816
	ds_read_b128 v[176:179], v161 offset:2832
	s_waitcnt vmcnt(38)
	s_waitcnt lgkmcnt(3)
	v_cndmask_b32_e64 v143, 0, v143, s[6:7]
	v_pk_mul_f32 v[180:181], v[26:27], v[172:173] op_sel:[0,1]
	v_pk_mul_f32 v[192:193], v[28:29], v[172:173] op_sel:[0,1]
	v_mfma_f32_16x16x4_f32 v[110:113], v143, v62, v[110:113]
	v_pk_fma_f32 v[180:181], v[30:31], v[172:173], v[180:181] op_sel_hi:[1,0,1]
	v_pk_fma_f32 v[192:193], v[32:33], v[172:173], v[192:193] op_sel_hi:[1,0,1]
	v_pk_fma_f32 v[180:181], v[22:23], v[174:175], v[180:181] op_sel_hi:[1,0,1]
	v_pk_fma_f32 v[192:193], v[24:25], v[174:175], v[192:193] op_sel_hi:[1,0,1]
	v_mfma_f32_16x16x4_f32 v[106:109], v143, v63, v[106:109]
	v_pk_fma_f32 v[180:181], v[18:19], v[174:175], v[180:181] op_sel:[0,1,0]
	v_pk_fma_f32 v[192:193], v[20:21], v[174:175], v[192:193] op_sel:[0,1,0]
	v_pk_fma_f32 v[180:181], v[14:15], v[232:233], v[180:181] op_sel_hi:[1,0,1]
	v_pk_fma_f32 v[192:193], v[16:17], v[232:233], v[192:193] op_sel_hi:[1,0,1]
	v_mfma_f32_16x16x4_f32 v[102:105], v143, v64, v[102:105]
	v_pk_fma_f32 v[180:181], v[10:11], v[232:233], v[180:181] op_sel:[0,1,0]
	v_pk_fma_f32 v[192:193], v[12:13], v[232:233], v[192:193] op_sel:[0,1,0]
	v_pk_fma_f32 v[180:181], v[6:7], v[234:235], v[180:181] op_sel_hi:[1,0,1]
	v_pk_fma_f32 v[192:193], v[8:9], v[234:235], v[192:193] op_sel_hi:[1,0,1]
	v_mfma_f32_16x16x4_f32 v[98:101], v143, v65, v[98:101]
	v_pk_fma_f32 v[180:181], v[2:3], v[234:235], v[180:181] op_sel:[0,1,0]
	v_pk_fma_f32 v[192:193], v[4:5], v[234:235], v[192:193] op_sel:[0,1,0]
	v_pk_mul_f32 v[180:181], v[146:147], v[180:181]
	v_pk_mul_f32 v[192:193], v[146:147], v[192:193]
	v_pk_fma_f32 v[236:237], v[144:145], v[62:63], v[180:181]
	v_pk_fma_f32 v[238:239], v[144:145], v[64:65], v[192:193]
	global_store_dwordx4 v[150:151], v[236:239], off nt
	v_lshl_add_u64 v[150:151], v[150:151], 0, s[58:59]
	global_load_dwordx4 v[62:65], v[148:149], off nt
	v_lshl_add_u64 v[148:149], v[148:149], 0, s[58:59]
	ds_read_b32 v143, v160 offset:368
	ds_read_b128 v[172:175], v161 offset:2944
	ds_read_b128 v[232:235], v161 offset:2960
	s_waitcnt vmcnt(38)
; #define RS_LOAD(dst, it0) do { _Pragma("unroll") for (int u = 0; u < 8; ++u) dst[u] = __builtin_nontemporal_load((const f32x4*)(S0 + (size_t)(4 * ((it0) + u)) * DV)); } while (0)
; __device__ __forceinline__ void ret_sample_item(Frame& F, int item) {
;     ...
;     for (int it0 = 0; it0 < 64; it0 += 16) {
;         RS_LOAD(sb, it0 + 8);
;         RS_PROC(sa, it0);
;         { const int itn = it0 + 16 < 64 ? it0 + 16 : it0; RS_LOAD(sa, itn); }
;         RS_PROC(sb, it0 + 8);
;     }
	s_waitcnt lgkmcnt(3)
	v_cndmask_b32_e64 v141, 0, v141, s[6:7]
	v_pk_mul_f32 v[180:181], v[26:27], v[114:115] op_sel:[0,1]
	v_pk_mul_f32 v[192:193], v[28:29], v[114:115] op_sel:[0,1]
	v_mfma_f32_16x16x4_f32 v[110:113], v141, v54, v[110:113]
	v_pk_fma_f32 v[180:181], v[30:31], v[114:115], v[180:181] op_sel_hi:[1,0,1]
	v_pk_fma_f32 v[192:193], v[32:33], v[114:115], v[192:193] op_sel_hi:[1,0,1]
	v_pk_fma_f32 v[180:181], v[22:23], v[116:117], v[180:181] op_sel_hi:[1,0,1]
	v_pk_fma_f32 v[192:193], v[24:25], v[116:117], v[192:193] op_sel_hi:[1,0,1]
	v_mfma_f32_16x16x4_f32 v[106:109], v141, v55, v[106:109]
	v_pk_fma_f32 v[180:181], v[18:19], v[116:117], v[180:181] op_sel:[0,1,0]
	v_pk_fma_f32 v[192:193], v[20:21], v[116:117], v[192:193] op_sel:[0,1,0]
	v_pk_fma_f32 v[180:181], v[14:15], v[176:177], v[180:181] op_sel_hi:[1,0,1]
	v_pk_fma_f32 v[192:193], v[16:17], v[176:177], v[192:193] op_sel_hi:[1,0,1]
	v_mfma_f32_16x16x4_f32 v[102:105], v141, v56, v[102:105]
	v_pk_fma_f32 v[180:181], v[10:11], v[176:177], v[180:181] op_sel:[0,1,0]
	v_pk_fma_f32 v[192:193], v[12:13], v[176:177], v[192:193] op_sel:[0,1,0]
	v_pk_fma_f32 v[180:181], v[6:7], v[178:179], v[180:181] op_sel_hi:[1,0,1]
	v_pk_fma_f32 v[192:193], v[8:9], v[178:179], v[192:193] op_sel_hi:[1,0,1]
	v_mfma_f32_16x16x4_f32 v[98:101], v141, v57, v[98:101]
	v_pk_fma_f32 v[180:181], v[2:3], v[178:179], v[180:181] op_sel:[0,1,0]
	v_pk_fma_f32 v[192:193], v[4:5], v[178:179], v[192:193] op_sel:[0,1,0]
	v_pk_mul_f32 v[180:181], v[146:147], v[180:181]
	v_pk_mul_f32 v[192:193], v[146:147], v[192:193]
	v_pk_fma_f32 v[236:237], v[144:145], v[54:55], v[180:181]
	v_pk_fma_f32 v[238:239], v[144:145], v[56:57], v[192:193]
	global_store_dwordx4 v[150:151], v[236:239], off nt
	v_lshl_add_u64 v[150:151], v[150:151], 0, s[58:59]
	global_load_dwordx4 v[54:57], v[148:149], off nt
	v_lshl_add_u64 v[148:149], v[148:149], 0, s[58:59]
	ds_read_b32 v141, v160 offset:384
	ds_read_b128 v[114:117], v161 offset:3072
	ds_read_b128 v[176:179], v161 offset:3088
	s_waitcnt vmcnt(38)
	s_waitcnt lgkmcnt(3)
	v_cndmask_b32_e64 v143, 0, v143, s[6:7]
	v_pk_mul_f32 v[180:181], v[26:27], v[172:173] op_sel:[0,1]
	v_pk_mul_f32 v[192:193], v[28:29], v[172:173] op_sel:[0,1]
	v_mfma_f32_16x16x4_f32 v[110:113], v143, v50, v[110:113]
	v_pk_fma_f32 v[180:181], v[30:31], v[172:173], v[180:181] op_sel_hi:[1,0,1]
	v_pk_fma_f32 v[192:193], v[32:33], v[172:173], v[192:193] op_sel_hi:[1,0,1]
	v_pk_fma_f32 v[180:181], v[22:23], v[174:175], v[180:181] op_sel_hi:[1,0,1]
	v_pk_fma_f32 v[192:193], v[24:25], v[174:175], v[192:193] op_sel_hi:[1,0,1]
	v_mfma_f32_16x16x4_f32 v[106:109], v143, v51, v[106:109]
	v_pk_fma_f32 v[180:181], v[18:19], v[174:175], v[180:181] op_sel:[0,1,0]
	v_pk_fma_f32 v[192:193], v[20:21], v[174:175], v[192:193] op_sel:[0,1,0]
	v_pk_fma_f32 v[180:181], v[14:15], v[232:233], v[180:181] op_sel_hi:[1,0,1]
	v_pk_fma_f32 v[192:193], v[16:17], v[232:233], v[192:193] op_sel_hi:[1,0,1]
	v_mfma_f32_16x16x4_f32 v[102:105], v143, v52, v[102:105]
	v_pk_fma_f32 v[180:181], v[10:11], v[232:233], v[180:181] op_sel:[0,1,0]
	v_pk_fma_f32 v[192:193], v[12:13], v[232:233], v[192:193] op_sel:[0,1,0]
	v_pk_fma_f32 v[180:181], v[6:7], v[234:235], v[180:181] op_sel_hi:[1,0,1]
	v_pk_fma_f32 v[192:193], v[8:9], v[234:235], v[192:193] op_sel_hi:[1,0,1]
	v_mfma_f32_16x16x4_f32 v[98:101], v143, v53, v[98:101]
	v_pk_fma_f32 v[180:181], v[2:3], v[234:235], v[180:181] op_sel:[0,1,0]
	v_pk_fma_f32 v[192:193], v[4:5], v[234:235], v[192:193] op_sel:[0,1,0]
	v_pk_mul_f32 v[180:181], v[146:147], v[180:181]
	v_pk_mul_f32 v[192:193], v[146:147], v[192:193]
	v_pk_fma_f32 v[236:237], v[144:145], v[50:51], v[180:181]
	v_pk_fma_f32 v[238:239], v[144:145], v[52:53], v[192:193]
	global_store_dwordx4 v[150:151], v[236:239], off nt
	v_lshl_add_u64 v[150:151], v[150:151], 0, s[58:59]
	global_load_dwordx4 v[50:53], v[148:149], off nt
	v_lshl_add_u64 v[148:149], v[148:149], 0, s[58:59]
	ds_read_b32 v143, v160 offset:400
	ds_read_b128 v[172:175], v161 offset:3200
	ds_read_b128 v[232:235], v161 offset:3216
	s_waitcnt vmcnt(38)
	s_waitcnt lgkmcnt(3)
	v_cndmask_b32_e64 v141, 0, v141, s[6:7]
	v_pk_mul_f32 v[180:181], v[26:27], v[114:115] op_sel:[0,1]
	v_pk_mul_f32 v[192:193], v[28:29], v[114:115] op_sel:[0,1]
	v_mfma_f32_16x16x4_f32 v[110:113], v141, v46, v[110:113]
	v_pk_fma_f32 v[180:181], v[30:31], v[114:115], v[180:181] op_sel_hi:[1,0,1]
	v_pk_fma_f32 v[192:193], v[32:33], v[114:115], v[192:193] op_sel_hi:[1,0,1]
	v_pk_fma_f32 v[180:181], v[22:23], v[116:117], v[180:181] op_sel_hi:[1,0,1]
	v_pk_fma_f32 v[192:193], v[24:25], v[116:117], v[192:193] op_sel_hi:[1,0,1]
	v_mfma_f32_16x16x4_f32 v[106:109], v141, v47, v[106:109]
	v_pk_fma_f32 v[180:181], v[18:19], v[116:117], v[180:181] op_sel:[0,1,0]
	v_pk_fma_f32 v[192:193], v[20:21], v[116:117], v[192:193] op_sel:[0,1,0]
	v_pk_fma_f32 v[180:181], v[14:15], v[176:177], v[180:181] op_sel_hi:[1,0,1]
	v_pk_fma_f32 v[192:193], v[16:17], v[176:177], v[192:193] op_sel_hi:[1,0,1]
	v_mfma_f32_16x16x4_f32 v[102:105], v141, v48, v[102:105]
	v_pk_fma_f32 v[180:181], v[10:11], v[176:177], v[180:181] op_sel:[0,1,0]
	v_pk_fma_f32 v[192:193], v[12:13], v[176:177], v[192:193] op_sel:[0,1,0]
	v_pk_fma_f32 v[180:181], v[6:7], v[178:179], v[180:181] op_sel_hi:[1,0,1]
	v_pk_fma_f32 v[192:193], v[8:9], v[178:179], v[192:193] op_sel_hi:[1,0,1]
	v_mfma_f32_16x16x4_f32 v[98:101], v141, v49, v[98:101]
	v_pk_fma_f32 v[180:181], v[2:3], v[178:179], v[180:181] op_sel:[0,1,0]
	v_pk_fma_f32 v[192:193], v[4:5], v[178:179], v[192:193] op_sel:[0,1,0]
	v_pk_mul_f32 v[180:181], v[146:147], v[180:181]
	v_pk_mul_f32 v[192:193], v[146:147], v[192:193]
	v_pk_fma_f32 v[236:237], v[144:145], v[46:47], v[180:181]
	v_pk_fma_f32 v[238:239], v[144:145], v[48:49], v[192:193]
	global_store_dwordx4 v[150:151], v[236:239], off nt
	v_lshl_add_u64 v[150:151], v[150:151], 0, s[58:59]
	global_load_dwordx4 v[46:49], v[148:149], off nt
	v_lshl_add_u64 v[148:149], v[148:149], 0, s[58:59]
	ds_read_b32 v141, v160 offset:416
	ds_read_b128 v[114:117], v161 offset:3328
	ds_read_b128 v[176:179], v161 offset:3344
	s_waitcnt vmcnt(38)
; #define RS_LOAD(dst, it0) do { _Pragma("unroll") for (int u = 0; u < 8; ++u) dst[u] = __builtin_nontemporal_load((const f32x4*)(S0 + (size_t)(4 * ((it0) + u)) * DV)); } while (0)
; __device__ __forceinline__ void ret_sample_item(Frame& F, int item) {
;     ...
;     for (int it0 = 0; it0 < 64; it0 += 16) {
;         RS_LOAD(sb, it0 + 8);
;         RS_PROC(sa, it0);
;         { const int itn = it0 + 16 < 64 ? it0 + 16 : it0; RS_LOAD(sa, itn); }
;         RS_PROC(sb, it0 + 8);
;     }
	s_waitcnt lgkmcnt(3)
	v_cndmask_b32_e64 v143, 0, v143, s[6:7]
	v_pk_mul_f32 v[180:181], v[26:27], v[172:173] op_sel:[0,1]
	v_pk_mul_f32 v[192:193], v[28:29], v[172:173] op_sel:[0,1]
	v_mfma_f32_16x16x4_f32 v[110:113], v143, v42, v[110:113]
	v_pk_fma_f32 v[180:181], v[30:31], v[172:173], v[180:181] op_sel_hi:[1,0,1]
	v_pk_fma_f32 v[192:193], v[32:33], v[172:173], v[192:193] op_sel_hi:[1,0,1]
	v_pk_fma_f32 v[180:181], v[22:23], v[174:175], v[180:181] op_sel_hi:[1,0,1]
	v_pk_fma_f32 v[192:193], v[24:25], v[174:175], v[192:193] op_sel_hi:[1,0,1]
	v_mfma_f32_16x16x4_f32 v[106:109], v143, v43, v[106:109]
	v_pk_fma_f32 v[180:181], v[18:19], v[174:175], v[180:181] op_sel:[0,1,0]
	v_pk_fma_f32 v[192:193], v[20:21], v[174:175], v[192:193] op_sel:[0,1,0]
	v_pk_fma_f32 v[180:181], v[14:15], v[232:233], v[180:181] op_sel_hi:[1,0,1]
	v_pk_fma_f32 v[192:193], v[16:17], v[232:233], v[192:193] op_sel_hi:[1,0,1]
	v_mfma_f32_16x16x4_f32 v[102:105], v143, v44, v[102:105]
	v_pk_fma_f32 v[180:181], v[10:11], v[232:233], v[180:181] op_sel:[0,1,0]
	v_pk_fma_f32 v[192:193], v[12:13], v[232:233], v[192:193] op_sel:[0,1,0]
	v_pk_fma_f32 v[180:181], v[6:7], v[234:235], v[180:181] op_sel_hi:[1,0,1]
	v_pk_fma_f32 v[192:193], v[8:9], v[234:235], v[192:193] op_sel_hi:[1,0,1]
	v_mfma_f32_16x16x4_f32 v[98:101], v143, v45, v[98:101]
	v_pk_fma_f32 v[180:181], v[2:3], v[234:235], v[180:181] op_sel:[0,1,0]
	v_pk_fma_f32 v[192:193], v[4:5], v[234:235], v[192:193] op_sel:[0,1,0]
	v_pk_mul_f32 v[180:181], v[146:147], v[180:181]
	v_pk_mul_f32 v[192:193], v[146:147], v[192:193]
	v_pk_fma_f32 v[236:237], v[144:145], v[42:43], v[180:181]
	v_pk_fma_f32 v[238:239], v[144:145], v[44:45], v[192:193]
	global_store_dwordx4 v[150:151], v[236:239], off nt
	v_lshl_add_u64 v[150:151], v[150:151], 0, s[58:59]
	global_load_dwordx4 v[42:45], v[148:149], off nt
	v_lshl_add_u64 v[148:149], v[148:149], 0, s[58:59]
	ds_read_b32 v143, v160 offset:432
	ds_read_b128 v[172:175], v161 offset:3456
	ds_read_b128 v[232:235], v161 offset:3472
	s_waitcnt vmcnt(38)
	s_waitcnt lgkmcnt(3)
	v_cndmask_b32_e64 v141, 0, v141, s[6:7]
	v_pk_mul_f32 v[180:181], v[26:27], v[114:115] op_sel:[0,1]
	v_pk_mul_f32 v[192:193], v[28:29], v[114:115] op_sel:[0,1]
	v_mfma_f32_16x16x4_f32 v[110:113], v141, v38, v[110:113]
	v_pk_fma_f32 v[180:181], v[30:31], v[114:115], v[180:181] op_sel_hi:[1,0,1]
	v_pk_fma_f32 v[192:193], v[32:33], v[114:115], v[192:193] op_sel_hi:[1,0,1]
	v_pk_fma_f32 v[180:181], v[22:23], v[116:117], v[180:181] op_sel_hi:[1,0,1]
	v_pk_fma_f32 v[192:193], v[24:25], v[116:117], v[192:193] op_sel_hi:[1,0,1]
	v_mfma_f32_16x16x4_f32 v[106:109], v141, v39, v[106:109]
	v_pk_fma_f32 v[180:181], v[18:19], v[116:117], v[180:181] op_sel:[0,1,0]
	v_pk_fma_f32 v[192:193], v[20:21], v[116:117], v[192:193] op_sel:[0,1,0]
	v_pk_fma_f32 v[180:181], v[14:15], v[176:177], v[180:181] op_sel_hi:[1,0,1]
	v_pk_fma_f32 v[192:193], v[16:17], v[176:177], v[192:193] op_sel_hi:[1,0,1]
	v_mfma_f32_16x16x4_f32 v[102:105], v141, v40, v[102:105]
	v_pk_fma_f32 v[180:181], v[10:11], v[176:177], v[180:181] op_sel:[0,1,0]
	v_pk_fma_f32 v[192:193], v[12:13], v[176:177], v[192:193] op_sel:[0,1,0]
	v_pk_fma_f32 v[180:181], v[6:7], v[178:179], v[180:181] op_sel_hi:[1,0,1]
	v_pk_fma_f32 v[192:193], v[8:9], v[178:179], v[192:193] op_sel_hi:[1,0,1]
	v_mfma_f32_16x16x4_f32 v[98:101], v141, v41, v[98:101]
	v_pk_fma_f32 v[180:181], v[2:3], v[178:179], v[180:181] op_sel:[0,1,0]
	v_pk_fma_f32 v[192:193], v[4:5], v[178:179], v[192:193] op_sel:[0,1,0]
	v_pk_mul_f32 v[180:181], v[146:147], v[180:181]
	v_pk_mul_f32 v[192:193], v[146:147], v[192:193]
	v_pk_fma_f32 v[236:237], v[144:145], v[38:39], v[180:181]
	v_pk_fma_f32 v[238:239], v[144:145], v[40:41], v[192:193]
	global_store_dwordx4 v[150:151], v[236:239], off nt
	v_lshl_add_u64 v[150:151], v[150:151], 0, s[58:59]
	global_load_dwordx4 v[38:41], v[148:149], off nt
	v_lshl_add_u64 v[148:149], v[148:149], 0, s[58:59]
	ds_read_b32 v141, v160 offset:448
	ds_read_b128 v[114:117], v161 offset:3584
	ds_read_b128 v[176:179], v161 offset:3600
	s_waitcnt vmcnt(38)
	s_waitcnt lgkmcnt(3)
	v_cndmask_b32_e64 v143, 0, v143, s[6:7]
	v_pk_mul_f32 v[180:181], v[26:27], v[172:173] op_sel:[0,1]
	v_pk_mul_f32 v[192:193], v[28:29], v[172:173] op_sel:[0,1]
	v_mfma_f32_16x16x4_f32 v[110:113], v143, v34, v[110:113]
	v_pk_fma_f32 v[180:181], v[30:31], v[172:173], v[180:181] op_sel_hi:[1,0,1]
	v_pk_fma_f32 v[192:193], v[32:33], v[172:173], v[192:193] op_sel_hi:[1,0,1]
	v_pk_fma_f32 v[180:181], v[22:23], v[174:175], v[180:181] op_sel_hi:[1,0,1]
	v_pk_fma_f32 v[192:193], v[24:25], v[174:175], v[192:193] op_sel_hi:[1,0,1]
	v_mfma_f32_16x16x4_f32 v[106:109], v143, v35, v[106:109]
	v_pk_fma_f32 v[180:181], v[18:19], v[174:175], v[180:181] op_sel:[0,1,0]
	v_pk_fma_f32 v[192:193], v[20:21], v[174:175], v[192:193] op_sel:[0,1,0]
	v_pk_fma_f32 v[180:181], v[14:15], v[232:233], v[180:181] op_sel_hi:[1,0,1]
	v_pk_fma_f32 v[192:193], v[16:17], v[232:233], v[192:193] op_sel_hi:[1,0,1]
	v_mfma_f32_16x16x4_f32 v[102:105], v143, v36, v[102:105]
	v_pk_fma_f32 v[180:181], v[10:11], v[232:233], v[180:181] op_sel:[0,1,0]
	v_pk_fma_f32 v[192:193], v[12:13], v[232:233], v[192:193] op_sel:[0,1,0]
	v_pk_fma_f32 v[180:181], v[6:7], v[234:235], v[180:181] op_sel_hi:[1,0,1]
	v_pk_fma_f32 v[192:193], v[8:9], v[234:235], v[192:193] op_sel_hi:[1,0,1]
	v_mfma_f32_16x16x4_f32 v[98:101], v143, v37, v[98:101]
	v_pk_fma_f32 v[180:181], v[2:3], v[234:235], v[180:181] op_sel:[0,1,0]
	v_pk_fma_f32 v[192:193], v[4:5], v[234:235], v[192:193] op_sel:[0,1,0]
	v_pk_mul_f32 v[180:181], v[146:147], v[180:181]
	v_pk_mul_f32 v[192:193], v[146:147], v[192:193]
	v_pk_fma_f32 v[236:237], v[144:145], v[34:35], v[180:181]
	v_pk_fma_f32 v[238:239], v[144:145], v[36:37], v[192:193]
	global_store_dwordx4 v[150:151], v[236:239], off nt
	v_lshl_add_u64 v[150:151], v[150:151], 0, s[58:59]
	global_load_dwordx4 v[34:37], v[148:149], off nt
	v_lshl_add_u64 v[148:149], v[148:149], 0, s[58:59]
	ds_read_b32 v143, v160 offset:464
	ds_read_b128 v[172:175], v161 offset:3712
	ds_read_b128 v[232:235], v161 offset:3728
	s_waitcnt vmcnt(38)
; #define RS_LOAD(dst, it0) do { _Pragma("unroll") for (int u = 0; u < 8; ++u) dst[u] = __builtin_nontemporal_load((const f32x4*)(S0 + (size_t)(4 * ((it0) + u)) * DV)); } while (0)
; __device__ __forceinline__ void ret_sample_item(Frame& F, int item) {
;     ...
;     for (int it0 = 0; it0 < 64; it0 += 16) {
;         RS_LOAD(sb, it0 + 8);
;         RS_PROC(sa, it0);
;         { const int itn = it0 + 16 < 64 ? it0 + 16 : it0; RS_LOAD(sa, itn); }
;         RS_PROC(sb, it0 + 8);
;     }
	s_waitcnt lgkmcnt(3)
	v_cndmask_b32_e64 v141, 0, v141, s[6:7]
	v_pk_mul_f32 v[180:181], v[26:27], v[114:115] op_sel:[0,1]
	v_pk_mul_f32 v[192:193], v[28:29], v[114:115] op_sel:[0,1]
	v_mfma_f32_16x16x4_f32 v[110:113], v141, v58, v[110:113]
	v_pk_fma_f32 v[180:181], v[30:31], v[114:115], v[180:181] op_sel_hi:[1,0,1]
	v_pk_fma_f32 v[192:193], v[32:33], v[114:115], v[192:193] op_sel_hi:[1,0,1]
	v_pk_fma_f32 v[180:181], v[22:23], v[116:117], v[180:181] op_sel_hi:[1,0,1]
	v_pk_fma_f32 v[192:193], v[24:25], v[116:117], v[192:193] op_sel_hi:[1,0,1]
	v_mfma_f32_16x16x4_f32 v[106:109], v141, v59, v[106:109]
	v_pk_fma_f32 v[180:181], v[18:19], v[116:117], v[180:181] op_sel:[0,1,0]
	v_pk_fma_f32 v[192:193], v[20:21], v[116:117], v[192:193] op_sel:[0,1,0]
	v_pk_fma_f32 v[180:181], v[14:15], v[176:177], v[180:181] op_sel_hi:[1,0,1]
	v_pk_fma_f32 v[192:193], v[16:17], v[176:177], v[192:193] op_sel_hi:[1,0,1]
	v_mfma_f32_16x16x4_f32 v[102:105], v141, v60, v[102:105]
	v_pk_fma_f32 v[180:181], v[10:11], v[176:177], v[180:181] op_sel:[0,1,0]
	v_pk_fma_f32 v[192:193], v[12:13], v[176:177], v[192:193] op_sel:[0,1,0]
	v_pk_fma_f32 v[180:181], v[6:7], v[178:179], v[180:181] op_sel_hi:[1,0,1]
	v_pk_fma_f32 v[192:193], v[8:9], v[178:179], v[192:193] op_sel_hi:[1,0,1]
	v_mfma_f32_16x16x4_f32 v[98:101], v141, v61, v[98:101]
	v_pk_fma_f32 v[180:181], v[2:3], v[178:179], v[180:181] op_sel:[0,1,0]
	v_pk_fma_f32 v[192:193], v[4:5], v[178:179], v[192:193] op_sel:[0,1,0]
	v_pk_mul_f32 v[180:181], v[146:147], v[180:181]
	v_pk_mul_f32 v[192:193], v[146:147], v[192:193]
	v_pk_fma_f32 v[236:237], v[144:145], v[58:59], v[180:181]
	v_pk_fma_f32 v[238:239], v[144:145], v[60:61], v[192:193]
	global_store_dwordx4 v[150:151], v[236:239], off nt
	v_lshl_add_u64 v[150:151], v[150:151], 0, s[58:59]
	global_load_dwordx4 v[58:61], v[148:149], off nt
	v_lshl_add_u64 v[148:149], v[148:149], 0, s[58:59]
	ds_read_b32 v141, v160 offset:480
	ds_read_b128 v[114:117], v161 offset:3840
	ds_read_b128 v[176:179], v161 offset:3856
	s_waitcnt vmcnt(38)
	s_waitcnt lgkmcnt(3)
	v_cndmask_b32_e64 v143, 0, v143, s[6:7]
	v_pk_mul_f32 v[180:181], v[26:27], v[172:173] op_sel:[0,1]
	v_pk_mul_f32 v[192:193], v[28:29], v[172:173] op_sel:[0,1]
	v_mfma_f32_16x16x4_f32 v[110:113], v143, v66, v[110:113]
	v_pk_fma_f32 v[180:181], v[30:31], v[172:173], v[180:181] op_sel_hi:[1,0,1]
	v_pk_fma_f32 v[192:193], v[32:33], v[172:173], v[192:193] op_sel_hi:[1,0,1]
	v_pk_fma_f32 v[180:181], v[22:23], v[174:175], v[180:181] op_sel_hi:[1,0,1]
	v_pk_fma_f32 v[192:193], v[24:25], v[174:175], v[192:193] op_sel_hi:[1,0,1]
	v_mfma_f32_16x16x4_f32 v[106:109], v143, v67, v[106:109]
	v_pk_fma_f32 v[180:181], v[18:19], v[174:175], v[180:181] op_sel:[0,1,0]
	v_pk_fma_f32 v[192:193], v[20:21], v[174:175], v[192:193] op_sel:[0,1,0]
	v_pk_fma_f32 v[180:181], v[14:15], v[232:233], v[180:181] op_sel_hi:[1,0,1]
	v_pk_fma_f32 v[192:193], v[16:17], v[232:233], v[192:193] op_sel_hi:[1,0,1]
	v_mfma_f32_16x16x4_f32 v[102:105], v143, v68, v[102:105]
	v_pk_fma_f32 v[180:181], v[10:11], v[232:233], v[180:181] op_sel:[0,1,0]
	v_pk_fma_f32 v[192:193], v[12:13], v[232:233], v[192:193] op_sel:[0,1,0]
	v_pk_fma_f32 v[180:181], v[6:7], v[234:235], v[180:181] op_sel_hi:[1,0,1]
	v_pk_fma_f32 v[192:193], v[8:9], v[234:235], v[192:193] op_sel_hi:[1,0,1]
	v_mfma_f32_16x16x4_f32 v[98:101], v143, v69, v[98:101]
	v_pk_fma_f32 v[180:181], v[2:3], v[234:235], v[180:181] op_sel:[0,1,0]
	v_pk_fma_f32 v[192:193], v[4:5], v[234:235], v[192:193] op_sel:[0,1,0]
	v_pk_mul_f32 v[180:181], v[146:147], v[180:181]
	v_pk_mul_f32 v[192:193], v[146:147], v[192:193]
	v_pk_fma_f32 v[236:237], v[144:145], v[66:67], v[180:181]
	v_pk_fma_f32 v[238:239], v[144:145], v[68:69], v[192:193]
	global_store_dwordx4 v[150:151], v[236:239], off nt
	v_lshl_add_u64 v[150:151], v[150:151], 0, s[58:59]
	global_load_dwordx4 v[66:69], v[148:149], off nt
	v_lshl_add_u64 v[148:149], v[148:149], 0, s[58:59]
	ds_read_b32 v143, v160 offset:496
	ds_read_b128 v[172:175], v161 offset:3968
	ds_read_b128 v[232:235], v161 offset:3984
	s_waitcnt vmcnt(38)
	s_waitcnt lgkmcnt(3)
	v_cndmask_b32_e64 v141, 0, v141, s[6:7]
	v_pk_mul_f32 v[180:181], v[26:27], v[114:115] op_sel:[0,1]
	v_pk_mul_f32 v[192:193], v[28:29], v[114:115] op_sel:[0,1]
	v_mfma_f32_16x16x4_f32 v[110:113], v141, v74, v[110:113]
	v_pk_fma_f32 v[180:181], v[30:31], v[114:115], v[180:181] op_sel_hi:[1,0,1]
	v_pk_fma_f32 v[192:193], v[32:33], v[114:115], v[192:193] op_sel_hi:[1,0,1]
	v_pk_fma_f32 v[180:181], v[22:23], v[116:117], v[180:181] op_sel_hi:[1,0,1]
	v_pk_fma_f32 v[192:193], v[24:25], v[116:117], v[192:193] op_sel_hi:[1,0,1]
	v_mfma_f32_16x16x4_f32 v[106:109], v141, v75, v[106:109]
	v_pk_fma_f32 v[180:181], v[18:19], v[116:117], v[180:181] op_sel:[0,1,0]
	v_pk_fma_f32 v[192:193], v[20:21], v[116:117], v[192:193] op_sel:[0,1,0]
	v_pk_fma_f32 v[180:181], v[14:15], v[176:177], v[180:181] op_sel_hi:[1,0,1]
	v_pk_fma_f32 v[192:193], v[16:17], v[176:177], v[192:193] op_sel_hi:[1,0,1]
	v_mfma_f32_16x16x4_f32 v[102:105], v141, v76, v[102:105]
	v_pk_fma_f32 v[180:181], v[10:11], v[176:177], v[180:181] op_sel:[0,1,0]
	v_pk_fma_f32 v[192:193], v[12:13], v[176:177], v[192:193] op_sel:[0,1,0]
	v_pk_fma_f32 v[180:181], v[6:7], v[178:179], v[180:181] op_sel_hi:[1,0,1]
	v_pk_fma_f32 v[192:193], v[8:9], v[178:179], v[192:193] op_sel_hi:[1,0,1]
	v_mfma_f32_16x16x4_f32 v[98:101], v141, v77, v[98:101]
	v_pk_fma_f32 v[180:181], v[2:3], v[178:179], v[180:181] op_sel:[0,1,0]
	v_pk_fma_f32 v[192:193], v[4:5], v[178:179], v[192:193] op_sel:[0,1,0]
	v_pk_mul_f32 v[180:181], v[146:147], v[180:181]
	v_pk_mul_f32 v[192:193], v[146:147], v[192:193]
	v_pk_fma_f32 v[236:237], v[144:145], v[74:75], v[180:181]
	v_pk_fma_f32 v[238:239], v[144:145], v[76:77], v[192:193]
	global_store_dwordx4 v[150:151], v[236:239], off nt
	v_lshl_add_u64 v[150:151], v[150:151], 0, s[58:59]
	global_load_dwordx4 v[74:77], v[148:149], off nt
	v_lshl_add_u64 v[148:149], v[148:149], 0, s[58:59]
	ds_read_b32 v141, v160 offset:512
	ds_read_b128 v[114:117], v161 offset:4096
	ds_read_b128 v[176:179], v161 offset:4112
	s_waitcnt vmcnt(38)
; #define RS_LOAD(dst, it0) do { _Pragma("unroll") for (int u = 0; u < 8; ++u) dst[u] = __builtin_nontemporal_load((const f32x4*)(S0 + (size_t)(4 * ((it0) + u)) * DV)); } while (0)
; __device__ __forceinline__ void ret_sample_item(Frame& F, int item) {
;     ...
;     for (int it0 = 0; it0 < 64; it0 += 16) {
;         RS_LOAD(sb, it0 + 8);
;         RS_PROC(sa, it0);
;         { const int itn = it0 + 16 < 64 ? it0 + 16 : it0; RS_LOAD(sa, itn); }
;         RS_PROC(sb, it0 + 8);
;     }
	s_waitcnt lgkmcnt(3)
	v_cndmask_b32_e64 v143, 0, v143, s[6:7]
	v_pk_mul_f32 v[180:181], v[26:27], v[172:173] op_sel:[0,1]
	v_pk_mul_f32 v[192:193], v[28:29], v[172:173] op_sel:[0,1]
	v_mfma_f32_16x16x4_f32 v[110:113], v143, v78, v[110:113]
	v_pk_fma_f32 v[180:181], v[30:31], v[172:173], v[180:181] op_sel_hi:[1,0,1]
	v_pk_fma_f32 v[192:193], v[32:33], v[172:173], v[192:193] op_sel_hi:[1,0,1]
	v_pk_fma_f32 v[180:181], v[22:23], v[174:175], v[180:181] op_sel_hi:[1,0,1]
	v_pk_fma_f32 v[192:193], v[24:25], v[174:175], v[192:193] op_sel_hi:[1,0,1]
	v_mfma_f32_16x16x4_f32 v[106:109], v143, v79, v[106:109]
	v_pk_fma_f32 v[180:181], v[18:19], v[174:175], v[180:181] op_sel:[0,1,0]
	v_pk_fma_f32 v[192:193], v[20:21], v[174:175], v[192:193] op_sel:[0,1,0]
	v_pk_fma_f32 v[180:181], v[14:15], v[232:233], v[180:181] op_sel_hi:[1,0,1]
	v_pk_fma_f32 v[192:193], v[16:17], v[232:233], v[192:193] op_sel_hi:[1,0,1]
	v_mfma_f32_16x16x4_f32 v[102:105], v143, v80, v[102:105]
	v_pk_fma_f32 v[180:181], v[10:11], v[232:233], v[180:181] op_sel:[0,1,0]
	v_pk_fma_f32 v[192:193], v[12:13], v[232:233], v[192:193] op_sel:[0,1,0]
	v_pk_fma_f32 v[180:181], v[6:7], v[234:235], v[180:181] op_sel_hi:[1,0,1]
	v_pk_fma_f32 v[192:193], v[8:9], v[234:235], v[192:193] op_sel_hi:[1,0,1]
	v_mfma_f32_16x16x4_f32 v[98:101], v143, v81, v[98:101]
	v_pk_fma_f32 v[180:181], v[2:3], v[234:235], v[180:181] op_sel:[0,1,0]
	v_pk_fma_f32 v[192:193], v[4:5], v[234:235], v[192:193] op_sel:[0,1,0]
	v_pk_mul_f32 v[180:181], v[146:147], v[180:181]
	v_pk_mul_f32 v[192:193], v[146:147], v[192:193]
	v_pk_fma_f32 v[236:237], v[144:145], v[78:79], v[180:181]
	v_pk_fma_f32 v[238:239], v[144:145], v[80:81], v[192:193]
	global_store_dwordx4 v[150:151], v[236:239], off nt
	v_lshl_add_u64 v[150:151], v[150:151], 0, s[58:59]
	global_load_dwordx4 v[78:81], v[148:149], off nt
	v_lshl_add_u64 v[148:149], v[148:149], 0, s[58:59]
	ds_read_b32 v143, v160 offset:528
	ds_read_b128 v[172:175], v161 offset:4224
	ds_read_b128 v[232:235], v161 offset:4240
	s_waitcnt vmcnt(38)
	s_waitcnt lgkmcnt(3)
	v_cndmask_b32_e64 v141, 0, v141, s[6:7]
	v_pk_mul_f32 v[180:181], v[26:27], v[114:115] op_sel:[0,1]
	v_pk_mul_f32 v[192:193], v[28:29], v[114:115] op_sel:[0,1]
	v_mfma_f32_16x16x4_f32 v[110:113], v141, v82, v[110:113]
	v_pk_fma_f32 v[180:181], v[30:31], v[114:115], v[180:181] op_sel_hi:[1,0,1]
	v_pk_fma_f32 v[192:193], v[32:33], v[114:115], v[192:193] op_sel_hi:[1,0,1]
	v_pk_fma_f32 v[180:181], v[22:23], v[116:117], v[180:181] op_sel_hi:[1,0,1]
	v_pk_fma_f32 v[192:193], v[24:25], v[116:117], v[192:193] op_sel_hi:[1,0,1]
	v_mfma_f32_16x16x4_f32 v[106:109], v141, v83, v[106:109]
	v_pk_fma_f32 v[180:181], v[18:19], v[116:117], v[180:181] op_sel:[0,1,0]
	v_pk_fma_f32 v[192:193], v[20:21], v[116:117], v[192:193] op_sel:[0,1,0]
	v_pk_fma_f32 v[180:181], v[14:15], v[176:177], v[180:181] op_sel_hi:[1,0,1]
	v_pk_fma_f32 v[192:193], v[16:17], v[176:177], v[192:193] op_sel_hi:[1,0,1]
	v_mfma_f32_16x16x4_f32 v[102:105], v141, v84, v[102:105]
	v_pk_fma_f32 v[180:181], v[10:11], v[176:177], v[180:181] op_sel:[0,1,0]
	v_pk_fma_f32 v[192:193], v[12:13], v[176:177], v[192:193] op_sel:[0,1,0]
	v_pk_fma_f32 v[180:181], v[6:7], v[178:179], v[180:181] op_sel_hi:[1,0,1]
	v_pk_fma_f32 v[192:193], v[8:9], v[178:179], v[192:193] op_sel_hi:[1,0,1]
	v_mfma_f32_16x16x4_f32 v[98:101], v141, v85, v[98:101]
	v_pk_fma_f32 v[180:181], v[2:3], v[178:179], v[180:181] op_sel:[0,1,0]
	v_pk_fma_f32 v[192:193], v[4:5], v[178:179], v[192:193] op_sel:[0,1,0]
	v_pk_mul_f32 v[180:181], v[146:147], v[180:181]
	v_pk_mul_f32 v[192:193], v[146:147], v[192:193]
	v_pk_fma_f32 v[236:237], v[144:145], v[82:83], v[180:181]
	v_pk_fma_f32 v[238:239], v[144:145], v[84:85], v[192:193]
	global_store_dwordx4 v[150:151], v[236:239], off nt
	v_lshl_add_u64 v[150:151], v[150:151], 0, s[58:59]
	global_load_dwordx4 v[82:85], v[148:149], off nt
	v_lshl_add_u64 v[148:149], v[148:149], 0, s[58:59]
	ds_read_b32 v141, v160 offset:544
	ds_read_b128 v[114:117], v161 offset:4352
	ds_read_b128 v[176:179], v161 offset:4368
	s_waitcnt vmcnt(38)
	s_waitcnt lgkmcnt(3)
	v_cndmask_b32_e64 v143, 0, v143, s[6:7]
	v_pk_mul_f32 v[180:181], v[26:27], v[172:173] op_sel:[0,1]
	v_pk_mul_f32 v[192:193], v[28:29], v[172:173] op_sel:[0,1]
	v_mfma_f32_16x16x4_f32 v[110:113], v143, v86, v[110:113]
	v_pk_fma_f32 v[180:181], v[30:31], v[172:173], v[180:181] op_sel_hi:[1,0,1]
	v_pk_fma_f32 v[192:193], v[32:33], v[172:173], v[192:193] op_sel_hi:[1,0,1]
	v_pk_fma_f32 v[180:181], v[22:23], v[174:175], v[180:181] op_sel_hi:[1,0,1]
	v_pk_fma_f32 v[192:193], v[24:25], v[174:175], v[192:193] op_sel_hi:[1,0,1]
	v_mfma_f32_16x16x4_f32 v[106:109], v143, v87, v[106:109]
	v_pk_fma_f32 v[180:181], v[18:19], v[174:175], v[180:181] op_sel:[0,1,0]
	v_pk_fma_f32 v[192:193], v[20:21], v[174:175], v[192:193] op_sel:[0,1,0]
	v_pk_fma_f32 v[180:181], v[14:15], v[232:233], v[180:181] op_sel_hi:[1,0,1]
	v_pk_fma_f32 v[192:193], v[16:17], v[232:233], v[192:193] op_sel_hi:[1,0,1]
	v_mfma_f32_16x16x4_f32 v[102:105], v143, v88, v[102:105]
	v_pk_fma_f32 v[180:181], v[10:11], v[232:233], v[180:181] op_sel:[0,1,0]
	v_pk_fma_f32 v[192:193], v[12:13], v[232:233], v[192:193] op_sel:[0,1,0]
	v_pk_fma_f32 v[180:181], v[6:7], v[234:235], v[180:181] op_sel_hi:[1,0,1]
	v_pk_fma_f32 v[192:193], v[8:9], v[234:235], v[192:193] op_sel_hi:[1,0,1]
	v_mfma_f32_16x16x4_f32 v[98:101], v143, v89, v[98:101]
	v_pk_fma_f32 v[180:181], v[2:3], v[234:235], v[180:181] op_sel:[0,1,0]
	v_pk_fma_f32 v[192:193], v[4:5], v[234:235], v[192:193] op_sel:[0,1,0]
	v_pk_mul_f32 v[180:181], v[146:147], v[180:181]
	v_pk_mul_f32 v[192:193], v[146:147], v[192:193]
	v_pk_fma_f32 v[236:237], v[144:145], v[86:87], v[180:181]
	v_pk_fma_f32 v[238:239], v[144:145], v[88:89], v[192:193]
	global_store_dwordx4 v[150:151], v[236:239], off nt
	v_lshl_add_u64 v[150:151], v[150:151], 0, s[58:59]
	global_load_dwordx4 v[86:89], v[148:149], off nt
	v_lshl_add_u64 v[148:149], v[148:149], 0, s[58:59]
	ds_read_b32 v143, v160 offset:560
	ds_read_b128 v[172:175], v161 offset:4480
	ds_read_b128 v[232:235], v161 offset:4496
	s_waitcnt vmcnt(38)
; #define RS_LOAD(dst, it0) do { _Pragma("unroll") for (int u = 0; u < 8; ++u) dst[u] = __builtin_nontemporal_load((const f32x4*)(S0 + (size_t)(4 * ((it0) + u)) * DV)); } while (0)
; __device__ __forceinline__ void ret_sample_item(Frame& F, int item) {
;     ...
;     for (int it0 = 0; it0 < 64; it0 += 16) {
;         RS_LOAD(sb, it0 + 8);
;         RS_PROC(sa, it0);
;         { const int itn = it0 + 16 < 64 ? it0 + 16 : it0; RS_LOAD(sa, itn); }
;         RS_PROC(sb, it0 + 8);
;     }
	s_waitcnt lgkmcnt(3)
	v_cndmask_b32_e64 v141, 0, v141, s[6:7]
	v_pk_mul_f32 v[180:181], v[26:27], v[114:115] op_sel:[0,1]
	v_pk_mul_f32 v[192:193], v[28:29], v[114:115] op_sel:[0,1]
	v_mfma_f32_16x16x4_f32 v[110:113], v141, v90, v[110:113]
	v_pk_fma_f32 v[180:181], v[30:31], v[114:115], v[180:181] op_sel_hi:[1,0,1]
	v_pk_fma_f32 v[192:193], v[32:33], v[114:115], v[192:193] op_sel_hi:[1,0,1]
	v_pk_fma_f32 v[180:181], v[22:23], v[116:117], v[180:181] op_sel_hi:[1,0,1]
	v_pk_fma_f32 v[192:193], v[24:25], v[116:117], v[192:193] op_sel_hi:[1,0,1]
	v_mfma_f32_16x16x4_f32 v[106:109], v141, v91, v[106:109]
	v_pk_fma_f32 v[180:181], v[18:19], v[116:117], v[180:181] op_sel:[0,1,0]
	v_pk_fma_f32 v[192:193], v[20:21], v[116:117], v[192:193] op_sel:[0,1,0]
	v_pk_fma_f32 v[180:181], v[14:15], v[176:177], v[180:181] op_sel_hi:[1,0,1]
	v_pk_fma_f32 v[192:193], v[16:17], v[176:177], v[192:193] op_sel_hi:[1,0,1]
	v_mfma_f32_16x16x4_f32 v[102:105], v141, v92, v[102:105]
	v_pk_fma_f32 v[180:181], v[10:11], v[176:177], v[180:181] op_sel:[0,1,0]
	v_pk_fma_f32 v[192:193], v[12:13], v[176:177], v[192:193] op_sel:[0,1,0]
	v_pk_fma_f32 v[180:181], v[6:7], v[178:179], v[180:181] op_sel_hi:[1,0,1]
	v_pk_fma_f32 v[192:193], v[8:9], v[178:179], v[192:193] op_sel_hi:[1,0,1]
	v_mfma_f32_16x16x4_f32 v[98:101], v141, v93, v[98:101]
	v_pk_fma_f32 v[180:181], v[2:3], v[178:179], v[180:181] op_sel:[0,1,0]
	v_pk_fma_f32 v[192:193], v[4:5], v[178:179], v[192:193] op_sel:[0,1,0]
	v_pk_mul_f32 v[180:181], v[146:147], v[180:181]
	v_pk_mul_f32 v[192:193], v[146:147], v[192:193]
	v_pk_fma_f32 v[236:237], v[144:145], v[90:91], v[180:181]
	v_pk_fma_f32 v[238:239], v[144:145], v[92:93], v[192:193]
	global_store_dwordx4 v[150:151], v[236:239], off nt
	v_lshl_add_u64 v[150:151], v[150:151], 0, s[58:59]
	global_load_dwordx4 v[90:93], v[148:149], off nt
	v_lshl_add_u64 v[148:149], v[148:149], 0, s[58:59]
	ds_read_b32 v141, v160 offset:576
	ds_read_b128 v[114:117], v161 offset:4608
	ds_read_b128 v[176:179], v161 offset:4624
	s_waitcnt vmcnt(38)
	s_waitcnt lgkmcnt(3)
	v_cndmask_b32_e64 v143, 0, v143, s[6:7]
	v_pk_mul_f32 v[180:181], v[26:27], v[172:173] op_sel:[0,1]
	v_pk_mul_f32 v[192:193], v[28:29], v[172:173] op_sel:[0,1]
	v_mfma_f32_16x16x4_f32 v[110:113], v143, v94, v[110:113]
	v_pk_fma_f32 v[180:181], v[30:31], v[172:173], v[180:181] op_sel_hi:[1,0,1]
	v_pk_fma_f32 v[192:193], v[32:33], v[172:173], v[192:193] op_sel_hi:[1,0,1]
	v_pk_fma_f32 v[180:181], v[22:23], v[174:175], v[180:181] op_sel_hi:[1,0,1]
	v_pk_fma_f32 v[192:193], v[24:25], v[174:175], v[192:193] op_sel_hi:[1,0,1]
	v_mfma_f32_16x16x4_f32 v[106:109], v143, v95, v[106:109]
	v_pk_fma_f32 v[180:181], v[18:19], v[174:175], v[180:181] op_sel:[0,1,0]
	v_pk_fma_f32 v[192:193], v[20:21], v[174:175], v[192:193] op_sel:[0,1,0]
	v_pk_fma_f32 v[180:181], v[14:15], v[232:233], v[180:181] op_sel_hi:[1,0,1]
	v_pk_fma_f32 v[192:193], v[16:17], v[232:233], v[192:193] op_sel_hi:[1,0,1]
	v_mfma_f32_16x16x4_f32 v[102:105], v143, v96, v[102:105]
	v_pk_fma_f32 v[180:181], v[10:11], v[232:233], v[180:181] op_sel:[0,1,0]
	v_pk_fma_f32 v[192:193], v[12:13], v[232:233], v[192:193] op_sel:[0,1,0]
	v_pk_fma_f32 v[180:181], v[6:7], v[234:235], v[180:181] op_sel_hi:[1,0,1]
	v_pk_fma_f32 v[192:193], v[8:9], v[234:235], v[192:193] op_sel_hi:[1,0,1]
	v_mfma_f32_16x16x4_f32 v[98:101], v143, v97, v[98:101]
	v_pk_fma_f32 v[180:181], v[2:3], v[234:235], v[180:181] op_sel:[0,1,0]
	v_pk_fma_f32 v[192:193], v[4:5], v[234:235], v[192:193] op_sel:[0,1,0]
	v_pk_mul_f32 v[180:181], v[146:147], v[180:181]
	v_pk_mul_f32 v[192:193], v[146:147], v[192:193]
	v_pk_fma_f32 v[236:237], v[144:145], v[94:95], v[180:181]
	v_pk_fma_f32 v[238:239], v[144:145], v[96:97], v[192:193]
	global_store_dwordx4 v[150:151], v[236:239], off nt
	v_lshl_add_u64 v[150:151], v[150:151], 0, s[58:59]
	global_load_dwordx4 v[94:97], v[148:149], off nt
	v_lshl_add_u64 v[148:149], v[148:149], 0, s[58:59]
	ds_read_b32 v143, v160 offset:592
	ds_read_b128 v[172:175], v161 offset:4736
	ds_read_b128 v[232:235], v161 offset:4752
	s_waitcnt vmcnt(38)
	s_waitcnt lgkmcnt(3)
	v_cndmask_b32_e64 v141, 0, v141, s[6:7]
	v_pk_mul_f32 v[180:181], v[26:27], v[114:115] op_sel:[0,1]
	v_pk_mul_f32 v[192:193], v[28:29], v[114:115] op_sel:[0,1]
	v_mfma_f32_16x16x4_f32 v[110:113], v141, v212, v[110:113]
	v_pk_fma_f32 v[180:181], v[30:31], v[114:115], v[180:181] op_sel_hi:[1,0,1]
	v_pk_fma_f32 v[192:193], v[32:33], v[114:115], v[192:193] op_sel_hi:[1,0,1]
	v_pk_fma_f32 v[180:181], v[22:23], v[116:117], v[180:181] op_sel_hi:[1,0,1]
	v_pk_fma_f32 v[192:193], v[24:25], v[116:117], v[192:193] op_sel_hi:[1,0,1]
	v_mfma_f32_16x16x4_f32 v[106:109], v141, v213, v[106:109]
	v_pk_fma_f32 v[180:181], v[18:19], v[116:117], v[180:181] op_sel:[0,1,0]
	v_pk_fma_f32 v[192:193], v[20:21], v[116:117], v[192:193] op_sel:[0,1,0]
	v_pk_fma_f32 v[180:181], v[14:15], v[176:177], v[180:181] op_sel_hi:[1,0,1]
	v_pk_fma_f32 v[192:193], v[16:17], v[176:177], v[192:193] op_sel_hi:[1,0,1]
	v_mfma_f32_16x16x4_f32 v[102:105], v141, v214, v[102:105]
	v_pk_fma_f32 v[180:181], v[10:11], v[176:177], v[180:181] op_sel:[0,1,0]
	v_pk_fma_f32 v[192:193], v[12:13], v[176:177], v[192:193] op_sel:[0,1,0]
	v_pk_fma_f32 v[180:181], v[6:7], v[178:179], v[180:181] op_sel_hi:[1,0,1]
	v_pk_fma_f32 v[192:193], v[8:9], v[178:179], v[192:193] op_sel_hi:[1,0,1]
	v_mfma_f32_16x16x4_f32 v[98:101], v141, v215, v[98:101]
	v_pk_fma_f32 v[180:181], v[2:3], v[178:179], v[180:181] op_sel:[0,1,0]
	v_pk_fma_f32 v[192:193], v[4:5], v[178:179], v[192:193] op_sel:[0,1,0]
	v_pk_mul_f32 v[180:181], v[146:147], v[180:181]
	v_pk_mul_f32 v[192:193], v[146:147], v[192:193]
	v_pk_fma_f32 v[236:237], v[144:145], v[212:213], v[180:181]
	v_pk_fma_f32 v[238:239], v[144:145], v[214:215], v[192:193]
	global_store_dwordx4 v[150:151], v[236:239], off nt
	v_lshl_add_u64 v[150:151], v[150:151], 0, s[58:59]
	global_load_dwordx4 v[212:215], v[148:149], off nt
	v_lshl_add_u64 v[148:149], v[148:149], 0, s[58:59]
	ds_read_b32 v141, v160 offset:608
	ds_read_b128 v[114:117], v161 offset:4864
	ds_read_b128 v[176:179], v161 offset:4880
	s_waitcnt vmcnt(38)
; #define RS_LOAD(dst, it0) do { _Pragma("unroll") for (int u = 0; u < 8; ++u) dst[u] = __builtin_nontemporal_load((const f32x4*)(S0 + (size_t)(4 * ((it0) + u)) * DV)); } while (0)
; __device__ __forceinline__ void ret_sample_item(Frame& F, int item) {
;     ...
;     for (int it0 = 0; it0 < 64; it0 += 16) {
;         RS_LOAD(sb, it0 + 8);
;         RS_PROC(sa, it0);
;         { const int itn = it0 + 16 < 64 ? it0 + 16 : it0; RS_LOAD(sa, itn); }
;         RS_PROC(sb, it0 + 8);
;     }
	s_waitcnt lgkmcnt(3)
	v_cndmask_b32_e64 v143, 0, v143, s[6:7]
	v_pk_mul_f32 v[180:181], v[26:27], v[172:173] op_sel:[0,1]
	v_pk_mul_f32 v[192:193], v[28:29], v[172:173] op_sel:[0,1]
	v_mfma_f32_16x16x4_f32 v[110:113], v143, v216, v[110:113]
	v_pk_fma_f32 v[180:181], v[30:31], v[172:173], v[180:181] op_sel_hi:[1,0,1]
	v_pk_fma_f32 v[192:193], v[32:33], v[172:173], v[192:193] op_sel_hi:[1,0,1]
	v_pk_fma_f32 v[180:181], v[22:23], v[174:175], v[180:181] op_sel_hi:[1,0,1]
	v_pk_fma_f32 v[192:193], v[24:25], v[174:175], v[192:193] op_sel_hi:[1,0,1]
	v_mfma_f32_16x16x4_f32 v[106:109], v143, v217, v[106:109]
	v_pk_fma_f32 v[180:181], v[18:19], v[174:175], v[180:181] op_sel:[0,1,0]
	v_pk_fma_f32 v[192:193], v[20:21], v[174:175], v[192:193] op_sel:[0,1,0]
	v_pk_fma_f32 v[180:181], v[14:15], v[232:233], v[180:181] op_sel_hi:[1,0,1]
	v_pk_fma_f32 v[192:193], v[16:17], v[232:233], v[192:193] op_sel_hi:[1,0,1]
	v_mfma_f32_16x16x4_f32 v[102:105], v143, v218, v[102:105]
	v_pk_fma_f32 v[180:181], v[10:11], v[232:233], v[180:181] op_sel:[0,1,0]
	v_pk_fma_f32 v[192:193], v[12:13], v[232:233], v[192:193] op_sel:[0,1,0]
	v_pk_fma_f32 v[180:181], v[6:7], v[234:235], v[180:181] op_sel_hi:[1,0,1]
	v_pk_fma_f32 v[192:193], v[8:9], v[234:235], v[192:193] op_sel_hi:[1,0,1]
	v_mfma_f32_16x16x4_f32 v[98:101], v143, v219, v[98:101]
	v_pk_fma_f32 v[180:181], v[2:3], v[234:235], v[180:181] op_sel:[0,1,0]
	v_pk_fma_f32 v[192:193], v[4:5], v[234:235], v[192:193] op_sel:[0,1,0]
	v_pk_mul_f32 v[180:181], v[146:147], v[180:181]
	v_pk_mul_f32 v[192:193], v[146:147], v[192:193]
	v_pk_fma_f32 v[236:237], v[144:145], v[216:217], v[180:181]
	v_pk_fma_f32 v[238:239], v[144:145], v[218:219], v[192:193]
	global_store_dwordx4 v[150:151], v[236:239], off nt
	v_lshl_add_u64 v[150:151], v[150:151], 0, s[58:59]
	global_load_dwordx4 v[216:219], v[148:149], off nt
	v_lshl_add_u64 v[148:149], v[148:149], 0, s[58:59]
	ds_read_b32 v143, v160 offset:624
	ds_read_b128 v[172:175], v161 offset:4992
	ds_read_b128 v[232:235], v161 offset:5008
	s_waitcnt vmcnt(38)
	s_waitcnt lgkmcnt(3)
	v_cndmask_b32_e64 v141, 0, v141, s[6:7]
	v_pk_mul_f32 v[180:181], v[26:27], v[114:115] op_sel:[0,1]
	v_pk_mul_f32 v[192:193], v[28:29], v[114:115] op_sel:[0,1]
	v_mfma_f32_16x16x4_f32 v[110:113], v141, v224, v[110:113]
	v_pk_fma_f32 v[180:181], v[30:31], v[114:115], v[180:181] op_sel_hi:[1,0,1]
	v_pk_fma_f32 v[192:193], v[32:33], v[114:115], v[192:193] op_sel_hi:[1,0,1]
	v_pk_fma_f32 v[180:181], v[22:23], v[116:117], v[180:181] op_sel_hi:[1,0,1]
	v_pk_fma_f32 v[192:193], v[24:25], v[116:117], v[192:193] op_sel_hi:[1,0,1]
	v_mfma_f32_16x16x4_f32 v[106:109], v141, v225, v[106:109]
	v_pk_fma_f32 v[180:181], v[18:19], v[116:117], v[180:181] op_sel:[0,1,0]
	v_pk_fma_f32 v[192:193], v[20:21], v[116:117], v[192:193] op_sel:[0,1,0]
	v_pk_fma_f32 v[180:181], v[14:15], v[176:177], v[180:181] op_sel_hi:[1,0,1]
	v_pk_fma_f32 v[192:193], v[16:17], v[176:177], v[192:193] op_sel_hi:[1,0,1]
	v_mfma_f32_16x16x4_f32 v[102:105], v141, v226, v[102:105]
	v_pk_fma_f32 v[180:181], v[10:11], v[176:177], v[180:181] op_sel:[0,1,0]
	v_pk_fma_f32 v[192:193], v[12:13], v[176:177], v[192:193] op_sel:[0,1,0]
	v_pk_fma_f32 v[180:181], v[6:7], v[178:179], v[180:181] op_sel_hi:[1,0,1]
	v_pk_fma_f32 v[192:193], v[8:9], v[178:179], v[192:193] op_sel_hi:[1,0,1]
	v_mfma_f32_16x16x4_f32 v[98:101], v141, v227, v[98:101]
	v_pk_fma_f32 v[180:181], v[2:3], v[178:179], v[180:181] op_sel:[0,1,0]
	v_pk_fma_f32 v[192:193], v[4:5], v[178:179], v[192:193] op_sel:[0,1,0]
	v_pk_mul_f32 v[180:181], v[146:147], v[180:181]
	v_pk_mul_f32 v[192:193], v[146:147], v[192:193]
	v_pk_fma_f32 v[236:237], v[144:145], v[224:225], v[180:181]
	v_pk_fma_f32 v[238:239], v[144:145], v[226:227], v[192:193]
	global_store_dwordx4 v[150:151], v[236:239], off nt
	v_lshl_add_u64 v[150:151], v[150:151], 0, s[58:59]
	global_load_dwordx4 v[224:227], v[148:149], off nt
	v_lshl_add_u64 v[148:149], v[148:149], 0, s[58:59]
	ds_read_b32 v141, v160 offset:640
	ds_read_b128 v[114:117], v161 offset:5120
	ds_read_b128 v[176:179], v161 offset:5136
	s_waitcnt vmcnt(38)
	s_waitcnt lgkmcnt(3)
	v_cndmask_b32_e64 v143, 0, v143, s[6:7]
	v_pk_mul_f32 v[180:181], v[26:27], v[172:173] op_sel:[0,1]
	v_pk_mul_f32 v[192:193], v[28:29], v[172:173] op_sel:[0,1]
	v_mfma_f32_16x16x4_f32 v[110:113], v143, v228, v[110:113]
	v_pk_fma_f32 v[180:181], v[30:31], v[172:173], v[180:181] op_sel_hi:[1,0,1]
	v_pk_fma_f32 v[192:193], v[32:33], v[172:173], v[192:193] op_sel_hi:[1,0,1]
	v_pk_fma_f32 v[180:181], v[22:23], v[174:175], v[180:181] op_sel_hi:[1,0,1]
	v_pk_fma_f32 v[192:193], v[24:25], v[174:175], v[192:193] op_sel_hi:[1,0,1]
	v_mfma_f32_16x16x4_f32 v[106:109], v143, v229, v[106:109]
	v_pk_fma_f32 v[180:181], v[18:19], v[174:175], v[180:181] op_sel:[0,1,0]
	v_pk_fma_f32 v[192:193], v[20:21], v[174:175], v[192:193] op_sel:[0,1,0]
	v_pk_fma_f32 v[180:181], v[14:15], v[232:233], v[180:181] op_sel_hi:[1,0,1]
	v_pk_fma_f32 v[192:193], v[16:17], v[232:233], v[192:193] op_sel_hi:[1,0,1]
	v_mfma_f32_16x16x4_f32 v[102:105], v143, v230, v[102:105]
	v_pk_fma_f32 v[180:181], v[10:11], v[232:233], v[180:181] op_sel:[0,1,0]
	v_pk_fma_f32 v[192:193], v[12:13], v[232:233], v[192:193] op_sel:[0,1,0]
	v_pk_fma_f32 v[180:181], v[6:7], v[234:235], v[180:181] op_sel_hi:[1,0,1]
	v_pk_fma_f32 v[192:193], v[8:9], v[234:235], v[192:193] op_sel_hi:[1,0,1]
	v_mfma_f32_16x16x4_f32 v[98:101], v143, v231, v[98:101]
	v_pk_fma_f32 v[180:181], v[2:3], v[234:235], v[180:181] op_sel:[0,1,0]
	v_pk_fma_f32 v[192:193], v[4:5], v[234:235], v[192:193] op_sel:[0,1,0]
	v_pk_mul_f32 v[180:181], v[146:147], v[180:181]
	v_pk_mul_f32 v[192:193], v[146:147], v[192:193]
	v_pk_fma_f32 v[236:237], v[144:145], v[228:229], v[180:181]
	v_pk_fma_f32 v[238:239], v[144:145], v[230:231], v[192:193]
	global_store_dwordx4 v[150:151], v[236:239], off nt
	v_lshl_add_u64 v[150:151], v[150:151], 0, s[58:59]
	global_load_dwordx4 v[228:231], v[148:149], off nt
	v_lshl_add_u64 v[148:149], v[148:149], 0, s[58:59]
	ds_read_b32 v143, v160 offset:656
	ds_read_b128 v[172:175], v161 offset:5248
	ds_read_b128 v[232:235], v161 offset:5264
	s_waitcnt vmcnt(38)
; #define RS_LOAD(dst, it0) do { _Pragma("unroll") for (int u = 0; u < 8; ++u) dst[u] = __builtin_nontemporal_load((const f32x4*)(S0 + (size_t)(4 * ((it0) + u)) * DV)); } while (0)
; __device__ __forceinline__ void ret_sample_item(Frame& F, int item) {
;     ...
;     for (int it0 = 0; it0 < 64; it0 += 16) {
;         RS_LOAD(sb, it0 + 8);
;         RS_PROC(sa, it0);
;         { const int itn = it0 + 16 < 64 ? it0 + 16 : it0; RS_LOAD(sa, itn); }
;         RS_PROC(sb, it0 + 8);
;     }
	s_waitcnt lgkmcnt(3)
	v_cndmask_b32_e64 v141, 0, v141, s[6:7]
	v_pk_mul_f32 v[180:181], v[26:27], v[114:115] op_sel:[0,1]
	v_pk_mul_f32 v[192:193], v[28:29], v[114:115] op_sel:[0,1]
	v_mfma_f32_16x16x4_f32 v[110:113], v141, v70, v[110:113]
	v_pk_fma_f32 v[180:181], v[30:31], v[114:115], v[180:181] op_sel_hi:[1,0,1]
	v_pk_fma_f32 v[192:193], v[32:33], v[114:115], v[192:193] op_sel_hi:[1,0,1]
	v_pk_fma_f32 v[180:181], v[22:23], v[116:117], v[180:181] op_sel_hi:[1,0,1]
	v_pk_fma_f32 v[192:193], v[24:25], v[116:117], v[192:193] op_sel_hi:[1,0,1]
	v_mfma_f32_16x16x4_f32 v[106:109], v141, v71, v[106:109]
	v_pk_fma_f32 v[180:181], v[18:19], v[116:117], v[180:181] op_sel:[0,1,0]
	v_pk_fma_f32 v[192:193], v[20:21], v[116:117], v[192:193] op_sel:[0,1,0]
	v_pk_fma_f32 v[180:181], v[14:15], v[176:177], v[180:181] op_sel_hi:[1,0,1]
	v_pk_fma_f32 v[192:193], v[16:17], v[176:177], v[192:193] op_sel_hi:[1,0,1]
	v_mfma_f32_16x16x4_f32 v[102:105], v141, v72, v[102:105]
	v_pk_fma_f32 v[180:181], v[10:11], v[176:177], v[180:181] op_sel:[0,1,0]
	v_pk_fma_f32 v[192:193], v[12:13], v[176:177], v[192:193] op_sel:[0,1,0]
	v_pk_fma_f32 v[180:181], v[6:7], v[178:179], v[180:181] op_sel_hi:[1,0,1]
	v_pk_fma_f32 v[192:193], v[8:9], v[178:179], v[192:193] op_sel_hi:[1,0,1]
	v_mfma_f32_16x16x4_f32 v[98:101], v141, v73, v[98:101]
	v_pk_fma_f32 v[180:181], v[2:3], v[178:179], v[180:181] op_sel:[0,1,0]
	v_pk_fma_f32 v[192:193], v[4:5], v[178:179], v[192:193] op_sel:[0,1,0]
	v_pk_mul_f32 v[180:181], v[146:147], v[180:181]
	v_pk_mul_f32 v[192:193], v[146:147], v[192:193]
	v_pk_fma_f32 v[236:237], v[144:145], v[70:71], v[180:181]
	v_pk_fma_f32 v[238:239], v[144:145], v[72:73], v[192:193]
	global_store_dwordx4 v[150:151], v[236:239], off nt
	v_lshl_add_u64 v[150:151], v[150:151], 0, s[58:59]
	global_load_dwordx4 v[70:73], v[148:149], off nt
	v_lshl_add_u64 v[148:149], v[148:149], 0, s[58:59]
	ds_read_b32 v141, v160 offset:672
	ds_read_b128 v[114:117], v161 offset:5376
	ds_read_b128 v[176:179], v161 offset:5392
	s_waitcnt vmcnt(38)
	s_waitcnt lgkmcnt(3)
	v_cndmask_b32_e64 v143, 0, v143, s[6:7]
	v_pk_mul_f32 v[180:181], v[26:27], v[172:173] op_sel:[0,1]
	v_pk_mul_f32 v[192:193], v[28:29], v[172:173] op_sel:[0,1]
	v_mfma_f32_16x16x4_f32 v[110:113], v143, v62, v[110:113]
	v_pk_fma_f32 v[180:181], v[30:31], v[172:173], v[180:181] op_sel_hi:[1,0,1]
	v_pk_fma_f32 v[192:193], v[32:33], v[172:173], v[192:193] op_sel_hi:[1,0,1]
	v_pk_fma_f32 v[180:181], v[22:23], v[174:175], v[180:181] op_sel_hi:[1,0,1]
	v_pk_fma_f32 v[192:193], v[24:25], v[174:175], v[192:193] op_sel_hi:[1,0,1]
	v_mfma_f32_16x16x4_f32 v[106:109], v143, v63, v[106:109]
	v_pk_fma_f32 v[180:181], v[18:19], v[174:175], v[180:181] op_sel:[0,1,0]
	v_pk_fma_f32 v[192:193], v[20:21], v[174:175], v[192:193] op_sel:[0,1,0]
	v_pk_fma_f32 v[180:181], v[14:15], v[232:233], v[180:181] op_sel_hi:[1,0,1]
	v_pk_fma_f32 v[192:193], v[16:17], v[232:233], v[192:193] op_sel_hi:[1,0,1]
	v_mfma_f32_16x16x4_f32 v[102:105], v143, v64, v[102:105]
	v_pk_fma_f32 v[180:181], v[10:11], v[232:233], v[180:181] op_sel:[0,1,0]
	v_pk_fma_f32 v[192:193], v[12:13], v[232:233], v[192:193] op_sel:[0,1,0]
	v_pk_fma_f32 v[180:181], v[6:7], v[234:235], v[180:181] op_sel_hi:[1,0,1]
	v_pk_fma_f32 v[192:193], v[8:9], v[234:235], v[192:193] op_sel_hi:[1,0,1]
	v_mfma_f32_16x16x4_f32 v[98:101], v143, v65, v[98:101]
	v_pk_fma_f32 v[180:181], v[2:3], v[234:235], v[180:181] op_sel:[0,1,0]
	v_pk_fma_f32 v[192:193], v[4:5], v[234:235], v[192:193] op_sel:[0,1,0]
	v_pk_mul_f32 v[180:181], v[146:147], v[180:181]
	v_pk_mul_f32 v[192:193], v[146:147], v[192:193]
	v_pk_fma_f32 v[236:237], v[144:145], v[62:63], v[180:181]
	v_pk_fma_f32 v[238:239], v[144:145], v[64:65], v[192:193]
	global_store_dwordx4 v[150:151], v[236:239], off nt
	v_lshl_add_u64 v[150:151], v[150:151], 0, s[58:59]
	global_load_dwordx4 v[62:65], v[148:149], off nt
	v_lshl_add_u64 v[148:149], v[148:149], 0, s[58:59]
	ds_read_b32 v143, v160 offset:688
	ds_read_b128 v[172:175], v161 offset:5504
	ds_read_b128 v[232:235], v161 offset:5520
	s_waitcnt vmcnt(38)
	s_waitcnt lgkmcnt(3)
	v_cndmask_b32_e64 v141, 0, v141, s[6:7]
	v_pk_mul_f32 v[180:181], v[26:27], v[114:115] op_sel:[0,1]
	v_pk_mul_f32 v[192:193], v[28:29], v[114:115] op_sel:[0,1]
	v_mfma_f32_16x16x4_f32 v[110:113], v141, v54, v[110:113]
	v_pk_fma_f32 v[180:181], v[30:31], v[114:115], v[180:181] op_sel_hi:[1,0,1]
	v_pk_fma_f32 v[192:193], v[32:33], v[114:115], v[192:193] op_sel_hi:[1,0,1]
	v_pk_fma_f32 v[180:181], v[22:23], v[116:117], v[180:181] op_sel_hi:[1,0,1]
	v_pk_fma_f32 v[192:193], v[24:25], v[116:117], v[192:193] op_sel_hi:[1,0,1]
	v_mfma_f32_16x16x4_f32 v[106:109], v141, v55, v[106:109]
	v_pk_fma_f32 v[180:181], v[18:19], v[116:117], v[180:181] op_sel:[0,1,0]
	v_pk_fma_f32 v[192:193], v[20:21], v[116:117], v[192:193] op_sel:[0,1,0]
	v_pk_fma_f32 v[180:181], v[14:15], v[176:177], v[180:181] op_sel_hi:[1,0,1]
	v_pk_fma_f32 v[192:193], v[16:17], v[176:177], v[192:193] op_sel_hi:[1,0,1]
	v_mfma_f32_16x16x4_f32 v[102:105], v141, v56, v[102:105]
	v_pk_fma_f32 v[180:181], v[10:11], v[176:177], v[180:181] op_sel:[0,1,0]
	v_pk_fma_f32 v[192:193], v[12:13], v[176:177], v[192:193] op_sel:[0,1,0]
	v_pk_fma_f32 v[180:181], v[6:7], v[178:179], v[180:181] op_sel_hi:[1,0,1]
	v_pk_fma_f32 v[192:193], v[8:9], v[178:179], v[192:193] op_sel_hi:[1,0,1]
	v_mfma_f32_16x16x4_f32 v[98:101], v141, v57, v[98:101]
	v_pk_fma_f32 v[180:181], v[2:3], v[178:179], v[180:181] op_sel:[0,1,0]
	v_pk_fma_f32 v[192:193], v[4:5], v[178:179], v[192:193] op_sel:[0,1,0]
	v_pk_mul_f32 v[180:181], v[146:147], v[180:181]
	v_pk_mul_f32 v[192:193], v[146:147], v[192:193]
	v_pk_fma_f32 v[236:237], v[144:145], v[54:55], v[180:181]
	v_pk_fma_f32 v[238:239], v[144:145], v[56:57], v[192:193]
	global_store_dwordx4 v[150:151], v[236:239], off nt
	v_lshl_add_u64 v[150:151], v[150:151], 0, s[58:59]
	global_load_dwordx4 v[54:57], v[148:149], off nt
	v_lshl_add_u64 v[148:149], v[148:149], 0, s[58:59]
	ds_read_b32 v141, v160 offset:704
	ds_read_b128 v[114:117], v161 offset:5632
	ds_read_b128 v[176:179], v161 offset:5648
	s_waitcnt vmcnt(38)
; #define RS_LOAD(dst, it0) do { _Pragma("unroll") for (int u = 0; u < 8; ++u) dst[u] = __builtin_nontemporal_load((const f32x4*)(S0 + (size_t)(4 * ((it0) + u)) * DV)); } while (0)
; __device__ __forceinline__ void ret_sample_item(Frame& F, int item) {
;     ...
;     for (int it0 = 0; it0 < 64; it0 += 16) {
;         RS_LOAD(sb, it0 + 8);
;         RS_PROC(sa, it0);
;         { const int itn = it0 + 16 < 64 ? it0 + 16 : it0; RS_LOAD(sa, itn); }
;         RS_PROC(sb, it0 + 8);
;     }
	s_waitcnt lgkmcnt(3)
	v_cndmask_b32_e64 v143, 0, v143, s[6:7]
	v_pk_mul_f32 v[180:181], v[26:27], v[172:173] op_sel:[0,1]
	v_pk_mul_f32 v[192:193], v[28:29], v[172:173] op_sel:[0,1]
	v_mfma_f32_16x16x4_f32 v[110:113], v143, v50, v[110:113]
	v_pk_fma_f32 v[180:181], v[30:31], v[172:173], v[180:181] op_sel_hi:[1,0,1]
	v_pk_fma_f32 v[192:193], v[32:33], v[172:173], v[192:193] op_sel_hi:[1,0,1]
	v_pk_fma_f32 v[180:181], v[22:23], v[174:175], v[180:181] op_sel_hi:[1,0,1]
	v_pk_fma_f32 v[192:193], v[24:25], v[174:175], v[192:193] op_sel_hi:[1,0,1]
	v_mfma_f32_16x16x4_f32 v[106:109], v143, v51, v[106:109]
	v_pk_fma_f32 v[180:181], v[18:19], v[174:175], v[180:181] op_sel:[0,1,0]
	v_pk_fma_f32 v[192:193], v[20:21], v[174:175], v[192:193] op_sel:[0,1,0]
	v_pk_fma_f32 v[180:181], v[14:15], v[232:233], v[180:181] op_sel_hi:[1,0,1]
	v_pk_fma_f32 v[192:193], v[16:17], v[232:233], v[192:193] op_sel_hi:[1,0,1]
	v_mfma_f32_16x16x4_f32 v[102:105], v143, v52, v[102:105]
	v_pk_fma_f32 v[180:181], v[10:11], v[232:233], v[180:181] op_sel:[0,1,0]
	v_pk_fma_f32 v[192:193], v[12:13], v[232:233], v[192:193] op_sel:[0,1,0]
	v_pk_fma_f32 v[180:181], v[6:7], v[234:235], v[180:181] op_sel_hi:[1,0,1]
	v_pk_fma_f32 v[192:193], v[8:9], v[234:235], v[192:193] op_sel_hi:[1,0,1]
	v_mfma_f32_16x16x4_f32 v[98:101], v143, v53, v[98:101]
	v_pk_fma_f32 v[180:181], v[2:3], v[234:235], v[180:181] op_sel:[0,1,0]
	v_pk_fma_f32 v[192:193], v[4:5], v[234:235], v[192:193] op_sel:[0,1,0]
	v_pk_mul_f32 v[180:181], v[146:147], v[180:181]
	v_pk_mul_f32 v[192:193], v[146:147], v[192:193]
	v_pk_fma_f32 v[236:237], v[144:145], v[50:51], v[180:181]
	v_pk_fma_f32 v[238:239], v[144:145], v[52:53], v[192:193]
	global_store_dwordx4 v[150:151], v[236:239], off nt
	v_lshl_add_u64 v[150:151], v[150:151], 0, s[58:59]
	global_load_dwordx4 v[50:53], v[148:149], off nt
	v_lshl_add_u64 v[148:149], v[148:149], 0, s[58:59]
	ds_read_b32 v143, v160 offset:720
	ds_read_b128 v[172:175], v161 offset:5760
	ds_read_b128 v[232:235], v161 offset:5776
	s_waitcnt vmcnt(38)
	s_waitcnt lgkmcnt(3)
	v_cndmask_b32_e64 v141, 0, v141, s[6:7]
	v_pk_mul_f32 v[180:181], v[26:27], v[114:115] op_sel:[0,1]
	v_pk_mul_f32 v[192:193], v[28:29], v[114:115] op_sel:[0,1]
	v_mfma_f32_16x16x4_f32 v[110:113], v141, v46, v[110:113]
	v_pk_fma_f32 v[180:181], v[30:31], v[114:115], v[180:181] op_sel_hi:[1,0,1]
	v_pk_fma_f32 v[192:193], v[32:33], v[114:115], v[192:193] op_sel_hi:[1,0,1]
	v_pk_fma_f32 v[180:181], v[22:23], v[116:117], v[180:181] op_sel_hi:[1,0,1]
	v_pk_fma_f32 v[192:193], v[24:25], v[116:117], v[192:193] op_sel_hi:[1,0,1]
	v_mfma_f32_16x16x4_f32 v[106:109], v141, v47, v[106:109]
	v_pk_fma_f32 v[180:181], v[18:19], v[116:117], v[180:181] op_sel:[0,1,0]
	v_pk_fma_f32 v[192:193], v[20:21], v[116:117], v[192:193] op_sel:[0,1,0]
	v_pk_fma_f32 v[180:181], v[14:15], v[176:177], v[180:181] op_sel_hi:[1,0,1]
	v_pk_fma_f32 v[192:193], v[16:17], v[176:177], v[192:193] op_sel_hi:[1,0,1]
	v_mfma_f32_16x16x4_f32 v[102:105], v141, v48, v[102:105]
	v_pk_fma_f32 v[180:181], v[10:11], v[176:177], v[180:181] op_sel:[0,1,0]
	v_pk_fma_f32 v[192:193], v[12:13], v[176:177], v[192:193] op_sel:[0,1,0]
	v_pk_fma_f32 v[180:181], v[6:7], v[178:179], v[180:181] op_sel_hi:[1,0,1]
	v_pk_fma_f32 v[192:193], v[8:9], v[178:179], v[192:193] op_sel_hi:[1,0,1]
	v_mfma_f32_16x16x4_f32 v[98:101], v141, v49, v[98:101]
	v_pk_fma_f32 v[180:181], v[2:3], v[178:179], v[180:181] op_sel:[0,1,0]
	v_pk_fma_f32 v[192:193], v[4:5], v[178:179], v[192:193] op_sel:[0,1,0]
	v_pk_mul_f32 v[180:181], v[146:147], v[180:181]
	v_pk_mul_f32 v[192:193], v[146:147], v[192:193]
	v_pk_fma_f32 v[236:237], v[144:145], v[46:47], v[180:181]
	v_pk_fma_f32 v[238:239], v[144:145], v[48:49], v[192:193]
	global_store_dwordx4 v[150:151], v[236:239], off nt
	v_lshl_add_u64 v[150:151], v[150:151], 0, s[58:59]
	ds_read_b32 v141, v160 offset:736
	ds_read_b128 v[114:117], v161 offset:5888
	ds_read_b128 v[176:179], v161 offset:5904
	s_waitcnt vmcnt(37)
	s_waitcnt lgkmcnt(3)
	v_cndmask_b32_e64 v143, 0, v143, s[6:7]
	v_pk_mul_f32 v[180:181], v[26:27], v[172:173] op_sel:[0,1]
	v_pk_mul_f32 v[192:193], v[28:29], v[172:173] op_sel:[0,1]
	v_mfma_f32_16x16x4_f32 v[110:113], v143, v42, v[110:113]
	v_pk_fma_f32 v[180:181], v[30:31], v[172:173], v[180:181] op_sel_hi:[1,0,1]
	v_pk_fma_f32 v[192:193], v[32:33], v[172:173], v[192:193] op_sel_hi:[1,0,1]
	v_pk_fma_f32 v[180:181], v[22:23], v[174:175], v[180:181] op_sel_hi:[1,0,1]
	v_pk_fma_f32 v[192:193], v[24:25], v[174:175], v[192:193] op_sel_hi:[1,0,1]
	v_mfma_f32_16x16x4_f32 v[106:109], v143, v43, v[106:109]
	v_pk_fma_f32 v[180:181], v[18:19], v[174:175], v[180:181] op_sel:[0,1,0]
	v_pk_fma_f32 v[192:193], v[20:21], v[174:175], v[192:193] op_sel:[0,1,0]
	v_pk_fma_f32 v[180:181], v[14:15], v[232:233], v[180:181] op_sel_hi:[1,0,1]
	v_pk_fma_f32 v[192:193], v[16:17], v[232:233], v[192:193] op_sel_hi:[1,0,1]
	v_mfma_f32_16x16x4_f32 v[102:105], v143, v44, v[102:105]
	v_pk_fma_f32 v[180:181], v[10:11], v[232:233], v[180:181] op_sel:[0,1,0]
	v_pk_fma_f32 v[192:193], v[12:13], v[232:233], v[192:193] op_sel:[0,1,0]
	v_pk_fma_f32 v[180:181], v[6:7], v[234:235], v[180:181] op_sel_hi:[1,0,1]
	v_pk_fma_f32 v[192:193], v[8:9], v[234:235], v[192:193] op_sel_hi:[1,0,1]
	v_mfma_f32_16x16x4_f32 v[98:101], v143, v45, v[98:101]
	v_pk_fma_f32 v[180:181], v[2:3], v[234:235], v[180:181] op_sel:[0,1,0]
	v_pk_fma_f32 v[192:193], v[4:5], v[234:235], v[192:193] op_sel:[0,1,0]
	v_pk_mul_f32 v[180:181], v[146:147], v[180:181]
	v_pk_mul_f32 v[192:193], v[146:147], v[192:193]
	v_pk_fma_f32 v[236:237], v[144:145], v[42:43], v[180:181]
	v_pk_fma_f32 v[238:239], v[144:145], v[44:45], v[192:193]
	global_store_dwordx4 v[150:151], v[236:239], off nt
	v_lshl_add_u64 v[150:151], v[150:151], 0, s[58:59]
	ds_read_b32 v143, v160 offset:752
	ds_read_b128 v[172:175], v161 offset:6016
	ds_read_b128 v[232:235], v161 offset:6032
	s_waitcnt vmcnt(36)
; #define RS_LOAD(dst, it0) do { _Pragma("unroll") for (int u = 0; u < 8; ++u) dst[u] = __builtin_nontemporal_load((const f32x4*)(S0 + (size_t)(4 * ((it0) + u)) * DV)); } while (0)
; __device__ __forceinline__ void ret_sample_item(Frame& F, int item) {
;     ...
;     for (int it0 = 0; it0 < 64; it0 += 16) {
;         RS_LOAD(sb, it0 + 8);
;         RS_PROC(sa, it0);
;         { const int itn = it0 + 16 < 64 ? it0 + 16 : it0; RS_LOAD(sa, itn); }
;         RS_PROC(sb, it0 + 8);
;     }
	s_waitcnt lgkmcnt(3)
	v_cndmask_b32_e64 v141, 0, v141, s[6:7]
	v_pk_mul_f32 v[180:181], v[26:27], v[114:115] op_sel:[0,1]
	v_pk_mul_f32 v[192:193], v[28:29], v[114:115] op_sel:[0,1]
	v_mfma_f32_16x16x4_f32 v[110:113], v141, v38, v[110:113]
	v_pk_fma_f32 v[180:181], v[30:31], v[114:115], v[180:181] op_sel_hi:[1,0,1]
	v_pk_fma_f32 v[192:193], v[32:33], v[114:115], v[192:193] op_sel_hi:[1,0,1]
	v_pk_fma_f32 v[180:181], v[22:23], v[116:117], v[180:181] op_sel_hi:[1,0,1]
	v_pk_fma_f32 v[192:193], v[24:25], v[116:117], v[192:193] op_sel_hi:[1,0,1]
	v_mfma_f32_16x16x4_f32 v[106:109], v141, v39, v[106:109]
	v_pk_fma_f32 v[180:181], v[18:19], v[116:117], v[180:181] op_sel:[0,1,0]
	v_pk_fma_f32 v[192:193], v[20:21], v[116:117], v[192:193] op_sel:[0,1,0]
	v_pk_fma_f32 v[180:181], v[14:15], v[176:177], v[180:181] op_sel_hi:[1,0,1]
	v_pk_fma_f32 v[192:193], v[16:17], v[176:177], v[192:193] op_sel_hi:[1,0,1]
	v_mfma_f32_16x16x4_f32 v[102:105], v141, v40, v[102:105]
	v_pk_fma_f32 v[180:181], v[10:11], v[176:177], v[180:181] op_sel:[0,1,0]
	v_pk_fma_f32 v[192:193], v[12:13], v[176:177], v[192:193] op_sel:[0,1,0]
	v_pk_fma_f32 v[180:181], v[6:7], v[178:179], v[180:181] op_sel_hi:[1,0,1]
	v_pk_fma_f32 v[192:193], v[8:9], v[178:179], v[192:193] op_sel_hi:[1,0,1]
	v_mfma_f32_16x16x4_f32 v[98:101], v141, v41, v[98:101]
	v_pk_fma_f32 v[180:181], v[2:3], v[178:179], v[180:181] op_sel:[0,1,0]
	v_pk_fma_f32 v[192:193], v[4:5], v[178:179], v[192:193] op_sel:[0,1,0]
	v_pk_mul_f32 v[180:181], v[146:147], v[180:181]
	v_pk_mul_f32 v[192:193], v[146:147], v[192:193]
	v_pk_fma_f32 v[236:237], v[144:145], v[38:39], v[180:181]
	v_pk_fma_f32 v[238:239], v[144:145], v[40:41], v[192:193]
	global_store_dwordx4 v[150:151], v[236:239], off nt
	v_lshl_add_u64 v[150:151], v[150:151], 0, s[58:59]
	ds_read_b32 v141, v160 offset:768
	ds_read_b128 v[114:117], v161 offset:6144
	ds_read_b128 v[176:179], v161 offset:6160
	s_waitcnt vmcnt(35)
	s_waitcnt lgkmcnt(3)
	v_cndmask_b32_e64 v143, 0, v143, s[6:7]
	v_pk_mul_f32 v[180:181], v[26:27], v[172:173] op_sel:[0,1]
	v_pk_mul_f32 v[192:193], v[28:29], v[172:173] op_sel:[0,1]
	v_mfma_f32_16x16x4_f32 v[110:113], v143, v34, v[110:113]
	v_pk_fma_f32 v[180:181], v[30:31], v[172:173], v[180:181] op_sel_hi:[1,0,1]
	v_pk_fma_f32 v[192:193], v[32:33], v[172:173], v[192:193] op_sel_hi:[1,0,1]
	v_pk_fma_f32 v[180:181], v[22:23], v[174:175], v[180:181] op_sel_hi:[1,0,1]
	v_pk_fma_f32 v[192:193], v[24:25], v[174:175], v[192:193] op_sel_hi:[1,0,1]
	v_mfma_f32_16x16x4_f32 v[106:109], v143, v35, v[106:109]
	v_pk_fma_f32 v[180:181], v[18:19], v[174:175], v[180:181] op_sel:[0,1,0]
	v_pk_fma_f32 v[192:193], v[20:21], v[174:175], v[192:193] op_sel:[0,1,0]
	v_pk_fma_f32 v[180:181], v[14:15], v[232:233], v[180:181] op_sel_hi:[1,0,1]
	v_pk_fma_f32 v[192:193], v[16:17], v[232:233], v[192:193] op_sel_hi:[1,0,1]
	v_mfma_f32_16x16x4_f32 v[102:105], v143, v36, v[102:105]
	v_pk_fma_f32 v[180:181], v[10:11], v[232:233], v[180:181] op_sel:[0,1,0]
	v_pk_fma_f32 v[192:193], v[12:13], v[232:233], v[192:193] op_sel:[0,1,0]
	v_pk_fma_f32 v[180:181], v[6:7], v[234:235], v[180:181] op_sel_hi:[1,0,1]
	v_pk_fma_f32 v[192:193], v[8:9], v[234:235], v[192:193] op_sel_hi:[1,0,1]
	v_mfma_f32_16x16x4_f32 v[98:101], v143, v37, v[98:101]
	v_pk_fma_f32 v[180:181], v[2:3], v[234:235], v[180:181] op_sel:[0,1,0]
	v_pk_fma_f32 v[192:193], v[4:5], v[234:235], v[192:193] op_sel:[0,1,0]
	v_pk_mul_f32 v[180:181], v[146:147], v[180:181]
	v_pk_mul_f32 v[192:193], v[146:147], v[192:193]
	v_pk_fma_f32 v[236:237], v[144:145], v[34:35], v[180:181]
	v_pk_fma_f32 v[238:239], v[144:145], v[36:37], v[192:193]
	global_store_dwordx4 v[150:151], v[236:239], off nt
	v_lshl_add_u64 v[150:151], v[150:151], 0, s[58:59]
	ds_read_b32 v143, v160 offset:784
	ds_read_b128 v[172:175], v161 offset:6272
	ds_read_b128 v[232:235], v161 offset:6288
	s_waitcnt vmcnt(34)
	s_waitcnt lgkmcnt(3)
	v_cndmask_b32_e64 v141, 0, v141, s[6:7]
	v_pk_mul_f32 v[180:181], v[26:27], v[114:115] op_sel:[0,1]
	v_pk_mul_f32 v[192:193], v[28:29], v[114:115] op_sel:[0,1]
	v_mfma_f32_16x16x4_f32 v[110:113], v141, v58, v[110:113]
	v_pk_fma_f32 v[180:181], v[30:31], v[114:115], v[180:181] op_sel_hi:[1,0,1]
	v_pk_fma_f32 v[192:193], v[32:33], v[114:115], v[192:193] op_sel_hi:[1,0,1]
	v_pk_fma_f32 v[180:181], v[22:23], v[116:117], v[180:181] op_sel_hi:[1,0,1]
	v_pk_fma_f32 v[192:193], v[24:25], v[116:117], v[192:193] op_sel_hi:[1,0,1]
	v_mfma_f32_16x16x4_f32 v[106:109], v141, v59, v[106:109]
	v_pk_fma_f32 v[180:181], v[18:19], v[116:117], v[180:181] op_sel:[0,1,0]
	v_pk_fma_f32 v[192:193], v[20:21], v[116:117], v[192:193] op_sel:[0,1,0]
	v_pk_fma_f32 v[180:181], v[14:15], v[176:177], v[180:181] op_sel_hi:[1,0,1]
	v_pk_fma_f32 v[192:193], v[16:17], v[176:177], v[192:193] op_sel_hi:[1,0,1]
	v_mfma_f32_16x16x4_f32 v[102:105], v141, v60, v[102:105]
	v_pk_fma_f32 v[180:181], v[10:11], v[176:177], v[180:181] op_sel:[0,1,0]
	v_pk_fma_f32 v[192:193], v[12:13], v[176:177], v[192:193] op_sel:[0,1,0]
	v_pk_fma_f32 v[180:181], v[6:7], v[178:179], v[180:181] op_sel_hi:[1,0,1]
	v_pk_fma_f32 v[192:193], v[8:9], v[178:179], v[192:193] op_sel_hi:[1,0,1]
	v_mfma_f32_16x16x4_f32 v[98:101], v141, v61, v[98:101]
	v_pk_fma_f32 v[180:181], v[2:3], v[178:179], v[180:181] op_sel:[0,1,0]
	v_pk_fma_f32 v[192:193], v[4:5], v[178:179], v[192:193] op_sel:[0,1,0]
	v_pk_mul_f32 v[180:181], v[146:147], v[180:181]
	v_pk_mul_f32 v[192:193], v[146:147], v[192:193]
	v_pk_fma_f32 v[236:237], v[144:145], v[58:59], v[180:181]
	v_pk_fma_f32 v[238:239], v[144:145], v[60:61], v[192:193]
	global_store_dwordx4 v[150:151], v[236:239], off nt
	v_lshl_add_u64 v[150:151], v[150:151], 0, s[58:59]
	ds_read_b32 v141, v160 offset:800
	ds_read_b128 v[114:117], v161 offset:6400
	ds_read_b128 v[176:179], v161 offset:6416
	s_waitcnt vmcnt(33)
; #define RS_LOAD(dst, it0) do { _Pragma("unroll") for (int u = 0; u < 8; ++u) dst[u] = __builtin_nontemporal_load((const f32x4*)(S0 + (size_t)(4 * ((it0) + u)) * DV)); } while (0)
; __device__ __forceinline__ void ret_sample_item(Frame& F, int item) {
;     ...
;     for (int it0 = 0; it0 < 64; it0 += 16) {
;         RS_LOAD(sb, it0 + 8);
;         RS_PROC(sa, it0);
;         { const int itn = it0 + 16 < 64 ? it0 + 16 : it0; RS_LOAD(sa, itn); }
;         RS_PROC(sb, it0 + 8);
;     }
	s_waitcnt lgkmcnt(3)
	v_cndmask_b32_e64 v143, 0, v143, s[6:7]
	v_pk_mul_f32 v[180:181], v[26:27], v[172:173] op_sel:[0,1]
	v_pk_mul_f32 v[192:193], v[28:29], v[172:173] op_sel:[0,1]
	v_mfma_f32_16x16x4_f32 v[110:113], v143, v66, v[110:113]
	v_pk_fma_f32 v[180:181], v[30:31], v[172:173], v[180:181] op_sel_hi:[1,0,1]
	v_pk_fma_f32 v[192:193], v[32:33], v[172:173], v[192:193] op_sel_hi:[1,0,1]
	v_pk_fma_f32 v[180:181], v[22:23], v[174:175], v[180:181] op_sel_hi:[1,0,1]
	v_pk_fma_f32 v[192:193], v[24:25], v[174:175], v[192:193] op_sel_hi:[1,0,1]
	v_mfma_f32_16x16x4_f32 v[106:109], v143, v67, v[106:109]
	v_pk_fma_f32 v[180:181], v[18:19], v[174:175], v[180:181] op_sel:[0,1,0]
	v_pk_fma_f32 v[192:193], v[20:21], v[174:175], v[192:193] op_sel:[0,1,0]
	v_pk_fma_f32 v[180:181], v[14:15], v[232:233], v[180:181] op_sel_hi:[1,0,1]
	v_pk_fma_f32 v[192:193], v[16:17], v[232:233], v[192:193] op_sel_hi:[1,0,1]
	v_mfma_f32_16x16x4_f32 v[102:105], v143, v68, v[102:105]
	v_pk_fma_f32 v[180:181], v[10:11], v[232:233], v[180:181] op_sel:[0,1,0]
	v_pk_fma_f32 v[192:193], v[12:13], v[232:233], v[192:193] op_sel:[0,1,0]
	v_pk_fma_f32 v[180:181], v[6:7], v[234:235], v[180:181] op_sel_hi:[1,0,1]
	v_pk_fma_f32 v[192:193], v[8:9], v[234:235], v[192:193] op_sel_hi:[1,0,1]
	v_mfma_f32_16x16x4_f32 v[98:101], v143, v69, v[98:101]
	v_pk_fma_f32 v[180:181], v[2:3], v[234:235], v[180:181] op_sel:[0,1,0]
	v_pk_fma_f32 v[192:193], v[4:5], v[234:235], v[192:193] op_sel:[0,1,0]
	v_pk_mul_f32 v[180:181], v[146:147], v[180:181]
	v_pk_mul_f32 v[192:193], v[146:147], v[192:193]
	v_pk_fma_f32 v[236:237], v[144:145], v[66:67], v[180:181]
	v_pk_fma_f32 v[238:239], v[144:145], v[68:69], v[192:193]
	global_store_dwordx4 v[150:151], v[236:239], off nt
	v_lshl_add_u64 v[150:151], v[150:151], 0, s[58:59]
	ds_read_b32 v143, v160 offset:816
	ds_read_b128 v[172:175], v161 offset:6528
	ds_read_b128 v[232:235], v161 offset:6544
	s_waitcnt vmcnt(32)
	s_waitcnt lgkmcnt(3)
	v_cndmask_b32_e64 v141, 0, v141, s[6:7]
	v_pk_mul_f32 v[180:181], v[26:27], v[114:115] op_sel:[0,1]
	v_pk_mul_f32 v[192:193], v[28:29], v[114:115] op_sel:[0,1]
	v_mfma_f32_16x16x4_f32 v[110:113], v141, v74, v[110:113]
	v_pk_fma_f32 v[180:181], v[30:31], v[114:115], v[180:181] op_sel_hi:[1,0,1]
	v_pk_fma_f32 v[192:193], v[32:33], v[114:115], v[192:193] op_sel_hi:[1,0,1]
	v_pk_fma_f32 v[180:181], v[22:23], v[116:117], v[180:181] op_sel_hi:[1,0,1]
	v_pk_fma_f32 v[192:193], v[24:25], v[116:117], v[192:193] op_sel_hi:[1,0,1]
	v_mfma_f32_16x16x4_f32 v[106:109], v141, v75, v[106:109]
	v_pk_fma_f32 v[180:181], v[18:19], v[116:117], v[180:181] op_sel:[0,1,0]
	v_pk_fma_f32 v[192:193], v[20:21], v[116:117], v[192:193] op_sel:[0,1,0]
	v_pk_fma_f32 v[180:181], v[14:15], v[176:177], v[180:181] op_sel_hi:[1,0,1]
	v_pk_fma_f32 v[192:193], v[16:17], v[176:177], v[192:193] op_sel_hi:[1,0,1]
	v_mfma_f32_16x16x4_f32 v[102:105], v141, v76, v[102:105]
	v_pk_fma_f32 v[180:181], v[10:11], v[176:177], v[180:181] op_sel:[0,1,0]
	v_pk_fma_f32 v[192:193], v[12:13], v[176:177], v[192:193] op_sel:[0,1,0]
	v_pk_fma_f32 v[180:181], v[6:7], v[178:179], v[180:181] op_sel_hi:[1,0,1]
	v_pk_fma_f32 v[192:193], v[8:9], v[178:179], v[192:193] op_sel_hi:[1,0,1]
	v_mfma_f32_16x16x4_f32 v[98:101], v141, v77, v[98:101]
	v_pk_fma_f32 v[180:181], v[2:3], v[178:179], v[180:181] op_sel:[0,1,0]
	v_pk_fma_f32 v[192:193], v[4:5], v[178:179], v[192:193] op_sel:[0,1,0]
	v_pk_mul_f32 v[180:181], v[146:147], v[180:181]
	v_pk_mul_f32 v[192:193], v[146:147], v[192:193]
	v_pk_fma_f32 v[236:237], v[144:145], v[74:75], v[180:181]
	v_pk_fma_f32 v[238:239], v[144:145], v[76:77], v[192:193]
	global_store_dwordx4 v[150:151], v[236:239], off nt
	v_lshl_add_u64 v[150:151], v[150:151], 0, s[58:59]
	ds_read_b32 v141, v160 offset:832
	ds_read_b128 v[114:117], v161 offset:6656
	ds_read_b128 v[176:179], v161 offset:6672
	s_waitcnt vmcnt(31)
	s_waitcnt lgkmcnt(3)
	v_cndmask_b32_e64 v143, 0, v143, s[6:7]
	v_pk_mul_f32 v[180:181], v[26:27], v[172:173] op_sel:[0,1]
	v_pk_mul_f32 v[192:193], v[28:29], v[172:173] op_sel:[0,1]
	v_mfma_f32_16x16x4_f32 v[110:113], v143, v78, v[110:113]
	v_pk_fma_f32 v[180:181], v[30:31], v[172:173], v[180:181] op_sel_hi:[1,0,1]
	v_pk_fma_f32 v[192:193], v[32:33], v[172:173], v[192:193] op_sel_hi:[1,0,1]
	v_pk_fma_f32 v[180:181], v[22:23], v[174:175], v[180:181] op_sel_hi:[1,0,1]
	v_pk_fma_f32 v[192:193], v[24:25], v[174:175], v[192:193] op_sel_hi:[1,0,1]
	v_mfma_f32_16x16x4_f32 v[106:109], v143, v79, v[106:109]
	v_pk_fma_f32 v[180:181], v[18:19], v[174:175], v[180:181] op_sel:[0,1,0]
	v_pk_fma_f32 v[192:193], v[20:21], v[174:175], v[192:193] op_sel:[0,1,0]
	v_pk_fma_f32 v[180:181], v[14:15], v[232:233], v[180:181] op_sel_hi:[1,0,1]
	v_pk_fma_f32 v[192:193], v[16:17], v[232:233], v[192:193] op_sel_hi:[1,0,1]
	v_mfma_f32_16x16x4_f32 v[102:105], v143, v80, v[102:105]
	v_pk_fma_f32 v[180:181], v[10:11], v[232:233], v[180:181] op_sel:[0,1,0]
	v_pk_fma_f32 v[192:193], v[12:13], v[232:233], v[192:193] op_sel:[0,1,0]
	v_pk_fma_f32 v[180:181], v[6:7], v[234:235], v[180:181] op_sel_hi:[1,0,1]
	v_pk_fma_f32 v[192:193], v[8:9], v[234:235], v[192:193] op_sel_hi:[1,0,1]
	v_mfma_f32_16x16x4_f32 v[98:101], v143, v81, v[98:101]
	v_pk_fma_f32 v[180:181], v[2:3], v[234:235], v[180:181] op_sel:[0,1,0]
	v_pk_fma_f32 v[192:193], v[4:5], v[234:235], v[192:193] op_sel:[0,1,0]
	v_pk_mul_f32 v[180:181], v[146:147], v[180:181]
	v_pk_mul_f32 v[192:193], v[146:147], v[192:193]
	v_pk_fma_f32 v[236:237], v[144:145], v[78:79], v[180:181]
	v_pk_fma_f32 v[238:239], v[144:145], v[80:81], v[192:193]
	global_store_dwordx4 v[150:151], v[236:239], off nt
	v_lshl_add_u64 v[150:151], v[150:151], 0, s[58:59]
	ds_read_b32 v143, v160 offset:848
	ds_read_b128 v[172:175], v161 offset:6784
	ds_read_b128 v[232:235], v161 offset:6800
	s_waitcnt vmcnt(30)
; #define RS_LOAD(dst, it0) do { _Pragma("unroll") for (int u = 0; u < 8; ++u) dst[u] = __builtin_nontemporal_load((const f32x4*)(S0 + (size_t)(4 * ((it0) + u)) * DV)); } while (0)
; __device__ __forceinline__ void ret_sample_item(Frame& F, int item) {
;     ...
;     for (int it0 = 0; it0 < 64; it0 += 16) {
;         RS_LOAD(sb, it0 + 8);
;         RS_PROC(sa, it0);
;         { const int itn = it0 + 16 < 64 ? it0 + 16 : it0; RS_LOAD(sa, itn); }
;         RS_PROC(sb, it0 + 8);
;     }
	s_waitcnt lgkmcnt(3)
	v_cndmask_b32_e64 v141, 0, v141, s[6:7]
	v_pk_mul_f32 v[180:181], v[26:27], v[114:115] op_sel:[0,1]
	v_pk_mul_f32 v[192:193], v[28:29], v[114:115] op_sel:[0,1]
	v_mfma_f32_16x16x4_f32 v[110:113], v141, v82, v[110:113]
	v_pk_fma_f32 v[180:181], v[30:31], v[114:115], v[180:181] op_sel_hi:[1,0,1]
	v_pk_fma_f32 v[192:193], v[32:33], v[114:115], v[192:193] op_sel_hi:[1,0,1]
	v_pk_fma_f32 v[180:181], v[22:23], v[116:117], v[180:181] op_sel_hi:[1,0,1]
	v_pk_fma_f32 v[192:193], v[24:25], v[116:117], v[192:193] op_sel_hi:[1,0,1]
	v_mfma_f32_16x16x4_f32 v[106:109], v141, v83, v[106:109]
	v_pk_fma_f32 v[180:181], v[18:19], v[116:117], v[180:181] op_sel:[0,1,0]
	v_pk_fma_f32 v[192:193], v[20:21], v[116:117], v[192:193] op_sel:[0,1,0]
	v_pk_fma_f32 v[180:181], v[14:15], v[176:177], v[180:181] op_sel_hi:[1,0,1]
	v_pk_fma_f32 v[192:193], v[16:17], v[176:177], v[192:193] op_sel_hi:[1,0,1]
	v_mfma_f32_16x16x4_f32 v[102:105], v141, v84, v[102:105]
	v_pk_fma_f32 v[180:181], v[10:11], v[176:177], v[180:181] op_sel:[0,1,0]
	v_pk_fma_f32 v[192:193], v[12:13], v[176:177], v[192:193] op_sel:[0,1,0]
	v_pk_fma_f32 v[180:181], v[6:7], v[178:179], v[180:181] op_sel_hi:[1,0,1]
	v_pk_fma_f32 v[192:193], v[8:9], v[178:179], v[192:193] op_sel_hi:[1,0,1]
	v_mfma_f32_16x16x4_f32 v[98:101], v141, v85, v[98:101]
	v_pk_fma_f32 v[180:181], v[2:3], v[178:179], v[180:181] op_sel:[0,1,0]
	v_pk_fma_f32 v[192:193], v[4:5], v[178:179], v[192:193] op_sel:[0,1,0]
	v_pk_mul_f32 v[180:181], v[146:147], v[180:181]
	v_pk_mul_f32 v[192:193], v[146:147], v[192:193]
	v_pk_fma_f32 v[236:237], v[144:145], v[82:83], v[180:181]
	v_pk_fma_f32 v[238:239], v[144:145], v[84:85], v[192:193]
	global_store_dwordx4 v[150:151], v[236:239], off nt
	v_lshl_add_u64 v[150:151], v[150:151], 0, s[58:59]
	ds_read_b32 v141, v160 offset:864
	ds_read_b128 v[114:117], v161 offset:6912
	ds_read_b128 v[176:179], v161 offset:6928
	s_waitcnt vmcnt(29)
	s_waitcnt lgkmcnt(3)
	v_cndmask_b32_e64 v143, 0, v143, s[6:7]
	v_pk_mul_f32 v[180:181], v[26:27], v[172:173] op_sel:[0,1]
	v_pk_mul_f32 v[192:193], v[28:29], v[172:173] op_sel:[0,1]
	v_mfma_f32_16x16x4_f32 v[110:113], v143, v86, v[110:113]
	v_pk_fma_f32 v[180:181], v[30:31], v[172:173], v[180:181] op_sel_hi:[1,0,1]
	v_pk_fma_f32 v[192:193], v[32:33], v[172:173], v[192:193] op_sel_hi:[1,0,1]
	v_pk_fma_f32 v[180:181], v[22:23], v[174:175], v[180:181] op_sel_hi:[1,0,1]
	v_pk_fma_f32 v[192:193], v[24:25], v[174:175], v[192:193] op_sel_hi:[1,0,1]
	v_mfma_f32_16x16x4_f32 v[106:109], v143, v87, v[106:109]
	v_pk_fma_f32 v[180:181], v[18:19], v[174:175], v[180:181] op_sel:[0,1,0]
	v_pk_fma_f32 v[192:193], v[20:21], v[174:175], v[192:193] op_sel:[0,1,0]
	v_pk_fma_f32 v[180:181], v[14:15], v[232:233], v[180:181] op_sel_hi:[1,0,1]
	v_pk_fma_f32 v[192:193], v[16:17], v[232:233], v[192:193] op_sel_hi:[1,0,1]
	v_mfma_f32_16x16x4_f32 v[102:105], v143, v88, v[102:105]
	v_pk_fma_f32 v[180:181], v[10:11], v[232:233], v[180:181] op_sel:[0,1,0]
	v_pk_fma_f32 v[192:193], v[12:13], v[232:233], v[192:193] op_sel:[0,1,0]
	v_pk_fma_f32 v[180:181], v[6:7], v[234:235], v[180:181] op_sel_hi:[1,0,1]
	v_pk_fma_f32 v[192:193], v[8:9], v[234:235], v[192:193] op_sel_hi:[1,0,1]
	v_mfma_f32_16x16x4_f32 v[98:101], v143, v89, v[98:101]
	v_pk_fma_f32 v[180:181], v[2:3], v[234:235], v[180:181] op_sel:[0,1,0]
	v_pk_fma_f32 v[192:193], v[4:5], v[234:235], v[192:193] op_sel:[0,1,0]
	v_pk_mul_f32 v[180:181], v[146:147], v[180:181]
	v_pk_mul_f32 v[192:193], v[146:147], v[192:193]
	v_pk_fma_f32 v[236:237], v[144:145], v[86:87], v[180:181]
	v_pk_fma_f32 v[238:239], v[144:145], v[88:89], v[192:193]
	global_store_dwordx4 v[150:151], v[236:239], off nt
	v_lshl_add_u64 v[150:151], v[150:151], 0, s[58:59]
	ds_read_b32 v143, v160 offset:880
	ds_read_b128 v[172:175], v161 offset:7040
	ds_read_b128 v[232:235], v161 offset:7056
	s_waitcnt vmcnt(28)
	s_waitcnt lgkmcnt(3)
	v_cndmask_b32_e64 v141, 0, v141, s[6:7]
	v_pk_mul_f32 v[180:181], v[26:27], v[114:115] op_sel:[0,1]
	v_pk_mul_f32 v[192:193], v[28:29], v[114:115] op_sel:[0,1]
	v_mfma_f32_16x16x4_f32 v[110:113], v141, v90, v[110:113]
	v_pk_fma_f32 v[180:181], v[30:31], v[114:115], v[180:181] op_sel_hi:[1,0,1]
	v_pk_fma_f32 v[192:193], v[32:33], v[114:115], v[192:193] op_sel_hi:[1,0,1]
	v_pk_fma_f32 v[180:181], v[22:23], v[116:117], v[180:181] op_sel_hi:[1,0,1]
	v_pk_fma_f32 v[192:193], v[24:25], v[116:117], v[192:193] op_sel_hi:[1,0,1]
	v_mfma_f32_16x16x4_f32 v[106:109], v141, v91, v[106:109]
	v_pk_fma_f32 v[180:181], v[18:19], v[116:117], v[180:181] op_sel:[0,1,0]
	v_pk_fma_f32 v[192:193], v[20:21], v[116:117], v[192:193] op_sel:[0,1,0]
	v_pk_fma_f32 v[180:181], v[14:15], v[176:177], v[180:181] op_sel_hi:[1,0,1]
	v_pk_fma_f32 v[192:193], v[16:17], v[176:177], v[192:193] op_sel_hi:[1,0,1]
	v_mfma_f32_16x16x4_f32 v[102:105], v141, v92, v[102:105]
	v_pk_fma_f32 v[180:181], v[10:11], v[176:177], v[180:181] op_sel:[0,1,0]
	v_pk_fma_f32 v[192:193], v[12:13], v[176:177], v[192:193] op_sel:[0,1,0]
	v_pk_fma_f32 v[180:181], v[6:7], v[178:179], v[180:181] op_sel_hi:[1,0,1]
	v_pk_fma_f32 v[192:193], v[8:9], v[178:179], v[192:193] op_sel_hi:[1,0,1]
	v_mfma_f32_16x16x4_f32 v[98:101], v141, v93, v[98:101]
	v_pk_fma_f32 v[180:181], v[2:3], v[178:179], v[180:181] op_sel:[0,1,0]
	v_pk_fma_f32 v[192:193], v[4:5], v[178:179], v[192:193] op_sel:[0,1,0]
	v_pk_mul_f32 v[180:181], v[146:147], v[180:181]
	v_pk_mul_f32 v[192:193], v[146:147], v[192:193]
	v_pk_fma_f32 v[236:237], v[144:145], v[90:91], v[180:181]
	v_pk_fma_f32 v[238:239], v[144:145], v[92:93], v[192:193]
	global_store_dwordx4 v[150:151], v[236:239], off nt
	v_lshl_add_u64 v[150:151], v[150:151], 0, s[58:59]
	ds_read_b32 v141, v160 offset:896
	ds_read_b128 v[114:117], v161 offset:7168
	ds_read_b128 v[176:179], v161 offset:7184
	s_waitcnt vmcnt(27)
; #define RS_LOAD(dst, it0) do { _Pragma("unroll") for (int u = 0; u < 8; ++u) dst[u] = __builtin_nontemporal_load((const f32x4*)(S0 + (size_t)(4 * ((it0) + u)) * DV)); } while (0)
; __device__ __forceinline__ void ret_sample_item(Frame& F, int item) {
;     ...
;     for (int it0 = 0; it0 < 64; it0 += 16) {
;         RS_LOAD(sb, it0 + 8);
;         RS_PROC(sa, it0);
;         { const int itn = it0 + 16 < 64 ? it0 + 16 : it0; RS_LOAD(sa, itn); }
;         RS_PROC(sb, it0 + 8);
;     }
	s_waitcnt lgkmcnt(3)
	v_cndmask_b32_e64 v143, 0, v143, s[6:7]
	v_pk_mul_f32 v[180:181], v[26:27], v[172:173] op_sel:[0,1]
	v_pk_mul_f32 v[192:193], v[28:29], v[172:173] op_sel:[0,1]
	v_mfma_f32_16x16x4_f32 v[110:113], v143, v94, v[110:113]
	v_pk_fma_f32 v[180:181], v[30:31], v[172:173], v[180:181] op_sel_hi:[1,0,1]
	v_pk_fma_f32 v[192:193], v[32:33], v[172:173], v[192:193] op_sel_hi:[1,0,1]
	v_pk_fma_f32 v[180:181], v[22:23], v[174:175], v[180:181] op_sel_hi:[1,0,1]
	v_pk_fma_f32 v[192:193], v[24:25], v[174:175], v[192:193] op_sel_hi:[1,0,1]
	v_mfma_f32_16x16x4_f32 v[106:109], v143, v95, v[106:109]
	v_pk_fma_f32 v[180:181], v[18:19], v[174:175], v[180:181] op_sel:[0,1,0]
	v_pk_fma_f32 v[192:193], v[20:21], v[174:175], v[192:193] op_sel:[0,1,0]
	v_pk_fma_f32 v[180:181], v[14:15], v[232:233], v[180:181] op_sel_hi:[1,0,1]
	v_pk_fma_f32 v[192:193], v[16:17], v[232:233], v[192:193] op_sel_hi:[1,0,1]
	v_mfma_f32_16x16x4_f32 v[102:105], v143, v96, v[102:105]
	v_pk_fma_f32 v[180:181], v[10:11], v[232:233], v[180:181] op_sel:[0,1,0]
	v_pk_fma_f32 v[192:193], v[12:13], v[232:233], v[192:193] op_sel:[0,1,0]
	v_pk_fma_f32 v[180:181], v[6:7], v[234:235], v[180:181] op_sel_hi:[1,0,1]
	v_pk_fma_f32 v[192:193], v[8:9], v[234:235], v[192:193] op_sel_hi:[1,0,1]
	v_mfma_f32_16x16x4_f32 v[98:101], v143, v97, v[98:101]
	v_pk_fma_f32 v[180:181], v[2:3], v[234:235], v[180:181] op_sel:[0,1,0]
	v_pk_fma_f32 v[192:193], v[4:5], v[234:235], v[192:193] op_sel:[0,1,0]
	v_pk_mul_f32 v[180:181], v[146:147], v[180:181]
	v_pk_mul_f32 v[192:193], v[146:147], v[192:193]
	v_pk_fma_f32 v[236:237], v[144:145], v[94:95], v[180:181]
	v_pk_fma_f32 v[238:239], v[144:145], v[96:97], v[192:193]
	global_store_dwordx4 v[150:151], v[236:239], off nt
	v_lshl_add_u64 v[150:151], v[150:151], 0, s[58:59]
	ds_read_b32 v143, v160 offset:912
	ds_read_b128 v[172:175], v161 offset:7296
	ds_read_b128 v[232:235], v161 offset:7312
	s_waitcnt vmcnt(26)
	s_waitcnt lgkmcnt(3)
	v_cndmask_b32_e64 v141, 0, v141, s[6:7]
	v_pk_mul_f32 v[180:181], v[26:27], v[114:115] op_sel:[0,1]
	v_pk_mul_f32 v[192:193], v[28:29], v[114:115] op_sel:[0,1]
	v_mfma_f32_16x16x4_f32 v[110:113], v141, v212, v[110:113]
	v_pk_fma_f32 v[180:181], v[30:31], v[114:115], v[180:181] op_sel_hi:[1,0,1]
	v_pk_fma_f32 v[192:193], v[32:33], v[114:115], v[192:193] op_sel_hi:[1,0,1]
	v_pk_fma_f32 v[180:181], v[22:23], v[116:117], v[180:181] op_sel_hi:[1,0,1]
	v_pk_fma_f32 v[192:193], v[24:25], v[116:117], v[192:193] op_sel_hi:[1,0,1]
	v_mfma_f32_16x16x4_f32 v[106:109], v141, v213, v[106:109]
	v_pk_fma_f32 v[180:181], v[18:19], v[116:117], v[180:181] op_sel:[0,1,0]
	v_pk_fma_f32 v[192:193], v[20:21], v[116:117], v[192:193] op_sel:[0,1,0]
	v_pk_fma_f32 v[180:181], v[14:15], v[176:177], v[180:181] op_sel_hi:[1,0,1]
	v_pk_fma_f32 v[192:193], v[16:17], v[176:177], v[192:193] op_sel_hi:[1,0,1]
	v_mfma_f32_16x16x4_f32 v[102:105], v141, v214, v[102:105]
	v_pk_fma_f32 v[180:181], v[10:11], v[176:177], v[180:181] op_sel:[0,1,0]
	v_pk_fma_f32 v[192:193], v[12:13], v[176:177], v[192:193] op_sel:[0,1,0]
	v_pk_fma_f32 v[180:181], v[6:7], v[178:179], v[180:181] op_sel_hi:[1,0,1]
	v_pk_fma_f32 v[192:193], v[8:9], v[178:179], v[192:193] op_sel_hi:[1,0,1]
	v_mfma_f32_16x16x4_f32 v[98:101], v141, v215, v[98:101]
	v_pk_fma_f32 v[180:181], v[2:3], v[178:179], v[180:181] op_sel:[0,1,0]
	v_pk_fma_f32 v[192:193], v[4:5], v[178:179], v[192:193] op_sel:[0,1,0]
	v_pk_mul_f32 v[180:181], v[146:147], v[180:181]
	v_pk_mul_f32 v[192:193], v[146:147], v[192:193]
	v_pk_fma_f32 v[236:237], v[144:145], v[212:213], v[180:181]
	v_pk_fma_f32 v[238:239], v[144:145], v[214:215], v[192:193]
	global_store_dwordx4 v[150:151], v[236:239], off nt
	v_lshl_add_u64 v[150:151], v[150:151], 0, s[58:59]
	ds_read_b32 v141, v160 offset:928
	ds_read_b128 v[114:117], v161 offset:7424
	ds_read_b128 v[176:179], v161 offset:7440
	s_waitcnt vmcnt(25)
	s_waitcnt lgkmcnt(3)
	v_cndmask_b32_e64 v143, 0, v143, s[6:7]
	v_pk_mul_f32 v[180:181], v[26:27], v[172:173] op_sel:[0,1]
	v_pk_mul_f32 v[192:193], v[28:29], v[172:173] op_sel:[0,1]
	v_mfma_f32_16x16x4_f32 v[110:113], v143, v216, v[110:113]
	v_pk_fma_f32 v[180:181], v[30:31], v[172:173], v[180:181] op_sel_hi:[1,0,1]
	v_pk_fma_f32 v[192:193], v[32:33], v[172:173], v[192:193] op_sel_hi:[1,0,1]
	v_pk_fma_f32 v[180:181], v[22:23], v[174:175], v[180:181] op_sel_hi:[1,0,1]
	v_pk_fma_f32 v[192:193], v[24:25], v[174:175], v[192:193] op_sel_hi:[1,0,1]
	v_mfma_f32_16x16x4_f32 v[106:109], v143, v217, v[106:109]
	v_pk_fma_f32 v[180:181], v[18:19], v[174:175], v[180:181] op_sel:[0,1,0]
	v_pk_fma_f32 v[192:193], v[20:21], v[174:175], v[192:193] op_sel:[0,1,0]
	v_pk_fma_f32 v[180:181], v[14:15], v[232:233], v[180:181] op_sel_hi:[1,0,1]
	v_pk_fma_f32 v[192:193], v[16:17], v[232:233], v[192:193] op_sel_hi:[1,0,1]
	v_mfma_f32_16x16x4_f32 v[102:105], v143, v218, v[102:105]
	v_pk_fma_f32 v[180:181], v[10:11], v[232:233], v[180:181] op_sel:[0,1,0]
	v_pk_fma_f32 v[192:193], v[12:13], v[232:233], v[192:193] op_sel:[0,1,0]
	v_pk_fma_f32 v[180:181], v[6:7], v[234:235], v[180:181] op_sel_hi:[1,0,1]
	v_pk_fma_f32 v[192:193], v[8:9], v[234:235], v[192:193] op_sel_hi:[1,0,1]
	v_mfma_f32_16x16x4_f32 v[98:101], v143, v219, v[98:101]
	v_pk_fma_f32 v[180:181], v[2:3], v[234:235], v[180:181] op_sel:[0,1,0]
	v_pk_fma_f32 v[192:193], v[4:5], v[234:235], v[192:193] op_sel:[0,1,0]
	v_pk_mul_f32 v[180:181], v[146:147], v[180:181]
	v_pk_mul_f32 v[192:193], v[146:147], v[192:193]
	v_pk_fma_f32 v[236:237], v[144:145], v[216:217], v[180:181]
	v_pk_fma_f32 v[238:239], v[144:145], v[218:219], v[192:193]
	global_store_dwordx4 v[150:151], v[236:239], off nt
	v_lshl_add_u64 v[150:151], v[150:151], 0, s[58:59]
	ds_read_b32 v143, v160 offset:944
	ds_read_b128 v[172:175], v161 offset:7552
	ds_read_b128 v[232:235], v161 offset:7568
	s_waitcnt vmcnt(24)
; #define RS_LOAD(dst, it0) do { _Pragma("unroll") for (int u = 0; u < 8; ++u) dst[u] = __builtin_nontemporal_load((const f32x4*)(S0 + (size_t)(4 * ((it0) + u)) * DV)); } while (0)
; __device__ __forceinline__ void ret_sample_item(Frame& F, int item) {
;     ...
;     for (int it0 = 0; it0 < 64; it0 += 16) {
;         RS_LOAD(sb, it0 + 8);
;         RS_PROC(sa, it0);
;         { const int itn = it0 + 16 < 64 ? it0 + 16 : it0; RS_LOAD(sa, itn); }
;         RS_PROC(sb, it0 + 8);
;     }
	s_waitcnt lgkmcnt(3)
	v_cndmask_b32_e64 v141, 0, v141, s[6:7]
	v_pk_mul_f32 v[180:181], v[26:27], v[114:115] op_sel:[0,1]
	v_pk_mul_f32 v[192:193], v[28:29], v[114:115] op_sel:[0,1]
	v_mfma_f32_16x16x4_f32 v[110:113], v141, v224, v[110:113]
	v_pk_fma_f32 v[180:181], v[30:31], v[114:115], v[180:181] op_sel_hi:[1,0,1]
	v_pk_fma_f32 v[192:193], v[32:33], v[114:115], v[192:193] op_sel_hi:[1,0,1]
	v_pk_fma_f32 v[180:181], v[22:23], v[116:117], v[180:181] op_sel_hi:[1,0,1]
	v_pk_fma_f32 v[192:193], v[24:25], v[116:117], v[192:193] op_sel_hi:[1,0,1]
	v_mfma_f32_16x16x4_f32 v[106:109], v141, v225, v[106:109]
	v_pk_fma_f32 v[180:181], v[18:19], v[116:117], v[180:181] op_sel:[0,1,0]
	v_pk_fma_f32 v[192:193], v[20:21], v[116:117], v[192:193] op_sel:[0,1,0]
	v_pk_fma_f32 v[180:181], v[14:15], v[176:177], v[180:181] op_sel_hi:[1,0,1]
	v_pk_fma_f32 v[192:193], v[16:17], v[176:177], v[192:193] op_sel_hi:[1,0,1]
	v_mfma_f32_16x16x4_f32 v[102:105], v141, v226, v[102:105]
	v_pk_fma_f32 v[180:181], v[10:11], v[176:177], v[180:181] op_sel:[0,1,0]
	v_pk_fma_f32 v[192:193], v[12:13], v[176:177], v[192:193] op_sel:[0,1,0]
	v_pk_fma_f32 v[180:181], v[6:7], v[178:179], v[180:181] op_sel_hi:[1,0,1]
	v_pk_fma_f32 v[192:193], v[8:9], v[178:179], v[192:193] op_sel_hi:[1,0,1]
	v_mfma_f32_16x16x4_f32 v[98:101], v141, v227, v[98:101]
	v_pk_fma_f32 v[180:181], v[2:3], v[178:179], v[180:181] op_sel:[0,1,0]
	v_pk_fma_f32 v[192:193], v[4:5], v[178:179], v[192:193] op_sel:[0,1,0]
	v_pk_mul_f32 v[180:181], v[146:147], v[180:181]
	v_pk_mul_f32 v[192:193], v[146:147], v[192:193]
	v_pk_fma_f32 v[236:237], v[144:145], v[224:225], v[180:181]
	v_pk_fma_f32 v[238:239], v[144:145], v[226:227], v[192:193]
	global_store_dwordx4 v[150:151], v[236:239], off nt
	v_lshl_add_u64 v[150:151], v[150:151], 0, s[58:59]
	ds_read_b32 v141, v160 offset:960
	ds_read_b128 v[114:117], v161 offset:7680
	ds_read_b128 v[176:179], v161 offset:7696
	s_waitcnt vmcnt(23)
	s_waitcnt lgkmcnt(3)
	v_cndmask_b32_e64 v143, 0, v143, s[6:7]
	v_pk_mul_f32 v[180:181], v[26:27], v[172:173] op_sel:[0,1]
	v_pk_mul_f32 v[192:193], v[28:29], v[172:173] op_sel:[0,1]
	v_mfma_f32_16x16x4_f32 v[110:113], v143, v228, v[110:113]
	v_pk_fma_f32 v[180:181], v[30:31], v[172:173], v[180:181] op_sel_hi:[1,0,1]
	v_pk_fma_f32 v[192:193], v[32:33], v[172:173], v[192:193] op_sel_hi:[1,0,1]
	v_pk_fma_f32 v[180:181], v[22:23], v[174:175], v[180:181] op_sel_hi:[1,0,1]
	v_pk_fma_f32 v[192:193], v[24:25], v[174:175], v[192:193] op_sel_hi:[1,0,1]
	v_mfma_f32_16x16x4_f32 v[106:109], v143, v229, v[106:109]
	v_pk_fma_f32 v[180:181], v[18:19], v[174:175], v[180:181] op_sel:[0,1,0]
	v_pk_fma_f32 v[192:193], v[20:21], v[174:175], v[192:193] op_sel:[0,1,0]
	v_pk_fma_f32 v[180:181], v[14:15], v[232:233], v[180:181] op_sel_hi:[1,0,1]
	v_pk_fma_f32 v[192:193], v[16:17], v[232:233], v[192:193] op_sel_hi:[1,0,1]
	v_mfma_f32_16x16x4_f32 v[102:105], v143, v230, v[102:105]
	v_pk_fma_f32 v[180:181], v[10:11], v[232:233], v[180:181] op_sel:[0,1,0]
	v_pk_fma_f32 v[192:193], v[12:13], v[232:233], v[192:193] op_sel:[0,1,0]
	v_pk_fma_f32 v[180:181], v[6:7], v[234:235], v[180:181] op_sel_hi:[1,0,1]
	v_pk_fma_f32 v[192:193], v[8:9], v[234:235], v[192:193] op_sel_hi:[1,0,1]
	v_mfma_f32_16x16x4_f32 v[98:101], v143, v231, v[98:101]
	v_pk_fma_f32 v[180:181], v[2:3], v[234:235], v[180:181] op_sel:[0,1,0]
	v_pk_fma_f32 v[192:193], v[4:5], v[234:235], v[192:193] op_sel:[0,1,0]
	v_pk_mul_f32 v[180:181], v[146:147], v[180:181]
	v_pk_mul_f32 v[192:193], v[146:147], v[192:193]
	v_pk_fma_f32 v[236:237], v[144:145], v[228:229], v[180:181]
	v_pk_fma_f32 v[238:239], v[144:145], v[230:231], v[192:193]
	global_store_dwordx4 v[150:151], v[236:239], off nt
	v_lshl_add_u64 v[150:151], v[150:151], 0, s[58:59]
	ds_read_b32 v143, v160 offset:976
	ds_read_b128 v[172:175], v161 offset:7808
	ds_read_b128 v[232:235], v161 offset:7824
	s_waitcnt vmcnt(22)
	s_waitcnt lgkmcnt(3)
	v_cndmask_b32_e64 v141, 0, v141, s[6:7]
	v_pk_mul_f32 v[180:181], v[26:27], v[114:115] op_sel:[0,1]
	v_pk_mul_f32 v[192:193], v[28:29], v[114:115] op_sel:[0,1]
	v_mfma_f32_16x16x4_f32 v[110:113], v141, v70, v[110:113]
	v_pk_fma_f32 v[180:181], v[30:31], v[114:115], v[180:181] op_sel_hi:[1,0,1]
	v_pk_fma_f32 v[192:193], v[32:33], v[114:115], v[192:193] op_sel_hi:[1,0,1]
	v_pk_fma_f32 v[180:181], v[22:23], v[116:117], v[180:181] op_sel_hi:[1,0,1]
	v_pk_fma_f32 v[192:193], v[24:25], v[116:117], v[192:193] op_sel_hi:[1,0,1]
	v_mfma_f32_16x16x4_f32 v[106:109], v141, v71, v[106:109]
	v_pk_fma_f32 v[180:181], v[18:19], v[116:117], v[180:181] op_sel:[0,1,0]
	v_pk_fma_f32 v[192:193], v[20:21], v[116:117], v[192:193] op_sel:[0,1,0]
	v_pk_fma_f32 v[180:181], v[14:15], v[176:177], v[180:181] op_sel_hi:[1,0,1]
	v_pk_fma_f32 v[192:193], v[16:17], v[176:177], v[192:193] op_sel_hi:[1,0,1]
	v_mfma_f32_16x16x4_f32 v[102:105], v141, v72, v[102:105]
	v_pk_fma_f32 v[180:181], v[10:11], v[176:177], v[180:181] op_sel:[0,1,0]
	v_pk_fma_f32 v[192:193], v[12:13], v[176:177], v[192:193] op_sel:[0,1,0]
	v_pk_fma_f32 v[180:181], v[6:7], v[178:179], v[180:181] op_sel_hi:[1,0,1]
	v_pk_fma_f32 v[192:193], v[8:9], v[178:179], v[192:193] op_sel_hi:[1,0,1]
	v_mfma_f32_16x16x4_f32 v[98:101], v141, v73, v[98:101]
	v_pk_fma_f32 v[180:181], v[2:3], v[178:179], v[180:181] op_sel:[0,1,0]
	v_pk_fma_f32 v[192:193], v[4:5], v[178:179], v[192:193] op_sel:[0,1,0]
	v_pk_mul_f32 v[180:181], v[146:147], v[180:181]
	v_pk_mul_f32 v[192:193], v[146:147], v[192:193]
	v_pk_fma_f32 v[236:237], v[144:145], v[70:71], v[180:181]
	v_pk_fma_f32 v[238:239], v[144:145], v[72:73], v[192:193]
	global_store_dwordx4 v[150:151], v[236:239], off nt
	v_lshl_add_u64 v[150:151], v[150:151], 0, s[58:59]
	ds_read_b32 v141, v160 offset:992
	ds_read_b128 v[114:117], v161 offset:7936
	ds_read_b128 v[176:179], v161 offset:7952
	s_waitcnt vmcnt(21)
; #define RS_LOAD(dst, it0) do { _Pragma("unroll") for (int u = 0; u < 8; ++u) dst[u] = __builtin_nontemporal_load((const f32x4*)(S0 + (size_t)(4 * ((it0) + u)) * DV)); } while (0)
; __device__ __forceinline__ void ret_sample_item(Frame& F, int item) {
;     ...
;     for (int it0 = 0; it0 < 64; it0 += 16) {
;         RS_LOAD(sb, it0 + 8);
;         RS_PROC(sa, it0);
;         { const int itn = it0 + 16 < 64 ? it0 + 16 : it0; RS_LOAD(sa, itn); }
;         RS_PROC(sb, it0 + 8);
;     }
	s_waitcnt lgkmcnt(3)
	v_cndmask_b32_e64 v143, 0, v143, s[6:7]
	v_pk_mul_f32 v[180:181], v[26:27], v[172:173] op_sel:[0,1]
	v_pk_mul_f32 v[192:193], v[28:29], v[172:173] op_sel:[0,1]
	v_mfma_f32_16x16x4_f32 v[110:113], v143, v62, v[110:113]
	v_pk_fma_f32 v[180:181], v[30:31], v[172:173], v[180:181] op_sel_hi:[1,0,1]
	v_pk_fma_f32 v[192:193], v[32:33], v[172:173], v[192:193] op_sel_hi:[1,0,1]
	v_pk_fma_f32 v[180:181], v[22:23], v[174:175], v[180:181] op_sel_hi:[1,0,1]
	v_pk_fma_f32 v[192:193], v[24:25], v[174:175], v[192:193] op_sel_hi:[1,0,1]
	v_mfma_f32_16x16x4_f32 v[106:109], v143, v63, v[106:109]
	v_pk_fma_f32 v[180:181], v[18:19], v[174:175], v[180:181] op_sel:[0,1,0]
	v_pk_fma_f32 v[192:193], v[20:21], v[174:175], v[192:193] op_sel:[0,1,0]
	v_pk_fma_f32 v[180:181], v[14:15], v[232:233], v[180:181] op_sel_hi:[1,0,1]
	v_pk_fma_f32 v[192:193], v[16:17], v[232:233], v[192:193] op_sel_hi:[1,0,1]
	v_mfma_f32_16x16x4_f32 v[102:105], v143, v64, v[102:105]
	v_pk_fma_f32 v[180:181], v[10:11], v[232:233], v[180:181] op_sel:[0,1,0]
	v_pk_fma_f32 v[192:193], v[12:13], v[232:233], v[192:193] op_sel:[0,1,0]
	v_pk_fma_f32 v[180:181], v[6:7], v[234:235], v[180:181] op_sel_hi:[1,0,1]
	v_pk_fma_f32 v[192:193], v[8:9], v[234:235], v[192:193] op_sel_hi:[1,0,1]
	v_mfma_f32_16x16x4_f32 v[98:101], v143, v65, v[98:101]
	v_pk_fma_f32 v[180:181], v[2:3], v[234:235], v[180:181] op_sel:[0,1,0]
	v_pk_fma_f32 v[192:193], v[4:5], v[234:235], v[192:193] op_sel:[0,1,0]
	v_pk_mul_f32 v[180:181], v[146:147], v[180:181]
	v_pk_mul_f32 v[192:193], v[146:147], v[192:193]
	v_pk_fma_f32 v[236:237], v[144:145], v[62:63], v[180:181]
	v_pk_fma_f32 v[238:239], v[144:145], v[64:65], v[192:193]
	global_store_dwordx4 v[150:151], v[236:239], off nt
	v_lshl_add_u64 v[150:151], v[150:151], 0, s[58:59]
	ds_read_b32 v143, v160 offset:1008
	ds_read_b128 v[172:175], v161 offset:8064
	ds_read_b128 v[232:235], v161 offset:8080
	s_waitcnt vmcnt(20)
	s_waitcnt lgkmcnt(3)
	v_cndmask_b32_e64 v141, 0, v141, s[6:7]
	v_pk_mul_f32 v[180:181], v[26:27], v[114:115] op_sel:[0,1]
	v_pk_mul_f32 v[192:193], v[28:29], v[114:115] op_sel:[0,1]
	v_mfma_f32_16x16x4_f32 v[110:113], v141, v54, v[110:113]
	v_pk_fma_f32 v[180:181], v[30:31], v[114:115], v[180:181] op_sel_hi:[1,0,1]
	v_pk_fma_f32 v[192:193], v[32:33], v[114:115], v[192:193] op_sel_hi:[1,0,1]
	v_pk_fma_f32 v[180:181], v[22:23], v[116:117], v[180:181] op_sel_hi:[1,0,1]
	v_pk_fma_f32 v[192:193], v[24:25], v[116:117], v[192:193] op_sel_hi:[1,0,1]
	v_mfma_f32_16x16x4_f32 v[106:109], v141, v55, v[106:109]
	v_pk_fma_f32 v[180:181], v[18:19], v[116:117], v[180:181] op_sel:[0,1,0]
	v_pk_fma_f32 v[192:193], v[20:21], v[116:117], v[192:193] op_sel:[0,1,0]
	v_pk_fma_f32 v[180:181], v[14:15], v[176:177], v[180:181] op_sel_hi:[1,0,1]
	v_pk_fma_f32 v[192:193], v[16:17], v[176:177], v[192:193] op_sel_hi:[1,0,1]
	v_mfma_f32_16x16x4_f32 v[102:105], v141, v56, v[102:105]
	v_pk_fma_f32 v[180:181], v[10:11], v[176:177], v[180:181] op_sel:[0,1,0]
	v_pk_fma_f32 v[192:193], v[12:13], v[176:177], v[192:193] op_sel:[0,1,0]
	v_pk_fma_f32 v[180:181], v[6:7], v[178:179], v[180:181] op_sel_hi:[1,0,1]
	v_pk_fma_f32 v[192:193], v[8:9], v[178:179], v[192:193] op_sel_hi:[1,0,1]
	v_mfma_f32_16x16x4_f32 v[98:101], v141, v57, v[98:101]
	v_pk_fma_f32 v[180:181], v[2:3], v[178:179], v[180:181] op_sel:[0,1,0]
	v_pk_fma_f32 v[192:193], v[4:5], v[178:179], v[192:193] op_sel:[0,1,0]
	v_pk_mul_f32 v[180:181], v[146:147], v[180:181]
	v_pk_mul_f32 v[192:193], v[146:147], v[192:193]
	v_pk_fma_f32 v[236:237], v[144:145], v[54:55], v[180:181]
	v_pk_fma_f32 v[238:239], v[144:145], v[56:57], v[192:193]
	global_store_dwordx4 v[150:151], v[236:239], off nt
	v_lshl_add_u64 v[150:151], v[150:151], 0, s[58:59]
	s_waitcnt vmcnt(19)
	s_waitcnt lgkmcnt(0)
	v_cndmask_b32_e64 v143, 0, v143, s[6:7]
	v_pk_mul_f32 v[180:181], v[26:27], v[172:173] op_sel:[0,1]
	v_pk_mul_f32 v[192:193], v[28:29], v[172:173] op_sel:[0,1]
	v_mfma_f32_16x16x4_f32 v[110:113], v143, v50, v[110:113]
	v_pk_fma_f32 v[180:181], v[30:31], v[172:173], v[180:181] op_sel_hi:[1,0,1]
	v_pk_fma_f32 v[192:193], v[32:33], v[172:173], v[192:193] op_sel_hi:[1,0,1]
	v_pk_fma_f32 v[180:181], v[22:23], v[174:175], v[180:181] op_sel_hi:[1,0,1]
	v_pk_fma_f32 v[192:193], v[24:25], v[174:175], v[192:193] op_sel_hi:[1,0,1]
	v_mfma_f32_16x16x4_f32 v[106:109], v143, v51, v[106:109]
	v_pk_fma_f32 v[180:181], v[18:19], v[174:175], v[180:181] op_sel:[0,1,0]
	v_pk_fma_f32 v[192:193], v[20:21], v[174:175], v[192:193] op_sel:[0,1,0]
	v_pk_fma_f32 v[180:181], v[14:15], v[232:233], v[180:181] op_sel_hi:[1,0,1]
	v_pk_fma_f32 v[192:193], v[16:17], v[232:233], v[192:193] op_sel_hi:[1,0,1]
	v_mfma_f32_16x16x4_f32 v[102:105], v143, v52, v[102:105]
	v_pk_fma_f32 v[180:181], v[10:11], v[232:233], v[180:181] op_sel:[0,1,0]
	v_pk_fma_f32 v[192:193], v[12:13], v[232:233], v[192:193] op_sel:[0,1,0]
	v_pk_fma_f32 v[180:181], v[6:7], v[234:235], v[180:181] op_sel_hi:[1,0,1]
	v_pk_fma_f32 v[192:193], v[8:9], v[234:235], v[192:193] op_sel_hi:[1,0,1]
	v_mfma_f32_16x16x4_f32 v[98:101], v143, v53, v[98:101]
	v_pk_fma_f32 v[180:181], v[2:3], v[234:235], v[180:181] op_sel:[0,1,0]
	v_pk_fma_f32 v[192:193], v[4:5], v[234:235], v[192:193] op_sel:[0,1,0]
	v_pk_mul_f32 v[180:181], v[146:147], v[180:181]
	v_pk_mul_f32 v[192:193], v[146:147], v[192:193]
	v_pk_fma_f32 v[236:237], v[144:145], v[50:51], v[180:181]
	v_pk_fma_f32 v[238:239], v[144:145], v[52:53], v[192:193]
	global_store_dwordx4 v[150:151], v[236:239], off nt
	v_lshl_add_u64 v[150:151], v[150:151], 0, s[58:59]
	s_nop 7
	s_nop 3
	s_branch .LBB0_677
	s_nop 0
	s_nop 0
	s_nop 0
	s_nop 0
	s_nop 0
	s_nop 0
